# prologue de-serialisation (dead tile-2 loads removed, LUT load wait deferred past Q loads) + K-first DMA order with counted vmcnt(2) so V DMA stays in flight across the barrier
# baseline (speedup 1.0000x reference)
; template <int MODE>
; __device__ __forceinline__ void attn_body(const bf16_t* __restrict__ Qb, const bf16_t* __restrict__ Kh, const bf16_t* __restrict__ Vh, int NT, int krel0,
;                                           char* lds, const float* __restrict__ lutg, const AttnEpi& E) {
;     ...
;   int tid_ = threadIdx.x; asm volatile("" : "+v"(tid_));
;   const int tid = tid_, wid = tid >> 6, lane = tid & 63, r32 = lane & 31, hi = lane >> 5;
;   char* V_lds = lds; char* K_lds = lds + ATT_NBUF * SHM_V;
;   float* wsm = (float*)(lds + ATT_WS_OFF) + wid * 64; float* li_l = wsm; float* al_l = wsm + 32;
;   float* lut = (float*)(lds + ATT_LUT_OFF);
;   __syncthreads();
;   if constexpr (MODE != 0) { if (tid < 259) lut[tid] = lutg[tid]; }
;   float m_reg = -1e30f, l_reg = 0; f32x16 o[4] = {}; bf16x8 qr[ND0];
;   const bf16_t* Qw = Qb + (size_t)(wid * 32 + r32) * LDQK + hi * 8;
;   {
;     float qf[ND0][8]; float ss = 0.f;
; #pragma unroll
;     for (int d0 = 0; d0 < ND0; ++d0) { const bf16x8 raw = *reinterpret_cast<const bf16x8*>(Qw + d0 * 16);
; #pragma unroll
;       for (int j = 0; j < 8; ++j) { const float v = __uint_as_float(((unsigned)(unsigned short)raw[j]) << 16); qf[d0][j] = v; ss += v * v; } }
;     { auto rr = __builtin_amdgcn_permlane32_swap(__float_as_uint(ss), __float_as_uint(ss), false, false);
;       ss = __uint_as_float(rr[0]) + __uint_as_float(rr[1]); }
;     const float rs = rsqrtf(ss * (MODE < 2 ? (1.f / 128.f) : (1.f / 64.f)) + EPS);
; #pragma unroll
;     for (int d0 = 0; d0 < ND0; ++d0) { const f32x4 g0 = *(const f32x4*)(E.gq + d0 * 16 + hi * 8), g1 = *(const f32x4*)(E.gq + d0 * 16 + hi * 8 + 4);
; #pragma unroll
;       for (int j = 0; j < 4; ++j) { qf[d0][j] = qf[d0][j] * rs * g0[j]; qf[d0][4 + j] = qf[d0][4 + j] * rs * g1[j]; } }
;     if constexpr (MODE == 0) {
;       const int sp = krel0 + wid * 32 + r32;
; #pragma unroll
;       for (int h = 0; h < 2; ++h) { const int pos = h == 0 ? (sp >> 6) : (sp & 63);
; #pragma unroll
;         for (int a = 0; a < 2; ++a) { const float* tb = lutg + (size_t)(pos * 32 + a * 16 + hi * 8) * 2;
; #pragma unroll
;           for (int jj = 0; jj < 4; ++jj) { const f32x4 cs = *(const f32x4*)(tb + jj * 4);
.LBB0_78:
	s_lshl_b32 s64, s58, 8
	s_and_b32 s0, s93, 4
	s_add_i32 s54, s2, s64
	s_lshl_b32 s84, s0, 6
	s_and_b32 s59, s10, 7
	s_ashr_i32 s55, s54, 31
	s_mul_i32 s1, s54, 0x2400
	v_readlane_b32 s6, v252, 6
	s_mul_hi_i32 s0, s54, 0x2400
	v_readlane_b32 s7, v252, 7
	s_add_u32 s17, s6, s1
	s_addc_u32 s18, s7, s0
	s_mul_i32 s1, s2, 0x2400
	s_mul_hi_u32 s0, s2, 0x2400
	s_add_u32 s67, s6, s1
	s_addc_u32 s65, s7, s0
	v_readlane_b32 s0, v255, 7
	s_or_b32 s0, s59, s0
	s_ashr_i32 s1, s0, 31
	v_readlane_b32 s68, v254, 41
	s_lshl_b32 s63, s59, 7
	s_lshl_b64 s[0:1], s[0:1], 2
	v_readlane_b32 s70, v254, 43
	v_readlane_b32 s71, v254, 44
	s_add_u32 s0, s70, s0
	s_addc_u32 s1, s71, s1
	global_load_dword v184, v1, s[0:1]
	s_lshl_b32 s0, s59, 8
	s_add_u32 s60, s17, s0
	v_mov_b32_e32 v188, v179
	s_addc_u32 s61, s18, 0
	s_movk_i32 s6, 0xffe0
	v_ashrrev_i32_e32 v4, 1, v188
	v_bfe_u32 v164, v188, 5, 1
	v_bfi_b32 v0, s6, v4, v188
	v_mov_b64_e32 v[2:3], s[60:61]
	s_movk_i32 s56, 0x2400
	v_mad_i64_i32 v[2:3], s[0:1], v0, s56, v[2:3]
	v_lshlrev_b32_e32 v0, 4, v164
	v_lshl_add_u64 v[2:3], v[2:3], 0, v[0:1]
	s_waitcnt lgkmcnt(0)
	s_barrier
	global_load_dwordx4 v[22:25], v[2:3], off offset:160
	global_load_dwordx4 v[48:51], v[2:3], off offset:224
	global_load_dwordx4 v[124:127], v[2:3], off offset:128
	global_load_dwordx4 v[128:131], v[2:3], off offset:192
	global_load_dwordx4 v[166:169], v[2:3], off
	global_load_dwordx4 v[170:173], v[2:3], off offset:32
	global_load_dwordx4 v[174:177], v[2:3], off offset:64
	global_load_dwordx4 v[206:209], v[2:3], off offset:96
	v_and_b32_e32 v2, 32, v188
	global_load_dwordx4 v[120:123], v2, s[12:13]
	global_load_dwordx4 v[116:119], v2, s[12:13] offset:16
	global_load_dwordx4 v[112:115], v2, s[12:13] offset:64
	global_load_dwordx4 v[108:111], v2, s[12:13] offset:80
	global_load_dwordx4 v[104:107], v2, s[12:13] offset:128
	global_load_dwordx4 v[100:103], v2, s[12:13] offset:144
	global_load_dwordx4 v[96:99], v2, s[12:13] offset:192
	global_load_dwordx4 v[92:95], v2, s[12:13] offset:208
	global_load_dwordx4 v[88:91], v2, s[12:13] offset:256
	global_load_dwordx4 v[84:87], v2, s[12:13] offset:272
	global_load_dwordx4 v[80:83], v2, s[12:13] offset:320
	global_load_dwordx4 v[76:79], v2, s[12:13] offset:336
	global_load_dwordx4 v[68:71], v2, s[12:13] offset:384
	global_load_dwordx4 v[64:67], v2, s[12:13] offset:400
	global_load_dwordx4 v[60:63], v2, s[12:13] offset:448
	global_load_dwordx4 v[52:55], v2, s[12:13] offset:464
	v_and_b32_e32 v189, 31, v188
	s_lshl_b32 s0, s10, 5
	v_and_b32_e32 v204, 0xffffffe0, v4
	v_or_b32_e32 v2, s64, v189
	s_and_b32 s62, s0, 0x80
	v_add_u32_e32 v7, v2, v204
	s_lshl_b32 s0, s62, 1
	v_lshlrev_b32_e32 v6, 3, v164
	v_ashrrev_i32_e32 v2, 1, v7
	s_add_u32 s0, s67, s0
	v_and_or_b32 v2, v2, s6, v6
	s_addc_u32 s1, s65, 0
	v_and_b32_e32 v5, 0x3fffffc0, v188
	s_add_i32 s89, 0, 0x18000
	v_ashrrev_i32_e32 v3, 31, v2
	v_lshl_add_u32 v163, v5, 2, s89
	v_lshl_add_u64 v[4:5], v[2:3], 3, s[96:97]
	global_load_dwordx4 v[30:33], v[4:5], off offset:48
	global_load_dwordx4 v[38:41], v[4:5], off offset:32
	global_load_dwordx4 v[56:59], v[4:5], off offset:16
	global_load_dwordx4 v[72:75], v[4:5], off
	v_or_b32_e32 v2, 16, v2
	v_ashrrev_i32_e32 v3, 31, v2
	v_lshl_add_u64 v[2:3], v[2:3], 3, s[96:97]
	global_load_dwordx4 v[18:21], v[2:3], off offset:48
	global_load_dwordx4 v[26:29], v[2:3], off offset:32
	global_load_dwordx4 v[34:37], v[2:3], off offset:16
	global_load_dwordx4 v[42:45], v[2:3], off
	v_lshlrev_b32_e32 v2, 5, v7
	s_movk_i32 s6, 0x7e0
	v_and_or_b32 v2, v2, s6, v6
	v_lshlrev_b32_e32 v165, 3, v2
	global_load_dwordx4 v[2:5], v165, s[96:97] offset:48
	global_load_dwordx4 v[6:9], v165, s[96:97] offset:32
	global_load_dwordx4 v[10:13], v165, s[96:97] offset:16
	global_load_dwordx4 v[14:17], v165, s[96:97]
	s_movk_i32 s57, 0x1200
	v_and_b32_e32 v162, 63, v188
	s_cmp_lg_u32 0, -1
	v_readlane_b32 s69, v254, 42
	s_mov_b32 s68, 0
	v_readlane_b32 s72, v254, 45
	v_readlane_b32 s73, v254, 46
	v_readlane_b32 s74, v254, 47
	v_readlane_b32 s75, v254, 48
	v_readlane_b32 s76, v254, 49
	v_readlane_b32 s77, v254, 50
	v_readlane_b32 s78, v254, 51
	v_readlane_b32 s79, v254, 52
	v_readlane_b32 s80, v254, 53
	v_readlane_b32 s81, v254, 54
	v_readlane_b32 s82, v254, 55
	v_readlane_b32 s83, v254, 56
	s_mov_b32 s69, s68
	s_mov_b32 s70, s68
	s_mov_b32 s71, s68
	s_mov_b32 s72, s68
	s_mov_b32 s73, s68
	s_mov_b32 s74, s68
	s_mov_b32 s75, s68
	s_mov_b32 s76, s68
	s_mov_b32 s77, s68
	s_mov_b32 s78, s68
	s_mov_b32 s79, s68
	s_mov_b32 s80, s68
	s_mov_b32 s81, s68
	s_mov_b32 s82, s68
	s_mov_b32 s83, s68
	s_mov_b32 s66, 4
	s_waitcnt vmcnt(35)
	v_and_b32_e32 v147, 0xffff0000, v22
	s_waitcnt vmcnt(31)
	v_and_b32_e32 v221, 0xffff0000, v167
	v_lshlrev_b32_e32 v220, 16, v167
	v_and_b32_e32 v167, 0xffff0000, v166
	v_lshlrev_b32_e32 v146, 16, v22
	v_lshlrev_b32_e32 v166, 16, v166
	v_mul_f32_e32 v22, v167, v167
	v_and_b32_e32 v141, 0xffff0000, v23
	v_lshlrev_b32_e32 v140, 16, v23
	v_pk_fma_f32 v[22:23], v[166:167], v[166:167], v[22:23] op_sel_hi:[1,1,0]
	v_and_b32_e32 v139, 0xffff0000, v24
	v_lshlrev_b32_e32 v138, 16, v24
	v_pk_fma_f32 v[22:23], v[220:221], v[220:221], v[22:23]
	v_mul_f32_e32 v24, v221, v221
	v_and_b32_e32 v217, 0xffff0000, v169
	v_lshlrev_b32_e32 v216, 16, v169
	v_and_b32_e32 v169, 0xffff0000, v168
	v_lshlrev_b32_e32 v168, 16, v168
	v_pk_add_f32 v[22:23], v[24:25], v[22:23] op_sel_hi:[0,1]
	v_pk_fma_f32 v[22:23], v[168:169], v[168:169], v[22:23]
	v_mul_f32_e32 v24, v169, v169
	v_pk_add_f32 v[22:23], v[24:25], v[22:23] op_sel_hi:[0,1]
	v_pk_fma_f32 v[22:23], v[216:217], v[216:217], v[22:23]
	v_mul_f32_e32 v24, v217, v217
	s_waitcnt vmcnt(30)
; template <int MODE>
; __device__ __forceinline__ void attn_body(const bf16_t* __restrict__ Qb, const bf16_t* __restrict__ Kh, const bf16_t* __restrict__ Vh, int NT, int krel0,
;                                           char* lds, const float* __restrict__ lutg, const AttnEpi& E) {
;     ...
;     float qf[ND0][8]; float ss = 0.f;
; #pragma unroll
;     for (int d0 = 0; d0 < ND0; ++d0) { const bf16x8 raw = *reinterpret_cast<const bf16x8*>(Qw + d0 * 16);
; #pragma unroll
;       for (int j = 0; j < 8; ++j) { const float v = __uint_as_float(((unsigned)(unsigned short)raw[j]) << 16); qf[d0][j] = v; ss += v * v; } }
;     { auto rr = __builtin_amdgcn_permlane32_swap(__float_as_uint(ss), __float_as_uint(ss), false, false);
;       ss = __uint_as_float(rr[0]) + __uint_as_float(rr[1]); }
;     const float rs = rsqrtf(ss * (MODE < 2 ? (1.f / 128.f) : (1.f / 64.f)) + EPS);
; #pragma unroll
;     for (int d0 = 0; d0 < ND0; ++d0) { const f32x4 g0 = *(const f32x4*)(E.gq + d0 * 16 + hi * 8), g1 = *(const f32x4*)(E.gq + d0 * 16 + hi * 8 + 4);
	v_and_b32_e32 v213, 0xffff0000, v171
	v_lshlrev_b32_e32 v212, 16, v171
	v_and_b32_e32 v171, 0xffff0000, v170
	v_lshlrev_b32_e32 v170, 16, v170
	v_pk_add_f32 v[22:23], v[24:25], v[22:23] op_sel_hi:[0,1]
	v_pk_fma_f32 v[22:23], v[170:171], v[170:171], v[22:23]
	v_mul_f32_e32 v24, v171, v171
	v_pk_add_f32 v[22:23], v[24:25], v[22:23] op_sel_hi:[0,1]
	v_pk_fma_f32 v[22:23], v[212:213], v[212:213], v[22:23]
	v_mul_f32_e32 v24, v213, v213
	v_and_b32_e32 v191, 0xffff0000, v173
	v_lshlrev_b32_e32 v190, 16, v173
	v_and_b32_e32 v173, 0xffff0000, v172
	v_lshlrev_b32_e32 v172, 16, v172
	v_pk_add_f32 v[22:23], v[24:25], v[22:23] op_sel_hi:[0,1]
	v_pk_fma_f32 v[22:23], v[172:173], v[172:173], v[22:23]
	v_mul_f32_e32 v24, v173, v173
	v_pk_add_f32 v[22:23], v[24:25], v[22:23] op_sel_hi:[0,1]
	v_pk_fma_f32 v[22:23], v[190:191], v[190:191], v[22:23]
	v_mul_f32_e32 v24, v191, v191
	s_waitcnt vmcnt(29)
	v_and_b32_e32 v223, 0xffff0000, v175
	v_lshlrev_b32_e32 v222, 16, v175
	v_and_b32_e32 v175, 0xffff0000, v174
	v_lshlrev_b32_e32 v174, 16, v174
	v_pk_add_f32 v[22:23], v[24:25], v[22:23] op_sel_hi:[0,1]
	v_pk_fma_f32 v[22:23], v[174:175], v[174:175], v[22:23]
	v_mul_f32_e32 v24, v175, v175
	v_pk_add_f32 v[22:23], v[24:25], v[22:23] op_sel_hi:[0,1]
	v_pk_fma_f32 v[22:23], v[222:223], v[222:223], v[22:23]
	v_mul_f32_e32 v24, v223, v223
	v_and_b32_e32 v219, 0xffff0000, v177
	v_lshlrev_b32_e32 v218, 16, v177
	v_and_b32_e32 v177, 0xffff0000, v176
	v_lshlrev_b32_e32 v176, 16, v176
	v_pk_add_f32 v[22:23], v[24:25], v[22:23] op_sel_hi:[0,1]
	v_pk_fma_f32 v[22:23], v[176:177], v[176:177], v[22:23]
	v_mul_f32_e32 v24, v177, v177
	v_pk_add_f32 v[22:23], v[24:25], v[22:23] op_sel_hi:[0,1]
	v_pk_fma_f32 v[22:23], v[218:219], v[218:219], v[22:23]
	v_mul_f32_e32 v24, v219, v219
	s_waitcnt vmcnt(28)
	v_and_b32_e32 v215, 0xffff0000, v207
	v_lshlrev_b32_e32 v214, 16, v207
	v_and_b32_e32 v207, 0xffff0000, v206
	v_lshlrev_b32_e32 v206, 16, v206
	v_pk_add_f32 v[22:23], v[24:25], v[22:23] op_sel_hi:[0,1]
	v_pk_fma_f32 v[22:23], v[206:207], v[206:207], v[22:23]
	v_mul_f32_e32 v24, v207, v207
	v_pk_add_f32 v[22:23], v[24:25], v[22:23] op_sel_hi:[0,1]
	v_pk_fma_f32 v[22:23], v[214:215], v[214:215], v[22:23]
	v_mul_f32_e32 v24, v215, v215
	v_and_b32_e32 v211, 0xffff0000, v209
	v_lshlrev_b32_e32 v210, 16, v209
	v_and_b32_e32 v209, 0xffff0000, v208
	v_lshlrev_b32_e32 v208, 16, v208
	v_pk_add_f32 v[22:23], v[24:25], v[22:23] op_sel_hi:[0,1]
	v_pk_fma_f32 v[22:23], v[208:209], v[208:209], v[22:23]
	v_mul_f32_e32 v24, v209, v209
	v_pk_add_f32 v[22:23], v[24:25], v[22:23] op_sel_hi:[0,1]
	v_pk_fma_f32 v[22:23], v[210:211], v[210:211], v[22:23]
	v_mul_f32_e32 v24, v211, v211
	v_and_b32_e32 v161, 0xffff0000, v124
	v_lshlrev_b32_e32 v160, 16, v124
	v_pk_add_f32 v[22:23], v[24:25], v[22:23] op_sel_hi:[0,1]
	v_pk_fma_f32 v[22:23], v[160:161], v[160:161], v[22:23]
	v_mul_f32_e32 v24, v161, v161
	v_and_b32_e32 v157, 0xffff0000, v125
	v_lshlrev_b32_e32 v156, 16, v125
	v_pk_add_f32 v[22:23], v[24:25], v[22:23] op_sel_hi:[0,1]
	v_pk_fma_f32 v[22:23], v[156:157], v[156:157], v[22:23]
	v_mul_f32_e32 v24, v157, v157
	v_and_b32_e32 v155, 0xffff0000, v126
	v_lshlrev_b32_e32 v154, 16, v126
	v_pk_add_f32 v[22:23], v[24:25], v[22:23] op_sel_hi:[0,1]
	v_pk_fma_f32 v[22:23], v[154:155], v[154:155], v[22:23]
	v_mul_f32_e32 v24, v155, v155
	v_and_b32_e32 v149, 0xffff0000, v127
	v_lshlrev_b32_e32 v148, 16, v127
	v_pk_add_f32 v[22:23], v[24:25], v[22:23] op_sel_hi:[0,1]
	v_pk_fma_f32 v[22:23], v[148:149], v[148:149], v[22:23]
	v_mul_f32_e32 v24, v149, v149
	v_pk_add_f32 v[22:23], v[24:25], v[22:23] op_sel_hi:[0,1]
	v_pk_fma_f32 v[22:23], v[146:147], v[146:147], v[22:23]
	v_mul_f32_e32 v24, v147, v147
	v_pk_add_f32 v[22:23], v[24:25], v[22:23] op_sel_hi:[0,1]
	v_pk_fma_f32 v[22:23], v[140:141], v[140:141], v[22:23]
	v_mul_f32_e32 v24, v141, v141
	v_pk_add_f32 v[22:23], v[24:25], v[22:23] op_sel_hi:[0,1]
	v_pk_fma_f32 v[22:23], v[138:139], v[138:139], v[22:23]
	v_mul_f32_e32 v24, v139, v139
	v_and_b32_e32 v133, 0xffff0000, v25
	v_lshlrev_b32_e32 v132, 16, v25
	v_pk_add_f32 v[22:23], v[24:25], v[22:23] op_sel_hi:[0,1]
	v_pk_fma_f32 v[22:23], v[132:133], v[132:133], v[22:23]
	v_mul_f32_e32 v24, v133, v133
	v_and_b32_e32 v159, 0xffff0000, v128
	v_lshlrev_b32_e32 v158, 16, v128
	v_pk_add_f32 v[22:23], v[24:25], v[22:23] op_sel_hi:[0,1]
	v_pk_fma_f32 v[22:23], v[158:159], v[158:159], v[22:23]
	v_mul_f32_e32 v24, v159, v159
	v_and_b32_e32 v153, 0xffff0000, v129
	v_lshlrev_b32_e32 v152, 16, v129
	v_pk_add_f32 v[22:23], v[24:25], v[22:23] op_sel_hi:[0,1]
	v_pk_fma_f32 v[22:23], v[152:153], v[152:153], v[22:23]
	v_mul_f32_e32 v24, v153, v153
	v_and_b32_e32 v151, 0xffff0000, v130
	v_lshlrev_b32_e32 v150, 16, v130
	v_pk_add_f32 v[22:23], v[24:25], v[22:23] op_sel_hi:[0,1]
	v_pk_fma_f32 v[22:23], v[150:151], v[150:151], v[22:23]
	v_mul_f32_e32 v24, v151, v151
	v_and_b32_e32 v145, 0xffff0000, v131
	v_lshlrev_b32_e32 v144, 16, v131
	v_pk_add_f32 v[22:23], v[24:25], v[22:23] op_sel_hi:[0,1]
	v_pk_fma_f32 v[22:23], v[144:145], v[144:145], v[22:23]
	v_mul_f32_e32 v24, v145, v145
	v_and_b32_e32 v143, 0xffff0000, v48
	v_lshlrev_b32_e32 v142, 16, v48
	v_pk_add_f32 v[22:23], v[24:25], v[22:23] op_sel_hi:[0,1]
	v_pk_fma_f32 v[22:23], v[142:143], v[142:143], v[22:23]
	v_mul_f32_e32 v24, v143, v143
	v_and_b32_e32 v137, 0xffff0000, v49
	v_lshlrev_b32_e32 v136, 16, v49
	v_pk_add_f32 v[22:23], v[24:25], v[22:23] op_sel_hi:[0,1]
	v_pk_fma_f32 v[22:23], v[136:137], v[136:137], v[22:23]
	v_mul_f32_e32 v24, v137, v137
	v_and_b32_e32 v135, 0xffff0000, v50
	v_lshlrev_b32_e32 v134, 16, v50
	v_pk_add_f32 v[22:23], v[24:25], v[22:23] op_sel_hi:[0,1]
	v_pk_fma_f32 v[22:23], v[134:135], v[134:135], v[22:23]
	v_mul_f32_e32 v24, v135, v135
	v_and_b32_e32 v47, 0xffff0000, v51
	v_lshlrev_b32_e32 v46, 16, v51
	v_pk_add_f32 v[22:23], v[24:25], v[22:23] op_sel_hi:[0,1]
	v_pk_fma_f32 v[22:23], v[46:47], v[46:47], v[22:23]
	v_mul_f32_e32 v24, v47, v47
	v_pk_add_f32 v[22:23], v[24:25], v[22:23] op_sel_hi:[0,1]
	v_mov_b32_e32 v23, v22
	s_nop 1
	v_permlane32_swap_b32_e32 v22, v23
	v_add_f32_e32 v22, v22, v23
	v_fmamk_f32 v22, v22, 0x3c000000, v178
	v_mul_f32_e32 v23, 0x4b800000, v22
	v_cmp_gt_f32_e32 vcc, s49, v22
	s_nop 1
	v_cndmask_b32_e32 v22, v22, v23, vcc
	v_rsq_f32_e32 v205, v22
	global_load_dwordx4 v[22:25], v165, s[96:97] offset:176
	global_load_dwordx4 v[48:51], v165, s[96:97] offset:160
	global_load_dwordx4 v[124:127], v165, s[96:97] offset:144
	global_load_dwordx4 v[128:131], v165, s[96:97] offset:128
	v_mul_f32_e32 v165, 0x45800000, v205
	v_cndmask_b32_e32 v224, v205, v165, vcc
	v_pk_mul_f32 v[166:167], v[224:225], v[166:167] op_sel_hi:[0,1]
	s_waitcnt vmcnt(31)
; template <int MODE>
; __device__ __forceinline__ void attn_body(const bf16_t* __restrict__ Qb, const bf16_t* __restrict__ Kh, const bf16_t* __restrict__ Vh, int NT, int krel0,
;                                           char* lds, const float* __restrict__ lutg, const AttnEpi& E) {
;     ...
;     const float rs = rsqrtf(ss * (MODE < 2 ? (1.f / 128.f) : (1.f / 64.f)) + EPS);
; #pragma unroll
;     for (int d0 = 0; d0 < ND0; ++d0) { const f32x4 g0 = *(const f32x4*)(E.gq + d0 * 16 + hi * 8), g1 = *(const f32x4*)(E.gq + d0 * 16 + hi * 8 + 4);
; #pragma unroll
;       for (int j = 0; j < 4; ++j) { qf[d0][j] = qf[d0][j] * rs * g0[j]; qf[d0][4 + j] = qf[d0][4 + j] * rs * g1[j]; } }
;     if constexpr (MODE == 0) {
;       const int sp = krel0 + wid * 32 + r32;
; #pragma unroll
;       for (int h = 0; h < 2; ++h) { const int pos = h == 0 ? (sp >> 6) : (sp & 63);
; #pragma unroll
;         for (int a = 0; a < 2; ++a) { const float* tb = lutg + (size_t)(pos * 32 + a * 16 + hi * 8) * 2;
; #pragma unroll
;           for (int jj = 0; jj < 4; ++jj) { const f32x4 cs = *(const f32x4*)(tb + jj * 4);
; #pragma unroll
;             for (int e = 0; e < 2; ++e) { const int j = 2 * jj + e; const float c = cs[2 * e], sn = cs[2 * e + 1];
;               const float x1 = qf[4 * h + a][j], x2 = qf[4 * h + 2 + a][j];
;               qf[4 * h + a][j] = x1 * c - x2 * sn; qf[4 * h + 2 + a][j] = x2 * c + x1 * sn; } } } }
	v_pk_mul_f32 v[120:121], v[120:121], v[166:167]
	v_pk_mul_f32 v[166:167], v[224:225], v[168:169] op_sel_hi:[0,1]
	s_waitcnt vmcnt(30)
	v_pk_mul_f32 v[116:117], v[116:117], v[166:167]
	v_pk_mul_f32 v[166:167], v[224:225], v[220:221] op_sel_hi:[0,1]
	v_pk_mul_f32 v[122:123], v[122:123], v[166:167]
	v_pk_mul_f32 v[166:167], v[224:225], v[216:217] op_sel_hi:[0,1]
	v_pk_mul_f32 v[118:119], v[118:119], v[166:167]
	v_pk_mul_f32 v[166:167], v[224:225], v[170:171] op_sel_hi:[0,1]
	s_waitcnt vmcnt(29)
	v_pk_mul_f32 v[112:113], v[112:113], v[166:167]
	v_pk_mul_f32 v[166:167], v[224:225], v[172:173] op_sel_hi:[0,1]
	s_waitcnt vmcnt(28)
	v_pk_mul_f32 v[108:109], v[108:109], v[166:167]
	v_pk_mul_f32 v[166:167], v[224:225], v[212:213] op_sel_hi:[0,1]
	v_pk_mul_f32 v[114:115], v[114:115], v[166:167]
	v_pk_mul_f32 v[166:167], v[224:225], v[190:191] op_sel_hi:[0,1]
	v_pk_mul_f32 v[110:111], v[110:111], v[166:167]
	v_pk_mul_f32 v[166:167], v[224:225], v[174:175] op_sel_hi:[0,1]
	s_waitcnt vmcnt(27)
	v_pk_mul_f32 v[166:167], v[104:105], v[166:167]
	v_pk_mul_f32 v[104:105], v[224:225], v[176:177] op_sel_hi:[0,1]
	s_waitcnt vmcnt(26)
	v_pk_mul_f32 v[168:169], v[100:101], v[104:105]
	v_pk_mul_f32 v[100:101], v[224:225], v[222:223] op_sel_hi:[0,1]
	v_pk_mul_f32 v[106:107], v[106:107], v[100:101]
	v_pk_mul_f32 v[100:101], v[224:225], v[218:219] op_sel_hi:[0,1]
	v_pk_mul_f32 v[170:171], v[102:103], v[100:101]
	v_pk_mul_f32 v[100:101], v[224:225], v[206:207] op_sel_hi:[0,1]
	s_waitcnt vmcnt(25)
	v_pk_mul_f32 v[96:97], v[96:97], v[100:101]
	v_pk_mul_f32 v[100:101], v[224:225], v[208:209] op_sel_hi:[0,1]
	s_waitcnt vmcnt(24)
	v_pk_mul_f32 v[172:173], v[92:93], v[100:101]
	v_pk_mul_f32 v[92:93], v[224:225], v[214:215] op_sel_hi:[0,1]
	v_pk_mul_f32 v[174:175], v[98:99], v[92:93]
	v_pk_mul_f32 v[92:93], v[224:225], v[210:211] op_sel_hi:[0,1]
	v_pk_mul_f32 v[176:177], v[94:95], v[92:93]
	v_pk_mul_f32 v[92:93], v[224:225], v[160:161] op_sel_hi:[0,1]
	s_waitcnt vmcnt(23)
	v_pk_mul_f32 v[160:161], v[88:89], v[92:93]
	v_pk_mul_f32 v[88:89], v[224:225], v[154:155] op_sel_hi:[0,1]
	s_waitcnt vmcnt(22)
	v_pk_mul_f32 v[102:103], v[84:85], v[88:89]
	v_pk_mul_f32 v[84:85], v[224:225], v[156:157] op_sel_hi:[0,1]
	v_pk_mul_f32 v[104:105], v[90:91], v[84:85]
	v_pk_mul_f32 v[84:85], v[224:225], v[148:149] op_sel_hi:[0,1]
	v_pk_mul_f32 v[100:101], v[86:87], v[84:85]
	v_pk_mul_f32 v[84:85], v[224:225], v[146:147] op_sel_hi:[0,1]
	s_waitcnt vmcnt(21)
	v_pk_mul_f32 v[98:99], v[84:85], v[80:81]
	v_pk_mul_f32 v[80:81], v[224:225], v[138:139] op_sel_hi:[0,1]
	s_waitcnt vmcnt(20)
	v_pk_mul_f32 v[80:81], v[80:81], v[76:77]
	v_pk_mul_f32 v[76:77], v[224:225], v[140:141] op_sel_hi:[0,1]
	v_pk_mul_f32 v[86:87], v[76:77], v[82:83]
	v_pk_mul_f32 v[76:77], v[224:225], v[132:133] op_sel_hi:[0,1]
	v_pk_mul_f32 v[76:77], v[76:77], v[78:79]
	v_pk_mul_f32 v[78:79], v[224:225], v[158:159] op_sel_hi:[0,1]
	s_waitcnt vmcnt(19)
	v_pk_mul_f32 v[132:133], v[78:79], v[68:69]
	v_pk_mul_f32 v[68:69], v[224:225], v[150:151] op_sel_hi:[0,1]
	s_waitcnt vmcnt(18)
	v_pk_mul_f32 v[64:65], v[68:69], v[64:65]
	v_pk_mul_f32 v[68:69], v[224:225], v[152:153] op_sel_hi:[0,1]
	v_pk_mul_f32 v[138:139], v[68:69], v[70:71]
	v_pk_mul_f32 v[68:69], v[224:225], v[144:145] op_sel_hi:[0,1]
	v_pk_mul_f32 v[66:67], v[68:69], v[66:67]
	v_pk_mul_f32 v[68:69], v[224:225], v[142:143] op_sel_hi:[0,1]
	s_waitcnt vmcnt(17)
	v_pk_mul_f32 v[60:61], v[68:69], v[60:61]
	v_pk_mul_f32 v[68:69], v[224:225], v[134:135] op_sel_hi:[0,1]
	s_waitcnt vmcnt(16)
	v_pk_mul_f32 v[78:79], v[68:69], v[52:53]
	v_pk_mul_f32 v[52:53], v[224:225], v[136:137] op_sel_hi:[0,1]
	v_pk_mul_f32 v[90:91], v[52:53], v[62:63]
	v_pk_mul_f32 v[46:47], v[224:225], v[46:47] op_sel_hi:[0,1]
	s_waitcnt vmcnt(12)
	v_mov_b32_e32 v53, v74
	v_mov_b32_e32 v74, v73
	v_pk_mul_f32 v[70:71], v[46:47], v[54:55]
	v_mov_b32_e32 v52, v72
	v_pk_mul_f32 v[46:47], v[166:167], v[74:75]
	v_ashrrev_i32_e32 v68, 4, v188
	v_pk_fma_f32 v[46:47], v[120:121], v[52:53], v[46:47] neg_lo:[0,0,1] neg_hi:[0,0,1]
	v_pk_mul_f32 v[52:53], v[166:167], v[52:53]
	v_add_u32_e32 v69, 32, v68
	v_pk_fma_f32 v[72:73], v[120:121], v[74:75], v[52:53]
	v_mov_b32_e32 v53, v58
	v_mov_b32_e32 v58, v57
	v_mov_b32_e32 v52, v56
	v_pk_mul_f32 v[54:55], v[106:107], v[58:59]
	v_lshlrev_b32_e32 v56, 3, v188
	v_pk_fma_f32 v[94:95], v[122:123], v[52:53], v[54:55] neg_lo:[0,0,1] neg_hi:[0,0,1]
	v_pk_mul_f32 v[52:53], v[106:107], v[52:53]
	v_and_b32_e32 v144, 0x78, v56
	v_pk_fma_f32 v[74:75], v[122:123], v[58:59], v[52:53]
	v_mov_b32_e32 v53, v40
	v_mov_b32_e32 v40, v39
	v_mov_b32_e32 v52, v38
	v_pk_mul_f32 v[38:39], v[168:169], v[40:41]
	v_lshlrev_b32_e32 v145, 4, v188
	v_pk_fma_f32 v[38:39], v[116:117], v[52:53], v[38:39] neg_lo:[0,0,1] neg_hi:[0,0,1]
	v_pk_mul_f32 v[52:53], v[168:169], v[52:53]
	v_lshlrev_b32_e32 v148, 8, v189
	v_pk_fma_f32 v[82:83], v[116:117], v[40:41], v[52:53]
	v_mov_b32_e32 v53, v32
	v_mov_b32_e32 v32, v31
	v_mov_b32_e32 v52, v30
	v_pk_mul_f32 v[30:31], v[170:171], v[32:33]
	v_and_b32_e32 v149, 0xf0, v145
	v_pk_fma_f32 v[40:41], v[118:119], v[52:53], v[30:31] neg_lo:[0,0,1] neg_hi:[0,0,1]
	v_pk_mul_f32 v[30:31], v[170:171], v[52:53]
	v_bitop3_b32 v214, v0, v148, v149 bitop3:0xde
	v_pk_fma_f32 v[84:85], v[118:119], v[32:33], v[30:31]
	s_waitcnt vmcnt(8)
; __device__ __forceinline__ unsigned cvtpk(float lo, float hi) { f32x2 v = {lo, hi}; bf16v2 b = __builtin_convertvector(v, bf16v2); return __builtin_bit_cast(unsigned, b); }
; __device__ __forceinline__ int v_st(int k, int c) { const int kk = (k & ~0xC) | ((k & 4) << 1) | ((k & 8) >> 1); return ((kk >> 3) * 4 + (c >> 5)) * 512 + ((kk & 7) * 32 + (c & 31)) * 2; }
; __device__ __forceinline__ int v_rd_base(int lane) { return ((lane & 3) << 3) | (((lane >> 2) & 3) << 6) | (((lane >> 4) & 1) << 5) | (((lane >> 5) & 1) << 8); }
; #define SWRITE(off, i) do { *(bf16x8*)(V_lds + (off) + vst0) = sr_[i].vs0;          \
;     *(bf16x8*)(V_lds + (off) + vst1) = sr_[i].vs1; int kc = sc * 2;               \
;     *(bf16x8*)(K_lds + (off) + KSWZ(sr, kc)) = sr_[i].ks0;                       \
;     *(bf16x8*)(K_lds + (off) + KSWZ(32 + sr, kc)) = sr_[i].ks1; } while (0)
; template <int MODE>
; __device__ __forceinline__ void attn_body(const bf16_t* __restrict__ Qb, const bf16_t* __restrict__ Kh, const bf16_t* __restrict__ Vh, int NT, int krel0,
;                                           char* lds, const float* __restrict__ lutg, const AttnEpi& E) {
;     ...
;           for (int jj = 0; jj < 4; ++jj) { const f32x4 cs = *(const f32x4*)(tb + jj * 4);
; #pragma unroll
;             for (int e = 0; e < 2; ++e) { const int j = 2 * jj + e; const float c = cs[2 * e], sn = cs[2 * e + 1];
;               const float x1 = qf[4 * h + a][j], x2 = qf[4 * h + 2 + a][j];
;               qf[4 * h + a][j] = x1 * c - x2 * sn; qf[4 * h + 2 + a][j] = x2 * c + x1 * sn; } } } }
;     }
; #pragma unroll
;     for (int d0 = 0; d0 < ND0; ++d0) { u32x4 w; w.x = cvtpk(qf[d0][0], qf[d0][1]); w.y = cvtpk(qf[d0][2], qf[d0][3]); w.z = cvtpk(qf[d0][4], qf[d0][5]); w.w = cvtpk(qf[d0][6], qf[d0][7]);
;       qr[d0] = *reinterpret_cast<bf16x8*>(&w); }
;   }
;   const int sr = tid >> 4, sc = (tid & 15) * 8, vst0 = v_st(sr, sc), vst1 = v_st(32 + sr, sc);
;   const int vb0 = (int)(uintptr_t)V_lds + v_rd_base(lane);
;   struct { bf16x8 vs0, vs1, ks0, ks1; } sr_[2];
;     ...
;   const int relq = krel0 - (wid * 32 + r32) + 4 * hi, relwmin = krel0 - (wid * 32 + 31), relwmax = krel0 + 63 - wid * 32;
;     ...
;   f32x16 pA0, pA1, pB0, pB1; float mnA, mnB, alA, alB; bf16x8 pa0, pa1, pa2, pa3;
;   constexpr int SE = 0, SO = 1;
;   SLOAD(SE, 0); SLOAD(SO, 64); asm volatile("s_waitcnt vmcnt(4)" ::: "memory"); SWRITE(0, SE); __syncthreads();
	v_mov_b32_e32 v31, v44
	v_mov_b32_e32 v44, v43
	v_mov_b32_e32 v30, v42
	v_pk_mul_f32 v[32:33], v[96:97], v[44:45]
	v_mad_i64_i32 v[42:43], s[6:7], v69, s57, 0
	v_pk_fma_f32 v[88:89], v[112:113], v[30:31], v[32:33] neg_lo:[0,0,1] neg_hi:[0,0,1]
	v_mov_b32_e32 v33, v36
	v_mov_b32_e32 v36, v35
	v_mov_b32_e32 v32, v34
	v_pk_mul_f32 v[34:35], v[174:175], v[36:37]
	v_pk_mul_f32 v[30:31], v[96:97], v[30:31]
	v_pk_fma_f32 v[92:93], v[114:115], v[32:33], v[34:35] neg_lo:[0,0,1] neg_hi:[0,0,1]
	v_mov_b32_e32 v35, v28
	v_mov_b32_e32 v28, v27
	v_mov_b32_e32 v34, v26
	v_pk_mul_f32 v[26:27], v[172:173], v[28:29]
	v_or_b32_e32 v42, v42, v144
	v_pk_fma_f32 v[96:97], v[108:109], v[34:35], v[26:27] neg_lo:[0,0,1] neg_hi:[0,0,1]
	v_pk_mul_f32 v[26:27], v[172:173], v[34:35]
	v_mov_b32_e32 v35, v20
	v_mov_b32_e32 v20, v19
	v_mov_b32_e32 v34, v18
	v_pk_mul_f32 v[18:19], v[176:177], v[20:21]
	v_pk_fma_f32 v[26:27], v[108:109], v[28:29], v[26:27]
	v_pk_fma_f32 v[28:29], v[110:111], v[34:35], v[18:19] neg_lo:[0,0,1] neg_hi:[0,0,1]
	v_pk_mul_f32 v[18:19], v[176:177], v[34:35]
	v_pk_mul_f32 v[32:33], v[174:175], v[32:33]
	v_pk_fma_f32 v[18:19], v[110:111], v[20:21], v[18:19]
	s_waitcnt vmcnt(4)
	v_mov_b32_e32 v20, v14
	v_mov_b32_e32 v21, v16
	v_mov_b32_e32 v16, v15
	v_mad_i64_i32 v[14:15], s[6:7], v68, s57, 0
	v_or_b32_e32 v14, v14, v144
	v_pk_mul_f32 v[54:55], v[132:133], v[16:17]
	v_lshl_add_u64 v[14:15], v[14:15], 1, s[0:1]
	v_lshl_add_u64 v[52:53], v[42:43], 1, s[0:1]
	v_pk_fma_f32 v[110:111], v[160:161], v[20:21], v[54:55] neg_lo:[0,0,1] neg_hi:[0,0,1]
	v_pk_mul_f32 v[20:21], v[132:133], v[20:21]
	v_pk_fma_f32 v[30:31], v[112:113], v[44:45], v[30:31]
	v_pk_fma_f32 v[32:33], v[114:115], v[36:37], v[32:33]
	global_load_dwordx4 v[34:37], v[14:15], off offset:2560
	global_load_dwordx4 v[42:45], v[52:53], off offset:2560
	v_pk_fma_f32 v[132:133], v[160:161], v[16:17], v[20:21]
	global_load_dwordx4 v[14:17], v[14:15], off offset:2048
	v_mov_b32_e32 v21, v12
	global_load_dwordx4 v[106:109], v[52:53], off offset:2048
	v_mov_b32_e32 v12, v11
	v_mov_b32_e32 v20, v10
	v_pk_mul_f32 v[10:11], v[138:139], v[12:13]
	v_cvt_pk_bf16_f32 v116, v38, v39
	v_pk_fma_f32 v[112:113], v[104:105], v[20:21], v[10:11] neg_lo:[0,0,1] neg_hi:[0,0,1]
	v_pk_mul_f32 v[10:11], v[138:139], v[20:21]
	v_or_b32_e32 v38, 32, v0
	v_pk_fma_f32 v[104:105], v[104:105], v[12:13], v[10:11]
	v_mov_b32_e32 v11, v8
	v_mov_b32_e32 v8, v7
	v_mov_b32_e32 v10, v6
	v_pk_mul_f32 v[6:7], v[64:65], v[8:9]
	s_waitcnt vmcnt(6)
	v_mov_b32_e32 v21, v50
	v_pk_fma_f32 v[134:135], v[102:103], v[10:11], v[6:7] neg_lo:[0,0,1] neg_hi:[0,0,1]
	v_pk_mul_f32 v[6:7], v[64:65], v[10:11]
	v_mov_b32_e32 v50, v49
	v_pk_fma_f32 v[136:137], v[102:103], v[8:9], v[6:7]
	v_mov_b32_e32 v7, v4
	v_mov_b32_e32 v4, v3
	v_mov_b32_e32 v6, v2
	v_pk_mul_f32 v[2:3], v[66:67], v[4:5]
	v_lshlrev_b32_e32 v8, 1, v144
	v_pk_fma_f32 v[102:103], v[100:101], v[6:7], v[2:3] neg_lo:[0,0,1] neg_hi:[0,0,1]
	v_pk_mul_f32 v[2:3], v[66:67], v[6:7]
	s_waitcnt vmcnt(5)
	v_mov_b32_e32 v7, v126
	v_pk_fma_f32 v[138:139], v[100:101], v[4:5], v[2:3]
	s_waitcnt vmcnt(4)
	v_mov_b32_e32 v3, v130
	v_mov_b32_e32 v130, v129
	v_mov_b32_e32 v2, v128
	v_pk_mul_f32 v[4:5], v[60:61], v[130:131]
	v_mov_b32_e32 v126, v125
	v_pk_fma_f32 v[140:141], v[98:99], v[2:3], v[4:5] neg_lo:[0,0,1] neg_hi:[0,0,1]
	v_pk_mul_f32 v[2:3], v[60:61], v[2:3]
	v_mov_b32_e32 v6, v124
	v_pk_fma_f32 v[130:131], v[98:99], v[130:131], v[2:3]
	v_pk_mul_f32 v[2:3], v[90:91], v[126:127]
	v_bfe_u32 v4, v56, 5, 2
	v_pk_fma_f32 v[142:143], v[86:87], v[6:7], v[2:3] neg_lo:[0,0,1] neg_hi:[0,0,1]
	v_and_b32_e32 v2, 0xfffff0, v68
	v_lshlrev_b32_e32 v3, 1, v68
	v_and_or_b32 v2, v3, 8, v2
	v_lshrrev_b32_e32 v3, 1, v68
	v_lshrrev_b32_e32 v2, 1, v2
	v_and_b32_e32 v5, 3, v68
	v_or_b32_e32 v2, v2, v4
	v_and_or_b32 v3, v3, 4, v5
	v_lshlrev_b32_e32 v2, 9, v2
	v_lshlrev_b32_e32 v3, 6, v3
	v_and_b32_e32 v5, 48, v8
	v_or3_b32 v210, v2, v3, v5
	v_and_b32_e32 v2, 0xfffff0, v69
	v_lshlrev_b32_e32 v9, 1, v69
	v_and_or_b32 v2, v9, 8, v2
	v_lshrrev_b32_e32 v2, 1, v2
	v_or_b32_e32 v2, v2, v4
	v_lshlrev_b32_e32 v2, 9, v2
	v_or3_b32 v211, v2, v3, v5
	v_add_u32_e32 v2, 64, v68
	v_mad_i64_i32 v[2:3], s[6:7], v2, s57, 0
	v_add_u32_e32 v4, 0x60, v68
	v_or_b32_e32 v2, v2, v144
	v_mad_i64_i32 v[4:5], s[6:7], v4, s57, 0
	v_lshl_add_u64 v[2:3], v[2:3], 1, s[0:1]
	v_or_b32_e32 v4, v4, v144
	v_lshl_add_u64 v[4:5], v[4:5], 1, s[0:1]
	global_load_dwordx4 v[60:63], v[2:3], off offset:2560
	global_load_dwordx4 v[52:55], v[2:3], off offset:2048
	global_load_dwordx4 v[64:67], v[4:5], off offset:2560
	global_load_dwordx4 v[56:59], v[4:5], off offset:2048
	v_lshlrev_b32_e32 v2, 8, v68
	v_and_b32_e32 v3, 0xf0, v188
	v_bitop3_b32 v212, v8, v2, v3 bitop3:0xde
	v_add_u32_e32 v146, 0, v210
	v_add_u32_e32 v147, 0, v211
	v_add_u32_e32 v2, 0, v212
	s_waitcnt vmcnt(4)
	s_waitcnt vmcnt(7)
	ds_write_b128 v146, v[34:37]
	s_waitcnt vmcnt(6)
	ds_write_b128 v147, v[42:45]
	s_waitcnt vmcnt(5)
	ds_write_b128 v2, v[14:17] offset:49152
	v_lshlrev_b32_e32 v2, 8, v69
	v_bitop3_b32 v213, v8, v2, v3 bitop3:0xde
	v_add_u32_e32 v2, 0, v213
	v_add_u32_e32 v8, 0, v214
	s_waitcnt vmcnt(4)
	ds_write_b128 v2, v[106:109] offset:49152
	s_waitcnt lgkmcnt(0)
	s_barrier
; __device__ __forceinline__ unsigned cvtpk(float lo, float hi) { f32x2 v = {lo, hi}; bf16v2 b = __builtin_convertvector(v, bf16v2); return __builtin_bit_cast(unsigned, b); }
; template <int ND0, int DOFF>
; __device__ __forceinline__ void qkt(f32x16& p0, f32x16& p1, const char* Ks, const bf16x8* qr, int r32, int hi) {
;   p0 = f32x16{}; p1 = f32x16{};
; #pragma unroll
;   for (int d0 = 0; d0 < ND0; ++d0) { const int cb = ((d0 + DOFF) * 16 + hi * 8) * 2;
;     bf16x8 b0 = *reinterpret_cast<const bf16x8*>(Ks + KSWZ(r32, cb));
;     bf16x8 b1 = *reinterpret_cast<const bf16x8*>(Ks + KSWZ(32 + r32, cb));
;     p0 = __builtin_amdgcn_mfma_f32_32x32x16_bf16(b0, qr[d0], p0, 0, 0, 0);
;     p1 = __builtin_amdgcn_mfma_f32_32x32x16_bf16(b1, qr[d0], p1, 0, 0, 0); }
; }
; template <int MODE>
; __device__ __forceinline__ void attn_body(const bf16_t* __restrict__ Qb, const bf16_t* __restrict__ Kh, const bf16_t* __restrict__ Vh, int NT, int krel0,
;                                           char* lds, const float* __restrict__ lutg, const AttnEpi& E) {
;     ...
;     for (int d0 = 0; d0 < ND0; ++d0) { u32x4 w; w.x = cvtpk(qf[d0][0], qf[d0][1]); w.y = cvtpk(qf[d0][2], qf[d0][3]); w.z = cvtpk(qf[d0][4], qf[d0][5]); w.w = cvtpk(qf[d0][6], qf[d0][7]);
;       qr[d0] = *reinterpret_cast<bf16x8*>(&w); }
	ds_read_b128 v[2:5], v8 offset:49152
	ds_read_b128 v[34:37], v8 offset:57344
	v_pk_mul_f32 v[6:7], v[90:91], v[6:7]
	v_bitop3_b32 v218, v38, v148, v149 bitop3:0xde
	v_pk_fma_f32 v[90:91], v[86:87], v[126:127], v[6:7]
	v_mov_b32_e32 v20, v48
	v_pk_mul_f32 v[86:87], v[78:79], v[50:51]
	v_add_u32_e32 v69, 0, v218
	v_cvt_pk_bf16_f32 v114, v46, v47
	v_cvt_pk_bf16_f32 v115, v94, v95
	v_cvt_pk_bf16_f32 v117, v40, v41
	v_pk_fma_f32 v[94:95], v[80:81], v[20:21], v[86:87] neg_lo:[0,0,1] neg_hi:[0,0,1]
	v_cvt_pk_bf16_f32 v126, v88, v89
	ds_read_b128 v[86:89], v69 offset:57344
	s_waitcnt lgkmcnt(1)
	v_mfma_f32_32x32x16_bf16 v[34:49], v[34:37], v[114:117], 0
	ds_read_b128 v[98:101], v69 offset:49152
	v_mul_f32_e64 v20, v78, v20
	v_mul_f32_e64 v21, v79, v21
	v_cvt_pk_bf16_f32 v127, v92, v93
	v_cvt_pk_bf16_f32 v128, v96, v97
	v_cvt_pk_bf16_f32 v129, v28, v29
	v_pk_fma_f32 v[28:29], v[80:81], v[50:51], v[20:21]
	v_mov_b32_e32 v51, v24
	v_mfma_f32_32x32x16_bf16 v[2:17], v[2:5], v[114:117], 0
	v_mov_b32_e32 v24, v23
	v_mov_b32_e32 v50, v22
	v_or_b32_e32 v20, 64, v0
	v_cvt_pk_bf16_f32 v119, v74, v75
	v_bitop3_b32 v219, v20, v148, v149 bitop3:0xde
	v_add_u32_e32 v20, 0, v219
	ds_read_b128 v[78:81], v20 offset:49152
	s_waitcnt lgkmcnt(2)
	v_mfma_f32_32x32x16_bf16 v[34:49], v[86:89], v[126:129], v[34:49]
	v_mul_f32_e64 v86, v70, v24
	v_mul_f32_e64 v87, v71, v25
	v_cvt_pk_bf16_f32 v118, v72, v73
	v_fma_f32 v74, v76, v50, -v86
	v_fma_f32 v75, v77, v51, -v87
	v_pk_mul_f32 v[50:51], v[70:71], v[50:51]
	v_cvt_pk_bf16_f32 v120, v82, v83
	v_pk_fma_f32 v[50:51], v[76:77], v[24:25], v[50:51]
	v_or_b32_e32 v24, 0x60, v0
	v_bitop3_b32 v216, v24, v148, v149 bitop3:0xde
	v_add_u32_e32 v24, 0, v216
	ds_read_b128 v[70:73], v24 offset:49152
	ds_read_b128 v[20:23], v20 offset:57344
	s_waitcnt lgkmcnt(3)
	v_mfma_f32_32x32x16_bf16 v[2:17], v[98:101], v[126:129], v[2:17]
	v_cvt_pk_bf16_f32 v121, v84, v85
	v_cvt_pk_bf16_f32 v124, v26, v27
	v_cvt_pk_bf16_f32 v122, v30, v31
	v_cvt_pk_bf16_f32 v123, v32, v33
	v_cvt_pk_bf16_f32 v125, v18, v19
	v_cvt_pk_bf16_f32 v110, v110, v111
	v_cvt_pk_bf16_f32 v111, v112, v113
	s_waitcnt lgkmcnt(2)
	v_mfma_f32_32x32x16_bf16 v[2:17], v[78:81], v[118:121], v[2:17]
	v_cvt_pk_bf16_f32 v112, v134, v135
	v_cvt_pk_bf16_f32 v113, v102, v103
	v_cvt_pk_bf16_f32 v106, v140, v141
	v_cvt_pk_bf16_f32 v107, v142, v143
	v_cvt_pk_bf16_f32 v108, v94, v95
	v_cvt_pk_bf16_f32 v109, v74, v75
	v_cvt_pk_bf16_f32 v100, v28, v29
	s_waitcnt lgkmcnt(0)
	v_mfma_f32_32x32x16_bf16 v[34:49], v[20:23], v[118:121], v[34:49]
	v_or_b32_e32 v22, 0x80, v0
	v_bitop3_b32 v217, v22, v148, v149 bitop3:0xde
	v_add_u32_e32 v26, 0, v217
	ds_read_b128 v[18:21], v24 offset:57344
	ds_read_b128 v[22:25], v26 offset:49152
	v_lshlrev_b32_e32 v27, 3, v162
	v_lshlrev_b32_e32 v29, 1, v188
	v_mfma_f32_32x32x16_bf16 v[2:17], v[70:73], v[122:125], v[2:17]
	v_cvt_pk_bf16_f32 v102, v132, v133
	v_cvt_pk_bf16_f32 v103, v104, v105
	v_cvt_pk_bf16_f32 v104, v136, v137
	v_cvt_pk_bf16_f32 v105, v138, v139
	s_cselect_b32 s6, 0, 0
	v_cvt_pk_bf16_f32 v98, v130, v131
	v_cvt_pk_bf16_f32 v99, v90, v91
	s_waitcnt lgkmcnt(1)
	v_mfma_f32_32x32x16_bf16 v[34:49], v[18:21], v[122:125], v[34:49]
	ds_read_b128 v[18:21], v26 offset:57344
	v_cvt_pk_bf16_f32 v101, v50, v51
	v_lshlrev_b32_e32 v205, 2, v164
	v_ashrrev_i32_e32 v69, 31, v68
	v_lshl_add_u32 v206, v189, 2, v163
	v_mov_b32_e32 v207, 0
	s_waitcnt lgkmcnt(1)
	v_mfma_f32_32x32x16_bf16 v[2:17], v[22:25], v[110:113], v[2:17]
	v_or_b32_e32 v22, 0xa0, v0
	v_bitop3_b32 v215, v22, v148, v149 bitop3:0xde
	v_add_u32_e32 v26, 0, v215
	ds_read_b128 v[22:25], v26 offset:49152
	s_waitcnt lgkmcnt(1)
	v_mfma_f32_32x32x16_bf16 v[34:49], v[18:21], v[110:113], v[34:49]
	v_and_b32_e32 v18, 0xc0, v145
	v_and_or_b32 v28, v27, 24, v18
	ds_read_b128 v[18:21], v26 offset:57344
	s_waitcnt lgkmcnt(1)
	v_mfma_f32_32x32x16_bf16 v[2:17], v[22:25], v[106:109], v[2:17]
	v_and_b32_e32 v22, 32, v29
	v_and_b32_e32 v23, 0x100, v27
	v_or3_b32 v26, v28, v22, v23
	v_or_b32_e32 v22, 0xc0, v0
	v_bitop3_b32 v220, v22, v148, v149 bitop3:0xde
	v_add_u32_e32 v27, 0, v220
	ds_read_b128 v[22:25], v27 offset:49152
	s_waitcnt lgkmcnt(1)
	v_mfma_f32_32x32x16_bf16 v[34:49], v[18:21], v[106:109], v[34:49]
	ds_read_b128 v[18:21], v27 offset:57344
	v_add_u32_e32 v209, s6, v26
	s_waitcnt lgkmcnt(1)
	v_mfma_f32_32x32x16_bf16 v[2:17], v[22:25], v[102:105], v[2:17]
	v_or_b32_e32 v22, 0xe0, v0
	v_bitop3_b32 v221, v22, v148, v149 bitop3:0xde
	v_add_u32_e32 v26, 0, v221
	ds_read_b128 v[22:25], v26 offset:49152
	ds_read_b128 v[70:73], v26 offset:57344
	v_add_u32_e32 v0, v163, v0
	s_waitcnt lgkmcnt(1)
	v_mfma_f32_32x32x16_bf16 v[2:17], v[22:25], v[98:101], v[2:17]
	v_mfma_f32_32x32x16_bf16 v[34:49], v[18:21], v[102:105], v[34:49]
	s_nop 10
	v_max_f32_e32 v50, v3, v3
	v_max_f32_e32 v51, v2, v2
	v_max_f32_e32 v50, v51, v50
	v_max3_f32 v50, v50, v4, v5
	v_max3_f32 v50, v50, v6, v7
	v_max3_f32 v50, v50, v8, v9
	v_max3_f32 v50, v50, v10, v11
	s_waitcnt lgkmcnt(0)
; #define SLOAD(i, k0) do { sr_[i].vs0 = *reinterpret_cast<const bf16x8*>(&Vh[(size_t)((k0) + sr) * LDQK + sc]); sr_[i].vs1 = *reinterpret_cast<const bf16x8*>(&Vh[(size_t)((k0) + 32 + sr) * LDQK + sc]); \
;     sr_[i].ks0 = *reinterpret_cast<const bf16x8*>(&Kh[(size_t)((k0) + sr) * LDQK + sc]); sr_[i].ks1 = *reinterpret_cast<const bf16x8*>(&Kh[(size_t)((k0) + 32 + sr) * LDQK + sc]); } while (0)
; #define SWRITE(off, i) do { *(bf16x8*)(V_lds + (off) + vst0) = sr_[i].vs0;          \
;     *(bf16x8*)(V_lds + (off) + vst1) = sr_[i].vs1; int kc = sc * 2;               \
;     *(bf16x8*)(K_lds + (off) + KSWZ(sr, kc)) = sr_[i].ks0;                       \
;     *(bf16x8*)(K_lds + (off) + KSWZ(32 + sr, kc)) = sr_[i].ks1; } while (0)
; template <int MODE>
; __device__ __forceinline__ void partialSM(f32x16& p0, f32x16& p1, float& m_reg, float& mn, float& alpha, int relh, int relw_min, int relw_max, const float* lut) {
;     ...
;     float pmax = p0[0];
; #pragma unroll
;     for (int r = 1; r < 16; ++r) pmax = fmaxf(pmax, p0[r]);
; #pragma unroll
;     for (int r = 0; r < 16; ++r) pmax = fmaxf(pmax, p1[r]);
;     { auto rr = __builtin_amdgcn_permlane32_swap(__float_as_uint(pmax), __float_as_uint(pmax), false, false);
;       pmax = fmaxf(__uint_as_float(rr[0]), __uint_as_float(rr[1])); }
;     if (__builtin_expect(__all(pmax - m_reg <= THR / SCALE), 1)) { mn = m_reg; alpha = 1.f; }
;     else { mn = fmaxf(m_reg, pmax); alpha = __builtin_amdgcn_exp2f((m_reg - mn) * C); m_reg = mn; }
;     const float mnC = -mn * C;
; #pragma unroll
;     for (int r = 0; r < 16; ++r) p0[r] = fmaf(p0[r], C, mnC);
; #pragma unroll
;     for (int r = 0; r < 16; ++r) p1[r] = fmaf(p1[r], C, mnC);
; #pragma unroll
;     for (int r = 0; r < 16; ++r) p0[r] = __builtin_amdgcn_exp2f(p0[r]);
; template <int MODE>
; __device__ __forceinline__ void attn_body(const bf16_t* __restrict__ Qb, const bf16_t* __restrict__ Kh, const bf16_t* __restrict__ Vh, int NT, int krel0,
;                                           char* lds, const float* __restrict__ lutg, const AttnEpi& E) {
;     ...
;   SLOAD(SE, 0); SLOAD(SO, 64); asm volatile("s_waitcnt vmcnt(4)" ::: "memory"); SWRITE(0, SE); __syncthreads();
;   qkt<ND0, DOFF>(pA0, pA1, K_lds, qr, r32, hi); PSM(pA0, pA1, mnA, alA, 0);
;   if (2 < NT) SLOAD(SE, 2 * 64);
;   SWAIT(); SWRITE(SHM_V, SO);
;   int op = 0, oq = SHM_V, ow = 2 * SHM_V;
	v_mfma_f32_32x32x16_bf16 v[34:49], v[70:73], v[98:101], v[34:49]
	v_max3_f32 v50, v50, v12, v13
	v_max3_f32 v50, v50, v14, v15
	v_max3_f32 v50, v50, v16, v17
	v_add_u32_e32 v70, 0x80, v68
	v_mad_i64_i32 v[70:71], s[6:7], v70, s57, 0
	v_or_b32_e32 v70, v70, v144
	s_nop 5
	v_max3_f32 v50, v50, v34, v35
	v_max3_f32 v50, v50, v36, v37
	v_max3_f32 v50, v50, v38, v39
	v_max3_f32 v50, v50, v40, v41
	v_max3_f32 v50, v50, v42, v43
	v_max3_f32 v50, v50, v44, v45
	v_max3_f32 v50, v50, v46, v47
	v_max3_f32 v72, v50, v48, v49
	v_mov_b32_e32 v50, v72
	s_nop 1
	v_permlane32_swap_b32_e32 v72, v50
	v_max_f32_e32 v73, v50, v50
	v_add_u32_e32 v50, 0xa0, v68
	v_mad_i64_i32 v[50:51], s[6:7], v50, s57, 0
	v_or_b32_e32 v50, v50, v144
	v_lshl_add_u64 v[50:51], v[50:51], 1, s[0:1]
	v_lshl_add_u64 v[70:71], v[70:71], 1, s[0:1]
	v_max_f32_e32 v50, v72, v72
	v_max_f32_e32 v50, v50, v73
	v_mov_b64_e32 v[18:19], s[68:69]
	v_add_f32_e32 v51, 0x7149f2ca, v50
	v_mov_b64_e32 v[20:21], s[70:71]
	v_mov_b64_e32 v[22:23], s[72:73]
	v_mov_b64_e32 v[24:25], s[74:75]
	v_mov_b64_e32 v[26:27], s[76:77]
	v_mov_b64_e32 v[28:29], s[78:79]
	v_mov_b64_e32 v[30:31], s[80:81]
	v_mov_b64_e32 v[32:33], s[82:83]
	v_cmp_ge_f32_e32 vcc, s40, v51
	s_add_i32 s75, 0, 0x10000
	s_add_i32 s70, s11, -1
	s_cmp_eq_u64 vcc, exec
	v_add_u32_e32 v51, s75, v212
	v_max_f32_e32 v50, 0xf149f2ca, v50
	s_cselect_b64 vcc, -1, 0
	s_waitcnt vmcnt(0)
	s_waitcnt vmcnt(3)
	ds_write_b128 v146, v[60:63] offset:16384
	s_waitcnt vmcnt(1)
	ds_write_b128 v147, v[64:67] offset:16384
	ds_write_b128 v51, v[52:55]
	v_add_u32_e32 v51, s75, v213
	v_cndmask_b32_e32 v166, v50, v197, vcc
	v_readlane_b32 s19, v255, 20
	s_nop 3
	v_mov_b32_e32 v166, s19
	s_waitcnt vmcnt(0)
	ds_write_b128 v51, v[56:59]
	v_sub_f32_e32 v51, 0xf149f2ca, v50
	v_mul_f32_e32 v50, 0xbe0293ee, v166
	v_fmamk_f32 v2, v2, 0x3e0293ee, v50
	v_exp_f32_e32 v164, v2
	v_fmamk_f32 v2, v3, 0x3e0293ee, v50
	v_exp_f32_e32 v165, v2
	v_fmamk_f32 v2, v4, 0x3e0293ee, v50
	v_exp_f32_e32 v175, v2
	v_fmamk_f32 v2, v5, 0x3e0293ee, v50
	v_exp_f32_e32 v177, v2
	v_fmamk_f32 v2, v6, 0x3e0293ee, v50
	v_exp_f32_e32 v227, v2
	v_fmamk_f32 v2, v7, 0x3e0293ee, v50
	v_exp_f32_e32 v228, v2
	v_fmamk_f32 v2, v8, 0x3e0293ee, v50
	v_exp_f32_e32 v176, v2
	v_fmamk_f32 v2, v9, 0x3e0293ee, v50
	v_exp_f32_e32 v226, v2
	v_fmamk_f32 v2, v10, 0x3e0293ee, v50
	v_exp_f32_e32 v167, v2
	v_fmamk_f32 v2, v11, 0x3e0293ee, v50
	v_exp_f32_e32 v169, v2
	v_fmamk_f32 v2, v12, 0x3e0293ee, v50
	v_mul_f32_e32 v51, 0x3e0293ee, v51
	v_exp_f32_e32 v171, v2
	v_fmamk_f32 v2, v13, 0x3e0293ee, v50
	v_exp_f32_e32 v51, v51
	v_exp_f32_e32 v173, v2
	v_fmamk_f32 v2, v14, 0x3e0293ee, v50
	v_exp_f32_e32 v168, v2
	v_fmamk_f32 v2, v15, 0x3e0293ee, v50
	v_exp_f32_e32 v170, v2
	v_fmamk_f32 v2, v16, 0x3e0293ee, v50
	v_exp_f32_e32 v172, v2
	v_lshl_add_u64 v[2:3], v[68:69], 0, s[2:3]
	v_pk_fma_f32 v[146:147], v[48:49], s[38:39], v[50:51] op_sel_hi:[1,0,0]
	v_pk_fma_f32 v[148:149], v[46:47], s[38:39], v[50:51] op_sel_hi:[1,0,0]
	v_pk_fma_f32 v[150:151], v[44:45], s[38:39], v[50:51] op_sel_hi:[1,0,0]
	v_pk_fma_f32 v[152:153], v[42:43], s[38:39], v[50:51] op_sel_hi:[1,0,0]
	v_pk_fma_f32 v[154:155], v[40:41], s[38:39], v[50:51] op_sel_hi:[1,0,0]
	v_pk_fma_f32 v[156:157], v[38:39], s[38:39], v[50:51] op_sel_hi:[1,0,0]
	v_pk_fma_f32 v[158:159], v[36:37], s[38:39], v[50:51] op_sel_hi:[1,0,0]
	v_pk_fma_f32 v[160:161], v[34:35], s[38:39], v[50:51] op_sel_hi:[1,0,0]
	v_fmac_f32_e32 v50, 0x3e0293ee, v17
	v_mad_u64_u32 v[4:5], s[0:1], v2, s56, 0
	v_and_b32_e32 v2, 15, v188
	s_mov_b32 s82, s84
	v_exp_f32_e32 v174, v50
	v_lshlrev_b32_e32 v2, 4, v2
	v_readlane_b32 s0, v254, 10
	v_mad_i32_i24 v3, v3, s56, v5
	v_or3_b32 v2, v4, s82, v2
	v_readlane_b32 s1, v254, 11
	v_cndmask_b32_e64 v222, v51, 1.0, vcc
	v_mov_b64_e32 v[64:65], v[32:33]
	v_lshl_add_u64 v[190:191], s[0:1], 0, v[2:3]
	v_mov_b64_e32 v[48:49], v[32:33]
	v_mov_b64_e32 v[2:3], v[18:19]
	s_mov_b64 s[86:87], s[22:23]
	v_cmp_gt_u32_e64 s[6:7], 32, v162
	s_movk_i32 s73, 0x2400
	s_movk_i32 s71, 0x4000
	s_mov_b32 s0, 0x8000
	v_mov_b64_e32 v[62:63], v[30:31]
	v_mov_b64_e32 v[60:61], v[28:29]
	v_mov_b64_e32 v[58:59], v[26:27]
	v_mov_b64_e32 v[56:57], v[24:25]
	v_mov_b64_e32 v[54:55], v[22:23]
	v_mov_b64_e32 v[52:53], v[20:21]
	v_mov_b64_e32 v[50:51], v[18:19]
	v_mov_b64_e32 v[46:47], v[30:31]
	v_mov_b64_e32 v[44:45], v[28:29]
	v_mov_b64_e32 v[42:43], v[26:27]
	v_mov_b64_e32 v[40:41], v[24:25]
	v_mov_b64_e32 v[38:39], v[22:23]
	v_mov_b64_e32 v[36:37], v[20:21]
	v_mov_b64_e32 v[34:35], v[18:19]
	v_mov_b64_e32 v[4:5], v[20:21]
	v_mov_b64_e32 v[6:7], v[22:23]
	v_mov_b64_e32 v[8:9], v[24:25]
	v_mov_b64_e32 v[10:11], v[26:27]
	v_mov_b64_e32 v[12:13], v[28:29]
	v_mov_b64_e32 v[14:15], v[30:31]
	v_mov_b64_e32 v[16:17], v[32:33]
	s_mov_b64 s[84:85], s[20:21]
	v_readlane_b32 s74, v254, 57
	s_waitcnt vmcnt(0)
	v_readfirstlane_b32 s31, v179
	s_nop 3
	s_lshr_b32 s31, s31, 6
	s_lshl_b32 s30, s31, 11
	v_and_b32_e32 v134, 63, v179
	v_bfe_u32 v135, v134, 2, 3
	s_lshl_b32 s29, s31, 3
	v_or_b32_e32 v135, s29, v135
	v_and_b32_e32 v136, 4, v135
	v_lshlrev_b32_e32 v136, 1, v136
	v_and_b32_e32 v137, 8, v135
	v_lshrrev_b32_e32 v137, 1, v137
	v_and_b32_e32 v135, 0xfffffff3, v135
	v_or3_b32 v135, v135, v136, v137
	v_mul_u32_u24_e32 v135, 0x2400, v135
	v_lshrrev_b32_e32 v136, 5, v134
	v_lshlrev_b32_e32 v136, 6, v136
	v_and_b32_e32 v137, 3, v134
	v_lshlrev_b32_e32 v137, 4, v137
	v_add3_u32 v130, v135, v136, v137
	v_add_u32_e32 v131, 0x80, v130
	v_lshrrev_b32_e32 v135, 4, v134
	v_add_u32_e32 v135, s29, v135
	v_and_b32_e32 v136, 15, v134
	v_and_b32_e32 v137, 15, v135
	v_xor_b32_e32 v137, v136, v137
	v_mul_u32_u24_e32 v138, 0x2400, v135
	v_lshl_add_u32 v132, v137, 4, v138
	v_add_u32_e32 v135, 4, v135
	v_and_b32_e32 v137, 15, v135
	v_xor_b32_e32 v137, v136, v137
	v_mul_u32_u24_e32 v138, 0x2400, v135
	v_lshl_add_u32 v133, v137, 4, v138
	v_readfirstlane_b32 s26, v190
	v_readfirstlane_b32 s27, v191
	s_mul_i32 s29, s31, 0x9000
	s_add_u32 s29, s29, 0x168000
	s_sub_u32 s26, s26, s29
	s_subb_u32 s27, s27, 0
	s_sub_u32 s28, s26, 0x200
	s_subb_u32 s29, s27, 0
; #define SBAR() __builtin_amdgcn_sched_barrier(0)
; #define SLOAD(i, k0) do { sr_[i].vs0 = *reinterpret_cast<const bf16x8*>(&Vh[(size_t)((k0) + sr) * LDQK + sc]); sr_[i].vs1 = *reinterpret_cast<const bf16x8*>(&Vh[(size_t)((k0) + 32 + sr) * LDQK + sc]); \
;     sr_[i].ks0 = *reinterpret_cast<const bf16x8*>(&Kh[(size_t)((k0) + sr) * LDQK + sc]); sr_[i].ks1 = *reinterpret_cast<const bf16x8*>(&Kh[(size_t)((k0) + 32 + sr) * LDQK + sc]); } while (0)
; #define PSM(P0, P1, MN, AL, J) partialSM<MODE>(P0, P1, m_reg, MN, AL, relq + 64 * (J), relwmin + 64 * (J), relwmax + 64 * (J), lut)
; __device__ __forceinline__ void finishSM(f32x16& p0, f32x16& p1, float alpha, float& l_reg, bf16x8& pa0, bf16x8& pa1, bf16x8& pa2, bf16x8& pa3) {
; #pragma unroll
;   for (int r = 0; r < 16; ++r) p1[r] = __builtin_amdgcn_exp2f(p1[r]);
;   float ps = 0;
; #pragma unroll
;   for (int r = 0; r < 16; ++r) ps += p0[r];
; #pragma unroll
;   for (int r = 0; r < 16; ++r) ps += p1[r];
;   { auto rr = __builtin_amdgcn_permlane32_swap(__float_as_uint(ps), __float_as_uint(ps), false, false);
;     ps = __uint_as_float(rr[0]) + __uint_as_float(rr[1]); }
;   l_reg = l_reg * alpha + ps;
;     ...
;   PK4(p0, 0, pa0); PK4(p0, 8, pa1); PK4(p1, 0, pa2); PK4(p1, 8, pa3);
; template <int MODE>
; __device__ __forceinline__ void attn_body(const bf16_t* __restrict__ Qb, const bf16_t* __restrict__ Kh, const bf16_t* __restrict__ Vh, int NT, int krel0,
;                                           char* lds, const float* __restrict__ lutg, const AttnEpi& E) {
;     ...
;   for (int j = 1; j + 1 < NT; j += 2) {
;     __syncthreads();
;     SBAR(); qkt<ND0, DOFF>(pB0, pB1, K_lds + oq, qr, r32, hi);
;     finishSM(pA0, pA1, alA, l_reg, pa0, pa1, pa2, pa3); SBAR();
;     SLOAD(SO, (j + 2) * 64); SBAR();
;     pv_d0(o, vb0 + op, pa0, pa1, pa2, pa3); PSM(pB0, pB1, mnB, alB, j);
.LBB0_79:
	s_mov_b32 s69, s0
	s_waitcnt vmcnt(2) lgkmcnt(0)
	s_barrier
	s_add_i32 s0, s71, 0
	v_add_u32_e32 v70, s0, v214
	ds_read_b128 v[66:69], v70 offset:49152
	ds_read_b128 v[70:73], v70 offset:57344
	v_add_u32_e32 v162, s0, v218
	ds_read_b128 v[230:233], v162 offset:49152
	ds_read_b128 v[234:237], v162 offset:57344
	v_add_u32_e32 v162, s0, v219
	s_waitcnt lgkmcnt(3)
	v_mfma_f32_32x32x16_bf16 v[82:97], v[66:69], v[114:117], 0
	v_exp_f32_e32 v160, v160
	v_exp_f32_e32 v161, v161
	v_exp_f32_e32 v158, v158
	v_exp_f32_e32 v159, v159
	v_exp_f32_e32 v156, v156
	v_exp_f32_e32 v157, v157
	v_exp_f32_e32 v154, v154
	s_waitcnt lgkmcnt(2)
	v_mfma_f32_32x32x16_bf16 v[66:81], v[70:73], v[114:117], 0
	v_exp_f32_e32 v155, v155
	v_exp_f32_e32 v152, v152
	v_exp_f32_e32 v153, v153
	v_exp_f32_e32 v150, v150
	v_exp_f32_e32 v151, v151
	v_exp_f32_e32 v148, v148
	v_exp_f32_e32 v149, v149
	s_waitcnt lgkmcnt(1)
	v_mfma_f32_32x32x16_bf16 v[82:97], v[230:233], v[126:129], v[82:97]
	v_exp_f32_e32 v146, v146
	v_exp_f32_e32 v147, v147
	v_cvt_pk_bf16_f32 v163, v175, v177
	v_cvt_pk_bf16_f32 v229, v172, v174
	s_waitcnt lgkmcnt(0)
	v_mfma_f32_32x32x16_bf16 v[66:81], v[234:237], v[126:129], v[66:81]
	ds_read_b128 v[230:233], v162 offset:49152
	ds_read_b128 v[234:237], v162 offset:57344
	v_add_u32_e32 v162, s0, v216
	s_waitcnt lgkmcnt(1)
	v_mfma_f32_32x32x16_bf16 v[82:97], v[230:233], v[118:121], v[82:97]
	s_waitcnt lgkmcnt(0)
	v_mfma_f32_32x32x16_bf16 v[66:81], v[234:237], v[118:121], v[66:81]
	ds_read_b128 v[230:233], v162 offset:49152
	ds_read_b128 v[234:237], v162 offset:57344
	v_add_u32_e32 v162, s0, v217
	s_waitcnt lgkmcnt(1)
	v_mfma_f32_32x32x16_bf16 v[82:97], v[230:233], v[122:125], v[82:97]
	s_waitcnt lgkmcnt(0)
	v_mfma_f32_32x32x16_bf16 v[66:81], v[234:237], v[122:125], v[66:81]
	ds_read_b128 v[230:233], v162 offset:49152
	ds_read_b128 v[234:237], v162 offset:57344
	v_add_u32_e32 v162, s0, v215
	s_waitcnt lgkmcnt(1)
	v_mfma_f32_32x32x16_bf16 v[82:97], v[230:233], v[110:113], v[82:97]
	s_waitcnt lgkmcnt(0)
	v_mfma_f32_32x32x16_bf16 v[66:81], v[234:237], v[110:113], v[66:81]
	ds_read_b128 v[230:233], v162 offset:49152
	ds_read_b128 v[234:237], v162 offset:57344
	v_add_u32_e32 v162, s0, v220
	s_waitcnt lgkmcnt(1)
	v_mfma_f32_32x32x16_bf16 v[82:97], v[230:233], v[106:109], v[82:97]
	s_waitcnt lgkmcnt(0)
	v_mfma_f32_32x32x16_bf16 v[66:81], v[234:237], v[106:109], v[66:81]
	ds_read_b128 v[230:233], v162 offset:49152
	ds_read_b128 v[234:237], v162 offset:57344
	v_add_u32_e32 v162, s0, v221
	s_waitcnt lgkmcnt(1)
	v_mfma_f32_32x32x16_bf16 v[82:97], v[230:233], v[102:105], v[82:97]
	s_waitcnt lgkmcnt(0)
	v_mfma_f32_32x32x16_bf16 v[66:81], v[234:237], v[102:105], v[66:81]
	ds_read_b128 v[230:233], v162 offset:49152
	ds_read_b128 v[234:237], v162 offset:57344
	v_add_f32_e32 v162, v165, v164
	v_add_f32_e32 v162, v175, v162
	v_add_f32_e32 v162, v177, v162
	v_add_f32_e32 v162, v227, v162
	v_add_f32_e32 v162, v228, v162
	v_add_f32_e32 v162, v176, v162
	v_add_f32_e32 v162, v226, v162
	v_add_f32_e32 v162, v167, v162
	v_add_f32_e32 v162, v169, v162
	v_add_f32_e32 v162, v171, v162
	v_add_f32_e32 v162, v173, v162
	v_add_f32_e32 v162, v168, v162
	v_add_f32_e32 v162, v170, v162
	v_add_f32_e32 v162, v172, v162
	v_add_f32_e32 v162, v174, v162
	v_add_f32_e32 v162, v160, v162
	v_add_f32_e32 v162, v161, v162
	v_add_f32_e32 v162, v158, v162
	v_add_f32_e32 v162, v159, v162
	v_add_f32_e32 v162, v156, v162
	v_add_f32_e32 v162, v157, v162
	v_add_f32_e32 v162, v154, v162
	v_add_f32_e32 v162, v155, v162
	v_add_f32_e32 v162, v152, v162
	v_add_f32_e32 v162, v153, v162
	s_waitcnt lgkmcnt(1)
	v_mfma_f32_32x32x16_bf16 v[82:97], v[230:233], v[98:101], v[82:97]
	v_add_f32_e32 v162, v150, v162
	v_add_f32_e32 v162, v151, v162
	v_add_f32_e32 v162, v148, v162
	v_add_f32_e32 v162, v149, v162
	v_add_f32_e32 v162, v146, v162
	v_add_f32_e32 v223, v147, v162
	v_mov_b32_e32 v224, v223
	s_waitcnt lgkmcnt(0)
	v_mfma_f32_32x32x16_bf16 v[66:81], v[234:237], v[98:101], v[66:81]
	v_cvt_pk_bf16_f32 v162, v164, v165
	v_cvt_pk_bf16_f32 v164, v227, v228
	v_permlane32_swap_b32_e32 v223, v224
	v_cvt_pk_bf16_f32 v165, v176, v226
	v_permlane32_swap_b32_e32 v162, v164
	v_cvt_pk_bf16_f32 v226, v167, v169
	v_cvt_pk_bf16_f32 v227, v171, v173
	v_cvt_pk_bf16_f32 v228, v168, v170
	v_cvt_pk_bf16_f32 v168, v160, v161
	v_cvt_pk_bf16_f32 v169, v158, v159
	v_cvt_pk_bf16_f32 v170, v156, v157
	v_cvt_pk_bf16_f32 v171, v154, v155
	v_cvt_pk_bf16_f32 v172, v152, v153
	v_cvt_pk_bf16_f32 v173, v150, v151
	v_cvt_pk_bf16_f32 v174, v148, v149
	v_cvt_pk_bf16_f32 v175, v146, v147
	v_permlane32_swap_b32_e32 v163, v165
	v_permlane32_swap_b32_e32 v226, v228
	v_permlane32_swap_b32_e32 v227, v229
	v_permlane32_swap_b32_e32 v168, v170
	v_permlane32_swap_b32_e32 v169, v171
	v_permlane32_swap_b32_e32 v172, v174
	v_permlane32_swap_b32_e32 v173, v175
	s_add_i32 m0, s69, s30
	s_add_i32 m0, m0, 0xc000
	s_nop 0
	global_load_lds_dwordx4 v132, s[28:29]
	s_add_i32 m0, m0, 0x400
	s_nop 0
	global_load_lds_dwordx4 v133, s[28:29]
	s_add_i32 m0, s69, s30
	s_nop 0
	global_load_lds_dwordx4 v130, s[26:27]
	s_add_i32 m0, m0, 0x400
	s_nop 0
	global_load_lds_dwordx4 v131, s[26:27]
	s_add_u32 s26, s26, 0x90000
	s_addc_u32 s27, s27, 0
	s_add_u32 s28, s28, 0x90000
	s_addc_u32 s29, s29, 0
	v_add_u32_e32 v208, s68, v209
	ds_read_b64_tr_b16 v[230:231], v208 offset:0
	ds_read_b64_tr_b16 v[232:233], v208 offset:0x800
	ds_read_b64_tr_b16 v[234:235], v208 offset:0x1000
	ds_read_b64_tr_b16 v[236:237], v208 offset:0x1800
	ds_read_b64_tr_b16 v[238:239], v208 offset:0x2000
	ds_read_b64_tr_b16 v[240:241], v208 offset:0x2800
	ds_read_b64_tr_b16 v[242:243], v208 offset:0x3000
	ds_read_b64_tr_b16 v[244:245], v208 offset:0x3800
	s_waitcnt lgkmcnt(0)
; #define SBAR() __builtin_amdgcn_sched_barrier(0)
; template <int MODE>
; __device__ __forceinline__ void partialSM(f32x16& p0, f32x16& p1, float& m_reg, float& mn, float& alpha, int relh, int relw_min, int relw_max, const float* lut) {
;     ...
;     const float mnC = -mn * C;
; #pragma unroll
;     for (int r = 0; r < 16; ++r) p0[r] = fmaf(p0[r], C, mnC);
; #pragma unroll
;     for (int r = 0; r < 16; ++r) p1[r] = fmaf(p1[r], C, mnC);
; #pragma unroll
;     for (int r = 0; r < 16; ++r) p0[r] = __builtin_amdgcn_exp2f(p0[r]);
; template <int D0> __device__ __forceinline__ void pv_one(f32x16& od, int vb, bf16x8 pa0, bf16x8 pa1, bf16x8 pa2, bf16x8 pa3) {
;   const s16x4 l0 = tr_read<v_rd_off(D0, 0, 0)>(vb), h0 = tr_read<v_rd_off(D0, 0, 1)>(vb), l1 = tr_read<v_rd_off(D0, 1, 0)>(vb), h1 = tr_read<v_rd_off(D0, 1, 1)>(vb);
;   const s16x4 l2 = tr_read<v_rd_off(D0, 2, 0)>(vb), h2 = tr_read<v_rd_off(D0, 2, 1)>(vb), l3 = tr_read<v_rd_off(D0, 3, 0)>(vb), h3 = tr_read<v_rd_off(D0, 3, 1)>(vb);
;   asm volatile("s_waitcnt lgkmcnt(0)" ::: "memory"); SBAR();
;     ...
;   od = __builtin_amdgcn_mfma_f32_32x32x16_bf16(pa0, PK(l0, h0), od, 0, 0, 0);
;   od = __builtin_amdgcn_mfma_f32_32x32x16_bf16(pa1, PK(l1, h1), od, 0, 0, 0);
;   od = __builtin_amdgcn_mfma_f32_32x32x16_bf16(pa2, PK(l2, h2), od, 0, 0, 0);
;   od = __builtin_amdgcn_mfma_f32_32x32x16_bf16(pa3, PK(l3, h3), od, 0, 0, 0);
;     ...
; }
; __device__ __forceinline__ void pv_d0(f32x16* o, int vb, bf16x8 pa0, bf16x8 pa1, bf16x8 pa2, bf16x8 pa3) {
;   pv_one<0>(o[0], vb, pa0, pa1, pa2, pa3); pv_one<1>(o[1], vb, pa0, pa1, pa2, pa3); pv_one<2>(o[2], vb, pa0, pa1, pa2, pa3); pv_one<3>(o[3], vb, pa0, pa1, pa2, pa3);
; template <int MODE>
; __device__ __forceinline__ void attn_body(const bf16_t* __restrict__ Qb, const bf16_t* __restrict__ Kh, const bf16_t* __restrict__ Vh, int NT, int krel0,
;                                           char* lds, const float* __restrict__ lutg, const AttnEpi& E) {
;     ...
;     __syncthreads();
;     SBAR(); qkt<ND0, DOFF>(pA0, pA1, K_lds + oq, qr, r32, hi);
	s_nop 0
	v_mfma_f32_32x32x16_bf16 v[18:33], v[162:165], v[230:233], v[18:33]
	ds_read_b64_tr_b16 v[230:231], v208 offset:0x200
	ds_read_b64_tr_b16 v[232:233], v208 offset:0xa00
	v_mfma_f32_32x32x16_bf16 v[18:33], v[226:229], v[234:237], v[18:33]
	ds_read_b64_tr_b16 v[234:235], v208 offset:0x1200
	ds_read_b64_tr_b16 v[236:237], v208 offset:0x1a00
	v_mfma_f32_32x32x16_bf16 v[18:33], v[168:171], v[238:241], v[18:33]
	ds_read_b64_tr_b16 v[238:239], v208 offset:0x2200
	ds_read_b64_tr_b16 v[240:241], v208 offset:0x2a00
	v_mfma_f32_32x32x16_bf16 v[18:33], v[172:175], v[242:245], v[18:33]
	ds_read_b64_tr_b16 v[242:243], v208 offset:0x3200
	ds_read_b64_tr_b16 v[244:245], v208 offset:0x3a00
	s_waitcnt lgkmcnt(0)
	v_mfma_f32_32x32x16_bf16 v[50:65], v[162:165], v[230:233], v[50:65]
	ds_read_b64_tr_b16 v[230:231], v208 offset:0x400
	ds_read_b64_tr_b16 v[232:233], v208 offset:0xc00
	v_mfma_f32_32x32x16_bf16 v[50:65], v[226:229], v[234:237], v[50:65]
	ds_read_b64_tr_b16 v[234:235], v208 offset:0x1400
	ds_read_b64_tr_b16 v[236:237], v208 offset:0x1c00
	v_mfma_f32_32x32x16_bf16 v[50:65], v[168:171], v[238:241], v[50:65]
	ds_read_b64_tr_b16 v[238:239], v208 offset:0x2400
	ds_read_b64_tr_b16 v[240:241], v208 offset:0x2c00
	v_mfma_f32_32x32x16_bf16 v[50:65], v[172:175], v[242:245], v[50:65]
	ds_read_b64_tr_b16 v[242:243], v208 offset:0x3400
	ds_read_b64_tr_b16 v[244:245], v208 offset:0x3c00
	s_waitcnt lgkmcnt(0)
	v_mfma_f32_32x32x16_bf16 v[34:49], v[162:165], v[230:233], v[34:49]
	ds_read_b64_tr_b16 v[230:231], v208 offset:0x600
	ds_read_b64_tr_b16 v[232:233], v208 offset:0xe00
	v_mfma_f32_32x32x16_bf16 v[34:49], v[226:229], v[234:237], v[34:49]
	ds_read_b64_tr_b16 v[234:235], v208 offset:0x1600
	ds_read_b64_tr_b16 v[236:237], v208 offset:0x1e00
	v_mfma_f32_32x32x16_bf16 v[34:49], v[168:171], v[238:241], v[34:49]
	ds_read_b64_tr_b16 v[238:239], v208 offset:0x2600
	ds_read_b64_tr_b16 v[240:241], v208 offset:0x2e00
	v_mfma_f32_32x32x16_bf16 v[34:49], v[172:175], v[242:245], v[34:49]
	ds_read_b64_tr_b16 v[242:243], v208 offset:0x3600
	ds_read_b64_tr_b16 v[244:245], v208 offset:0x3e00
	s_waitcnt lgkmcnt(0)
	v_mfma_f32_32x32x16_bf16 v[2:17], v[162:165], v[230:233], v[2:17]
	v_mfma_f32_32x32x16_bf16 v[2:17], v[226:229], v[234:237], v[2:17]
	v_mfma_f32_32x32x16_bf16 v[2:17], v[168:171], v[238:241], v[2:17]
	v_mfma_f32_32x32x16_bf16 v[2:17], v[172:175], v[242:245], v[2:17]
	s_add_i32 s72, s69, 0
.LBB0_83:
	v_mov_b32_e32 v226, v166
	v_mul_f32_e32 v170, 0xbe0293ee, v226
	v_fmamk_f32 v82, v82, 0x3e0293ee, v170
	v_fmamk_f32 v83, v83, 0x3e0293ee, v170
	v_fmamk_f32 v84, v84, 0x3e0293ee, v170
	v_fmamk_f32 v85, v85, 0x3e0293ee, v170
	v_fmamk_f32 v86, v86, 0x3e0293ee, v170
	v_fmamk_f32 v87, v87, 0x3e0293ee, v170
	v_fmamk_f32 v88, v88, 0x3e0293ee, v170
	v_fmamk_f32 v89, v89, 0x3e0293ee, v170
	v_fmamk_f32 v90, v90, 0x3e0293ee, v170
	v_fmamk_f32 v91, v91, 0x3e0293ee, v170
	v_fmamk_f32 v92, v92, 0x3e0293ee, v170
	v_fmamk_f32 v93, v93, 0x3e0293ee, v170
	v_fmamk_f32 v94, v94, 0x3e0293ee, v170
	v_fmamk_f32 v95, v95, 0x3e0293ee, v170
	v_fmamk_f32 v96, v96, 0x3e0293ee, v170
	v_fmamk_f32 v97, v97, 0x3e0293ee, v170
	v_fmamk_f32 v171, v66, 0x3e0293ee, v170
	v_fmamk_f32 v172, v67, 0x3e0293ee, v170
	v_fmamk_f32 v173, v68, 0x3e0293ee, v170
	v_fmamk_f32 v174, v69, 0x3e0293ee, v170
	v_fmamk_f32 v175, v70, 0x3e0293ee, v170
	v_fmamk_f32 v176, v71, 0x3e0293ee, v170
	v_fmamk_f32 v177, v72, 0x3e0293ee, v170
	v_fmamk_f32 v227, v73, 0x3e0293ee, v170
	v_fmamk_f32 v228, v74, 0x3e0293ee, v170
	v_fmamk_f32 v229, v75, 0x3e0293ee, v170
	v_fmamk_f32 v230, v76, 0x3e0293ee, v170
	v_fmamk_f32 v231, v77, 0x3e0293ee, v170
	v_fmamk_f32 v232, v78, 0x3e0293ee, v170
	v_fmamk_f32 v233, v79, 0x3e0293ee, v170
	v_fmamk_f32 v234, v80, 0x3e0293ee, v170
	v_fmac_f32_e32 v170, 0x3e0293ee, v81
	v_exp_f32_e32 v235, v82
	v_exp_f32_e32 v236, v83
	v_exp_f32_e32 v237, v84
	v_exp_f32_e32 v238, v85
	v_exp_f32_e32 v239, v86
	v_exp_f32_e32 v240, v87
	v_exp_f32_e32 v241, v88
	v_exp_f32_e32 v242, v89
	v_exp_f32_e32 v243, v90
	v_exp_f32_e32 v244, v91
	v_exp_f32_e32 v245, v92
	v_exp_f32_e32 v246, v93
	v_exp_f32_e32 v247, v94
	v_exp_f32_e32 v248, v95
	v_exp_f32_e32 v249, v96
	v_exp_f32_e32 v250, v97
	s_waitcnt vmcnt(2) lgkmcnt(0)
	s_barrier
	v_add_u32_e32 v70, s72, v214
	ds_read_b128 v[66:69], v70 offset:49152
	ds_read_b128 v[70:73], v70 offset:57344
	v_add_u32_e32 v166, s72, v218
	ds_read_b128 v[162:165], v166 offset:49152
	ds_read_b128 v[166:169], v166 offset:57344
	v_exp_f32_e32 v171, v171
	s_waitcnt lgkmcnt(3)
	v_mfma_f32_32x32x16_bf16 v[82:97], v[66:69], v[114:117], 0
	v_exp_f32_e32 v172, v172
	v_exp_f32_e32 v173, v173
	v_exp_f32_e32 v174, v174
	v_exp_f32_e32 v175, v175
	v_exp_f32_e32 v176, v176
	v_exp_f32_e32 v177, v177
	v_exp_f32_e32 v227, v227
	s_waitcnt lgkmcnt(2)
	v_mfma_f32_32x32x16_bf16 v[66:81], v[70:73], v[114:117], 0
	v_exp_f32_e32 v228, v228
	v_exp_f32_e32 v251, v229
	v_exp_f32_e32 v195, v230
	v_exp_f32_e32 v231, v231
	v_exp_f32_e32 v232, v232
	v_exp_f32_e32 v233, v233
	v_exp_f32_e32 v234, v234
	s_waitcnt lgkmcnt(1)
	v_mfma_f32_32x32x16_bf16 v[82:97], v[162:165], v[126:129], v[82:97]
	v_exp_f32_e32 v194, v170
	v_cvt_pk_bf16_f32 v170, v171, v172
	s_waitcnt lgkmcnt(0)
	v_mfma_f32_32x32x16_bf16 v[66:81], v[166:169], v[126:129], v[66:81]
	v_add_u32_e32 v166, s72, v219
	ds_read_b128 v[162:165], v166 offset:49152
	ds_read_b128 v[166:169], v166 offset:57344
	s_waitcnt lgkmcnt(1)
	v_mfma_f32_32x32x16_bf16 v[82:97], v[162:165], v[118:121], v[82:97]
	s_waitcnt lgkmcnt(0)
	v_mfma_f32_32x32x16_bf16 v[66:81], v[166:169], v[118:121], v[66:81]
	v_add_u32_e32 v166, s72, v216
	ds_read_b128 v[162:165], v166 offset:49152
	ds_read_b128 v[166:169], v166 offset:57344
	s_waitcnt lgkmcnt(1)
; #define SBAR() __builtin_amdgcn_sched_barrier(0)
; #define SLOAD(i, k0) do { sr_[i].vs0 = *reinterpret_cast<const bf16x8*>(&Vh[(size_t)((k0) + sr) * LDQK + sc]); sr_[i].vs1 = *reinterpret_cast<const bf16x8*>(&Vh[(size_t)((k0) + 32 + sr) * LDQK + sc]); \
;     sr_[i].ks0 = *reinterpret_cast<const bf16x8*>(&Kh[(size_t)((k0) + sr) * LDQK + sc]); sr_[i].ks1 = *reinterpret_cast<const bf16x8*>(&Kh[(size_t)((k0) + 32 + sr) * LDQK + sc]); } while (0)
; #define PSM(P0, P1, MN, AL, J) partialSM<MODE>(P0, P1, m_reg, MN, AL, relq + 64 * (J), relwmin + 64 * (J), relwmax + 64 * (J), lut)
; __device__ __forceinline__ void finishSM(f32x16& p0, f32x16& p1, float alpha, float& l_reg, bf16x8& pa0, bf16x8& pa1, bf16x8& pa2, bf16x8& pa3) {
; #pragma unroll
;   for (int r = 0; r < 16; ++r) p1[r] = __builtin_amdgcn_exp2f(p1[r]);
;   float ps = 0;
; #pragma unroll
;   for (int r = 0; r < 16; ++r) ps += p0[r];
; #pragma unroll
;   for (int r = 0; r < 16; ++r) ps += p1[r];
;   { auto rr = __builtin_amdgcn_permlane32_swap(__float_as_uint(ps), __float_as_uint(ps), false, false);
;     ps = __uint_as_float(rr[0]) + __uint_as_float(rr[1]); }
;   l_reg = l_reg * alpha + ps;
;     ...
;   PK4(p0, 0, pa0); PK4(p0, 8, pa1); PK4(p1, 0, pa2); PK4(p1, 8, pa3);
; template <int MODE>
; __device__ __forceinline__ void attn_body(const bf16_t* __restrict__ Qb, const bf16_t* __restrict__ Kh, const bf16_t* __restrict__ Vh, int NT, int krel0,
;                                           char* lds, const float* __restrict__ lutg, const AttnEpi& E) {
;     ...
;     SBAR(); qkt<ND0, DOFF>(pA0, pA1, K_lds + oq, qr, r32, hi);
;     finishSM(pB0, pB1, alB, l_reg, pa0, pa1, pa2, pa3); SBAR();
;     if (j + 3 < NT) SLOAD(SE, (j + 3) * 64); SBAR();
;     pv_d0(o, vb0 + op, pa0, pa1, pa2, pa3); PSM(pA0, pA1, mnA, alA, j + 1);
	v_mfma_f32_32x32x16_bf16 v[82:97], v[162:165], v[122:125], v[82:97]
	s_waitcnt lgkmcnt(0)
	v_mfma_f32_32x32x16_bf16 v[66:81], v[166:169], v[122:125], v[66:81]
	v_add_u32_e32 v166, s72, v217
	ds_read_b128 v[162:165], v166 offset:49152
	ds_read_b128 v[166:169], v166 offset:57344
	s_waitcnt lgkmcnt(1)
	v_mfma_f32_32x32x16_bf16 v[82:97], v[162:165], v[110:113], v[82:97]
	s_waitcnt lgkmcnt(0)
	v_mfma_f32_32x32x16_bf16 v[66:81], v[166:169], v[110:113], v[66:81]
	v_add_u32_e32 v166, s72, v215
	ds_read_b128 v[162:165], v166 offset:49152
	ds_read_b128 v[166:169], v166 offset:57344
	s_waitcnt lgkmcnt(1)
	v_mfma_f32_32x32x16_bf16 v[82:97], v[162:165], v[106:109], v[82:97]
	s_waitcnt lgkmcnt(0)
	v_mfma_f32_32x32x16_bf16 v[66:81], v[166:169], v[106:109], v[66:81]
	v_add_u32_e32 v166, s72, v220
	ds_read_b128 v[162:165], v166 offset:49152
	ds_read_b128 v[166:169], v166 offset:57344
	s_waitcnt lgkmcnt(1)
	v_mfma_f32_32x32x16_bf16 v[82:97], v[162:165], v[102:105], v[82:97]
	s_waitcnt lgkmcnt(0)
	v_mfma_f32_32x32x16_bf16 v[66:81], v[166:169], v[102:105], v[66:81]
	v_add_u32_e32 v166, s72, v221
	ds_read_b128 v[162:165], v166 offset:49152
	ds_read_b128 v[166:169], v166 offset:57344
	s_waitcnt lgkmcnt(1)
	v_mfma_f32_32x32x16_bf16 v[82:97], v[162:165], v[98:101], v[82:97]
	v_add_f32_e32 v162, v236, v235
	v_add_f32_e32 v162, v237, v162
	v_add_f32_e32 v162, v238, v162
	v_add_f32_e32 v162, v239, v162
	v_add_f32_e32 v162, v240, v162
	v_add_f32_e32 v162, v241, v162
	v_add_f32_e32 v162, v242, v162
	v_add_f32_e32 v162, v243, v162
	v_add_f32_e32 v162, v244, v162
	v_add_f32_e32 v162, v245, v162
	v_add_f32_e32 v162, v246, v162
	v_add_f32_e32 v162, v247, v162
	v_add_f32_e32 v162, v248, v162
	v_add_f32_e32 v162, v249, v162
	v_add_f32_e32 v162, v250, v162
	v_add_f32_e32 v162, v171, v162
	v_add_f32_e32 v162, v172, v162
	v_add_f32_e32 v162, v173, v162
	v_add_f32_e32 v162, v174, v162
	v_add_f32_e32 v162, v175, v162
	v_add_f32_e32 v162, v176, v162
	v_add_f32_e32 v162, v177, v162
	v_add_f32_e32 v162, v227, v162
	v_add_f32_e32 v162, v228, v162
	v_add_f32_e32 v162, v251, v162
	s_waitcnt lgkmcnt(0)
	v_mfma_f32_32x32x16_bf16 v[66:81], v[166:169], v[98:101], v[66:81]
	v_add_f32_e32 v162, v195, v162
	v_add_f32_e32 v162, v231, v162
	v_add_f32_e32 v162, v232, v162
	v_add_f32_e32 v162, v233, v162
	v_add_f32_e32 v162, v234, v162
	v_add_f32_e32 v229, v194, v162
	v_mov_b32_e32 v230, v229
	v_cvt_pk_bf16_f32 v162, v235, v236
	v_cvt_pk_bf16_f32 v163, v237, v238
	v_cvt_pk_bf16_f32 v164, v239, v240
	v_cvt_pk_bf16_f32 v165, v241, v242
	v_cvt_pk_bf16_f32 v166, v243, v244
	v_cvt_pk_bf16_f32 v167, v245, v246
	v_cvt_pk_bf16_f32 v168, v247, v248
	v_cvt_pk_bf16_f32 v169, v249, v250
	v_cvt_pk_bf16_f32 v171, v173, v174
	v_cvt_pk_bf16_f32 v172, v175, v176
	v_cvt_pk_bf16_f32 v173, v177, v227
	v_cvt_pk_bf16_f32 v174, v228, v251
	v_cvt_pk_bf16_f32 v175, v195, v231
	v_cvt_pk_bf16_f32 v176, v232, v233
	v_cvt_pk_bf16_f32 v177, v234, v194
	v_permlane32_swap_b32_e32 v229, v230
	v_permlane32_swap_b32_e32 v162, v164
	v_permlane32_swap_b32_e32 v163, v165
	v_permlane32_swap_b32_e32 v166, v168
	v_permlane32_swap_b32_e32 v167, v169
	v_permlane32_swap_b32_e32 v170, v172
	v_permlane32_swap_b32_e32 v171, v173
	v_permlane32_swap_b32_e32 v174, v176
	v_permlane32_swap_b32_e32 v175, v177
.LBB0_85:
	s_add_i32 m0, s68, s30
	s_add_i32 m0, m0, 0xc000
	s_nop 0
	global_load_lds_dwordx4 v132, s[28:29]
	s_add_i32 m0, m0, 0x400
	s_nop 0
	global_load_lds_dwordx4 v133, s[28:29]
	s_add_i32 m0, s68, s30
	s_nop 0
	global_load_lds_dwordx4 v130, s[26:27]
	s_add_i32 m0, m0, 0x400
	s_nop 0
	global_load_lds_dwordx4 v131, s[26:27]
	s_add_u32 s26, s26, 0x90000
	s_addc_u32 s27, s27, 0
	s_add_u32 s28, s28, 0x90000
	s_addc_u32 s29, s29, 0
	v_add_u32_e32 v194, s71, v209
	ds_read_b64_tr_b16 v[232:233], v194 offset:0
	ds_read_b64_tr_b16 v[234:235], v194 offset:0x800
	ds_read_b64_tr_b16 v[236:237], v194 offset:0x1000
	ds_read_b64_tr_b16 v[238:239], v194 offset:0x1800
	ds_read_b64_tr_b16 v[240:241], v194 offset:0x2000
	ds_read_b64_tr_b16 v[242:243], v194 offset:0x2800
	ds_read_b64_tr_b16 v[244:245], v194 offset:0x3000
	ds_read_b64_tr_b16 v[246:247], v194 offset:0x3800
	s_waitcnt lgkmcnt(0)
	s_nop 0
	v_mfma_f32_32x32x16_bf16 v[18:33], v[162:165], v[232:235], v[18:33]
	ds_read_b64_tr_b16 v[232:233], v194 offset:0x200
	ds_read_b64_tr_b16 v[234:235], v194 offset:0xa00
	v_mfma_f32_32x32x16_bf16 v[18:33], v[166:169], v[236:239], v[18:33]
	ds_read_b64_tr_b16 v[236:237], v194 offset:0x1200
	ds_read_b64_tr_b16 v[238:239], v194 offset:0x1a00
	v_mfma_f32_32x32x16_bf16 v[18:33], v[170:173], v[240:243], v[18:33]
	ds_read_b64_tr_b16 v[240:241], v194 offset:0x2200
	ds_read_b64_tr_b16 v[242:243], v194 offset:0x2a00
	v_mfma_f32_32x32x16_bf16 v[18:33], v[174:177], v[244:247], v[18:33]
	ds_read_b64_tr_b16 v[244:245], v194 offset:0x3200
	ds_read_b64_tr_b16 v[246:247], v194 offset:0x3a00
	s_waitcnt lgkmcnt(0)
	v_mfma_f32_32x32x16_bf16 v[50:65], v[162:165], v[232:235], v[50:65]
	ds_read_b64_tr_b16 v[232:233], v194 offset:0x400
	ds_read_b64_tr_b16 v[234:235], v194 offset:0xc00
	v_mfma_f32_32x32x16_bf16 v[50:65], v[166:169], v[236:239], v[50:65]
	ds_read_b64_tr_b16 v[236:237], v194 offset:0x1400
	ds_read_b64_tr_b16 v[238:239], v194 offset:0x1c00
	v_mfma_f32_32x32x16_bf16 v[50:65], v[170:173], v[240:243], v[50:65]
	ds_read_b64_tr_b16 v[240:241], v194 offset:0x2400
	ds_read_b64_tr_b16 v[242:243], v194 offset:0x2c00
	v_mfma_f32_32x32x16_bf16 v[50:65], v[174:177], v[244:247], v[50:65]
	ds_read_b64_tr_b16 v[244:245], v194 offset:0x3400
	ds_read_b64_tr_b16 v[246:247], v194 offset:0x3c00
	s_waitcnt lgkmcnt(0)
	v_mfma_f32_32x32x16_bf16 v[34:49], v[162:165], v[232:235], v[34:49]
	ds_read_b64_tr_b16 v[232:233], v194 offset:0x600
	ds_read_b64_tr_b16 v[234:235], v194 offset:0xe00
	v_mfma_f32_32x32x16_bf16 v[34:49], v[166:169], v[236:239], v[34:49]
	ds_read_b64_tr_b16 v[236:237], v194 offset:0x1600
	ds_read_b64_tr_b16 v[238:239], v194 offset:0x1e00
	v_mfma_f32_32x32x16_bf16 v[34:49], v[170:173], v[240:243], v[34:49]
	ds_read_b64_tr_b16 v[240:241], v194 offset:0x2600
	ds_read_b64_tr_b16 v[242:243], v194 offset:0x2e00
	v_mfma_f32_32x32x16_bf16 v[34:49], v[174:177], v[244:247], v[34:49]
	ds_read_b64_tr_b16 v[244:245], v194 offset:0x3600
	ds_read_b64_tr_b16 v[246:247], v194 offset:0x3e00
	s_waitcnt lgkmcnt(0)
	v_mfma_f32_32x32x16_bf16 v[2:17], v[162:165], v[232:235], v[2:17]
	v_mfma_f32_32x32x16_bf16 v[2:17], v[166:169], v[236:239], v[2:17]
	v_mfma_f32_32x32x16_bf16 v[2:17], v[170:173], v[240:243], v[2:17]
	v_mfma_f32_32x32x16_bf16 v[2:17], v[174:177], v[244:247], v[2:17]
	s_add_i32 s72, s68, 0

; #define SBAR() __builtin_amdgcn_sched_barrier(0)
; #define RESC(a) do { if (__any((a) < 1.f)) { if (hi == 0) al_l[r32] = (a); asm volatile("s_waitcnt lgkmcnt(0)" ::: "memory"); \
;     _Pragma("unroll") for (int d = 0; d < 4; ++d) _Pragma("unroll") for (int r = 0; r < 16; ++r) o[d][r] *= al_l[crow(r, hi)]; } } while (0)
; #define PSM(P0, P1, MN, AL, J) partialSM<MODE>(P0, P1, m_reg, MN, AL, relq + 64 * (J), relwmin + 64 * (J), relwmax + 64 * (J), lut)
; __device__ __forceinline__ void finishSM(f32x16& p0, f32x16& p1, float alpha, float& l_reg, bf16x8& pa0, bf16x8& pa1, bf16x8& pa2, bf16x8& pa3) {
; #pragma unroll
;   for (int r = 0; r < 16; ++r) p1[r] = __builtin_amdgcn_exp2f(p1[r]);
;   float ps = 0;
; #pragma unroll
;   for (int r = 0; r < 16; ++r) ps += p0[r];
; #pragma unroll
;   for (int r = 0; r < 16; ++r) ps += p1[r];
;   { auto rr = __builtin_amdgcn_permlane32_swap(__float_as_uint(ps), __float_as_uint(ps), false, false);
;     ps = __uint_as_float(rr[0]) + __uint_as_float(rr[1]); }
;   l_reg = l_reg * alpha + ps;
;     ...
;   PK4(p0, 0, pa0); PK4(p0, 8, pa1); PK4(p1, 0, pa2); PK4(p1, 8, pa3);
; template <int MODE>
; __device__ __forceinline__ void attn_body(const bf16_t* __restrict__ Qb, const bf16_t* __restrict__ Kh, const bf16_t* __restrict__ Vh, int NT, int krel0,
;                                           char* lds, const float* __restrict__ lutg, const AttnEpi& E) {
;     ...
;   SBAR(); qkt<ND0, DOFF>(pB0, pB1, K_lds + oq, qr, r32, hi);
;   finishSM(pA0, pA1, alA, l_reg, pa0, pa1, pa2, pa3); SBAR();
;   pv_d0(o, vb0 + op, pa0, pa1, pa2, pa3); PSM(pB0, pB1, mnB, alB, NT - 1);
;   RESC(alB);
;   finishSM(pB0, pB1, alB, l_reg, pa0, pa1, pa2, pa3); SBAR();
;   pv_d0(o, vb0 + oq, pa0, pa1, pa2, pa3);
.LBB0_95:
	v_cndmask_b32_e64 v101, v101, v166, s[0:1]
	v_mul_f32_e32 v101, 0xbe0293ee, v101
	v_fmamk_f32 v82, v82, 0x3e0293ee, v101
	v_fmamk_f32 v83, v83, 0x3e0293ee, v101
	v_fmamk_f32 v84, v84, 0x3e0293ee, v101
	v_fmamk_f32 v85, v85, 0x3e0293ee, v101
	v_fmamk_f32 v86, v86, 0x3e0293ee, v101
	v_fmamk_f32 v87, v87, 0x3e0293ee, v101
	v_fmamk_f32 v88, v88, 0x3e0293ee, v101
	v_fmamk_f32 v89, v89, 0x3e0293ee, v101
	v_fmamk_f32 v90, v90, 0x3e0293ee, v101
	v_fmamk_f32 v91, v91, 0x3e0293ee, v101
	v_fmamk_f32 v92, v92, 0x3e0293ee, v101
	v_fmamk_f32 v93, v93, 0x3e0293ee, v101
	v_fmamk_f32 v94, v94, 0x3e0293ee, v101
	v_fmamk_f32 v95, v95, 0x3e0293ee, v101
	v_fmamk_f32 v96, v96, 0x3e0293ee, v101
	v_fmamk_f32 v97, v97, 0x3e0293ee, v101
	v_fmamk_f32 v66, v66, 0x3e0293ee, v101
	v_fmamk_f32 v67, v67, 0x3e0293ee, v101
	v_fmamk_f32 v68, v68, 0x3e0293ee, v101
	v_fmamk_f32 v69, v69, 0x3e0293ee, v101
	v_fmamk_f32 v70, v70, 0x3e0293ee, v101
	v_fmamk_f32 v71, v71, 0x3e0293ee, v101
	v_fmamk_f32 v72, v72, 0x3e0293ee, v101
	v_fmamk_f32 v73, v73, 0x3e0293ee, v101
	v_fmamk_f32 v74, v74, 0x3e0293ee, v101
	v_fmamk_f32 v75, v75, 0x3e0293ee, v101
	v_fmamk_f32 v76, v76, 0x3e0293ee, v101
	v_fmamk_f32 v77, v77, 0x3e0293ee, v101
	v_fmamk_f32 v78, v78, 0x3e0293ee, v101
	v_fmamk_f32 v79, v79, 0x3e0293ee, v101
	v_fmamk_f32 v80, v80, 0x3e0293ee, v101
	v_fmac_f32_e32 v101, 0x3e0293ee, v81
	v_exp_f32_e32 v81, v82
	v_exp_f32_e32 v82, v83
	v_exp_f32_e32 v83, v84
	v_exp_f32_e32 v84, v85
	v_exp_f32_e32 v85, v86
	v_exp_f32_e32 v86, v87
	v_exp_f32_e32 v87, v88
	v_exp_f32_e32 v88, v89
	v_exp_f32_e32 v89, v90
	v_exp_f32_e32 v90, v91
	v_exp_f32_e32 v91, v92
	v_exp_f32_e32 v92, v93
	v_exp_f32_e32 v93, v94
	v_exp_f32_e32 v94, v95
	v_exp_f32_e32 v95, v96
	v_exp_f32_e32 v96, v97
	v_exp_f32_e32 v97, v66
	v_add_f32_e32 v66, 0, v81
	v_add_f32_e32 v66, v82, v66
	v_add_f32_e32 v66, v83, v66
	v_add_f32_e32 v66, v84, v66
	v_add_f32_e32 v66, v85, v66
	v_add_f32_e32 v66, v86, v66
	v_add_f32_e32 v66, v87, v66
	v_add_f32_e32 v66, v88, v66
	v_add_f32_e32 v66, v89, v66
	v_add_f32_e32 v66, v90, v66
	v_add_f32_e32 v66, v91, v66
	v_add_f32_e32 v66, v92, v66
	v_add_f32_e32 v66, v93, v66
	v_exp_f32_e32 v102, v67
	v_add_f32_e32 v66, v94, v66
	v_exp_f32_e32 v103, v68
	v_add_f32_e32 v66, v95, v66
	v_exp_f32_e32 v104, v69
	v_add_f32_e32 v66, v96, v66
	v_exp_f32_e32 v105, v70
	v_add_f32_e32 v66, v97, v66
	v_exp_f32_e32 v106, v71
	v_add_f32_e32 v66, v102, v66
	v_exp_f32_e32 v107, v72
	v_add_f32_e32 v66, v103, v66
	v_exp_f32_e32 v108, v73
	v_add_f32_e32 v66, v104, v66
	v_exp_f32_e32 v109, v74
	v_add_f32_e32 v66, v105, v66
	v_exp_f32_e32 v110, v75
	v_add_f32_e32 v66, v106, v66
	v_exp_f32_e32 v111, v76
	v_add_f32_e32 v66, v107, v66
	v_exp_f32_e32 v112, v77
	v_add_f32_e32 v66, v108, v66
	v_exp_f32_e32 v113, v78
	v_add_f32_e32 v66, v109, v66
	v_exp_f32_e32 v114, v79
	v_add_f32_e32 v66, v110, v66
	v_exp_f32_e32 v115, v80
	v_add_f32_e32 v66, v111, v66
	v_exp_f32_e32 v101, v101
	v_add_f32_e32 v66, v112, v66
	v_add_f32_e32 v66, v113, v66
	v_add_f32_e32 v66, v114, v66
	v_add_f32_e32 v66, v115, v66
	v_add_f32_e32 v66, v101, v66
	v_mov_b32_e32 v67, v66
	s_nop 1
	v_permlane32_swap_b32_e32 v66, v67
	v_cvt_pk_bf16_f32 v68, v81, v82
	v_cvt_pk_bf16_f32 v69, v83, v84
	v_cvt_pk_bf16_f32 v70, v85, v86
	v_cvt_pk_bf16_f32 v71, v87, v88
	v_cvt_pk_bf16_f32 v72, v89, v90
	v_cvt_pk_bf16_f32 v73, v91, v92
	v_cvt_pk_bf16_f32 v74, v93, v94
	v_cvt_pk_bf16_f32 v75, v95, v96
	v_cvt_pk_bf16_f32 v76, v97, v102
	v_cvt_pk_bf16_f32 v77, v103, v104
	v_cvt_pk_bf16_f32 v78, v105, v106
	v_cvt_pk_bf16_f32 v79, v107, v108
	v_cvt_pk_bf16_f32 v80, v109, v110
	v_cvt_pk_bf16_f32 v81, v111, v112
	v_cvt_pk_bf16_f32 v82, v113, v114
	v_cvt_pk_bf16_f32 v83, v115, v101
	v_permlane32_swap_b32_e32 v68, v70
	v_permlane32_swap_b32_e32 v69, v71
	v_permlane32_swap_b32_e32 v72, v74
	v_permlane32_swap_b32_e32 v73, v75
	v_permlane32_swap_b32_e32 v76, v78
	v_permlane32_swap_b32_e32 v77, v79
	v_permlane32_swap_b32_e32 v80, v82
	v_permlane32_swap_b32_e32 v81, v83
	ds_read_b64_tr_b16 v[84:85], v208 offset:0
	ds_read_b64_tr_b16 v[86:87], v208 offset:0x800
	ds_read_b64_tr_b16 v[88:89], v208 offset:0x1000
	ds_read_b64_tr_b16 v[90:91], v208 offset:0x1800
	ds_read_b64_tr_b16 v[92:93], v208 offset:0x2000
	ds_read_b64_tr_b16 v[94:95], v208 offset:0x2800
	ds_read_b64_tr_b16 v[102:103], v208 offset:0x3000
	ds_read_b64_tr_b16 v[104:105], v208 offset:0x3800
	s_waitcnt lgkmcnt(0)
	s_nop 0
	v_mfma_f32_32x32x16_bf16 v[18:33], v[68:71], v[84:87], v[18:33]
	ds_read_b64_tr_b16 v[84:85], v208 offset:0x200
	ds_read_b64_tr_b16 v[86:87], v208 offset:0xa00
	v_mfma_f32_32x32x16_bf16 v[18:33], v[72:75], v[88:91], v[18:33]
	ds_read_b64_tr_b16 v[88:89], v208 offset:0x1200
	ds_read_b64_tr_b16 v[90:91], v208 offset:0x1a00
	v_mfma_f32_32x32x16_bf16 v[18:33], v[76:79], v[92:95], v[18:33]
	ds_read_b64_tr_b16 v[92:93], v208 offset:0x2200
	ds_read_b64_tr_b16 v[94:95], v208 offset:0x2a00
	v_mfma_f32_32x32x16_bf16 v[18:33], v[80:83], v[102:105], v[18:33]
	ds_read_b64_tr_b16 v[102:103], v208 offset:0x3200
	ds_read_b64_tr_b16 v[104:105], v208 offset:0x3a00
	s_waitcnt lgkmcnt(0)
	v_mfma_f32_32x32x16_bf16 v[50:65], v[68:71], v[84:87], v[50:65]
	ds_read_b64_tr_b16 v[84:85], v208 offset:0x400
	ds_read_b64_tr_b16 v[86:87], v208 offset:0xc00
	v_mfma_f32_32x32x16_bf16 v[50:65], v[72:75], v[88:91], v[50:65]
	ds_read_b64_tr_b16 v[88:89], v208 offset:0x1400
	ds_read_b64_tr_b16 v[90:91], v208 offset:0x1c00
	v_mfma_f32_32x32x16_bf16 v[50:65], v[76:79], v[92:95], v[50:65]
	ds_read_b64_tr_b16 v[92:93], v208 offset:0x2400
	ds_read_b64_tr_b16 v[94:95], v208 offset:0x2c00
	v_mfma_f32_32x32x16_bf16 v[50:65], v[80:83], v[102:105], v[50:65]
	ds_read_b64_tr_b16 v[102:103], v208 offset:0x3400
	ds_read_b64_tr_b16 v[104:105], v208 offset:0x3c00
	s_waitcnt lgkmcnt(0)
; __device__ __forceinline__ float bf2f(bf16_t v) { return __uint_as_float(((unsigned)v) << 16); }
; #define SBAR() __builtin_amdgcn_sched_barrier(0)
; __device__ __forceinline__ int crow(int r, int hi) { return (r & 3) + 8 * (r >> 2) + 4 * hi; }
; template <int MODE>
; __device__ __forceinline__ void attn_body(const bf16_t* __restrict__ Qb, const bf16_t* __restrict__ Kh, const bf16_t* __restrict__ Vh, int NT, int krel0,
;                                           char* lds, const float* __restrict__ lutg, const AttnEpi& E) {
;     ...
;   finishSM(pB0, pB1, alB, l_reg, pa0, pa1, pa2, pa3); SBAR();
;   pv_d0(o, vb0 + oq, pa0, pa1, pa2, pa3);
;   if constexpr (MODE == 1) l_reg += __builtin_amdgcn_exp2f(E.sinkl2 - m_reg);
;   if (hi == 0) li_l[r32] = l_reg; asm volatile("s_waitcnt lgkmcnt(0)" ::: "memory");
;   float rli[16];
; #pragma unroll
;   for (int r = 0; r < 16; ++r) rli[r] = __builtin_amdgcn_rcpf(li_l[crow(r, hi)]);
;   float* pk0 = E.park; float* pk1 = E.park + 64 * 512;
;   const int rowb = wid * 32;
;   if constexpr (MODE == 0 || MODE == 1) {
; #pragma unroll
;     for (int r = 0; r < 16; ++r) { const int row = rowb + crow(r, hi);
; #pragma unroll
;       for (int d0 = 0; d0 < 4; ++d0) { const int idx = (d0 * 16 + r) * 512 + tid;
;         const float g = bf2f(E.gate[(size_t)row * GW + d0 * 32 + r32]);
;         const float v = o[d0][r] * rli[r] * g;
;         if constexpr (MODE == 0) pk0[idx] = v; else pk0[idx] += v; } }
	v_mfma_f32_32x32x16_bf16 v[34:49], v[68:71], v[84:87], v[34:49]
	ds_read_b64_tr_b16 v[84:85], v208 offset:0x600
	ds_read_b64_tr_b16 v[86:87], v208 offset:0xe00
	v_mfma_f32_32x32x16_bf16 v[34:49], v[72:75], v[88:91], v[34:49]
	ds_read_b64_tr_b16 v[88:89], v208 offset:0x1600
	ds_read_b64_tr_b16 v[90:91], v208 offset:0x1e00
	v_mfma_f32_32x32x16_bf16 v[34:49], v[76:79], v[92:95], v[34:49]
	ds_read_b64_tr_b16 v[92:93], v208 offset:0x2600
	ds_read_b64_tr_b16 v[94:95], v208 offset:0x2e00
	v_mfma_f32_32x32x16_bf16 v[34:49], v[80:83], v[102:105], v[34:49]
	ds_read_b64_tr_b16 v[102:103], v208 offset:0x3600
	ds_read_b64_tr_b16 v[104:105], v208 offset:0x3e00
	s_waitcnt lgkmcnt(0)
	v_mfma_f32_32x32x16_bf16 v[2:17], v[68:71], v[84:87], v[2:17]
	v_mfma_f32_32x32x16_bf16 v[2:17], v[72:75], v[88:91], v[2:17]
	v_mfma_f32_32x32x16_bf16 v[2:17], v[76:79], v[92:95], v[2:17]
	v_mfma_f32_32x32x16_bf16 v[2:17], v[80:83], v[102:105], v[2:17]
	s_and_saveexec_b64 s[0:1], s[6:7]
	v_add_f32_e32 v68, v98, v99
	v_fmac_f32_e32 v68, v207, v162
	v_add_f32_e32 v66, v66, v67
	v_fmac_f32_e32 v66, v68, v100
	ds_write_b32 v206, v66
	s_or_b64 exec, exec, s[0:1]
	s_waitcnt lgkmcnt(0)
	ds_read_b128 v[66:69], v0
	ds_read_b128 v[70:73], v0 offset:32
	s_mul_i32 s1, s54, 0x1800
	v_readlane_b32 s6, v252, 37
	s_mul_hi_i32 s0, s54, 0x1800
	s_waitcnt lgkmcnt(1)
	v_rcp_f32_e32 v81, v66
	v_rcp_f32_e32 v88, v67
	v_rcp_f32_e32 v89, v68
	v_rcp_f32_e32 v80, v69
	ds_read_b128 v[66:69], v0 offset:64
	ds_read_b128 v[82:85], v0 offset:96
	v_readlane_b32 s7, v252, 38
	s_add_u32 s1, s6, s1
	s_addc_u32 s0, s7, s0
	s_lshl_b32 s16, s63, 1
	s_add_u32 s56, s1, s16
	s_addc_u32 s57, s0, 0
	v_lshlrev_b32_e32 v0, 1, v189
	s_waitcnt lgkmcnt(1)
	v_rcp_f32_e32 v75, v66
	v_rcp_f32_e32 v74, v67
	v_lshl_add_u64 v[66:67], s[56:57], 0, v[0:1]
	v_or_b32_e32 v0, v205, v204
	v_rcp_f32_e32 v79, v70
	v_rcp_f32_e32 v78, v71
	s_waitcnt lgkmcnt(0)
	v_rcp_f32_e32 v71, v82
	v_rcp_f32_e32 v70, v83
	v_rcp_f32_e32 v77, v72
	v_rcp_f32_e32 v72, v69
	v_rcp_f32_e32 v69, v84
	v_ashrrev_i32_e32 v189, 31, v188
	v_rcp_f32_e32 v76, v73
	v_rcp_f32_e32 v73, v68
	v_rcp_f32_e32 v68, v85
	v_lshlrev_b32_e32 v134, 2, v188
	v_mad_i64_i32 v[130:131], s[28:29], v0, s88, v[66:67]
	global_load_ushort v98, v[130:131], off
	global_load_ushort v99, v[130:131], off offset:64
	global_load_ushort v100, v[130:131], off offset:128
	global_load_ushort v101, v[130:131], off offset:192
	v_or_b32_e32 v132, 1, v0
	v_mad_i64_i32 v[130:131], s[28:29], v132, s88, v[66:67]
	global_load_ushort v102, v[130:131], off
	global_load_ushort v103, v[130:131], off offset:64
	global_load_ushort v104, v[130:131], off offset:128
	global_load_ushort v105, v[130:131], off offset:192
	v_or_b32_e32 v132, 2, v0
	v_mad_i64_i32 v[130:131], s[28:29], v132, s88, v[66:67]
	global_load_ushort v106, v[130:131], off
	global_load_ushort v107, v[130:131], off offset:64
	global_load_ushort v108, v[130:131], off offset:128
	global_load_ushort v109, v[130:131], off offset:192
	v_or_b32_e32 v132, 3, v0
	v_mad_i64_i32 v[130:131], s[28:29], v132, s88, v[66:67]
	global_load_ushort v110, v[130:131], off
	global_load_ushort v111, v[130:131], off offset:64
	global_load_ushort v112, v[130:131], off offset:128
	global_load_ushort v113, v[130:131], off offset:192
	v_or_b32_e32 v132, 8, v0
	v_mad_i64_i32 v[130:131], s[28:29], v132, s88, v[66:67]
	global_load_ushort v114, v[130:131], off
	global_load_ushort v115, v[130:131], off offset:64
	global_load_ushort v116, v[130:131], off offset:128
	global_load_ushort v117, v[130:131], off offset:192
	v_or_b32_e32 v132, 9, v0
	v_mad_i64_i32 v[130:131], s[28:29], v132, s88, v[66:67]
	global_load_ushort v118, v[130:131], off
	global_load_ushort v119, v[130:131], off offset:64
	global_load_ushort v120, v[130:131], off offset:128
	global_load_ushort v121, v[130:131], off offset:192
	v_or_b32_e32 v132, 10, v0
	v_mad_i64_i32 v[130:131], s[28:29], v132, s88, v[66:67]
	global_load_ushort v122, v[130:131], off
	global_load_ushort v123, v[130:131], off offset:64
	global_load_ushort v124, v[130:131], off offset:128
	global_load_ushort v125, v[130:131], off offset:192
	v_or_b32_e32 v132, 11, v0
	v_mad_i64_i32 v[130:131], s[28:29], v132, s88, v[66:67]
	global_load_ushort v126, v[130:131], off
	global_load_ushort v127, v[130:131], off offset:64
	global_load_ushort v128, v[130:131], off offset:128
	global_load_ushort v129, v[130:131], off offset:192
	s_add_u32 s20, s34, 0x0
	s_addc_u32 s21, s35, 0
	s_add_u32 s22, s34, 0x8000
	s_addc_u32 s23, s35, 0
	s_add_u32 s24, s34, 0x10000
	s_addc_u32 s25, s35, 0
	s_add_u32 s26, s34, 0x18000
	s_addc_u32 s27, s35, 0
	s_waitcnt vmcnt(31)
	v_lshlrev_b32_e32 v98, 16, v98
	v_mul_f32_e32 v18, v18, v81
	v_mul_f32_e32 v98, v18, v98
	global_store_dword v134, v98, s[20:21]
	s_waitcnt vmcnt(31)
	v_lshlrev_b32_e32 v99, 16, v99
	v_mul_f32_e32 v50, v50, v81
	v_mul_f32_e32 v99, v50, v99
	global_store_dword v134, v99, s[22:23]
	s_waitcnt vmcnt(31)
	v_lshlrev_b32_e32 v100, 16, v100
	v_mul_f32_e32 v34, v34, v81
	v_mul_f32_e32 v100, v34, v100
	global_store_dword v134, v100, s[24:25]
	s_waitcnt vmcnt(31)
	v_lshlrev_b32_e32 v101, 16, v101
	v_mul_f32_e32 v2, v2, v81
	v_mul_f32_e32 v101, v2, v101
	global_store_dword v134, v101, s[26:27]
	s_waitcnt vmcnt(31)
	v_lshlrev_b32_e32 v102, 16, v102
	v_mul_f32_e32 v19, v19, v88
	v_mul_f32_e32 v102, v19, v102
	global_store_dword v134, v102, s[20:21] offset:2048
	s_waitcnt vmcnt(31)
	v_lshlrev_b32_e32 v103, 16, v103
	v_mul_f32_e32 v51, v51, v88
	v_mul_f32_e32 v103, v51, v103
	global_store_dword v134, v103, s[22:23] offset:2048
	s_waitcnt vmcnt(31)
; __device__ __forceinline__ float bf2f(bf16_t v) { return __uint_as_float(((unsigned)v) << 16); }
; __device__ __forceinline__ int crow(int r, int hi) { return (r & 3) + 8 * (r >> 2) + 4 * hi; }
; template <int MODE>
; __device__ __forceinline__ void attn_body(const bf16_t* __restrict__ Qb, const bf16_t* __restrict__ Kh, const bf16_t* __restrict__ Vh, int NT, int krel0,
;                                           char* lds, const float* __restrict__ lutg, const AttnEpi& E) {
;     ...
;     for (int r = 0; r < 16; ++r) { const int row = rowb + crow(r, hi);
; #pragma unroll
;       for (int d0 = 0; d0 < 4; ++d0) { const int idx = (d0 * 16 + r) * 512 + tid;
;         const float g = bf2f(E.gate[(size_t)row * GW + d0 * 32 + r32]);
;         const float v = o[d0][r] * rli[r] * g;
;         if constexpr (MODE == 0) pk0[idx] = v; else pk0[idx] += v; } }
	v_lshlrev_b32_e32 v104, 16, v104
	v_mul_f32_e32 v35, v35, v88
	v_mul_f32_e32 v104, v35, v104
	global_store_dword v134, v104, s[24:25] offset:2048
	s_waitcnt vmcnt(31)
	v_lshlrev_b32_e32 v105, 16, v105
	v_mul_f32_e32 v3, v3, v88
	v_mul_f32_e32 v105, v3, v105
	global_store_dword v134, v105, s[26:27] offset:2048
	s_add_u32 s20, s34, 0x1000
	s_addc_u32 s21, s35, 0
	s_add_u32 s22, s34, 0x9000
	s_addc_u32 s23, s35, 0
	s_add_u32 s24, s34, 0x11000
	s_addc_u32 s25, s35, 0
	s_add_u32 s26, s34, 0x19000
	s_addc_u32 s27, s35, 0
	s_waitcnt vmcnt(31)
	v_lshlrev_b32_e32 v106, 16, v106
	v_mul_f32_e32 v20, v20, v89
	v_mul_f32_e32 v106, v20, v106
	global_store_dword v134, v106, s[20:21]
	s_waitcnt vmcnt(31)
	v_lshlrev_b32_e32 v107, 16, v107
	v_mul_f32_e32 v52, v52, v89
	v_mul_f32_e32 v107, v52, v107
	global_store_dword v134, v107, s[22:23]
	s_waitcnt vmcnt(31)
	v_lshlrev_b32_e32 v108, 16, v108
	v_mul_f32_e32 v36, v36, v89
	v_mul_f32_e32 v108, v36, v108
	global_store_dword v134, v108, s[24:25]
	s_waitcnt vmcnt(31)
	v_lshlrev_b32_e32 v109, 16, v109
	v_mul_f32_e32 v4, v4, v89
	v_mul_f32_e32 v109, v4, v109
	global_store_dword v134, v109, s[26:27]
	s_waitcnt vmcnt(31)
	v_lshlrev_b32_e32 v110, 16, v110
	v_mul_f32_e32 v21, v21, v80
	v_mul_f32_e32 v110, v21, v110
	global_store_dword v134, v110, s[20:21] offset:2048
	s_waitcnt vmcnt(31)
	v_lshlrev_b32_e32 v111, 16, v111
	v_mul_f32_e32 v53, v53, v80
	v_mul_f32_e32 v111, v53, v111
	global_store_dword v134, v111, s[22:23] offset:2048
	s_waitcnt vmcnt(31)
	v_lshlrev_b32_e32 v112, 16, v112
	v_mul_f32_e32 v37, v37, v80
	v_mul_f32_e32 v112, v37, v112
	global_store_dword v134, v112, s[24:25] offset:2048
	s_waitcnt vmcnt(31)
	v_lshlrev_b32_e32 v113, 16, v113
	v_mul_f32_e32 v5, v5, v80
	v_mul_f32_e32 v113, v5, v113
	global_store_dword v134, v113, s[26:27] offset:2048
	s_add_u32 s20, s34, 0x2000
	s_addc_u32 s21, s35, 0
	s_add_u32 s22, s34, 0xa000
	s_addc_u32 s23, s35, 0
	s_add_u32 s24, s34, 0x12000
	s_addc_u32 s25, s35, 0
	s_add_u32 s26, s34, 0x1a000
	s_addc_u32 s27, s35, 0
	s_waitcnt vmcnt(31)
	v_lshlrev_b32_e32 v114, 16, v114
	v_mul_f32_e32 v22, v22, v79
	v_mul_f32_e32 v114, v22, v114
	global_store_dword v134, v114, s[20:21]
	s_waitcnt vmcnt(31)
	v_lshlrev_b32_e32 v115, 16, v115
	v_mul_f32_e32 v54, v54, v79
	v_mul_f32_e32 v115, v54, v115
	global_store_dword v134, v115, s[22:23]
	s_waitcnt vmcnt(31)
	v_lshlrev_b32_e32 v116, 16, v116
	v_mul_f32_e32 v38, v38, v79
	v_mul_f32_e32 v116, v38, v116
	global_store_dword v134, v116, s[24:25]
	s_waitcnt vmcnt(31)
	v_lshlrev_b32_e32 v117, 16, v117
	v_mul_f32_e32 v6, v6, v79
	v_mul_f32_e32 v117, v6, v117
	global_store_dword v134, v117, s[26:27]
	s_waitcnt vmcnt(31)
	v_lshlrev_b32_e32 v118, 16, v118
	v_mul_f32_e32 v23, v23, v78
	v_mul_f32_e32 v118, v23, v118
	global_store_dword v134, v118, s[20:21] offset:2048
	s_waitcnt vmcnt(31)
	v_lshlrev_b32_e32 v119, 16, v119
	v_mul_f32_e32 v55, v55, v78
	v_mul_f32_e32 v119, v55, v119
	global_store_dword v134, v119, s[22:23] offset:2048
	s_waitcnt vmcnt(31)
	v_lshlrev_b32_e32 v120, 16, v120
	v_mul_f32_e32 v39, v39, v78
	v_mul_f32_e32 v120, v39, v120
	global_store_dword v134, v120, s[24:25] offset:2048
	s_waitcnt vmcnt(31)
	v_lshlrev_b32_e32 v121, 16, v121
	v_mul_f32_e32 v7, v7, v78
	v_mul_f32_e32 v121, v7, v121
	global_store_dword v134, v121, s[26:27] offset:2048
	s_add_u32 s20, s34, 0x3000
	s_addc_u32 s21, s35, 0
	s_add_u32 s22, s34, 0xb000
	s_addc_u32 s23, s35, 0
	s_add_u32 s24, s34, 0x13000
	s_addc_u32 s25, s35, 0
	s_add_u32 s26, s34, 0x1b000
	s_addc_u32 s27, s35, 0
	s_waitcnt vmcnt(31)
	v_lshlrev_b32_e32 v122, 16, v122
	v_mul_f32_e32 v24, v24, v77
	v_mul_f32_e32 v122, v24, v122
	global_store_dword v134, v122, s[20:21]
	s_waitcnt vmcnt(31)
	v_lshlrev_b32_e32 v123, 16, v123
	v_mul_f32_e32 v56, v56, v77
	v_mul_f32_e32 v123, v56, v123
	global_store_dword v134, v123, s[22:23]
	s_waitcnt vmcnt(31)
	v_lshlrev_b32_e32 v124, 16, v124
	v_mul_f32_e32 v40, v40, v77
	v_mul_f32_e32 v124, v40, v124
	global_store_dword v134, v124, s[24:25]
	s_waitcnt vmcnt(31)
	v_lshlrev_b32_e32 v125, 16, v125
	v_mul_f32_e32 v8, v8, v77
	v_mul_f32_e32 v125, v8, v125
	global_store_dword v134, v125, s[26:27]
	s_waitcnt vmcnt(31)
	v_lshlrev_b32_e32 v126, 16, v126
	v_mul_f32_e32 v25, v25, v76
	v_mul_f32_e32 v126, v25, v126
	global_store_dword v134, v126, s[20:21] offset:2048
	s_waitcnt vmcnt(31)
	v_lshlrev_b32_e32 v127, 16, v127
	v_mul_f32_e32 v57, v57, v76
	v_mul_f32_e32 v127, v57, v127
	global_store_dword v134, v127, s[22:23] offset:2048
	s_waitcnt vmcnt(31)
	v_lshlrev_b32_e32 v128, 16, v128
	v_mul_f32_e32 v41, v41, v76
	v_mul_f32_e32 v128, v41, v128
	global_store_dword v134, v128, s[24:25] offset:2048
	s_waitcnt vmcnt(31)
; __device__ __forceinline__ float bf2f(bf16_t v) { return __uint_as_float(((unsigned)v) << 16); }
; __device__ __forceinline__ int crow(int r, int hi) { return (r & 3) + 8 * (r >> 2) + 4 * hi; }
; template <int MODE>
; __device__ __forceinline__ void attn_body(const bf16_t* __restrict__ Qb, const bf16_t* __restrict__ Kh, const bf16_t* __restrict__ Vh, int NT, int krel0,
;                                           char* lds, const float* __restrict__ lutg, const AttnEpi& E) {
;     ...
;     for (int r = 0; r < 16; ++r) { const int row = rowb + crow(r, hi);
; #pragma unroll
;       for (int d0 = 0; d0 < 4; ++d0) { const int idx = (d0 * 16 + r) * 512 + tid;
;         const float g = bf2f(E.gate[(size_t)row * GW + d0 * 32 + r32]);
;         const float v = o[d0][r] * rli[r] * g;
;         if constexpr (MODE == 0) pk0[idx] = v; else pk0[idx] += v; } }
	v_lshlrev_b32_e32 v129, 16, v129
	v_mul_f32_e32 v9, v9, v76
	v_mul_f32_e32 v129, v9, v129
	global_store_dword v134, v129, s[26:27] offset:2048
	v_or_b32_e32 v132, 16, v0
	v_mad_i64_i32 v[130:131], s[28:29], v132, s88, v[66:67]
	global_load_ushort v136, v[130:131], off
	global_load_ushort v137, v[130:131], off offset:64
	global_load_ushort v138, v[130:131], off offset:128
	global_load_ushort v139, v[130:131], off offset:192
	v_or_b32_e32 v132, 17, v0
	v_mad_i64_i32 v[130:131], s[28:29], v132, s88, v[66:67]
	global_load_ushort v140, v[130:131], off
	global_load_ushort v141, v[130:131], off offset:64
	global_load_ushort v142, v[130:131], off offset:128
	global_load_ushort v143, v[130:131], off offset:192
	v_or_b32_e32 v132, 18, v0
	v_mad_i64_i32 v[130:131], s[28:29], v132, s88, v[66:67]
	global_load_ushort v144, v[130:131], off
	global_load_ushort v145, v[130:131], off offset:64
	global_load_ushort v146, v[130:131], off offset:128
	global_load_ushort v147, v[130:131], off offset:192
	v_or_b32_e32 v132, 19, v0
	v_mad_i64_i32 v[130:131], s[28:29], v132, s88, v[66:67]
	global_load_ushort v148, v[130:131], off
	global_load_ushort v149, v[130:131], off offset:64
	global_load_ushort v150, v[130:131], off offset:128
	global_load_ushort v151, v[130:131], off offset:192
	v_or_b32_e32 v132, 24, v0
	v_mad_i64_i32 v[130:131], s[28:29], v132, s88, v[66:67]
	global_load_ushort v152, v[130:131], off
	global_load_ushort v153, v[130:131], off offset:64
	global_load_ushort v154, v[130:131], off offset:128
	global_load_ushort v155, v[130:131], off offset:192
	v_or_b32_e32 v132, 25, v0
	v_mad_i64_i32 v[130:131], s[28:29], v132, s88, v[66:67]
	global_load_ushort v156, v[130:131], off
	global_load_ushort v157, v[130:131], off offset:64
	global_load_ushort v158, v[130:131], off offset:128
	global_load_ushort v159, v[130:131], off offset:192
	v_or_b32_e32 v132, 26, v0
	v_mad_i64_i32 v[130:131], s[28:29], v132, s88, v[66:67]
	global_load_ushort v160, v[130:131], off
	global_load_ushort v161, v[130:131], off offset:64
	global_load_ushort v162, v[130:131], off offset:128
	global_load_ushort v163, v[130:131], off offset:192
	v_or_b32_e32 v132, 27, v0
	v_mad_i64_i32 v[130:131], s[28:29], v132, s88, v[66:67]
	global_load_ushort v164, v[130:131], off
	global_load_ushort v165, v[130:131], off offset:64
	global_load_ushort v166, v[130:131], off offset:128
	global_load_ushort v167, v[130:131], off offset:192
	s_add_u32 s20, s34, 0x4000
	s_addc_u32 s21, s35, 0
	s_add_u32 s22, s34, 0xc000
	s_addc_u32 s23, s35, 0
	s_add_u32 s24, s34, 0x14000
	s_addc_u32 s25, s35, 0
	s_add_u32 s26, s34, 0x1c000
	s_addc_u32 s27, s35, 0
	s_waitcnt vmcnt(31)
	v_lshlrev_b32_e32 v136, 16, v136
	v_mul_f32_e32 v26, v26, v75
	v_mul_f32_e32 v136, v26, v136
	global_store_dword v134, v136, s[20:21]
	s_waitcnt vmcnt(31)
	v_lshlrev_b32_e32 v137, 16, v137
	v_mul_f32_e32 v58, v58, v75
	v_mul_f32_e32 v137, v58, v137
	global_store_dword v134, v137, s[22:23]
	s_waitcnt vmcnt(31)
	v_lshlrev_b32_e32 v138, 16, v138
	v_mul_f32_e32 v42, v42, v75
	v_mul_f32_e32 v138, v42, v138
	global_store_dword v134, v138, s[24:25]
	s_waitcnt vmcnt(31)
	v_lshlrev_b32_e32 v139, 16, v139
	v_mul_f32_e32 v10, v10, v75
	v_mul_f32_e32 v139, v10, v139
	global_store_dword v134, v139, s[26:27]
	s_waitcnt vmcnt(31)
	v_lshlrev_b32_e32 v140, 16, v140
	v_mul_f32_e32 v27, v27, v74
	v_mul_f32_e32 v140, v27, v140
	global_store_dword v134, v140, s[20:21] offset:2048
	s_waitcnt vmcnt(31)
	v_lshlrev_b32_e32 v141, 16, v141
	v_mul_f32_e32 v59, v59, v74
	v_mul_f32_e32 v141, v59, v141
	global_store_dword v134, v141, s[22:23] offset:2048
	s_waitcnt vmcnt(31)
	v_lshlrev_b32_e32 v142, 16, v142
	v_mul_f32_e32 v43, v43, v74
	v_mul_f32_e32 v142, v43, v142
	global_store_dword v134, v142, s[24:25] offset:2048
	s_waitcnt vmcnt(31)
	v_lshlrev_b32_e32 v143, 16, v143
	v_mul_f32_e32 v11, v11, v74
	v_mul_f32_e32 v143, v11, v143
	global_store_dword v134, v143, s[26:27] offset:2048
	s_add_u32 s20, s34, 0x5000
	s_addc_u32 s21, s35, 0
	s_add_u32 s22, s34, 0xd000
	s_addc_u32 s23, s35, 0
	s_add_u32 s24, s34, 0x15000
	s_addc_u32 s25, s35, 0
	s_add_u32 s26, s34, 0x1d000
	s_addc_u32 s27, s35, 0
	s_waitcnt vmcnt(31)
	v_lshlrev_b32_e32 v144, 16, v144
	v_mul_f32_e32 v28, v28, v73
	v_mul_f32_e32 v144, v28, v144
	global_store_dword v134, v144, s[20:21]
	s_waitcnt vmcnt(31)
	v_lshlrev_b32_e32 v145, 16, v145
	v_mul_f32_e32 v60, v60, v73
	v_mul_f32_e32 v145, v60, v145
	global_store_dword v134, v145, s[22:23]
	s_waitcnt vmcnt(31)
	v_lshlrev_b32_e32 v146, 16, v146
	v_mul_f32_e32 v44, v44, v73
	v_mul_f32_e32 v146, v44, v146
	global_store_dword v134, v146, s[24:25]
	s_waitcnt vmcnt(31)
	v_lshlrev_b32_e32 v147, 16, v147
	v_mul_f32_e32 v12, v12, v73
	v_mul_f32_e32 v147, v12, v147
	global_store_dword v134, v147, s[26:27]
	s_waitcnt vmcnt(31)
	v_lshlrev_b32_e32 v148, 16, v148
	v_mul_f32_e32 v29, v29, v72
	v_mul_f32_e32 v148, v29, v148
	global_store_dword v134, v148, s[20:21] offset:2048
	s_waitcnt vmcnt(31)
	v_lshlrev_b32_e32 v149, 16, v149
	v_mul_f32_e32 v61, v61, v72
	v_mul_f32_e32 v149, v61, v149
	global_store_dword v134, v149, s[22:23] offset:2048
	s_waitcnt vmcnt(31)
	v_lshlrev_b32_e32 v150, 16, v150
	v_mul_f32_e32 v45, v45, v72
	v_mul_f32_e32 v150, v45, v150
	global_store_dword v134, v150, s[24:25] offset:2048
	s_waitcnt vmcnt(31)
	v_lshlrev_b32_e32 v151, 16, v151
	v_mul_f32_e32 v13, v13, v72
	v_mul_f32_e32 v151, v13, v151
	global_store_dword v134, v151, s[26:27] offset:2048
	s_add_u32 s20, s34, 0x6000
	s_addc_u32 s21, s35, 0
	s_add_u32 s22, s34, 0xe000
	s_addc_u32 s23, s35, 0
	s_add_u32 s24, s34, 0x16000
	s_addc_u32 s25, s35, 0
	s_add_u32 s26, s34, 0x1e000
	s_addc_u32 s27, s35, 0
	s_waitcnt vmcnt(31)
; __device__ __forceinline__ float bf2f(bf16_t v) { return __uint_as_float(((unsigned)v) << 16); }
; __device__ __forceinline__ int crow(int r, int hi) { return (r & 3) + 8 * (r >> 2) + 4 * hi; }
; template <int MODE>
; __device__ __forceinline__ void attn_body(const bf16_t* __restrict__ Qb, const bf16_t* __restrict__ Kh, const bf16_t* __restrict__ Vh, int NT, int krel0,
;                                           char* lds, const float* __restrict__ lutg, const AttnEpi& E) {
;     ...
;   __syncthreads();
;   if constexpr (MODE != 0) { if (tid < 259) lut[tid] = lutg[tid]; }
;   float m_reg = -1e30f, l_reg = 0; f32x16 o[4] = {}; bf16x8 qr[ND0];
;   const bf16_t* Qw = Qb + (size_t)(wid * 32 + r32) * LDQK + hi * 8;
;   {
;     float qf[ND0][8]; float ss = 0.f;
; #pragma unroll
;     for (int d0 = 0; d0 < ND0; ++d0) { const bf16x8 raw = *reinterpret_cast<const bf16x8*>(Qw + d0 * 16);
; #pragma unroll
;       for (int j = 0; j < 8; ++j) { const float v = __uint_as_float(((unsigned)(unsigned short)raw[j]) << 16); qf[d0][j] = v; ss += v * v; } }
;     ...
;     for (int r = 0; r < 16; ++r) { const int row = rowb + crow(r, hi);
; #pragma unroll
;       for (int d0 = 0; d0 < 4; ++d0) { const int idx = (d0 * 16 + r) * 512 + tid;
;         const float g = bf2f(E.gate[(size_t)row * GW + d0 * 32 + r32]);
;         const float v = o[d0][r] * rli[r] * g;
;         if constexpr (MODE == 0) pk0[idx] = v; else pk0[idx] += v; } }
	v_lshlrev_b32_e32 v152, 16, v152
	v_mul_f32_e32 v30, v30, v71
	v_mul_f32_e32 v152, v30, v152
	global_store_dword v134, v152, s[20:21]
	s_waitcnt vmcnt(31)
	v_lshlrev_b32_e32 v153, 16, v153
	v_mul_f32_e32 v62, v62, v71
	v_mul_f32_e32 v153, v62, v153
	global_store_dword v134, v153, s[22:23]
	s_waitcnt vmcnt(31)
	v_lshlrev_b32_e32 v154, 16, v154
	v_mul_f32_e32 v46, v46, v71
	v_mul_f32_e32 v154, v46, v154
	global_store_dword v134, v154, s[24:25]
	s_waitcnt vmcnt(31)
	v_lshlrev_b32_e32 v155, 16, v155
	v_mul_f32_e32 v14, v14, v71
	v_mul_f32_e32 v155, v14, v155
	global_store_dword v134, v155, s[26:27]
	s_waitcnt vmcnt(31)
	v_lshlrev_b32_e32 v156, 16, v156
	v_mul_f32_e32 v31, v31, v70
	v_mul_f32_e32 v156, v31, v156
	global_store_dword v134, v156, s[20:21] offset:2048
	s_waitcnt vmcnt(31)
	v_lshlrev_b32_e32 v157, 16, v157
	v_mul_f32_e32 v63, v63, v70
	v_mul_f32_e32 v157, v63, v157
	global_store_dword v134, v157, s[22:23] offset:2048
	s_waitcnt vmcnt(31)
	v_lshlrev_b32_e32 v158, 16, v158
	v_mul_f32_e32 v47, v47, v70
	v_mul_f32_e32 v158, v47, v158
	global_store_dword v134, v158, s[24:25] offset:2048
	s_waitcnt vmcnt(31)
	v_lshlrev_b32_e32 v159, 16, v159
	v_mul_f32_e32 v15, v15, v70
	v_mul_f32_e32 v159, v15, v159
	global_store_dword v134, v159, s[26:27] offset:2048
	s_add_u32 s20, s34, 0x7000
	s_addc_u32 s21, s35, 0
	s_add_u32 s22, s34, 0xf000
	s_addc_u32 s23, s35, 0
	s_add_u32 s24, s34, 0x17000
	s_addc_u32 s25, s35, 0
	s_add_u32 s26, s34, 0x1f000
	s_addc_u32 s27, s35, 0
	s_waitcnt vmcnt(31)
	v_lshlrev_b32_e32 v160, 16, v160
	v_mul_f32_e32 v32, v32, v69
	v_mul_f32_e32 v160, v32, v160
	global_store_dword v134, v160, s[20:21]
	s_waitcnt vmcnt(31)
	v_lshlrev_b32_e32 v161, 16, v161
	v_mul_f32_e32 v64, v64, v69
	v_mul_f32_e32 v161, v64, v161
	global_store_dword v134, v161, s[22:23]
	s_waitcnt vmcnt(31)
	v_lshlrev_b32_e32 v162, 16, v162
	v_mul_f32_e32 v48, v48, v69
	v_mul_f32_e32 v162, v48, v162
	global_store_dword v134, v162, s[24:25]
	s_waitcnt vmcnt(31)
	v_lshlrev_b32_e32 v163, 16, v163
	v_mul_f32_e32 v16, v16, v69
	v_mul_f32_e32 v163, v16, v163
	global_store_dword v134, v163, s[26:27]
	s_waitcnt vmcnt(31)
	v_lshlrev_b32_e32 v164, 16, v164
	v_mul_f32_e32 v33, v33, v68
	v_mul_f32_e32 v164, v33, v164
	global_store_dword v134, v164, s[20:21] offset:2048
	s_waitcnt vmcnt(31)
	v_lshlrev_b32_e32 v165, 16, v165
	v_mul_f32_e32 v65, v65, v68
	v_mul_f32_e32 v165, v65, v165
	global_store_dword v134, v165, s[22:23] offset:2048
	s_waitcnt vmcnt(31)
	v_lshlrev_b32_e32 v166, 16, v166
	v_mul_f32_e32 v49, v49, v68
	v_mul_f32_e32 v166, v49, v166
	global_store_dword v134, v166, s[24:25] offset:2048
	s_waitcnt vmcnt(31)
	v_lshlrev_b32_e32 v167, 16, v167
	v_mul_f32_e32 v17, v17, v68
	v_mul_f32_e32 v167, v17, v167
	global_store_dword v134, v167, s[26:27] offset:2048
	s_mulk_i32 s59, 0x40c
	s_lshl_b32 s0, s58, 2
	s_max_i32 s63, s0, 2
	s_add_i32 s0, s0, 6
	s_min_i32 s66, s11, s0
	v_readlane_b32 s0, v252, 45
	v_readlane_b32 s1, v252, 46
	s_add_u32 s58, s0, s59
	s_movk_i32 s0, 0x103
	s_addc_u32 s59, s1, 0
	v_mov_b32_e32 v188, v179
	s_nop 0
	v_cmp_gt_i32_e32 vcc, s0, v188
	v_ashrrev_i32_e32 v189, 31, v188
	s_barrier
	v_lshl_add_u64 v[2:3], v[188:189], 2, s[58:59]
	global_load_dword v114, v[2:3], off
	v_lshl_add_u32 v115, v188, 2, 0
	v_add_u32_e32 v115, 0x18800, v115
.LBB0_99:
	s_add_i32 s71, s63, -2
	s_mul_i32 s72, s71, 0x90000
	s_mul_hi_u32 s70, s71, 0x90000
	s_add_u32 s0, s67, s72
	s_addc_u32 s1, s65, s70
	s_lshl_b32 s68, s62, 1
	s_add_u32 s6, s0, s68
	s_addc_u32 s7, s1, 0
	s_add_u32 s0, s6, 0x1400
	s_addc_u32 s1, s7, 0
	s_add_u32 s6, s6, 0x1600
	s_addc_u32 s7, s7, 0
	s_sub_i32 s69, s66, s71
	v_ashrrev_i32_e32 v206, 1, v188
	s_movk_i32 s66, 0xffe0
	v_bfe_u32 v96, v188, 5, 1
	v_bfi_b32 v97, s66, v206, v188
	v_mov_b64_e32 v[2:3], s[60:61]
	v_mad_i64_i32 v[2:3], s[60:61], v97, s73, v[2:3]
	v_lshlrev_b32_e32 v0, 4, v96
	v_lshl_add_u64 v[2:3], v[2:3], 0, v[0:1]
	global_load_dwordx4 v[66:69], v[2:3], off offset:3072
	global_load_dwordx4 v[98:101], v[2:3], off offset:3104
	global_load_dwordx4 v[102:105], v[2:3], off offset:3136
	global_load_dwordx4 v[106:109], v[2:3], off offset:3168
	global_load_dwordx4 v[110:113], v[2:3], off offset:3200
	global_load_dwordx4 v[92:95], v[2:3], off offset:3232
	global_load_dwordx4 v[84:87], v[2:3], off offset:3264
	global_load_dwordx4 v[76:79], v[2:3], off offset:3296
	v_and_b32_e32 v6, 32, v188
	global_load_dwordx4 v[58:61], v6, s[42:43] offset:16
	global_load_dwordx4 v[62:65], v6, s[42:43]
	global_load_dwordx4 v[50:53], v6, s[42:43] offset:80
	global_load_dwordx4 v[54:57], v6, s[42:43] offset:64
	global_load_dwordx4 v[42:45], v6, s[42:43] offset:144
	global_load_dwordx4 v[46:49], v6, s[42:43] offset:128
	global_load_dwordx4 v[34:37], v6, s[42:43] offset:208
	global_load_dwordx4 v[38:41], v6, s[42:43] offset:192
	global_load_dwordx4 v[26:29], v6, s[42:43] offset:272
	global_load_dwordx4 v[30:33], v6, s[42:43] offset:256
	global_load_dwordx4 v[18:21], v6, s[42:43] offset:336
	global_load_dwordx4 v[22:25], v6, s[42:43] offset:320
	global_load_dwordx4 v[10:13], v6, s[42:43] offset:400
	global_load_dwordx4 v[14:17], v6, s[42:43] offset:384
	global_load_dwordx4 v[2:5], v6, s[42:43] offset:464
	s_nop 0
	global_load_dwordx4 v[6:9], v6, s[42:43] offset:448
	s_lshl_b32 s62, s71, 6
	v_lshlrev_b32_e32 v205, 2, v96
	v_and_b32_e32 v204, 31, v188
	s_add_i32 s76, 0, 0x18800
	s_waitcnt vmcnt(24)
	ds_write_b32 v115, v114
	s_waitcnt vmcnt(23)
; template <int MODE>
; __device__ __forceinline__ void attn_body(const bf16_t* __restrict__ Qb, const bf16_t* __restrict__ Kh, const bf16_t* __restrict__ Vh, int NT, int krel0,
;                                           char* lds, const float* __restrict__ lutg, const AttnEpi& E) {
;     ...
;     float qf[ND0][8]; float ss = 0.f;
; #pragma unroll
;     for (int d0 = 0; d0 < ND0; ++d0) { const bf16x8 raw = *reinterpret_cast<const bf16x8*>(Qw + d0 * 16);
; #pragma unroll
;       for (int j = 0; j < 8; ++j) { const float v = __uint_as_float(((unsigned)(unsigned short)raw[j]) << 16); qf[d0][j] = v; ss += v * v; } }
;     { auto rr = __builtin_amdgcn_permlane32_swap(__float_as_uint(ss), __float_as_uint(ss), false, false);
;       ss = __uint_as_float(rr[0]) + __uint_as_float(rr[1]); }
	v_and_b32_e32 v131, 0xffff0000, v67
	v_lshlrev_b32_e32 v130, 16, v67
	v_and_b32_e32 v67, 0xffff0000, v66
	v_lshlrev_b32_e32 v66, 16, v66
	v_mul_f32_e32 v132, v67, v67
	v_pk_fma_f32 v[132:133], v[66:67], v[66:67], v[132:133] op_sel_hi:[1,1,0]
	v_mul_f32_e32 v134, v131, v131
	v_pk_fma_f32 v[132:133], v[130:131], v[130:131], v[132:133]
	v_and_b32_e32 v129, 0xffff0000, v69
	v_lshlrev_b32_e32 v128, 16, v69
	v_and_b32_e32 v69, 0xffff0000, v68
	v_lshlrev_b32_e32 v68, 16, v68
	v_pk_add_f32 v[132:133], v[134:135], v[132:133] op_sel_hi:[0,1]
	v_pk_fma_f32 v[132:133], v[68:69], v[68:69], v[132:133]
	v_mul_f32_e32 v134, v69, v69
	v_pk_add_f32 v[132:133], v[134:135], v[132:133] op_sel_hi:[0,1]
	v_pk_fma_f32 v[132:133], v[128:129], v[128:129], v[132:133]
	v_mul_f32_e32 v134, v129, v129
	s_waitcnt vmcnt(22)
	v_and_b32_e32 v127, 0xffff0000, v99
	v_lshlrev_b32_e32 v126, 16, v99
	v_and_b32_e32 v99, 0xffff0000, v98
	v_lshlrev_b32_e32 v98, 16, v98
	v_pk_add_f32 v[132:133], v[134:135], v[132:133] op_sel_hi:[0,1]
	v_pk_fma_f32 v[132:133], v[98:99], v[98:99], v[132:133]
	v_mul_f32_e32 v134, v99, v99
	v_pk_add_f32 v[132:133], v[134:135], v[132:133] op_sel_hi:[0,1]
	v_pk_fma_f32 v[132:133], v[126:127], v[126:127], v[132:133]
	v_mul_f32_e32 v134, v127, v127
	v_and_b32_e32 v125, 0xffff0000, v101
	v_lshlrev_b32_e32 v124, 16, v101
	v_and_b32_e32 v101, 0xffff0000, v100
	v_lshlrev_b32_e32 v100, 16, v100
	v_pk_add_f32 v[132:133], v[134:135], v[132:133] op_sel_hi:[0,1]
	v_pk_fma_f32 v[132:133], v[100:101], v[100:101], v[132:133]
	v_mul_f32_e32 v134, v101, v101
	v_pk_add_f32 v[132:133], v[134:135], v[132:133] op_sel_hi:[0,1]
	v_pk_fma_f32 v[132:133], v[124:125], v[124:125], v[132:133]
	v_mul_f32_e32 v134, v125, v125
	s_waitcnt vmcnt(21)
	v_and_b32_e32 v123, 0xffff0000, v103
	v_lshlrev_b32_e32 v122, 16, v103
	v_and_b32_e32 v103, 0xffff0000, v102
	v_lshlrev_b32_e32 v102, 16, v102
	v_pk_add_f32 v[132:133], v[134:135], v[132:133] op_sel_hi:[0,1]
	v_pk_fma_f32 v[132:133], v[102:103], v[102:103], v[132:133]
	v_mul_f32_e32 v134, v103, v103
	v_pk_add_f32 v[132:133], v[134:135], v[132:133] op_sel_hi:[0,1]
	v_pk_fma_f32 v[132:133], v[122:123], v[122:123], v[132:133]
	v_mul_f32_e32 v134, v123, v123
	v_and_b32_e32 v121, 0xffff0000, v105
	v_lshlrev_b32_e32 v120, 16, v105
	v_and_b32_e32 v105, 0xffff0000, v104
	v_lshlrev_b32_e32 v104, 16, v104
	v_pk_add_f32 v[132:133], v[134:135], v[132:133] op_sel_hi:[0,1]
	v_pk_fma_f32 v[132:133], v[104:105], v[104:105], v[132:133]
	v_mul_f32_e32 v134, v105, v105
	v_pk_add_f32 v[132:133], v[134:135], v[132:133] op_sel_hi:[0,1]
	v_pk_fma_f32 v[132:133], v[120:121], v[120:121], v[132:133]
	v_mul_f32_e32 v134, v121, v121
	s_waitcnt vmcnt(20)
	v_and_b32_e32 v119, 0xffff0000, v107
	v_lshlrev_b32_e32 v118, 16, v107
	v_and_b32_e32 v107, 0xffff0000, v106
	v_lshlrev_b32_e32 v106, 16, v106
	v_pk_add_f32 v[132:133], v[134:135], v[132:133] op_sel_hi:[0,1]
	v_pk_fma_f32 v[132:133], v[106:107], v[106:107], v[132:133]
	v_mul_f32_e32 v134, v107, v107
	v_pk_add_f32 v[132:133], v[134:135], v[132:133] op_sel_hi:[0,1]
	v_pk_fma_f32 v[132:133], v[118:119], v[118:119], v[132:133]
	v_mul_f32_e32 v134, v119, v119
	v_and_b32_e32 v117, 0xffff0000, v109
	v_lshlrev_b32_e32 v116, 16, v109
	v_and_b32_e32 v109, 0xffff0000, v108
	v_lshlrev_b32_e32 v108, 16, v108
	v_pk_add_f32 v[132:133], v[134:135], v[132:133] op_sel_hi:[0,1]
	v_pk_fma_f32 v[132:133], v[108:109], v[108:109], v[132:133]
	v_mul_f32_e32 v134, v109, v109
	v_pk_add_f32 v[132:133], v[134:135], v[132:133] op_sel_hi:[0,1]
	v_pk_fma_f32 v[132:133], v[116:117], v[116:117], v[132:133]
	v_mul_f32_e32 v134, v117, v117
	s_waitcnt vmcnt(19)
	v_and_b32_e32 v115, 0xffff0000, v111
	v_lshlrev_b32_e32 v114, 16, v111
	v_and_b32_e32 v111, 0xffff0000, v110
	v_lshlrev_b32_e32 v110, 16, v110
	v_pk_add_f32 v[132:133], v[134:135], v[132:133] op_sel_hi:[0,1]
	v_pk_fma_f32 v[132:133], v[110:111], v[110:111], v[132:133]
	v_mul_f32_e32 v134, v111, v111
	v_pk_add_f32 v[132:133], v[134:135], v[132:133] op_sel_hi:[0,1]
	v_pk_fma_f32 v[132:133], v[114:115], v[114:115], v[132:133]
	v_mul_f32_e32 v134, v115, v115
	s_waitcnt vmcnt(16)
	v_and_b32_e32 v71, 0xffff0000, v79
	v_lshlrev_b32_e32 v70, 16, v79
	v_and_b32_e32 v73, 0xffff0000, v78
	v_lshlrev_b32_e32 v72, 16, v78
	v_and_b32_e32 v79, 0xffff0000, v87
	v_lshlrev_b32_e32 v78, 16, v87
	v_and_b32_e32 v81, 0xffff0000, v86
	v_lshlrev_b32_e32 v80, 16, v86
	v_and_b32_e32 v87, 0xffff0000, v95
	v_lshlrev_b32_e32 v86, 16, v95
	v_and_b32_e32 v89, 0xffff0000, v94
	v_lshlrev_b32_e32 v88, 16, v94
	v_and_b32_e32 v95, 0xffff0000, v113
	v_lshlrev_b32_e32 v94, 16, v113
	v_and_b32_e32 v113, 0xffff0000, v112
	v_lshlrev_b32_e32 v112, 16, v112
	v_pk_add_f32 v[132:133], v[134:135], v[132:133] op_sel_hi:[0,1]
	v_pk_fma_f32 v[132:133], v[112:113], v[112:113], v[132:133]
	v_mul_f32_e32 v134, v113, v113
	v_pk_add_f32 v[132:133], v[134:135], v[132:133] op_sel_hi:[0,1]
	v_pk_fma_f32 v[132:133], v[94:95], v[94:95], v[132:133]
	v_mul_f32_e32 v134, v95, v95
	v_and_b32_e32 v91, 0xffff0000, v93
	v_lshlrev_b32_e32 v90, 16, v93
	v_and_b32_e32 v93, 0xffff0000, v92
	v_lshlrev_b32_e32 v92, 16, v92
	v_pk_add_f32 v[132:133], v[134:135], v[132:133] op_sel_hi:[0,1]
	v_pk_fma_f32 v[132:133], v[92:93], v[92:93], v[132:133]
	v_mul_f32_e32 v134, v93, v93
	v_pk_add_f32 v[132:133], v[134:135], v[132:133] op_sel_hi:[0,1]
	v_pk_fma_f32 v[132:133], v[90:91], v[90:91], v[132:133]
	v_mul_f32_e32 v134, v91, v91
	v_pk_add_f32 v[132:133], v[134:135], v[132:133] op_sel_hi:[0,1]
	v_pk_fma_f32 v[132:133], v[88:89], v[88:89], v[132:133]
	v_mul_f32_e32 v134, v89, v89
	v_pk_add_f32 v[132:133], v[134:135], v[132:133] op_sel_hi:[0,1]
; template <int MODE>
; __device__ __forceinline__ void attn_body(const bf16_t* __restrict__ Qb, const bf16_t* __restrict__ Kh, const bf16_t* __restrict__ Vh, int NT, int krel0,
;                                           char* lds, const float* __restrict__ lutg, const AttnEpi& E) {
;     ...
;     { auto rr = __builtin_amdgcn_permlane32_swap(__float_as_uint(ss), __float_as_uint(ss), false, false);
;       ss = __uint_as_float(rr[0]) + __uint_as_float(rr[1]); }
;     const float rs = rsqrtf(ss * (MODE < 2 ? (1.f / 128.f) : (1.f / 64.f)) + EPS);
; #pragma unroll
;     for (int d0 = 0; d0 < ND0; ++d0) { const f32x4 g0 = *(const f32x4*)(E.gq + d0 * 16 + hi * 8), g1 = *(const f32x4*)(E.gq + d0 * 16 + hi * 8 + 4);
; #pragma unroll
;       for (int j = 0; j < 4; ++j) { qf[d0][j] = qf[d0][j] * rs * g0[j]; qf[d0][4 + j] = qf[d0][4 + j] * rs * g1[j]; } }
	v_pk_fma_f32 v[132:133], v[86:87], v[86:87], v[132:133]
	v_mul_f32_e32 v134, v87, v87
	v_and_b32_e32 v83, 0xffff0000, v85
	v_lshlrev_b32_e32 v82, 16, v85
	v_and_b32_e32 v85, 0xffff0000, v84
	v_lshlrev_b32_e32 v84, 16, v84
	v_pk_add_f32 v[132:133], v[134:135], v[132:133] op_sel_hi:[0,1]
	v_pk_fma_f32 v[132:133], v[84:85], v[84:85], v[132:133]
	v_mul_f32_e32 v134, v85, v85
	v_pk_add_f32 v[132:133], v[134:135], v[132:133] op_sel_hi:[0,1]
	v_pk_fma_f32 v[132:133], v[82:83], v[82:83], v[132:133]
	v_mul_f32_e32 v134, v83, v83
	v_pk_add_f32 v[132:133], v[134:135], v[132:133] op_sel_hi:[0,1]
	v_pk_fma_f32 v[132:133], v[80:81], v[80:81], v[132:133]
	v_mul_f32_e32 v134, v81, v81
	v_pk_add_f32 v[132:133], v[134:135], v[132:133] op_sel_hi:[0,1]
	v_pk_fma_f32 v[132:133], v[78:79], v[78:79], v[132:133]
	v_mul_f32_e32 v134, v79, v79
	v_and_b32_e32 v75, 0xffff0000, v77
	v_lshlrev_b32_e32 v74, 16, v77
	v_and_b32_e32 v77, 0xffff0000, v76
	v_lshlrev_b32_e32 v76, 16, v76
	v_pk_add_f32 v[132:133], v[134:135], v[132:133] op_sel_hi:[0,1]
	v_pk_fma_f32 v[132:133], v[76:77], v[76:77], v[132:133]
	v_mul_f32_e32 v134, v77, v77
	v_pk_add_f32 v[132:133], v[134:135], v[132:133] op_sel_hi:[0,1]
	v_pk_fma_f32 v[132:133], v[74:75], v[74:75], v[132:133]
	v_mul_f32_e32 v134, v75, v75
	v_pk_add_f32 v[132:133], v[134:135], v[132:133] op_sel_hi:[0,1]
	v_pk_fma_f32 v[132:133], v[72:73], v[72:73], v[132:133]
	v_mul_f32_e32 v134, v73, v73
	v_pk_add_f32 v[132:133], v[134:135], v[132:133] op_sel_hi:[0,1]
	v_pk_fma_f32 v[132:133], v[70:71], v[70:71], v[132:133]
	v_mul_f32_e32 v134, v71, v71
	v_pk_add_f32 v[132:133], v[134:135], v[132:133] op_sel_hi:[0,1]
	v_mov_b32_e32 v133, v132
	s_nop 1
	v_permlane32_swap_b32_e32 v132, v133
	v_add_f32_e32 v132, v132, v133
	v_fmamk_f32 v132, v132, 0x3c000000, v178
	v_cmp_gt_f32_e32 vcc, s49, v132
	v_mul_f32_e32 v133, 0x4b800000, v132
	s_nop 0
	v_cndmask_b32_e32 v132, v132, v133, vcc
	v_rsq_f32_e32 v132, v132
	s_nop 0
	v_mul_f32_e32 v133, 0x45800000, v132
	v_cndmask_b32_e32 v132, v132, v133, vcc
	v_pk_mul_f32 v[66:67], v[132:133], v[66:67] op_sel_hi:[0,1]
	s_waitcnt vmcnt(14)
	v_pk_mul_f32 v[62:63], v[62:63], v[66:67]
	v_pk_mul_f32 v[66:67], v[132:133], v[68:69] op_sel_hi:[0,1]
	v_pk_mul_f32 v[58:59], v[58:59], v[66:67]
	v_pk_mul_f32 v[66:67], v[132:133], v[130:131] op_sel_hi:[0,1]
	v_pk_mul_f32 v[64:65], v[64:65], v[66:67]
	v_pk_mul_f32 v[66:67], v[132:133], v[128:129] op_sel_hi:[0,1]
	v_pk_mul_f32 v[60:61], v[60:61], v[66:67]
	v_pk_mul_f32 v[66:67], v[132:133], v[98:99] op_sel_hi:[0,1]
	s_waitcnt vmcnt(12)
	v_pk_mul_f32 v[54:55], v[54:55], v[66:67]
	v_pk_mul_f32 v[66:67], v[132:133], v[100:101] op_sel_hi:[0,1]
	v_pk_mul_f32 v[50:51], v[50:51], v[66:67]
	v_pk_mul_f32 v[66:67], v[132:133], v[126:127] op_sel_hi:[0,1]
	v_pk_mul_f32 v[56:57], v[56:57], v[66:67]
	v_pk_mul_f32 v[66:67], v[132:133], v[124:125] op_sel_hi:[0,1]
	v_pk_mul_f32 v[52:53], v[52:53], v[66:67]
	v_pk_mul_f32 v[66:67], v[132:133], v[102:103] op_sel_hi:[0,1]
	s_waitcnt vmcnt(10)
	v_pk_mul_f32 v[46:47], v[46:47], v[66:67]
	v_pk_mul_f32 v[66:67], v[132:133], v[104:105] op_sel_hi:[0,1]
	v_pk_mul_f32 v[42:43], v[42:43], v[66:67]
	v_pk_mul_f32 v[66:67], v[132:133], v[122:123] op_sel_hi:[0,1]
	v_pk_mul_f32 v[48:49], v[48:49], v[66:67]
	v_pk_mul_f32 v[66:67], v[132:133], v[120:121] op_sel_hi:[0,1]
	v_pk_mul_f32 v[44:45], v[44:45], v[66:67]
	v_pk_mul_f32 v[66:67], v[132:133], v[106:107] op_sel_hi:[0,1]
	s_waitcnt vmcnt(8)
	v_pk_mul_f32 v[38:39], v[38:39], v[66:67]
	v_pk_mul_f32 v[66:67], v[132:133], v[108:109] op_sel_hi:[0,1]
	v_pk_mul_f32 v[34:35], v[34:35], v[66:67]
	v_pk_mul_f32 v[66:67], v[132:133], v[118:119] op_sel_hi:[0,1]
	v_pk_mul_f32 v[40:41], v[40:41], v[66:67]
	v_pk_mul_f32 v[66:67], v[132:133], v[116:117] op_sel_hi:[0,1]
	v_pk_mul_f32 v[36:37], v[36:37], v[66:67]
	v_pk_mul_f32 v[66:67], v[132:133], v[110:111] op_sel_hi:[0,1]
	s_waitcnt vmcnt(6)
	v_pk_mul_f32 v[30:31], v[30:31], v[66:67]
	v_pk_mul_f32 v[66:67], v[132:133], v[112:113] op_sel_hi:[0,1]
	v_pk_mul_f32 v[26:27], v[26:27], v[66:67]
	v_pk_mul_f32 v[66:67], v[132:133], v[114:115] op_sel_hi:[0,1]
	v_pk_mul_f32 v[32:33], v[32:33], v[66:67]
	v_pk_mul_f32 v[66:67], v[132:133], v[94:95] op_sel_hi:[0,1]
	v_pk_mul_f32 v[28:29], v[28:29], v[66:67]
	v_pk_mul_f32 v[66:67], v[132:133], v[92:93] op_sel_hi:[0,1]
	s_waitcnt vmcnt(4)
	v_pk_mul_f32 v[22:23], v[66:67], v[22:23]
	v_pk_mul_f32 v[66:67], v[132:133], v[88:89] op_sel_hi:[0,1]
	v_pk_mul_f32 v[18:19], v[66:67], v[18:19]
	v_pk_mul_f32 v[66:67], v[132:133], v[90:91] op_sel_hi:[0,1]
	v_pk_mul_f32 v[24:25], v[66:67], v[24:25]
	v_pk_mul_f32 v[66:67], v[132:133], v[86:87] op_sel_hi:[0,1]
	v_pk_mul_f32 v[20:21], v[66:67], v[20:21]
	v_pk_mul_f32 v[66:67], v[132:133], v[84:85] op_sel_hi:[0,1]
	s_waitcnt vmcnt(2)
	v_pk_mul_f32 v[14:15], v[66:67], v[14:15]
	v_pk_mul_f32 v[66:67], v[132:133], v[80:81] op_sel_hi:[0,1]
	v_pk_mul_f32 v[10:11], v[66:67], v[10:11]
	v_pk_mul_f32 v[66:67], v[132:133], v[82:83] op_sel_hi:[0,1]
	v_pk_mul_f32 v[16:17], v[66:67], v[16:17]
	v_pk_mul_f32 v[66:67], v[132:133], v[78:79] op_sel_hi:[0,1]
	v_pk_mul_f32 v[12:13], v[66:67], v[12:13]
	v_pk_mul_f32 v[66:67], v[132:133], v[76:77] op_sel_hi:[0,1]
	s_waitcnt vmcnt(0)
; __device__ __forceinline__ unsigned cvtpk(float lo, float hi) { f32x2 v = {lo, hi}; bf16v2 b = __builtin_convertvector(v, bf16v2); return __builtin_bit_cast(unsigned, b); }
; __device__ __forceinline__ int v_st(int k, int c) { const int kk = (k & ~0xC) | ((k & 4) << 1) | ((k & 8) >> 1); return ((kk >> 3) * 4 + (c >> 5)) * 512 + ((kk & 7) * 32 + (c & 31)) * 2; }
; __device__ __forceinline__ int v_rd_base(int lane) { return ((lane & 3) << 3) | (((lane >> 2) & 3) << 6) | (((lane >> 4) & 1) << 5) | (((lane >> 5) & 1) << 8); }
; template <int ND0, int DOFF>
; __device__ __forceinline__ void qkt(f32x16& p0, f32x16& p1, const char* Ks, const bf16x8* qr, int r32, int hi) {
;   p0 = f32x16{}; p1 = f32x16{};
; #pragma unroll
;   for (int d0 = 0; d0 < ND0; ++d0) { const int cb = ((d0 + DOFF) * 16 + hi * 8) * 2;
;     bf16x8 b0 = *reinterpret_cast<const bf16x8*>(Ks + KSWZ(r32, cb));
;     bf16x8 b1 = *reinterpret_cast<const bf16x8*>(Ks + KSWZ(32 + r32, cb));
;     p0 = __builtin_amdgcn_mfma_f32_32x32x16_bf16(b0, qr[d0], p0, 0, 0, 0);
;     p1 = __builtin_amdgcn_mfma_f32_32x32x16_bf16(b1, qr[d0], p1, 0, 0, 0); }
; }
; template <int MODE>
; __device__ __forceinline__ void attn_body(const bf16_t* __restrict__ Qb, const bf16_t* __restrict__ Kh, const bf16_t* __restrict__ Vh, int NT, int krel0,
;                                           char* lds, const float* __restrict__ lutg, const AttnEpi& E) {
;     ...
;     for (int d0 = 0; d0 < ND0; ++d0) { u32x4 w; w.x = cvtpk(qf[d0][0], qf[d0][1]); w.y = cvtpk(qf[d0][2], qf[d0][3]); w.z = cvtpk(qf[d0][4], qf[d0][5]); w.w = cvtpk(qf[d0][6], qf[d0][7]);
;       qr[d0] = *reinterpret_cast<bf16x8*>(&w); }
;   }
;   const int sr = tid >> 4, sc = (tid & 15) * 8, vst0 = v_st(sr, sc), vst1 = v_st(32 + sr, sc);
;   const int vb0 = (int)(uintptr_t)V_lds + v_rd_base(lane);
;   struct { bf16x8 vs0, vs1, ks0, ks1; } sr_[2];
;     ...
;   const int relq = krel0 - (wid * 32 + r32) + 4 * hi, relwmin = krel0 - (wid * 32 + 31), relwmax = krel0 + 63 - wid * 32;
;     ...
;   f32x16 pA0, pA1, pB0, pB1; float mnA, mnB, alA, alB; bf16x8 pa0, pa1, pa2, pa3;
;   constexpr int SE = 0, SO = 1;
;   SLOAD(SE, 0); SLOAD(SO, 64); asm volatile("s_waitcnt vmcnt(4)" ::: "memory"); SWRITE(0, SE); __syncthreads();
;   qkt<ND0, DOFF>(pA0, pA1, K_lds, qr, r32, hi); PSM(pA0, pA1, mnA, alA, 0);
	v_pk_mul_f32 v[6:7], v[66:67], v[6:7]
	v_pk_mul_f32 v[66:67], v[132:133], v[72:73] op_sel_hi:[0,1]
	v_pk_mul_f32 v[2:3], v[66:67], v[2:3]
	v_pk_mul_f32 v[66:67], v[132:133], v[74:75] op_sel_hi:[0,1]
	v_pk_mul_f32 v[8:9], v[66:67], v[8:9]
	v_pk_mul_f32 v[66:67], v[132:133], v[70:71] op_sel_hi:[0,1]
	v_pk_mul_f32 v[4:5], v[66:67], v[4:5]
	v_cvt_pk_bf16_f32 v140, v50, v51
	v_ashrrev_i32_e32 v50, 4, v188
	v_cvt_pk_bf16_f32 v116, v2, v3
	v_cvt_pk_bf16_f32 v117, v4, v5
	v_and_b32_e32 v3, 0xfffff0, v50
	v_lshlrev_b32_e32 v4, 1, v50
	v_lshlrev_b32_e32 v2, 3, v188
	v_and_or_b32 v3, v4, 8, v3
	v_cvt_pk_bf16_f32 v141, v52, v53
	v_and_b32_e32 v53, 0x78, v2
	v_lshrrev_b32_e32 v4, 1, v50
	v_lshrrev_b32_e32 v3, 1, v3
	v_bfe_u32 v2, v2, 5, 2
	v_and_b32_e32 v5, 3, v50
	v_cvt_pk_bf16_f32 v115, v8, v9
	v_or_b32_e32 v3, v3, v2
	v_and_or_b32 v4, v4, 4, v5
	v_lshlrev_b32_e32 v8, 1, v53
	v_lshlrev_b32_e32 v3, 9, v3
	v_lshlrev_b32_e32 v4, 6, v4
	v_and_b32_e32 v5, 48, v8
	v_add_u32_e32 v9, 32, v50
	v_cvt_pk_bf16_f32 v114, v6, v7
	v_or3_b32 v212, v3, v4, v5
	v_and_b32_e32 v3, 0xfffff0, v9
	v_lshlrev_b32_e32 v6, 1, v9
	v_and_or_b32 v3, v6, 8, v3
	v_lshrrev_b32_e32 v3, 1, v3
	v_or_b32_e32 v2, v3, v2
	v_lshlrev_b32_e32 v2, 9, v2
	v_add_u32_e32 v52, s64, v97
	v_or3_b32 v217, v2, v4, v5
	v_sub_u32_e32 v2, s62, v52
	s_movk_i32 s62, 0x1200
	v_add_u32_e32 v207, v2, v205
	v_mad_i64_i32 v[2:3], s[60:61], v50, s62, 0
	v_or_b32_e32 v2, v2, v53
	v_lshlrev_b64 v[2:3], 1, v[2:3]
	v_lshl_add_u64 v[4:5], s[6:7], 0, v[2:3]
	v_lshl_add_u64 v[2:3], s[0:1], 0, v[2:3]
	global_load_dwordx4 v[146:149], v[4:5], off
	global_load_dwordx4 v[154:157], v[2:3], off
	v_mad_i64_i32 v[4:5], s[60:61], v9, s62, 0
	v_or_b32_e32 v4, v4, v53
	v_lshlrev_b64 v[4:5], 1, v[4:5]
	v_lshl_add_u64 v[6:7], s[6:7], 0, v[4:5]
	global_load_dwordx4 v[150:153], v[6:7], off
	v_lshl_add_u64 v[2:3], s[0:1], 0, v[4:5]
	global_load_dwordx4 v[158:161], v[2:3], off
	v_add_u32_e32 v2, 64, v50
	v_mad_i64_i32 v[2:3], s[60:61], v2, s62, 0
	v_or_b32_e32 v2, v2, v53
	v_lshlrev_b64 v[2:3], 1, v[2:3]
	v_lshl_add_u64 v[4:5], s[6:7], 0, v[2:3]
	v_lshl_add_u64 v[2:3], s[0:1], 0, v[2:3]
	v_cvt_pk_bf16_f32 v130, v38, v39
	v_cvt_pk_bf16_f32 v131, v40, v41
	v_cvt_pk_bf16_f32 v132, v34, v35
	v_cvt_pk_bf16_f32 v133, v36, v37
	global_load_dwordx4 v[34:37], v[4:5], off
	global_load_dwordx4 v[38:41], v[2:3], off
	v_add_u32_e32 v4, 0x60, v50
	v_mad_i64_i32 v[4:5], s[60:61], v4, s62, 0
	v_or_b32_e32 v4, v4, v53
	v_lshlrev_b64 v[4:5], 1, v[4:5]
	v_lshl_add_u64 v[6:7], s[6:7], 0, v[4:5]
	v_lshl_add_u64 v[2:3], s[0:1], 0, v[4:5]
	v_cvt_pk_bf16_f32 v134, v46, v47
	v_cvt_pk_bf16_f32 v135, v48, v49
	v_cvt_pk_bf16_f32 v136, v42, v43
	v_cvt_pk_bf16_f32 v137, v44, v45
	global_load_dwordx4 v[46:49], v[6:7], off
	global_load_dwordx4 v[42:45], v[2:3], off
	v_lshlrev_b32_e32 v2, 8, v50
	v_and_b32_e32 v3, 0xf0, v188
	v_bitop3_b32 v223, v8, v2, v3 bitop3:0xde
	v_cvt_pk_bf16_f32 v138, v54, v55
	v_add_u32_e32 v55, 0, v212
	v_add_u32_e32 v54, 0, v217
	v_add_u32_e32 v2, 0, v223
	s_waitcnt vmcnt(4)
	v_cvt_pk_bf16_f32 v143, v64, v65
	v_lshlrev_b32_e32 v64, 8, v204
	v_cvt_pk_bf16_f32 v142, v62, v63
	v_cvt_pk_bf16_f32 v144, v58, v59
	v_cvt_pk_bf16_f32 v145, v60, v61
	v_cvt_pk_bf16_f32 v126, v30, v31
	v_cvt_pk_bf16_f32 v127, v32, v33
	v_cvt_pk_bf16_f32 v128, v26, v27
	v_cvt_pk_bf16_f32 v129, v28, v29
	v_cvt_pk_bf16_f32 v122, v22, v23
	v_cvt_pk_bf16_f32 v123, v24, v25
	v_cvt_pk_bf16_f32 v124, v18, v19
	v_cvt_pk_bf16_f32 v125, v20, v21
	v_cvt_pk_bf16_f32 v139, v56, v57
	v_or_b32_e32 v56, 32, v0
	v_cvt_pk_bf16_f32 v118, v14, v15
	v_cvt_pk_bf16_f32 v119, v16, v17
	v_cvt_pk_bf16_f32 v120, v10, v11
	v_cvt_pk_bf16_f32 v121, v12, v13
	v_ashrrev_i32_e32 v51, 31, v50
	s_waitcnt vmcnt(7)
	ds_write_b128 v55, v[146:149]
	s_waitcnt vmcnt(5)
	ds_write_b128 v54, v[150:153]
	ds_write_b128 v2, v[154:157] offset:49152
	v_lshlrev_b32_e32 v2, 8, v9
	v_bitop3_b32 v224, v8, v2, v3 bitop3:0xde
	v_add_u32_e32 v2, 0, v224
	s_waitcnt vmcnt(4)
	ds_write_b128 v2, v[158:161] offset:49152
	v_lshlrev_b32_e32 v2, 4, v188
	v_and_b32_e32 v65, 0xf0, v2
	v_bitop3_b32 v213, v0, v64, v65 bitop3:0xde
	v_add_u32_e32 v6, 0, v213
	s_waitcnt lgkmcnt(0)
	s_barrier
	ds_read_b128 v[2:5], v6 offset:49152
	ds_read_b128 v[6:9], v6 offset:57344
	s_waitcnt lgkmcnt(1)
	v_mfma_f32_32x32x16_bf16 v[18:33], v[2:5], v[142:145], 0
	v_bitop3_b32 v214, v56, v64, v65 bitop3:0xde
	v_add_u32_e32 v60, 0, v214
	ds_read_b128 v[56:59], v60 offset:49152
	ds_read_b128 v[60:63], v60 offset:57344
	s_waitcnt lgkmcnt(2)
	v_mfma_f32_32x32x16_bf16 v[2:17], v[6:9], v[142:145], 0
	s_waitcnt lgkmcnt(1)
	v_mfma_f32_32x32x16_bf16 v[18:33], v[56:59], v[138:141], v[18:33]
	v_or_b32_e32 v56, 64, v0
	v_bitop3_b32 v216, v56, v64, v65 bitop3:0xde
	s_waitcnt lgkmcnt(0)
	v_mfma_f32_32x32x16_bf16 v[2:17], v[60:63], v[138:141], v[2:17]
	v_add_u32_e32 v60, 0, v216
	ds_read_b128 v[56:59], v60 offset:49152
	ds_read_b128 v[60:63], v60 offset:57344
	s_waitcnt lgkmcnt(1)
	v_mfma_f32_32x32x16_bf16 v[18:33], v[56:59], v[134:137], v[18:33]
	v_or_b32_e32 v56, 0x60, v0
	v_bitop3_b32 v218, v56, v64, v65 bitop3:0xde
	s_waitcnt lgkmcnt(0)
	v_mfma_f32_32x32x16_bf16 v[2:17], v[60:63], v[134:137], v[2:17]
	v_add_u32_e32 v60, 0, v218
	ds_read_b128 v[56:59], v60 offset:49152
	ds_read_b128 v[60:63], v60 offset:57344
	s_waitcnt lgkmcnt(1)
	v_mfma_f32_32x32x16_bf16 v[18:33], v[56:59], v[130:133], v[18:33]
	v_or_b32_e32 v56, 0x80, v0
	v_bitop3_b32 v219, v56, v64, v65 bitop3:0xde
	s_waitcnt lgkmcnt(0)
	v_mfma_f32_32x32x16_bf16 v[2:17], v[60:63], v[130:133], v[2:17]
	v_add_u32_e32 v60, 0, v219
	ds_read_b128 v[56:59], v60 offset:49152
	ds_read_b128 v[60:63], v60 offset:57344
	s_waitcnt lgkmcnt(1)
; template <int MODE>
; __device__ __forceinline__ void partialSM(f32x16& p0, f32x16& p1, float& m_reg, float& mn, float& alpha, int relh, int relw_min, int relw_max, const float* lut) {
;     ...
;       for (int r = 0; r < 16; ++r) { const int i0 = relh + (r & 3) + 8 * (r >> 2);
;         const int a0 = min(max(i0, -129), 129) + 129, a1 = min(max(i0 + 32, -129), 129) + 129;
;         p0[r] = fmaf(p0[r], C, lut[a0]); p1[r] = fmaf(p1[r], C, lut[a1]); }
; template <int ND0, int DOFF>
; __device__ __forceinline__ void qkt(f32x16& p0, f32x16& p1, const char* Ks, const bf16x8* qr, int r32, int hi) {
;     ...
;     p0 = __builtin_amdgcn_mfma_f32_32x32x16_bf16(b0, qr[d0], p0, 0, 0, 0);
;     p1 = __builtin_amdgcn_mfma_f32_32x32x16_bf16(b1, qr[d0], p1, 0, 0, 0); }
	v_mfma_f32_32x32x16_bf16 v[18:33], v[56:59], v[126:129], v[18:33]
	v_or_b32_e32 v56, 0xa0, v0
	v_bitop3_b32 v220, v56, v64, v65 bitop3:0xde
	s_waitcnt lgkmcnt(0)
	v_mfma_f32_32x32x16_bf16 v[2:17], v[60:63], v[126:129], v[2:17]
	v_add_u32_e32 v60, 0, v220
	ds_read_b128 v[56:59], v60 offset:49152
	ds_read_b128 v[60:63], v60 offset:57344
	s_waitcnt lgkmcnt(1)
	v_mfma_f32_32x32x16_bf16 v[18:33], v[56:59], v[122:125], v[18:33]
	v_or_b32_e32 v56, 0xc0, v0
	v_bitop3_b32 v221, v56, v64, v65 bitop3:0xde
	v_or_b32_e32 v0, 0xe0, v0
	v_bitop3_b32 v222, v0, v64, v65 bitop3:0xde
	v_add_u32_e32 v0, 0, v222
	s_waitcnt lgkmcnt(0)
	v_mfma_f32_32x32x16_bf16 v[2:17], v[60:63], v[122:125], v[2:17]
	v_add_u32_e32 v60, 0, v221
	ds_read_b128 v[56:59], v60 offset:49152
	ds_read_b128 v[60:63], v60 offset:57344
	s_waitcnt lgkmcnt(1)
	v_mfma_f32_32x32x16_bf16 v[18:33], v[56:59], v[118:121], v[18:33]
	s_waitcnt lgkmcnt(0)
	v_mfma_f32_32x32x16_bf16 v[2:17], v[60:63], v[118:121], v[2:17]
	ds_read_b128 v[56:59], v0 offset:49152
	ds_read_b128 v[60:63], v0 offset:57344
	v_med3_i32 v0, v207, s39, v198
	v_lshl_add_u32 v0, v0, 2, s76
	ds_read_b32 v0, v0 offset:516
	s_waitcnt lgkmcnt(2)
	v_mfma_f32_32x32x16_bf16 v[18:33], v[56:59], v[114:117], v[18:33]
	v_med3_i32 v56, v207, s33, v199
	s_waitcnt lgkmcnt(1)
	v_mfma_f32_32x32x16_bf16 v[2:17], v[60:63], v[114:117], v[2:17]
	s_waitcnt lgkmcnt(0)
	s_nop 7
	v_fmac_f32_e32 v0, 0x3e0293ee, v18
	v_lshl_add_u32 v18, v56, 2, s76
	v_add_u32_e32 v56, 1, v207
	v_med3_i32 v57, v56, s39, v198
	v_med3_i32 v58, v56, s33, v199
	v_lshl_add_u32 v56, v57, 2, s76
	ds_read_b32 v56, v56 offset:516
	v_add_u32_e32 v57, 2, v207
	v_med3_i32 v59, v57, s33, v199
	ds_read_b32 v18, v18 offset:644
	s_waitcnt lgkmcnt(1)
	v_fmac_f32_e32 v56, 0x3e0293ee, v19
	v_lshl_add_u32 v19, v58, 2, s76
	v_med3_i32 v58, v57, s39, v198
	v_lshl_add_u32 v57, v58, 2, s76
	ds_read_b32 v57, v57 offset:516
	v_add_u32_e32 v58, 3, v207
	v_med3_i32 v60, v58, s33, v199
	ds_read_b32 v19, v19 offset:644
	s_waitcnt lgkmcnt(1)
	v_fmac_f32_e32 v57, 0x3e0293ee, v20
	v_lshl_add_u32 v20, v59, 2, s76
	v_med3_i32 v59, v58, s39, v198
	v_lshl_add_u32 v58, v59, 2, s76
	ds_read_b32 v58, v58 offset:516
	v_add_u32_e32 v59, 8, v207
	v_med3_i32 v61, v59, s33, v199
	ds_read_b32 v20, v20 offset:644
	s_waitcnt lgkmcnt(1)
	v_fmac_f32_e32 v58, 0x3e0293ee, v21
	v_lshl_add_u32 v21, v60, 2, s76
	v_med3_i32 v60, v59, s39, v198
	v_lshl_add_u32 v59, v60, 2, s76
	ds_read_b32 v59, v59 offset:516
	v_add_u32_e32 v60, 9, v207
	v_med3_i32 v62, v60, s33, v199
	ds_read_b32 v21, v21 offset:644
	s_waitcnt lgkmcnt(1)
	v_fmac_f32_e32 v59, 0x3e0293ee, v22
	v_lshl_add_u32 v22, v61, 2, s76
	v_med3_i32 v61, v60, s39, v198
	v_lshl_add_u32 v60, v61, 2, s76
	ds_read_b32 v60, v60 offset:516
	v_add_u32_e32 v61, 10, v207
	v_med3_i32 v63, v61, s33, v199
	ds_read_b32 v22, v22 offset:644
	s_waitcnt lgkmcnt(1)
	v_fmac_f32_e32 v60, 0x3e0293ee, v23
	v_lshl_add_u32 v23, v62, 2, s76
	v_med3_i32 v62, v61, s39, v198
	v_lshl_add_u32 v61, v62, 2, s76
	ds_read_b32 v61, v61 offset:516
	v_add_u32_e32 v62, 11, v207
	v_med3_i32 v64, v62, s33, v199
	ds_read_b32 v23, v23 offset:644
	s_waitcnt lgkmcnt(1)
	v_fmac_f32_e32 v61, 0x3e0293ee, v24
	v_lshl_add_u32 v24, v63, 2, s76
	v_med3_i32 v63, v62, s39, v198
	v_lshl_add_u32 v62, v63, 2, s76
	ds_read_b32 v62, v62 offset:516
	v_add_u32_e32 v63, 16, v207
	v_med3_i32 v65, v63, s33, v199
	ds_read_b32 v24, v24 offset:644
	s_waitcnt lgkmcnt(1)
	v_fmac_f32_e32 v62, 0x3e0293ee, v25
	v_lshl_add_u32 v25, v64, 2, s76
	v_med3_i32 v64, v63, s39, v198
	v_lshl_add_u32 v63, v64, 2, s76
	ds_read_b32 v63, v63 offset:516
	v_add_u32_e32 v64, 17, v207
	v_med3_i32 v66, v64, s33, v199
	ds_read_b32 v25, v25 offset:644
	v_pk_fma_f32 v[2:3], v[2:3], s[38:39], v[18:19] op_sel_hi:[1,0,1]
	s_waitcnt lgkmcnt(1)
; #define SLOAD(i, k0) do { sr_[i].vs0 = *reinterpret_cast<const bf16x8*>(&Vh[(size_t)((k0) + sr) * LDQK + sc]); sr_[i].vs1 = *reinterpret_cast<const bf16x8*>(&Vh[(size_t)((k0) + 32 + sr) * LDQK + sc]); \
;     sr_[i].ks0 = *reinterpret_cast<const bf16x8*>(&Kh[(size_t)((k0) + sr) * LDQK + sc]); sr_[i].ks1 = *reinterpret_cast<const bf16x8*>(&Kh[(size_t)((k0) + 32 + sr) * LDQK + sc]); } while (0)
; template <int MODE>
; __device__ __forceinline__ void partialSM(f32x16& p0, f32x16& p1, float& m_reg, float& mn, float& alpha, int relh, int relw_min, int relw_max, const float* lut) {
;     ...
;         p0[r] = fmaf(p0[r], C, lut[a0]); p1[r] = fmaf(p1[r], C, lut[a1]); }
;     } else {
; #pragma unroll
;       for (int r = 0; r < 16; ++r) { p0[r] = fmaf(p0[r], C, cfar); p1[r] = fmaf(p1[r], C, cfar); }
;     }
;     float pmax = p0[0];
; #pragma unroll
;     for (int r = 1; r < 16; ++r) pmax = fmaxf(pmax, p0[r]);
; #pragma unroll
;     for (int r = 0; r < 16; ++r) pmax = fmaxf(pmax, p1[r]);
;     { auto rr = __builtin_amdgcn_permlane32_swap(__float_as_uint(pmax), __float_as_uint(pmax), false, false);
;       pmax = fmaxf(__uint_as_float(rr[0]), __uint_as_float(rr[1])); }
;     if (__builtin_expect(__all(pmax - m_reg <= THR2), 1)) { mn = m_reg; alpha = 1.f; }
;     else { mn = fmaxf(m_reg, pmax); alpha = __builtin_amdgcn_exp2f(m_reg - mn); m_reg = mn; }
; template <int MODE>
; __device__ __forceinline__ void attn_body(const bf16_t* __restrict__ Qb, const bf16_t* __restrict__ Kh, const bf16_t* __restrict__ Vh, int NT, int krel0,
;                                           char* lds, const float* __restrict__ lutg, const AttnEpi& E) {
;     ...
;   if (2 < NT) SLOAD(SE, 2 * 64);
	v_fmac_f32_e32 v63, 0x3e0293ee, v26
	v_lshl_add_u32 v26, v65, 2, s76
	v_med3_i32 v65, v64, s39, v198
	v_lshl_add_u32 v64, v65, 2, s76
	ds_read_b32 v64, v64 offset:516
	v_add_u32_e32 v65, 18, v207
	v_med3_i32 v67, v65, s33, v199
	ds_read_b32 v26, v26 offset:644
	v_pk_fma_f32 v[4:5], v[4:5], s[38:39], v[20:21] op_sel_hi:[1,0,1]
	s_waitcnt lgkmcnt(1)
	v_fmac_f32_e32 v64, 0x3e0293ee, v27
	v_lshl_add_u32 v27, v66, 2, s76
	v_med3_i32 v66, v65, s39, v198
	v_lshl_add_u32 v65, v66, 2, s76
	ds_read_b32 v65, v65 offset:516
	ds_read_b32 v27, v27 offset:644
	v_pk_fma_f32 v[6:7], v[6:7], s[38:39], v[22:23] op_sel_hi:[1,0,1]
	v_pk_fma_f32 v[8:9], v[8:9], s[38:39], v[24:25] op_sel_hi:[1,0,1]
	s_waitcnt lgkmcnt(1)
	v_fmac_f32_e32 v65, 0x3e0293ee, v28
	v_lshl_add_u32 v28, v67, 2, s76
	ds_read_b32 v66, v28 offset:644
	v_add_u32_e32 v28, 19, v207
	v_med3_i32 v67, v28, s39, v198
	v_med3_i32 v68, v28, s33, v199
	v_lshl_add_u32 v28, v67, 2, s76
	ds_read_b32 v28, v28 offset:516
	s_waitcnt lgkmcnt(2)
	v_pk_fma_f32 v[10:11], v[10:11], s[38:39], v[26:27] op_sel_hi:[1,0,1]
	s_waitcnt lgkmcnt(0)
	v_fmac_f32_e32 v28, 0x3e0293ee, v29
	v_lshl_add_u32 v29, v68, 2, s76
	ds_read_b32 v67, v29 offset:644
	v_add_u32_e32 v29, 24, v207
	v_med3_i32 v68, v29, s39, v198
	v_med3_i32 v69, v29, s33, v199
	v_lshl_add_u32 v29, v68, 2, s76
	ds_read_b32 v29, v29 offset:516
	s_waitcnt lgkmcnt(1)
	v_pk_fma_f32 v[12:13], v[12:13], s[38:39], v[66:67] op_sel_hi:[1,0,1]
	s_waitcnt lgkmcnt(0)
	v_fmac_f32_e32 v29, 0x3e0293ee, v30
	v_lshl_add_u32 v30, v69, 2, s76
	ds_read_b32 v68, v30 offset:644
	v_add_u32_e32 v30, 25, v207
	v_med3_i32 v69, v30, s39, v198
	v_med3_i32 v70, v30, s33, v199
	v_lshl_add_u32 v30, v69, 2, s76
	ds_read_b32 v30, v30 offset:516
	s_waitcnt lgkmcnt(0)
	v_fmac_f32_e32 v30, 0x3e0293ee, v31
	v_lshl_add_u32 v31, v70, 2, s76
	ds_read_b32 v69, v31 offset:644
	v_add_u32_e32 v31, 26, v207
	v_med3_i32 v70, v31, s39, v198
	v_med3_i32 v71, v31, s33, v199
	v_lshl_add_u32 v31, v70, 2, s76
	ds_read_b32 v31, v31 offset:516
	s_waitcnt lgkmcnt(1)
	v_pk_fma_f32 v[14:15], v[14:15], s[38:39], v[68:69] op_sel_hi:[1,0,1]
	s_waitcnt lgkmcnt(0)
	v_fmac_f32_e32 v31, 0x3e0293ee, v32
	v_lshl_add_u32 v32, v71, 2, s76
	ds_read_b32 v70, v32 offset:644
	v_add_u32_e32 v32, 27, v207
	v_med3_i32 v71, v32, s39, v198
	v_med3_i32 v72, v32, s33, v199
	v_lshl_add_u32 v32, v71, 2, s76
	ds_read_b32 v32, v32 offset:516
	s_waitcnt lgkmcnt(0)
	v_fmac_f32_e32 v32, 0x3e0293ee, v33
	v_lshl_add_u32 v33, v72, 2, s76
	ds_read_b32 v71, v33 offset:644
	v_max_f32_e32 v33, v0, v56
	v_max3_f32 v33, v33, v57, v58
	v_max3_f32 v33, v33, v59, v60
	v_max3_f32 v33, v33, v61, v62
	v_max3_f32 v33, v33, v63, v64
	v_max3_f32 v33, v33, v65, v28
	v_max3_f32 v33, v33, v29, v30
	v_max3_f32 v33, v33, v31, v32
	v_max3_f32 v18, v33, v2, v3
	v_max3_f32 v18, v18, v4, v5
	v_max3_f32 v18, v18, v6, v7
	v_max3_f32 v18, v18, v8, v9
	v_max3_f32 v18, v18, v10, v11
	v_max3_f32 v18, v18, v12, v13
	v_max3_f32 v18, v18, v14, v15
	s_waitcnt lgkmcnt(0)
	v_pk_fma_f32 v[16:17], v[16:17], s[38:39], v[70:71] op_sel_hi:[1,0,1]
	s_nop 0
	v_max3_f32 v18, v18, v16, v17
	v_mov_b32_e32 v19, v18
	s_nop 1
	v_permlane32_swap_b32_e32 v18, v19
	v_max_f32_e32 v19, v19, v19
	v_max_f32_e32 v18, v18, v18
	v_max_f32_e32 v18, v18, v19
	v_add_f32_e32 v19, 0x7149f2ca, v18
	v_cmp_ge_f32_e32 vcc, s94, v19
	s_cmp_eq_u64 vcc, exec
	s_cselect_b64 vcc, -1, 0
	s_cmp_gt_i32 s69, 2
	s_cselect_b64 s[60:61], -1, 0
	s_cmp_lt_i32 s69, 3
	s_cbranch_scc1 .LBB0_101
	v_add_u32_e32 v19, 0x80, v50
	v_mad_i64_i32 v[20:21], s[78:79], v19, s62, 0
	v_add_u32_e32 v19, 0xa0, v50
	v_or_b32_e32 v20, v20, v53
	v_mad_i64_i32 v[24:25], s[78:79], v19, s62, 0
	v_lshlrev_b64 v[20:21], 1, v[20:21]
	v_or_b32_e32 v24, v24, v53
	v_lshl_add_u64 v[22:23], s[6:7], 0, v[20:21]
	v_lshlrev_b64 v[24:25], 1, v[24:25]
	v_lshl_add_u64 v[20:21], s[0:1], 0, v[20:21]
	v_lshl_add_u64 v[26:27], s[6:7], 0, v[24:25]
	global_load_dwordx4 v[146:149], v[22:23], off
	global_load_dwordx4 v[150:153], v[26:27], off
	v_lshl_add_u64 v[22:23], s[0:1], 0, v[24:25]
	global_load_dwordx4 v[154:157], v[20:21], off
	global_load_dwordx4 v[158:161], v[22:23], off

; __device__ __forceinline__ float bf2f(bf16_t v) { return __uint_as_float(((unsigned)v) << 16); }
; __device__ __forceinline__ int crow(int r, int hi) { return (r & 3) + 8 * (r >> 2) + 4 * hi; }
; template <int MODE>
; __device__ __forceinline__ void attn_body(const bf16_t* __restrict__ Qb, const bf16_t* __restrict__ Kh, const bf16_t* __restrict__ Vh, int NT, int krel0,
;                                           char* lds, const float* __restrict__ lutg, const AttnEpi& E) {
;     ...
;   if (hi == 0) li_l[r32] = l_reg; asm volatile("s_waitcnt lgkmcnt(0)" ::: "memory");
;   float rli[16];
; #pragma unroll
;   for (int r = 0; r < 16; ++r) rli[r] = __builtin_amdgcn_rcpf(li_l[crow(r, hi)]);
;   float* pk0 = E.park; float* pk1 = E.park + 64 * 512;
;   const int rowb = wid * 32;
;   if constexpr (MODE == 0 || MODE == 1) {
; #pragma unroll
;     for (int r = 0; r < 16; ++r) { const int row = rowb + crow(r, hi);
; #pragma unroll
;       for (int d0 = 0; d0 < 4; ++d0) { const int idx = (d0 * 16 + r) * 512 + tid;
;         const float g = bf2f(E.gate[(size_t)row * GW + d0 * 32 + r32]);
;         const float v = o[d0][r] * rli[r] * g;
;         if constexpr (MODE == 0) pk0[idx] = v; else pk0[idx] += v; } }
.LBB0_123:
	s_or_b64 exec, exec, s[0:1]
	s_waitcnt lgkmcnt(0)
	ds_read_b128 v[66:69], v209
	ds_read_b128 v[70:73], v209 offset:32
	v_lshlrev_b32_e32 v0, 1, v204
	s_add_u32 s60, s58, 0x2060
	s_addc_u32 s61, s59, 0
	s_waitcnt lgkmcnt(1)
	v_rcp_f32_e32 v88, v66
	v_rcp_f32_e32 v89, v67
	v_rcp_f32_e32 v81, v68
	v_rcp_f32_e32 v80, v69
	ds_read_b128 v[66:69], v209 offset:64
	ds_read_b128 v[82:85], v209 offset:96
	s_waitcnt lgkmcnt(2)
	v_rcp_f32_e32 v79, v70
	v_rcp_f32_e32 v78, v71
	v_rcp_f32_e32 v77, v72
	s_waitcnt lgkmcnt(1)
	v_rcp_f32_e32 v75, v66
	v_rcp_f32_e32 v74, v67
	v_lshl_add_u64 v[66:67], s[56:57], 0, v[0:1]
	v_or_b32_e32 v0, v205, v108
	s_waitcnt lgkmcnt(0)
	v_rcp_f32_e32 v71, v82
	v_rcp_f32_e32 v70, v83
	v_rcp_f32_e32 v72, v69
	v_rcp_f32_e32 v69, v84
	v_rcp_f32_e32 v76, v73
	v_rcp_f32_e32 v73, v68
	v_rcp_f32_e32 v68, v85
	v_lshlrev_b32_e32 v134, 2, v188
	s_add_u32 s20, s34, 0x0
	s_addc_u32 s21, s35, 0
	s_add_u32 s22, s34, 0x8000
	s_addc_u32 s23, s35, 0
	s_add_u32 s24, s34, 0x10000
	s_addc_u32 s25, s35, 0
	s_add_u32 s26, s34, 0x18000
	s_addc_u32 s27, s35, 0
	v_mad_i64_i32 v[130:131], s[28:29], v0, s88, v[66:67]
	global_load_ushort v98, v[130:131], off offset:2048
	global_load_dword v114, v134, s[20:21]
	global_load_ushort v99, v[130:131], off offset:2112
	global_load_dword v115, v134, s[22:23]
	global_load_ushort v100, v[130:131], off offset:2176
	global_load_dword v116, v134, s[24:25]
	global_load_ushort v101, v[130:131], off offset:2240
	global_load_dword v117, v134, s[26:27]
	v_or_b32_e32 v132, 1, v0
	v_mad_i64_i32 v[130:131], s[28:29], v132, s88, v[66:67]
	global_load_ushort v102, v[130:131], off offset:2048
	global_load_dword v118, v134, s[20:21] offset:2048
	global_load_ushort v103, v[130:131], off offset:2112
	global_load_dword v119, v134, s[22:23] offset:2048
	global_load_ushort v104, v[130:131], off offset:2176
	global_load_dword v120, v134, s[24:25] offset:2048
	global_load_ushort v105, v[130:131], off offset:2240
	global_load_dword v121, v134, s[26:27] offset:2048
	s_add_u32 s20, s34, 0x1000
	s_addc_u32 s21, s35, 0
	s_add_u32 s22, s34, 0x9000
	s_addc_u32 s23, s35, 0
	s_add_u32 s24, s34, 0x11000
	s_addc_u32 s25, s35, 0
	s_add_u32 s26, s34, 0x19000
	s_addc_u32 s27, s35, 0
	v_or_b32_e32 v132, 2, v0
	v_mad_i64_i32 v[130:131], s[28:29], v132, s88, v[66:67]
	global_load_ushort v106, v[130:131], off offset:2048
	global_load_dword v122, v134, s[20:21]
	global_load_ushort v107, v[130:131], off offset:2112
	global_load_dword v123, v134, s[22:23]
	global_load_ushort v108, v[130:131], off offset:2176
	global_load_dword v124, v134, s[24:25]
	global_load_ushort v109, v[130:131], off offset:2240
	global_load_dword v125, v134, s[26:27]
	v_or_b32_e32 v132, 3, v0
	v_mad_i64_i32 v[130:131], s[28:29], v132, s88, v[66:67]
	global_load_ushort v110, v[130:131], off offset:2048
	global_load_dword v126, v134, s[20:21] offset:2048
	global_load_ushort v111, v[130:131], off offset:2112
	global_load_dword v127, v134, s[22:23] offset:2048
	global_load_ushort v112, v[130:131], off offset:2176
	global_load_dword v128, v134, s[24:25] offset:2048
	global_load_ushort v113, v[130:131], off offset:2240
	global_load_dword v129, v134, s[26:27] offset:2048
	s_add_u32 s20, s34, 0x0
	s_addc_u32 s21, s35, 0
	s_add_u32 s22, s34, 0x8000
	s_addc_u32 s23, s35, 0
	s_add_u32 s24, s34, 0x10000
	s_addc_u32 s25, s35, 0
	s_add_u32 s26, s34, 0x18000
	s_addc_u32 s27, s35, 0
	s_waitcnt vmcnt(30)
	v_lshlrev_b32_e32 v98, 16, v98
	v_mul_f32_e32 v50, v50, v88
	v_fmac_f32_e32 v114, v50, v98
	global_store_dword v134, v114, s[20:21]
	s_waitcnt vmcnt(29)
	v_lshlrev_b32_e32 v99, 16, v99
	v_mul_f32_e32 v34, v34, v88
	v_fmac_f32_e32 v115, v34, v99
	global_store_dword v134, v115, s[22:23]
	s_waitcnt vmcnt(28)
	v_lshlrev_b32_e32 v100, 16, v100
	v_mul_f32_e32 v18, v18, v88
	v_fmac_f32_e32 v116, v18, v100
	global_store_dword v134, v116, s[24:25]
	s_waitcnt vmcnt(27)
	v_lshlrev_b32_e32 v101, 16, v101
	v_mul_f32_e32 v2, v2, v88
	v_fmac_f32_e32 v117, v2, v101
	global_store_dword v134, v117, s[26:27]
	s_waitcnt vmcnt(26)
	v_lshlrev_b32_e32 v102, 16, v102
	v_mul_f32_e32 v51, v51, v89
	v_fmac_f32_e32 v118, v51, v102
	global_store_dword v134, v118, s[20:21] offset:2048
	s_waitcnt vmcnt(25)
	v_lshlrev_b32_e32 v103, 16, v103
	v_mul_f32_e32 v35, v35, v89
	v_fmac_f32_e32 v119, v35, v103
	global_store_dword v134, v119, s[22:23] offset:2048
	s_waitcnt vmcnt(24)
	v_lshlrev_b32_e32 v104, 16, v104
	v_mul_f32_e32 v19, v19, v89
	v_fmac_f32_e32 v120, v19, v104
	global_store_dword v134, v120, s[24:25] offset:2048
	s_waitcnt vmcnt(23)
	v_lshlrev_b32_e32 v105, 16, v105
	v_mul_f32_e32 v3, v3, v89
	v_fmac_f32_e32 v121, v3, v105
	global_store_dword v134, v121, s[26:27] offset:2048
	s_add_u32 s20, s34, 0x1000
	s_addc_u32 s21, s35, 0
	s_add_u32 s22, s34, 0x9000
	s_addc_u32 s23, s35, 0
	s_add_u32 s24, s34, 0x11000
	s_addc_u32 s25, s35, 0
	s_add_u32 s26, s34, 0x19000
	s_addc_u32 s27, s35, 0
	s_waitcnt vmcnt(22)
	v_lshlrev_b32_e32 v106, 16, v106
	v_mul_f32_e32 v52, v52, v81
	v_fmac_f32_e32 v122, v52, v106
	global_store_dword v134, v122, s[20:21]
	s_waitcnt vmcnt(21)
	v_lshlrev_b32_e32 v107, 16, v107
	v_mul_f32_e32 v36, v36, v81
	v_fmac_f32_e32 v123, v36, v107
	global_store_dword v134, v123, s[22:23]
	s_waitcnt vmcnt(20)
	v_lshlrev_b32_e32 v108, 16, v108
	v_mul_f32_e32 v20, v20, v81
	v_fmac_f32_e32 v124, v20, v108
	global_store_dword v134, v124, s[24:25]
	s_waitcnt vmcnt(19)
	v_lshlrev_b32_e32 v109, 16, v109
	v_mul_f32_e32 v4, v4, v81
	v_fmac_f32_e32 v125, v4, v109
	global_store_dword v134, v125, s[26:27]
	s_waitcnt vmcnt(18)
	v_lshlrev_b32_e32 v110, 16, v110
	v_mul_f32_e32 v53, v53, v80
	v_fmac_f32_e32 v126, v53, v110
	global_store_dword v134, v126, s[20:21] offset:2048
	s_waitcnt vmcnt(17)
; __device__ __forceinline__ float bf2f(bf16_t v) { return __uint_as_float(((unsigned)v) << 16); }
; __device__ __forceinline__ int crow(int r, int hi) { return (r & 3) + 8 * (r >> 2) + 4 * hi; }
; template <int MODE>
; __device__ __forceinline__ void attn_body(const bf16_t* __restrict__ Qb, const bf16_t* __restrict__ Kh, const bf16_t* __restrict__ Vh, int NT, int krel0,
;                                           char* lds, const float* __restrict__ lutg, const AttnEpi& E) {
;     ...
; #pragma unroll
;     for (int r = 0; r < 16; ++r) { const int row = rowb + crow(r, hi);
; #pragma unroll
;       for (int d0 = 0; d0 < 4; ++d0) { const int idx = (d0 * 16 + r) * 512 + tid;
;         const float g = bf2f(E.gate[(size_t)row * GW + d0 * 32 + r32]);
;         const float v = o[d0][r] * rli[r] * g;
;         if constexpr (MODE == 0) pk0[idx] = v; else pk0[idx] += v; } }
	v_lshlrev_b32_e32 v111, 16, v111
	v_mul_f32_e32 v37, v37, v80
	v_fmac_f32_e32 v127, v37, v111
	global_store_dword v134, v127, s[22:23] offset:2048
	s_waitcnt vmcnt(16)
	v_lshlrev_b32_e32 v112, 16, v112
	v_mul_f32_e32 v21, v21, v80
	v_fmac_f32_e32 v128, v21, v112
	global_store_dword v134, v128, s[24:25] offset:2048
	s_waitcnt vmcnt(15)
	v_lshlrev_b32_e32 v113, 16, v113
	v_mul_f32_e32 v5, v5, v80
	v_fmac_f32_e32 v129, v5, v113
	global_store_dword v134, v129, s[26:27] offset:2048
	s_add_u32 s20, s34, 0x2000
	s_addc_u32 s21, s35, 0
	s_add_u32 s22, s34, 0xa000
	s_addc_u32 s23, s35, 0
	s_add_u32 s24, s34, 0x12000
	s_addc_u32 s25, s35, 0
	s_add_u32 s26, s34, 0x1a000
	s_addc_u32 s27, s35, 0
	v_or_b32_e32 v132, 8, v0
	v_mad_i64_i32 v[130:131], s[28:29], v132, s88, v[66:67]
	global_load_ushort v136, v[130:131], off offset:2048
	global_load_dword v152, v134, s[20:21]
	global_load_ushort v137, v[130:131], off offset:2112
	global_load_dword v153, v134, s[22:23]
	global_load_ushort v138, v[130:131], off offset:2176
	global_load_dword v154, v134, s[24:25]
	global_load_ushort v139, v[130:131], off offset:2240
	global_load_dword v155, v134, s[26:27]
	v_or_b32_e32 v132, 9, v0
	v_mad_i64_i32 v[130:131], s[28:29], v132, s88, v[66:67]
	global_load_ushort v140, v[130:131], off offset:2048
	global_load_dword v156, v134, s[20:21] offset:2048
	global_load_ushort v141, v[130:131], off offset:2112
	global_load_dword v157, v134, s[22:23] offset:2048
	global_load_ushort v142, v[130:131], off offset:2176
	global_load_dword v158, v134, s[24:25] offset:2048
	global_load_ushort v143, v[130:131], off offset:2240
	global_load_dword v159, v134, s[26:27] offset:2048
	s_add_u32 s20, s34, 0x3000
	s_addc_u32 s21, s35, 0
	s_add_u32 s22, s34, 0xb000
	s_addc_u32 s23, s35, 0
	s_add_u32 s24, s34, 0x13000
	s_addc_u32 s25, s35, 0
	s_add_u32 s26, s34, 0x1b000
	s_addc_u32 s27, s35, 0
	v_or_b32_e32 v132, 10, v0
	v_mad_i64_i32 v[130:131], s[28:29], v132, s88, v[66:67]
	global_load_ushort v144, v[130:131], off offset:2048
	global_load_dword v160, v134, s[20:21]
	global_load_ushort v145, v[130:131], off offset:2112
	global_load_dword v161, v134, s[22:23]
	global_load_ushort v146, v[130:131], off offset:2176
	global_load_dword v162, v134, s[24:25]
	global_load_ushort v147, v[130:131], off offset:2240
	global_load_dword v163, v134, s[26:27]
	v_or_b32_e32 v132, 11, v0
	v_mad_i64_i32 v[130:131], s[28:29], v132, s88, v[66:67]
	global_load_ushort v148, v[130:131], off offset:2048
	global_load_dword v164, v134, s[20:21] offset:2048
	global_load_ushort v149, v[130:131], off offset:2112
	global_load_dword v165, v134, s[22:23] offset:2048
	global_load_ushort v150, v[130:131], off offset:2176
	global_load_dword v166, v134, s[24:25] offset:2048
	global_load_ushort v151, v[130:131], off offset:2240
	global_load_dword v167, v134, s[26:27] offset:2048
	s_add_u32 s20, s34, 0x2000
	s_addc_u32 s21, s35, 0
	s_add_u32 s22, s34, 0xa000
	s_addc_u32 s23, s35, 0
	s_add_u32 s24, s34, 0x12000
	s_addc_u32 s25, s35, 0
	s_add_u32 s26, s34, 0x1a000
	s_addc_u32 s27, s35, 0
	s_waitcnt vmcnt(30)
	v_lshlrev_b32_e32 v136, 16, v136
	v_mul_f32_e32 v54, v54, v79
	v_fmac_f32_e32 v152, v54, v136
	global_store_dword v134, v152, s[20:21]
	s_waitcnt vmcnt(29)
	v_lshlrev_b32_e32 v137, 16, v137
	v_mul_f32_e32 v38, v38, v79
	v_fmac_f32_e32 v153, v38, v137
	global_store_dword v134, v153, s[22:23]
	s_waitcnt vmcnt(28)
	v_lshlrev_b32_e32 v138, 16, v138
	v_mul_f32_e32 v22, v22, v79
	v_fmac_f32_e32 v154, v22, v138
	global_store_dword v134, v154, s[24:25]
	s_waitcnt vmcnt(27)
	v_lshlrev_b32_e32 v139, 16, v139
	v_mul_f32_e32 v6, v6, v79
	v_fmac_f32_e32 v155, v6, v139
	global_store_dword v134, v155, s[26:27]
	s_waitcnt vmcnt(26)
	v_lshlrev_b32_e32 v140, 16, v140
	v_mul_f32_e32 v55, v55, v78
	v_fmac_f32_e32 v156, v55, v140
	global_store_dword v134, v156, s[20:21] offset:2048
	s_waitcnt vmcnt(25)
	v_lshlrev_b32_e32 v141, 16, v141
	v_mul_f32_e32 v39, v39, v78
	v_fmac_f32_e32 v157, v39, v141
	global_store_dword v134, v157, s[22:23] offset:2048
	s_waitcnt vmcnt(24)
	v_lshlrev_b32_e32 v142, 16, v142
	v_mul_f32_e32 v23, v23, v78
	v_fmac_f32_e32 v158, v23, v142
	global_store_dword v134, v158, s[24:25] offset:2048
	s_waitcnt vmcnt(23)
	v_lshlrev_b32_e32 v143, 16, v143
	v_mul_f32_e32 v7, v7, v78
	v_fmac_f32_e32 v159, v7, v143
	global_store_dword v134, v159, s[26:27] offset:2048
	s_add_u32 s20, s34, 0x3000
	s_addc_u32 s21, s35, 0
	s_add_u32 s22, s34, 0xb000
	s_addc_u32 s23, s35, 0
	s_add_u32 s24, s34, 0x13000
	s_addc_u32 s25, s35, 0
	s_add_u32 s26, s34, 0x1b000
	s_addc_u32 s27, s35, 0
	s_waitcnt vmcnt(22)
	v_lshlrev_b32_e32 v144, 16, v144
	v_mul_f32_e32 v56, v56, v77
	v_fmac_f32_e32 v160, v56, v144
	global_store_dword v134, v160, s[20:21]
	s_waitcnt vmcnt(21)
	v_lshlrev_b32_e32 v145, 16, v145
	v_mul_f32_e32 v40, v40, v77
	v_fmac_f32_e32 v161, v40, v145
	global_store_dword v134, v161, s[22:23]
	s_waitcnt vmcnt(20)
	v_lshlrev_b32_e32 v146, 16, v146
	v_mul_f32_e32 v24, v24, v77
	v_fmac_f32_e32 v162, v24, v146
	global_store_dword v134, v162, s[24:25]
	s_waitcnt vmcnt(19)
	v_lshlrev_b32_e32 v147, 16, v147
	v_mul_f32_e32 v8, v8, v77
	v_fmac_f32_e32 v163, v8, v147
	global_store_dword v134, v163, s[26:27]
	s_waitcnt vmcnt(18)
	v_lshlrev_b32_e32 v148, 16, v148
	v_mul_f32_e32 v57, v57, v76
	v_fmac_f32_e32 v164, v57, v148
	global_store_dword v134, v164, s[20:21] offset:2048
	s_waitcnt vmcnt(17)
	v_lshlrev_b32_e32 v149, 16, v149
	v_mul_f32_e32 v41, v41, v76
	v_fmac_f32_e32 v165, v41, v149
	global_store_dword v134, v165, s[22:23] offset:2048
	s_waitcnt vmcnt(16)
	v_lshlrev_b32_e32 v150, 16, v150
	v_mul_f32_e32 v25, v25, v76
	v_fmac_f32_e32 v166, v25, v150
	global_store_dword v134, v166, s[24:25] offset:2048
	s_waitcnt vmcnt(15)
; __device__ __forceinline__ float bf2f(bf16_t v) { return __uint_as_float(((unsigned)v) << 16); }
; __device__ __forceinline__ int crow(int r, int hi) { return (r & 3) + 8 * (r >> 2) + 4 * hi; }
; template <int MODE>
; __device__ __forceinline__ void attn_body(const bf16_t* __restrict__ Qb, const bf16_t* __restrict__ Kh, const bf16_t* __restrict__ Vh, int NT, int krel0,
;                                           char* lds, const float* __restrict__ lutg, const AttnEpi& E) {
;     ...
; #pragma unroll
;     for (int r = 0; r < 16; ++r) { const int row = rowb + crow(r, hi);
; #pragma unroll
;       for (int d0 = 0; d0 < 4; ++d0) { const int idx = (d0 * 16 + r) * 512 + tid;
;         const float g = bf2f(E.gate[(size_t)row * GW + d0 * 32 + r32]);
;         const float v = o[d0][r] * rli[r] * g;
;         if constexpr (MODE == 0) pk0[idx] = v; else pk0[idx] += v; } }
	v_lshlrev_b32_e32 v151, 16, v151
	v_mul_f32_e32 v9, v9, v76
	v_fmac_f32_e32 v167, v9, v151
	global_store_dword v134, v167, s[26:27] offset:2048
	s_add_u32 s20, s34, 0x4000
	s_addc_u32 s21, s35, 0
	s_add_u32 s22, s34, 0xc000
	s_addc_u32 s23, s35, 0
	s_add_u32 s24, s34, 0x14000
	s_addc_u32 s25, s35, 0
	s_add_u32 s26, s34, 0x1c000
	s_addc_u32 s27, s35, 0
	v_or_b32_e32 v132, 16, v0
	v_mad_i64_i32 v[130:131], s[28:29], v132, s88, v[66:67]
	global_load_ushort v98, v[130:131], off offset:2048
	global_load_dword v114, v134, s[20:21]
	global_load_ushort v99, v[130:131], off offset:2112
	global_load_dword v115, v134, s[22:23]
	global_load_ushort v100, v[130:131], off offset:2176
	global_load_dword v116, v134, s[24:25]
	global_load_ushort v101, v[130:131], off offset:2240
	global_load_dword v117, v134, s[26:27]
	v_or_b32_e32 v132, 17, v0
	v_mad_i64_i32 v[130:131], s[28:29], v132, s88, v[66:67]
	global_load_ushort v102, v[130:131], off offset:2048
	global_load_dword v118, v134, s[20:21] offset:2048
	global_load_ushort v103, v[130:131], off offset:2112
	global_load_dword v119, v134, s[22:23] offset:2048
	global_load_ushort v104, v[130:131], off offset:2176
	global_load_dword v120, v134, s[24:25] offset:2048
	global_load_ushort v105, v[130:131], off offset:2240
	global_load_dword v121, v134, s[26:27] offset:2048
	s_add_u32 s20, s34, 0x5000
	s_addc_u32 s21, s35, 0
	s_add_u32 s22, s34, 0xd000
	s_addc_u32 s23, s35, 0
	s_add_u32 s24, s34, 0x15000
	s_addc_u32 s25, s35, 0
	s_add_u32 s26, s34, 0x1d000
	s_addc_u32 s27, s35, 0
	v_or_b32_e32 v132, 18, v0
	v_mad_i64_i32 v[130:131], s[28:29], v132, s88, v[66:67]
	global_load_ushort v106, v[130:131], off offset:2048
	global_load_dword v122, v134, s[20:21]
	global_load_ushort v107, v[130:131], off offset:2112
	global_load_dword v123, v134, s[22:23]
	global_load_ushort v108, v[130:131], off offset:2176
	global_load_dword v124, v134, s[24:25]
	global_load_ushort v109, v[130:131], off offset:2240
	global_load_dword v125, v134, s[26:27]
	v_or_b32_e32 v132, 19, v0
	v_mad_i64_i32 v[130:131], s[28:29], v132, s88, v[66:67]
	global_load_ushort v110, v[130:131], off offset:2048
	global_load_dword v126, v134, s[20:21] offset:2048
	global_load_ushort v111, v[130:131], off offset:2112
	global_load_dword v127, v134, s[22:23] offset:2048
	global_load_ushort v112, v[130:131], off offset:2176
	global_load_dword v128, v134, s[24:25] offset:2048
	global_load_ushort v113, v[130:131], off offset:2240
	global_load_dword v129, v134, s[26:27] offset:2048
	s_add_u32 s20, s34, 0x4000
	s_addc_u32 s21, s35, 0
	s_add_u32 s22, s34, 0xc000
	s_addc_u32 s23, s35, 0
	s_add_u32 s24, s34, 0x14000
	s_addc_u32 s25, s35, 0
	s_add_u32 s26, s34, 0x1c000
	s_addc_u32 s27, s35, 0
	s_waitcnt vmcnt(30)
	v_lshlrev_b32_e32 v98, 16, v98
	v_mul_f32_e32 v58, v58, v75
	v_fmac_f32_e32 v114, v58, v98
	global_store_dword v134, v114, s[20:21]
	s_waitcnt vmcnt(29)
	v_lshlrev_b32_e32 v99, 16, v99
	v_mul_f32_e32 v42, v42, v75
	v_fmac_f32_e32 v115, v42, v99
	global_store_dword v134, v115, s[22:23]
	s_waitcnt vmcnt(28)
	v_lshlrev_b32_e32 v100, 16, v100
	v_mul_f32_e32 v26, v26, v75
	v_fmac_f32_e32 v116, v26, v100
	global_store_dword v134, v116, s[24:25]
	s_waitcnt vmcnt(27)
	v_lshlrev_b32_e32 v101, 16, v101
	v_mul_f32_e32 v10, v10, v75
	v_fmac_f32_e32 v117, v10, v101
	global_store_dword v134, v117, s[26:27]
	s_waitcnt vmcnt(26)
	v_lshlrev_b32_e32 v102, 16, v102
	v_mul_f32_e32 v59, v59, v74
	v_fmac_f32_e32 v118, v59, v102
	global_store_dword v134, v118, s[20:21] offset:2048
	s_waitcnt vmcnt(25)
	v_lshlrev_b32_e32 v103, 16, v103
	v_mul_f32_e32 v43, v43, v74
	v_fmac_f32_e32 v119, v43, v103
	global_store_dword v134, v119, s[22:23] offset:2048
	s_waitcnt vmcnt(24)
	v_lshlrev_b32_e32 v104, 16, v104
	v_mul_f32_e32 v27, v27, v74
	v_fmac_f32_e32 v120, v27, v104
	global_store_dword v134, v120, s[24:25] offset:2048
	s_waitcnt vmcnt(23)
	v_lshlrev_b32_e32 v105, 16, v105
	v_mul_f32_e32 v11, v11, v74
	v_fmac_f32_e32 v121, v11, v105
	global_store_dword v134, v121, s[26:27] offset:2048
	s_add_u32 s20, s34, 0x5000
	s_addc_u32 s21, s35, 0
	s_add_u32 s22, s34, 0xd000
	s_addc_u32 s23, s35, 0
	s_add_u32 s24, s34, 0x15000
	s_addc_u32 s25, s35, 0
	s_add_u32 s26, s34, 0x1d000
	s_addc_u32 s27, s35, 0
	s_waitcnt vmcnt(22)
	v_lshlrev_b32_e32 v106, 16, v106
	v_mul_f32_e32 v60, v60, v73
	v_fmac_f32_e32 v122, v60, v106
	global_store_dword v134, v122, s[20:21]
	s_waitcnt vmcnt(21)
	v_lshlrev_b32_e32 v107, 16, v107
	v_mul_f32_e32 v44, v44, v73
	v_fmac_f32_e32 v123, v44, v107
	global_store_dword v134, v123, s[22:23]
	s_waitcnt vmcnt(20)
	v_lshlrev_b32_e32 v108, 16, v108
	v_mul_f32_e32 v28, v28, v73
	v_fmac_f32_e32 v124, v28, v108
	global_store_dword v134, v124, s[24:25]
	s_waitcnt vmcnt(19)
	v_lshlrev_b32_e32 v109, 16, v109
	v_mul_f32_e32 v12, v12, v73
	v_fmac_f32_e32 v125, v12, v109
	global_store_dword v134, v125, s[26:27]
	s_waitcnt vmcnt(18)
	v_lshlrev_b32_e32 v110, 16, v110
	v_mul_f32_e32 v61, v61, v72
	v_fmac_f32_e32 v126, v61, v110
	global_store_dword v134, v126, s[20:21] offset:2048
	s_waitcnt vmcnt(17)
	v_lshlrev_b32_e32 v111, 16, v111
	v_mul_f32_e32 v45, v45, v72
	v_fmac_f32_e32 v127, v45, v111
	global_store_dword v134, v127, s[22:23] offset:2048
	s_waitcnt vmcnt(16)
	v_lshlrev_b32_e32 v112, 16, v112
	v_mul_f32_e32 v29, v29, v72
	v_fmac_f32_e32 v128, v29, v112
	global_store_dword v134, v128, s[24:25] offset:2048
	s_waitcnt vmcnt(15)
; __device__ __forceinline__ float bf2f(bf16_t v) { return __uint_as_float(((unsigned)v) << 16); }
; template <int MODE>
; __device__ __forceinline__ void attn_body(const bf16_t* __restrict__ Qb, const bf16_t* __restrict__ Kh, const bf16_t* __restrict__ Vh, int NT, int krel0,
;                                           char* lds, const float* __restrict__ lutg, const AttnEpi& E) {
;     ...
;   __syncthreads();
;   if constexpr (MODE != 0) { if (tid < 259) lut[tid] = lutg[tid]; }
;     ...
;         const float g = bf2f(E.gate[(size_t)row * GW + d0 * 32 + r32]);
;         const float v = o[d0][r] * rli[r] * g;
;         if constexpr (MODE == 0) pk0[idx] = v; else pk0[idx] += v; } }
	v_lshlrev_b32_e32 v113, 16, v113
	v_mul_f32_e32 v13, v13, v72
	v_fmac_f32_e32 v129, v13, v113
	global_store_dword v134, v129, s[26:27] offset:2048
	s_add_u32 s20, s34, 0x6000
	s_addc_u32 s21, s35, 0
	s_add_u32 s22, s34, 0xe000
	s_addc_u32 s23, s35, 0
	s_add_u32 s24, s34, 0x16000
	s_addc_u32 s25, s35, 0
	s_add_u32 s26, s34, 0x1e000
	s_addc_u32 s27, s35, 0
	v_or_b32_e32 v132, 24, v0
	v_mad_i64_i32 v[130:131], s[28:29], v132, s88, v[66:67]
	global_load_ushort v136, v[130:131], off offset:2048
	global_load_dword v152, v134, s[20:21]
	global_load_ushort v137, v[130:131], off offset:2112
	global_load_dword v153, v134, s[22:23]
	global_load_ushort v138, v[130:131], off offset:2176
	global_load_dword v154, v134, s[24:25]
	global_load_ushort v139, v[130:131], off offset:2240
	global_load_dword v155, v134, s[26:27]
	v_or_b32_e32 v132, 25, v0
	v_mad_i64_i32 v[130:131], s[28:29], v132, s88, v[66:67]
	global_load_ushort v140, v[130:131], off offset:2048
	global_load_dword v156, v134, s[20:21] offset:2048
	global_load_ushort v141, v[130:131], off offset:2112
	global_load_dword v157, v134, s[22:23] offset:2048
	global_load_ushort v142, v[130:131], off offset:2176
	global_load_dword v158, v134, s[24:25] offset:2048
	global_load_ushort v143, v[130:131], off offset:2240
	global_load_dword v159, v134, s[26:27] offset:2048
	s_add_u32 s20, s34, 0x7000
	s_addc_u32 s21, s35, 0
	s_add_u32 s22, s34, 0xf000
	s_addc_u32 s23, s35, 0
	s_add_u32 s24, s34, 0x17000
	s_addc_u32 s25, s35, 0
	s_add_u32 s26, s34, 0x1f000
	s_addc_u32 s27, s35, 0
	v_or_b32_e32 v132, 26, v0
	v_mad_i64_i32 v[130:131], s[28:29], v132, s88, v[66:67]
	global_load_ushort v144, v[130:131], off offset:2048
	global_load_dword v160, v134, s[20:21]
	global_load_ushort v145, v[130:131], off offset:2112
	global_load_dword v161, v134, s[22:23]
	global_load_ushort v146, v[130:131], off offset:2176
	global_load_dword v162, v134, s[24:25]
	global_load_ushort v147, v[130:131], off offset:2240
	global_load_dword v163, v134, s[26:27]
	v_or_b32_e32 v132, 27, v0
	v_mad_i64_i32 v[130:131], s[28:29], v132, s88, v[66:67]
	global_load_ushort v148, v[130:131], off offset:2048
	global_load_dword v164, v134, s[20:21] offset:2048
	global_load_ushort v149, v[130:131], off offset:2112
	global_load_dword v165, v134, s[22:23] offset:2048
	global_load_ushort v150, v[130:131], off offset:2176
	global_load_dword v166, v134, s[24:25] offset:2048
	global_load_ushort v151, v[130:131], off offset:2240
	global_load_dword v167, v134, s[26:27] offset:2048
	s_add_u32 s20, s34, 0x6000
	s_addc_u32 s21, s35, 0
	s_add_u32 s22, s34, 0xe000
	s_addc_u32 s23, s35, 0
	s_add_u32 s24, s34, 0x16000
	s_addc_u32 s25, s35, 0
	s_add_u32 s26, s34, 0x1e000
	s_addc_u32 s27, s35, 0
	s_waitcnt vmcnt(30)
	v_lshlrev_b32_e32 v136, 16, v136
	v_mul_f32_e32 v62, v62, v71
	v_fmac_f32_e32 v152, v62, v136
	global_store_dword v134, v152, s[20:21]
	s_waitcnt vmcnt(29)
	v_lshlrev_b32_e32 v137, 16, v137
	v_mul_f32_e32 v46, v46, v71
	v_fmac_f32_e32 v153, v46, v137
	global_store_dword v134, v153, s[22:23]
	s_waitcnt vmcnt(28)
	v_lshlrev_b32_e32 v138, 16, v138
	v_mul_f32_e32 v30, v30, v71
	v_fmac_f32_e32 v154, v30, v138
	global_store_dword v134, v154, s[24:25]
	s_waitcnt vmcnt(27)
	v_lshlrev_b32_e32 v139, 16, v139
	v_mul_f32_e32 v14, v14, v71
	v_fmac_f32_e32 v155, v14, v139
	global_store_dword v134, v155, s[26:27]
	s_waitcnt vmcnt(26)
	v_lshlrev_b32_e32 v140, 16, v140
	v_mul_f32_e32 v63, v63, v70
	v_fmac_f32_e32 v156, v63, v140
	global_store_dword v134, v156, s[20:21] offset:2048
	s_waitcnt vmcnt(25)
	v_lshlrev_b32_e32 v141, 16, v141
	v_mul_f32_e32 v47, v47, v70
	v_fmac_f32_e32 v157, v47, v141
	global_store_dword v134, v157, s[22:23] offset:2048
	s_waitcnt vmcnt(24)
	v_lshlrev_b32_e32 v142, 16, v142
	v_mul_f32_e32 v31, v31, v70
	v_fmac_f32_e32 v158, v31, v142
	global_store_dword v134, v158, s[24:25] offset:2048
	s_waitcnt vmcnt(23)
	v_lshlrev_b32_e32 v143, 16, v143
	v_mul_f32_e32 v15, v15, v70
	v_fmac_f32_e32 v159, v15, v143
	global_store_dword v134, v159, s[26:27] offset:2048
	s_add_u32 s20, s34, 0x7000
	s_addc_u32 s21, s35, 0
	s_add_u32 s22, s34, 0xf000
	s_addc_u32 s23, s35, 0
	s_add_u32 s24, s34, 0x17000
	s_addc_u32 s25, s35, 0
	s_add_u32 s26, s34, 0x1f000
	s_addc_u32 s27, s35, 0
	s_waitcnt vmcnt(22)
	v_lshlrev_b32_e32 v144, 16, v144
	v_mul_f32_e32 v64, v64, v69
	v_fmac_f32_e32 v160, v64, v144
	global_store_dword v134, v160, s[20:21]
	s_waitcnt vmcnt(21)
	v_lshlrev_b32_e32 v145, 16, v145
	v_mul_f32_e32 v48, v48, v69
	v_fmac_f32_e32 v161, v48, v145
	global_store_dword v134, v161, s[22:23]
	s_waitcnt vmcnt(20)
	v_lshlrev_b32_e32 v146, 16, v146
	v_mul_f32_e32 v32, v32, v69
	v_fmac_f32_e32 v162, v32, v146
	global_store_dword v134, v162, s[24:25]
	s_waitcnt vmcnt(19)
	v_lshlrev_b32_e32 v147, 16, v147
	v_mul_f32_e32 v16, v16, v69
	v_fmac_f32_e32 v163, v16, v147
	global_store_dword v134, v163, s[26:27]
	s_waitcnt vmcnt(18)
	v_lshlrev_b32_e32 v148, 16, v148
	v_mul_f32_e32 v65, v65, v68
	v_fmac_f32_e32 v164, v65, v148
	global_store_dword v134, v164, s[20:21] offset:2048
	s_waitcnt vmcnt(17)
	v_lshlrev_b32_e32 v149, 16, v149
	v_mul_f32_e32 v49, v49, v68
	v_fmac_f32_e32 v165, v49, v149
	global_store_dword v134, v165, s[22:23] offset:2048
	s_waitcnt vmcnt(16)
	v_lshlrev_b32_e32 v150, 16, v150
	v_mul_f32_e32 v33, v33, v68
	v_fmac_f32_e32 v166, v33, v150
	global_store_dword v134, v166, s[24:25] offset:2048
	s_waitcnt vmcnt(15)
	v_lshlrev_b32_e32 v151, 16, v151
	v_mul_f32_e32 v17, v17, v68
	v_fmac_f32_e32 v167, v17, v151
	global_store_dword v134, v167, s[26:27] offset:2048
	s_movk_i32 s0, 0x103
	v_mov_b32_e32 v188, v179
	s_nop 0
	v_cmp_gt_i32_e32 vcc, s0, v188
	v_ashrrev_i32_e32 v189, 31, v188
	s_barrier
	v_lshl_add_u64 v[2:3], v[188:189], 2, s[60:61]
	global_load_dword v100, v[2:3], off
	v_lshl_add_u32 v101, v188, 2, 0
	v_add_u32_e32 v101, 0x18800, v101
; template <int MODE>
; __device__ __forceinline__ void attn_body(const bf16_t* __restrict__ Qb, const bf16_t* __restrict__ Kh, const bf16_t* __restrict__ Vh, int NT, int krel0,
;                                           char* lds, const float* __restrict__ lutg, const AttnEpi& E) {
;     ...
;   if constexpr (MODE != 0) { if (tid < 259) lut[tid] = lutg[tid]; }
;   float m_reg = -1e30f, l_reg = 0; f32x16 o[4] = {}; bf16x8 qr[ND0];
;   const bf16_t* Qw = Qb + (size_t)(wid * 32 + r32) * LDQK + hi * 8;
;   {
;     float qf[ND0][8]; float ss = 0.f;
; #pragma unroll
;     for (int d0 = 0; d0 < ND0; ++d0) { const bf16x8 raw = *reinterpret_cast<const bf16x8*>(Qw + d0 * 16);
; #pragma unroll
;       for (int j = 0; j < 8; ++j) { const float v = __uint_as_float(((unsigned)(unsigned short)raw[j]) << 16); qf[d0][j] = v; ss += v * v; } }
;     { auto rr = __builtin_amdgcn_permlane32_swap(__float_as_uint(ss), __float_as_uint(ss), false, false);
;       ss = __uint_as_float(rr[0]) + __uint_as_float(rr[1]); }
;     const float rs = rsqrtf(ss * (MODE < 2 ? (1.f / 128.f) : (1.f / 64.f)) + EPS);
.LBB0_125:
	s_add_u32 s0, s17, s16
	s_addc_u32 s1, s18, 0
	s_add_u32 s62, s0, 0x1800
	s_addc_u32 s63, s1, 0
	v_ashrrev_i32_e32 v3, 1, v188
	s_movk_i32 s6, 0xffe0
	v_bfe_u32 v2, v188, 5, 1
	v_bfi_b32 v4, s6, v3, v188
	v_mov_b64_e32 v[6:7], s[62:63]
	v_mad_i64_i32 v[6:7], s[6:7], v4, s73, v[6:7]
	v_lshlrev_b32_e32 v0, 4, v2
	v_lshl_add_u64 v[18:19], v[6:7], 0, v[0:1]
	global_load_dwordx4 v[6:9], v[18:19], off
	global_load_dwordx4 v[10:13], v[18:19], off offset:32
	global_load_dwordx4 v[14:17], v[18:19], off offset:64
	s_nop 0
	global_load_dwordx4 v[18:21], v[18:19], off offset:96
	v_and_b32_e32 v5, 32, v188
	global_load_dwordx4 v[22:25], v5, s[52:53] offset:16
	global_load_dwordx4 v[26:29], v5, s[52:53]
	global_load_dwordx4 v[30:33], v5, s[52:53] offset:80
	global_load_dwordx4 v[34:37], v5, s[52:53] offset:64
	global_load_dwordx4 v[38:41], v5, s[52:53] offset:144
	global_load_dwordx4 v[42:45], v5, s[52:53] offset:128
	global_load_dwordx4 v[46:49], v5, s[52:53] offset:208
	global_load_dwordx4 v[54:57], v5, s[52:53] offset:192
	s_add_u32 s0, s67, s68
	s_addc_u32 s1, s65, 0
	s_add_u32 s58, s0, 0x2000
	s_addc_u32 s59, s1, 0
	s_add_u32 s0, s0, 0x2200
	s_addc_u32 s1, s1, 0
	s_sub_i32 s77, 0, s64
	s_sub_i32 s78, 63, s64
	s_movk_i32 s64, 0x1200
	v_and_b32_e32 v53, 0xffffffe0, v3
	v_sub_u32_e32 v4, s77, v4
	v_and_b32_e32 v52, 31, v188
	v_sub_u32_e32 v205, s78, v53
	s_waitcnt vmcnt(12)
	ds_write_b32 v101, v100
	s_waitcnt vmcnt(11)
	v_and_b32_e32 v71, 0xffff0000, v7
	v_lshlrev_b32_e32 v70, 16, v7
	v_and_b32_e32 v7, 0xffff0000, v6
	v_lshlrev_b32_e32 v6, 16, v6
	v_mul_f32_e32 v72, v7, v7
	v_pk_fma_f32 v[72:73], v[6:7], v[6:7], v[72:73] op_sel_hi:[1,1,0]
	v_mul_f32_e32 v74, v71, v71
	v_pk_fma_f32 v[72:73], v[70:71], v[70:71], v[72:73]
	v_and_b32_e32 v69, 0xffff0000, v9
	v_lshlrev_b32_e32 v68, 16, v9
	v_and_b32_e32 v9, 0xffff0000, v8
	v_lshlrev_b32_e32 v8, 16, v8
	v_pk_add_f32 v[72:73], v[74:75], v[72:73] op_sel_hi:[0,1]
	v_pk_fma_f32 v[72:73], v[8:9], v[8:9], v[72:73]
	v_mul_f32_e32 v74, v9, v9
	v_pk_add_f32 v[72:73], v[74:75], v[72:73] op_sel_hi:[0,1]
	v_pk_fma_f32 v[72:73], v[68:69], v[68:69], v[72:73]
	v_mul_f32_e32 v74, v69, v69
	s_waitcnt vmcnt(10)
	v_and_b32_e32 v67, 0xffff0000, v11
	v_lshlrev_b32_e32 v66, 16, v11
	v_and_b32_e32 v11, 0xffff0000, v10
	v_lshlrev_b32_e32 v10, 16, v10
	v_pk_add_f32 v[72:73], v[74:75], v[72:73] op_sel_hi:[0,1]
	v_pk_fma_f32 v[72:73], v[10:11], v[10:11], v[72:73]
	v_mul_f32_e32 v74, v11, v11
	v_pk_add_f32 v[72:73], v[74:75], v[72:73] op_sel_hi:[0,1]
	v_pk_fma_f32 v[72:73], v[66:67], v[66:67], v[72:73]
	v_mul_f32_e32 v74, v67, v67
	v_and_b32_e32 v65, 0xffff0000, v13
	v_lshlrev_b32_e32 v64, 16, v13
	v_and_b32_e32 v13, 0xffff0000, v12
	v_lshlrev_b32_e32 v12, 16, v12
	v_pk_add_f32 v[72:73], v[74:75], v[72:73] op_sel_hi:[0,1]
	v_pk_fma_f32 v[72:73], v[12:13], v[12:13], v[72:73]
	v_mul_f32_e32 v74, v13, v13
	v_pk_add_f32 v[72:73], v[74:75], v[72:73] op_sel_hi:[0,1]
	v_pk_fma_f32 v[72:73], v[64:65], v[64:65], v[72:73]
	v_mul_f32_e32 v74, v65, v65
	s_waitcnt vmcnt(9)
	v_and_b32_e32 v63, 0xffff0000, v15
	v_lshlrev_b32_e32 v62, 16, v15
	v_and_b32_e32 v15, 0xffff0000, v14
	v_lshlrev_b32_e32 v14, 16, v14
	v_pk_add_f32 v[72:73], v[74:75], v[72:73] op_sel_hi:[0,1]
	v_pk_fma_f32 v[72:73], v[14:15], v[14:15], v[72:73]
	v_mul_f32_e32 v74, v15, v15
	v_pk_add_f32 v[72:73], v[74:75], v[72:73] op_sel_hi:[0,1]
	v_pk_fma_f32 v[72:73], v[62:63], v[62:63], v[72:73]
	v_mul_f32_e32 v74, v63, v63
	v_and_b32_e32 v61, 0xffff0000, v17
	v_lshlrev_b32_e32 v60, 16, v17
	v_and_b32_e32 v17, 0xffff0000, v16
	v_lshlrev_b32_e32 v16, 16, v16
	v_pk_add_f32 v[72:73], v[74:75], v[72:73] op_sel_hi:[0,1]
	v_pk_fma_f32 v[72:73], v[16:17], v[16:17], v[72:73]
	v_mul_f32_e32 v74, v17, v17
	v_pk_add_f32 v[72:73], v[74:75], v[72:73] op_sel_hi:[0,1]
	v_pk_fma_f32 v[72:73], v[60:61], v[60:61], v[72:73]
	v_mul_f32_e32 v74, v61, v61
	s_waitcnt vmcnt(8)
	v_and_b32_e32 v59, 0xffff0000, v19
	v_lshlrev_b32_e32 v58, 16, v19
	v_and_b32_e32 v19, 0xffff0000, v18
	v_lshlrev_b32_e32 v18, 16, v18
	v_pk_add_f32 v[72:73], v[74:75], v[72:73] op_sel_hi:[0,1]
	v_pk_fma_f32 v[72:73], v[18:19], v[18:19], v[72:73]
	v_mul_f32_e32 v74, v19, v19
	v_pk_add_f32 v[72:73], v[74:75], v[72:73] op_sel_hi:[0,1]
	v_pk_fma_f32 v[72:73], v[58:59], v[58:59], v[72:73]
	v_mul_f32_e32 v74, v59, v59
	v_and_b32_e32 v51, 0xffff0000, v21
	v_lshlrev_b32_e32 v50, 16, v21
	v_and_b32_e32 v21, 0xffff0000, v20
	v_lshlrev_b32_e32 v20, 16, v20
	v_pk_add_f32 v[72:73], v[74:75], v[72:73] op_sel_hi:[0,1]
	v_pk_fma_f32 v[72:73], v[20:21], v[20:21], v[72:73]
	v_mul_f32_e32 v74, v21, v21
	v_pk_add_f32 v[72:73], v[74:75], v[72:73] op_sel_hi:[0,1]
	v_pk_fma_f32 v[72:73], v[50:51], v[50:51], v[72:73]
	v_mul_f32_e32 v74, v51, v51
	v_pk_add_f32 v[72:73], v[74:75], v[72:73] op_sel_hi:[0,1]
	v_mov_b32_e32 v5, v72
	s_nop 1
	v_permlane32_swap_b32_e32 v72, v5
	v_add_f32_e32 v5, v72, v5
	v_fmamk_f32 v5, v5, 0x3c800000, v178
	v_cmp_gt_f32_e32 vcc, s49, v5
	v_mul_f32_e32 v72, 0x4b800000, v5
	s_nop 0
	v_cndmask_b32_e32 v5, v5, v72, vcc
	v_rsq_f32_e32 v5, v5
	s_nop 0
	v_mul_f32_e32 v72, 0x45800000, v5
	v_cndmask_b32_e32 v72, v5, v72, vcc
	v_pk_mul_f32 v[6:7], v[72:73], v[6:7] op_sel_hi:[0,1]
	s_waitcnt vmcnt(6)
	v_pk_mul_f32 v[6:7], v[26:27], v[6:7]
	v_pk_mul_f32 v[26:27], v[72:73], v[68:69] op_sel_hi:[0,1]
	v_pk_mul_f32 v[24:25], v[24:25], v[26:27]
	v_pk_mul_f32 v[26:27], v[72:73], v[66:67] op_sel_hi:[0,1]
	s_waitcnt vmcnt(4)
; __device__ __forceinline__ unsigned cvtpk(float lo, float hi) { f32x2 v = {lo, hi}; bf16v2 b = __builtin_convertvector(v, bf16v2); return __builtin_bit_cast(unsigned, b); }
; template <int MODE>
; __device__ __forceinline__ void attn_body(const bf16_t* __restrict__ Qb, const bf16_t* __restrict__ Kh, const bf16_t* __restrict__ Vh, int NT, int krel0,
;                                           char* lds, const float* __restrict__ lutg, const AttnEpi& E) {
;     ...
;     for (int d0 = 0; d0 < ND0; ++d0) { const f32x4 g0 = *(const f32x4*)(E.gq + d0 * 16 + hi * 8), g1 = *(const f32x4*)(E.gq + d0 * 16 + hi * 8 + 4);
; #pragma unroll
;       for (int j = 0; j < 4; ++j) { qf[d0][j] = qf[d0][j] * rs * g0[j]; qf[d0][4 + j] = qf[d0][4 + j] * rs * g1[j]; } }
;     if constexpr (MODE == 0) {
;       const int sp = krel0 + wid * 32 + r32;
; #pragma unroll
;       for (int h = 0; h < 2; ++h) { const int pos = h == 0 ? (sp >> 6) : (sp & 63);
; #pragma unroll
;         for (int a = 0; a < 2; ++a) { const float* tb = lutg + (size_t)(pos * 32 + a * 16 + hi * 8) * 2;
; #pragma unroll
;           for (int jj = 0; jj < 4; ++jj) { const f32x4 cs = *(const f32x4*)(tb + jj * 4);
; #pragma unroll
;             for (int e = 0; e < 2; ++e) { const int j = 2 * jj + e; const float c = cs[2 * e], sn = cs[2 * e + 1];
;               const float x1 = qf[4 * h + a][j], x2 = qf[4 * h + 2 + a][j];
;               qf[4 * h + a][j] = x1 * c - x2 * sn; qf[4 * h + 2 + a][j] = x2 * c + x1 * sn; } } } }
;     }
; #pragma unroll
;     for (int d0 = 0; d0 < ND0; ++d0) { u32x4 w; w.x = cvtpk(qf[d0][0], qf[d0][1]); w.y = cvtpk(qf[d0][2], qf[d0][3]); w.z = cvtpk(qf[d0][4], qf[d0][5]); w.w = cvtpk(qf[d0][6], qf[d0][7]);
;       qr[d0] = *reinterpret_cast<bf16x8*>(&w); }
;   }
;   const int sr = tid >> 4, sc = (tid & 15) * 8, vst0 = v_st(sr, sc), vst1 = v_st(32 + sr, sc);
;   const int vb0 = (int)(uintptr_t)V_lds + v_rd_base(lane);
;   struct { bf16x8 vs0, vs1, ks0, ks1; } sr_[2];
;     ...
;   const int relq = krel0 - (wid * 32 + r32) + 4 * hi, relwmin = krel0 - (wid * 32 + 31), relwmax = krel0 + 63 - wid * 32;
;     ...
;   f32x16 pA0, pA1, pB0, pB1; float mnA, mnB, alA, alB; bf16x8 pa0, pa1, pa2, pa3;
;   constexpr int SE = 0, SO = 1;
;   SLOAD(SE, 0); SLOAD(SO, 64); asm volatile("s_waitcnt vmcnt(4)" ::: "memory"); SWRITE(0, SE); __syncthreads();
;   qkt<ND0, DOFF>(pA0, pA1, K_lds, qr, r32, hi); PSM(pA0, pA1, mnA, alA, 0);
	v_pk_mul_f32 v[26:27], v[36:37], v[26:27]
	v_pk_mul_f32 v[36:37], v[72:73], v[50:51] op_sel_hi:[0,1]
	v_ashrrev_i32_e32 v50, 4, v188
	v_pk_mul_f32 v[8:9], v[72:73], v[8:9] op_sel_hi:[0,1]
	v_cvt_pk_bf16_f32 v142, v6, v7
	v_and_b32_e32 v6, 0xfffff0, v50
	v_lshlrev_b32_e32 v7, 1, v50
	v_pk_mul_f32 v[8:9], v[22:23], v[8:9]
	v_pk_mul_f32 v[10:11], v[72:73], v[10:11] op_sel_hi:[0,1]
	v_lshlrev_b32_e32 v5, 3, v188
	v_and_or_b32 v6, v7, 8, v6
	v_pk_mul_f32 v[10:11], v[34:35], v[10:11]
	v_cvt_pk_bf16_f32 v144, v8, v9
	v_and_b32_e32 v51, 0x78, v5
	v_lshrrev_b32_e32 v7, 1, v50
	v_lshrrev_b32_e32 v6, 1, v6
	v_bfe_u32 v5, v5, 5, 2
	v_and_b32_e32 v8, 3, v50
	v_cvt_pk_bf16_f32 v138, v10, v11
	v_or_b32_e32 v6, v6, v5
	v_and_or_b32 v7, v7, 4, v8
	v_lshlrev_b32_e32 v10, 1, v51
	v_lshlrev_b32_e32 v6, 9, v6
	v_lshlrev_b32_e32 v7, 6, v7
	v_and_b32_e32 v8, 48, v10
	v_add_u32_e32 v11, 32, v50
	v_or3_b32 v206, v6, v7, v8
	v_and_b32_e32 v6, 0xfffff0, v11
	v_lshlrev_b32_e32 v9, 1, v11
	v_and_or_b32 v6, v9, 8, v6
	v_pk_mul_f32 v[18:19], v[72:73], v[18:19] op_sel_hi:[0,1]
	v_lshrrev_b32_e32 v6, 1, v6
	s_waitcnt vmcnt(0)
	v_pk_mul_f32 v[18:19], v[54:55], v[18:19]
	v_or_b32_e32 v5, v6, v5
	v_lshlrev_b32_e32 v54, 2, v2
	v_or_b32_e32 v55, 31, v3
	v_mad_i64_i32 v[2:3], s[6:7], v50, s64, 0
	v_lshlrev_b32_e32 v5, 9, v5
	v_or_b32_e32 v2, v2, v51
	v_or3_b32 v207, v5, v7, v8
	v_lshlrev_b64 v[6:7], 1, v[2:3]
	v_pk_mul_f32 v[16:17], v[72:73], v[16:17] op_sel_hi:[0,1]
	v_lshl_add_u64 v[2:3], s[0:1], 0, v[6:7]
	v_mad_i64_i32 v[8:9], s[6:7], v11, s64, 0
	v_pk_mul_f32 v[16:17], v[38:39], v[16:17]
	v_add_u32_e32 v184, v4, v54
	global_load_dwordx4 v[2:5], v[2:3], off
	v_or_b32_e32 v8, v8, v51
	v_pk_mul_f32 v[12:13], v[72:73], v[12:13] op_sel_hi:[0,1]
	v_pk_mul_f32 v[14:15], v[72:73], v[14:15] op_sel_hi:[0,1]
	v_cvt_pk_bf16_f32 v136, v16, v17
	v_lshlrev_b64 v[16:17], 1, v[8:9]
	v_pk_mul_f32 v[12:13], v[30:31], v[12:13]
	v_pk_mul_f32 v[14:15], v[42:43], v[14:15]
	v_lshl_add_u64 v[8:9], s[0:1], 0, v[16:17]
	v_lshl_add_u64 v[6:7], s[58:59], 0, v[6:7]
	v_lshl_add_u64 v[16:17], s[58:59], 0, v[16:17]
	v_cvt_pk_bf16_f32 v140, v12, v13
	v_cvt_pk_bf16_f32 v134, v14, v15
	v_cvt_pk_bf16_f32 v130, v18, v19
	global_load_dwordx4 v[12:15], v[8:9], off
	v_pk_mul_f32 v[20:21], v[72:73], v[20:21] op_sel_hi:[0,1]
	global_load_dwordx4 v[16:19], v[16:17], off
	v_pk_mul_f32 v[20:21], v[46:47], v[20:21]
	global_load_dwordx4 v[6:9], v[6:7], off
	v_cvt_pk_bf16_f32 v132, v20, v21
	v_add_u32_e32 v20, 64, v50
	v_mad_i64_i32 v[20:21], s[6:7], v20, s64, 0
	v_pk_mul_f32 v[22:23], v[72:73], v[70:71] op_sel_hi:[0,1]
	v_or_b32_e32 v20, v20, v51
	v_pk_mul_f32 v[22:23], v[28:29], v[22:23]
	v_pk_mul_f32 v[34:35], v[72:73], v[58:59] op_sel_hi:[0,1]
	v_lshlrev_b64 v[20:21], 1, v[20:21]
	v_pk_mul_f32 v[30:31], v[72:73], v[62:63] op_sel_hi:[0,1]
	v_pk_mul_f32 v[34:35], v[56:57], v[34:35]
	v_pk_mul_f32 v[36:37], v[48:49], v[36:37]
	v_cvt_pk_bf16_f32 v143, v22, v23
	v_lshl_add_u64 v[22:23], s[0:1], 0, v[20:21]
	v_lshl_add_u64 v[20:21], s[58:59], 0, v[20:21]
	v_pk_mul_f32 v[30:31], v[44:45], v[30:31]
	v_cvt_pk_bf16_f32 v131, v34, v35
	v_cvt_pk_bf16_f32 v133, v36, v37
	global_load_dwordx4 v[34:37], v[22:23], off
	global_load_dwordx4 v[42:45], v[20:21], off
	v_add_u32_e32 v22, 0x60, v50
	v_mad_i64_i32 v[22:23], s[6:7], v22, s64, 0
	v_or_b32_e32 v22, v22, v51
	v_pk_mul_f32 v[28:29], v[72:73], v[64:65] op_sel_hi:[0,1]
	v_lshlrev_b64 v[22:23], 1, v[22:23]
	v_pk_mul_f32 v[28:29], v[32:33], v[28:29]
	v_pk_mul_f32 v[32:33], v[72:73], v[60:61] op_sel_hi:[0,1]
	v_cvt_pk_bf16_f32 v145, v24, v25
	v_lshl_add_u64 v[24:25], s[0:1], 0, v[22:23]
	v_lshl_add_u64 v[20:21], s[58:59], 0, v[22:23]
	v_pk_mul_f32 v[32:33], v[40:41], v[32:33]
	global_load_dwordx4 v[38:41], v[24:25], off
	global_load_dwordx4 v[46:49], v[20:21], off
	v_add_u32_e32 v56, 0, v206
	s_waitcnt vmcnt(4)
	v_add_u32_e32 v57, 0, v207
	v_lshlrev_b32_e32 v66, 8, v52
	v_cvt_pk_bf16_f32 v139, v26, v27
	v_cvt_pk_bf16_f32 v141, v28, v29
	v_cvt_pk_bf16_f32 v135, v30, v31
	v_cvt_pk_bf16_f32 v137, v32, v33
	v_or_b32_e32 v58, 32, v0
	v_sub_u32_e32 v204, s77, v55
	v_cmp_gt_i32_e64 s[6:7], s95, v205
	v_cmp_lt_i32_e32 vcc, s15, v205
	s_waitcnt vmcnt(7)
	ds_write_b128 v56, v[2:5]
	v_lshlrev_b32_e32 v2, 8, v50
	v_and_b32_e32 v3, 0xf0, v188
	v_bitop3_b32 v211, v10, v2, v3 bitop3:0xde
	v_add_u32_e32 v2, 0, v211
	s_waitcnt vmcnt(6)
	ds_write_b128 v57, v[12:15]
	s_waitcnt vmcnt(4)
	ds_write_b128 v2, v[6:9] offset:49152
	v_lshlrev_b32_e32 v2, 8, v11
	v_bitop3_b32 v212, v10, v2, v3 bitop3:0xde
	v_add_u32_e32 v2, 0, v212
	ds_write_b128 v2, v[16:19] offset:49152
	v_lshlrev_b32_e32 v2, 4, v188
	v_and_b32_e32 v67, 0xf0, v2
	v_bitop3_b32 v213, v0, v66, v67 bitop3:0xde
	v_add_u32_e32 v6, 0, v213
	s_waitcnt lgkmcnt(0)
	s_barrier
	ds_read_b128 v[2:5], v6 offset:49152
	ds_read_b128 v[6:9], v6 offset:57344
	s_waitcnt lgkmcnt(1)
	v_mfma_f32_32x32x16_bf16 v[18:33], v[2:5], v[142:145], 0
	v_bitop3_b32 v214, v58, v66, v67 bitop3:0xde
	v_add_u32_e32 v62, 0, v214
	ds_read_b128 v[58:61], v62 offset:49152
	ds_read_b128 v[62:65], v62 offset:57344
	s_waitcnt lgkmcnt(2)
	v_mfma_f32_32x32x16_bf16 v[2:17], v[6:9], v[142:145], 0
	s_waitcnt lgkmcnt(1)
	v_mfma_f32_32x32x16_bf16 v[18:33], v[58:61], v[138:141], v[18:33]
	v_or_b32_e32 v58, 64, v0
	v_bitop3_b32 v215, v58, v66, v67 bitop3:0xde
	v_or_b32_e32 v0, 0x60, v0
	v_bitop3_b32 v216, v0, v66, v67 bitop3:0xde
	v_add_u32_e32 v0, 0, v216
	s_waitcnt lgkmcnt(0)
	v_mfma_f32_32x32x16_bf16 v[2:17], v[62:65], v[138:141], v[2:17]
	v_add_u32_e32 v62, 0, v215
	ds_read_b128 v[58:61], v62 offset:49152
	ds_read_b128 v[62:65], v62 offset:57344
	s_waitcnt lgkmcnt(1)
	v_mfma_f32_32x32x16_bf16 v[18:33], v[58:61], v[134:137], v[18:33]
	s_waitcnt lgkmcnt(0)
	v_mfma_f32_32x32x16_bf16 v[2:17], v[62:65], v[134:137], v[2:17]
	ds_read_b128 v[58:61], v0 offset:49152
	ds_read_b128 v[62:65], v0 offset:57344
	v_mov_b32_e32 v0, s76
	s_waitcnt lgkmcnt(1)
	v_mfma_f32_32x32x16_bf16 v[18:33], v[58:61], v[130:133], v[18:33]
	s_waitcnt lgkmcnt(0)
	v_mfma_f32_32x32x16_bf16 v[2:17], v[62:65], v[130:133], v[2:17]
	s_and_saveexec_b64 s[64:65], vcc
	s_cbranch_execz .LBB0_129
; template <int MODE>
; __device__ __forceinline__ void partialSM(f32x16& p0, f32x16& p1, float& m_reg, float& mn, float& alpha, int relh, int relw_min, int relw_max, const float* lut) {
;     ...
;     if constexpr (MODE >= 2) {
;       if (relw_max <= -128) { nearT = false; cfar = lut[0]; }
;       else if (relw_min >= 128) { nearT = false; cfar = lut[258]; }
;       if (!nearT) {
;         float pmax = p0[0];
; #pragma unroll
;         for (int r = 1; r < 16; ++r) pmax = fmaxf(pmax, p0[r]);
; #pragma unroll
;         for (int r = 0; r < 16; ++r) pmax = fmaxf(pmax, p1[r]);
;         { auto rr = __builtin_amdgcn_permlane32_swap(__float_as_uint(pmax), __float_as_uint(pmax), false, false);
;           pmax = fmaxf(__uint_as_float(rr[0]), __uint_as_float(rr[1])); }
;         const float tmax = fmaf(pmax, C, cfar);
;         if (__builtin_expect(__all(tmax - m_reg <= THR2), 1)) { mn = m_reg; alpha = 1.f; }
;         else { mn = fmaxf(m_reg, tmax); alpha = __builtin_amdgcn_exp2f(m_reg - mn); m_reg = mn; }
;         const float off = cfar - mn;
; #pragma unroll
;         for (int r = 0; r < 16; ++r) p0[r] = fmaf(p0[r], C, off);
; #pragma unroll
;         for (int r = 0; r < 16; ++r) p1[r] = fmaf(p1[r], C, off);
; #pragma unroll
;         for (int r = 0; r < 16; ++r) p0[r] = __builtin_amdgcn_exp2f(p0[r]);
;         return;
;       }
;     }
;     if (nearT) {
; #pragma unroll
;       for (int r = 0; r < 16; ++r) { const int i0 = relh + (r & 3) + 8 * (r >> 2);
;         const int a0 = min(max(i0, -129), 129) + 129, a1 = min(max(i0 + 32, -129), 129) + 129;
;         p0[r] = fmaf(p0[r], C, lut[a0]); p1[r] = fmaf(p1[r], C, lut[a1]); }
	v_cmp_gt_i32_e32 vcc, s91, v204
	s_mov_b64 s[68:69], -1
	s_and_saveexec_b64 s[66:67], vcc
	s_cbranch_execz .LBB0_128
	v_add_u32_e32 v59, 1, v184
	v_add_u32_e32 v61, 2, v184
	v_add_u32_e32 v63, 3, v184
	v_med3_i32 v0, v184, s39, v198
	v_med3_i32 v58, v184, s33, v199
	v_med3_i32 v60, v59, s39, v198
	v_med3_i32 v59, v59, s33, v199
	v_med3_i32 v62, v61, s39, v198
	v_med3_i32 v61, v61, s33, v199
	v_med3_i32 v64, v63, s39, v198
	v_lshl_add_u32 v0, v0, 2, s76
	v_lshl_add_u32 v58, v58, 2, s76
	v_lshl_add_u32 v60, v60, 2, s76
	v_lshl_add_u32 v59, v59, 2, s76
	v_lshl_add_u32 v62, v62, 2, s76
	v_lshl_add_u32 v61, v61, 2, s76
	v_med3_i32 v63, v63, s33, v199
	v_lshl_add_u32 v64, v64, 2, s76
	v_lshl_add_u32 v63, v63, 2, s76
	ds_read_b32 v0, v0 offset:516
	ds_read_b32 v58, v58 offset:644
	ds_read_b32 v74, v60 offset:516
	ds_read_b32 v59, v59 offset:644
	ds_read_b32 v75, v62 offset:516
	ds_read_b32 v60, v61 offset:644
	ds_read_b32 v76, v64 offset:516
	ds_read_b32 v61, v63 offset:644
	v_add_u32_e32 v62, 8, v184
	v_add_u32_e32 v64, 9, v184
	v_add_u32_e32 v66, 10, v184
	v_add_u32_e32 v68, 11, v184
	v_med3_i32 v63, v62, s39, v198
	v_med3_i32 v62, v62, s33, v199
	v_med3_i32 v65, v64, s39, v198
	v_med3_i32 v64, v64, s33, v199
	v_med3_i32 v67, v66, s39, v198
	v_med3_i32 v66, v66, s33, v199
	v_med3_i32 v69, v68, s39, v198
	v_med3_i32 v68, v68, s33, v199
	v_lshl_add_u32 v63, v63, 2, s76
	v_lshl_add_u32 v62, v62, 2, s76
	v_lshl_add_u32 v65, v65, 2, s76
	v_lshl_add_u32 v64, v64, 2, s76
	v_lshl_add_u32 v66, v66, 2, s76
	v_lshl_add_u32 v68, v68, 2, s76
	v_lshl_add_u32 v67, v67, 2, s76
	v_lshl_add_u32 v69, v69, 2, s76
	ds_read_b32 v77, v63 offset:516
	ds_read_b32 v62, v62 offset:644
	ds_read_b32 v78, v65 offset:516
	ds_read_b32 v63, v64 offset:644
	ds_read_b32 v79, v67 offset:516
	ds_read_b32 v64, v66 offset:644
	ds_read_b32 v80, v69 offset:516
	ds_read_b32 v65, v68 offset:644
	v_add_u32_e32 v66, 16, v184
	v_add_u32_e32 v68, 17, v184
	v_add_u32_e32 v70, 18, v184
	v_add_u32_e32 v72, 19, v184
	v_med3_i32 v67, v66, s39, v198
	v_med3_i32 v66, v66, s33, v199
	v_med3_i32 v69, v68, s39, v198
	v_med3_i32 v68, v68, s33, v199
	v_med3_i32 v71, v70, s39, v198
	v_med3_i32 v70, v70, s33, v199
	v_med3_i32 v73, v72, s39, v198
	v_med3_i32 v72, v72, s33, v199
	v_lshl_add_u32 v67, v67, 2, s76
	v_lshl_add_u32 v66, v66, 2, s76
	v_lshl_add_u32 v69, v69, 2, s76
	v_lshl_add_u32 v68, v68, 2, s76
	v_lshl_add_u32 v70, v70, 2, s76
	v_lshl_add_u32 v72, v72, 2, s76
	v_lshl_add_u32 v71, v71, 2, s76
	v_lshl_add_u32 v73, v73, 2, s76
	ds_read_b32 v81, v67 offset:516
	ds_read_b32 v66, v66 offset:644
	ds_read_b32 v90, v69 offset:516
	ds_read_b32 v67, v68 offset:644
	ds_read_b32 v91, v71 offset:516
	ds_read_b32 v68, v70 offset:644
	ds_read_b32 v92, v73 offset:516
	ds_read_b32 v69, v72 offset:644
	v_add_u32_e32 v70, 24, v184
	v_add_u32_e32 v72, 25, v184
	v_add_u32_e32 v82, 26, v184
	v_med3_i32 v71, v70, s39, v198
	v_med3_i32 v70, v70, s33, v199
	v_med3_i32 v73, v72, s39, v198
	v_med3_i32 v72, v72, s33, v199
	v_med3_i32 v83, v82, s39, v198
	v_med3_i32 v82, v82, s33, v199
	v_add_u32_e32 v84, 27, v184
	s_waitcnt lgkmcnt(14)
	v_fmac_f32_e32 v0, 0x3e38aa3b, v18
	v_fmac_f32_e32 v74, 0x3e38aa3b, v19
	v_lshl_add_u32 v71, v71, 2, s76
	v_lshl_add_u32 v70, v70, 2, s76
	v_lshl_add_u32 v73, v73, 2, s76
	v_lshl_add_u32 v72, v72, 2, s76
	v_lshl_add_u32 v82, v82, 2, s76
	v_med3_i32 v85, v84, s39, v198
	v_med3_i32 v84, v84, s33, v199
	v_fmac_f32_e32 v75, 0x3e38aa3b, v20
	v_fmac_f32_e32 v76, 0x3e38aa3b, v21
	v_lshl_add_u32 v83, v83, 2, s76
	v_lshl_add_u32 v85, v85, 2, s76
	v_lshl_add_u32 v84, v84, 2, s76
	ds_read_b32 v93, v71 offset:516
	ds_read_b32 v70, v70 offset:644
	ds_read_b32 v94, v73 offset:516
	ds_read_b32 v71, v72 offset:644
	ds_read_b32 v95, v83 offset:516
	ds_read_b32 v72, v82 offset:644
	ds_read_b32 v96, v85 offset:516
	ds_read_b32 v73, v84 offset:644
	v_max_f32_e32 v82, v0, v74
	v_fmac_f32_e32 v77, 0x3e38aa3b, v22
	s_waitcnt lgkmcnt(14)
; template <int MODE>
; __device__ __forceinline__ void partialSM(f32x16& p0, f32x16& p1, float& m_reg, float& mn, float& alpha, int relh, int relw_min, int relw_max, const float* lut) {
;     ...
;     float pmax = p0[0];
; #pragma unroll
;     for (int r = 1; r < 16; ++r) pmax = fmaxf(pmax, p0[r]);
; #pragma unroll
;     for (int r = 0; r < 16; ++r) pmax = fmaxf(pmax, p1[r]);
;     { auto rr = __builtin_amdgcn_permlane32_swap(__float_as_uint(pmax), __float_as_uint(pmax), false, false);
;       pmax = fmaxf(__uint_as_float(rr[0]), __uint_as_float(rr[1])); }
;     if (__builtin_expect(__all(pmax - m_reg <= THR2), 1)) { mn = m_reg; alpha = 1.f; }
;     else { mn = fmaxf(m_reg, pmax); alpha = __builtin_amdgcn_exp2f(m_reg - mn); m_reg = mn; }
; #pragma unroll
;     for (int r = 0; r < 16; ++r) p0[r] = __builtin_amdgcn_exp2f(p0[r] - mn);
; #pragma unroll
;     for (int r = 0; r < 16; ++r) p1[r] = p1[r] - mn;
	v_fmac_f32_e32 v78, 0x3e38aa3b, v23
	v_max3_f32 v82, v82, v75, v76
	v_fmac_f32_e32 v79, 0x3e38aa3b, v24
	v_fmac_f32_e32 v80, 0x3e38aa3b, v25
	v_max3_f32 v82, v82, v77, v78
	v_fmac_f32_e32 v81, 0x3e38aa3b, v26
	s_waitcnt lgkmcnt(13)
	v_fmac_f32_e32 v90, 0x3e38aa3b, v27
	v_max3_f32 v82, v82, v79, v80
	s_waitcnt lgkmcnt(11)
	v_fmac_f32_e32 v91, 0x3e38aa3b, v28
	s_waitcnt lgkmcnt(9)
	v_fmac_f32_e32 v92, 0x3e38aa3b, v29
	v_max3_f32 v82, v82, v81, v90
	s_waitcnt lgkmcnt(7)
	v_fmac_f32_e32 v93, 0x3e38aa3b, v30
	s_waitcnt lgkmcnt(5)
	v_fmac_f32_e32 v94, 0x3e38aa3b, v31
	v_max3_f32 v82, v82, v91, v92
	s_waitcnt lgkmcnt(3)
	v_fmac_f32_e32 v95, 0x3e38aa3b, v32
	s_waitcnt lgkmcnt(1)
	v_fmac_f32_e32 v96, 0x3e38aa3b, v33
	v_max3_f32 v82, v82, v93, v94
	v_max3_f32 v82, v82, v95, v96
	v_pk_fma_f32 v[58:59], v[2:3], s[48:49], v[58:59] op_sel_hi:[1,0,1]
	v_pk_fma_f32 v[60:61], v[4:5], s[48:49], v[60:61] op_sel_hi:[1,0,1]
	v_max3_f32 v82, v82, v58, v59
	v_max3_f32 v82, v82, v60, v61
	v_pk_fma_f32 v[62:63], v[6:7], s[48:49], v[62:63] op_sel_hi:[1,0,1]
	v_pk_fma_f32 v[64:65], v[8:9], s[48:49], v[64:65] op_sel_hi:[1,0,1]
	v_max3_f32 v82, v82, v62, v63
	v_max3_f32 v84, v82, v64, v65
	v_pk_fma_f32 v[82:83], v[10:11], s[48:49], v[66:67] op_sel_hi:[1,0,1]
	v_pk_fma_f32 v[86:87], v[14:15], s[48:49], v[70:71] op_sel_hi:[1,0,1]
	v_max3_f32 v66, v84, v82, v83
	v_pk_fma_f32 v[84:85], v[12:13], s[48:49], v[68:69] op_sel_hi:[1,0,1]
	s_waitcnt lgkmcnt(0)
	v_pk_fma_f32 v[88:89], v[16:17], s[48:49], v[72:73] op_sel_hi:[1,0,1]
	v_max3_f32 v66, v66, v84, v85
	v_max3_f32 v66, v66, v86, v87
	v_max3_f32 v66, v66, v88, v89
	v_mov_b32_e32 v67, v66
	s_nop 1
	v_permlane32_swap_b32_e32 v66, v67
	v_max_f32_e32 v67, v67, v67
	v_max_f32_e32 v66, v66, v66
	v_max_f32_e32 v66, v66, v67
	v_add_f32_e32 v67, 0x7149f2ca, v66
	v_cmp_ge_f32_e32 vcc, s94, v67
	v_max_f32_e32 v66, 0xf149f2ca, v66
	v_sub_f32_e32 v67, 0xf149f2ca, v66
	s_cmp_eq_u64 vcc, exec
	v_exp_f32_e32 v67, v67
	s_cselect_b64 vcc, -1, 0
	v_cndmask_b32_e32 v219, v66, v197, vcc
	v_mov_b32_e32 v100, s76
	ds_read_b32 v101, v100
	ds_read_b32 v100, v100 offset:1032
	v_readlane_b32 s19, v255, 21
	s_waitcnt lgkmcnt(0)
	v_max_f32_e32 v101, v101, v100
	v_add_f32_e32 v219, s19, v101
	v_sub_f32_e32 v0, v0, v219
	v_exp_f32_e32 v66, v0
	v_sub_f32_e32 v0, v74, v219
	v_cndmask_b32_e64 v217, v67, 1.0, vcc
	v_exp_f32_e32 v67, v0
	v_sub_f32_e32 v0, v75, v219
	v_exp_f32_e32 v68, v0
	v_sub_f32_e32 v0, v76, v219
	v_exp_f32_e32 v69, v0
	v_sub_f32_e32 v0, v77, v219
	v_exp_f32_e32 v70, v0
	v_sub_f32_e32 v0, v78, v219
	v_exp_f32_e32 v71, v0
	v_sub_f32_e32 v0, v79, v219
	v_exp_f32_e32 v72, v0
	v_sub_f32_e32 v0, v80, v219
	v_exp_f32_e32 v73, v0
	v_sub_f32_e32 v0, v81, v219
	v_exp_f32_e32 v74, v0
	v_sub_f32_e32 v0, v90, v219
	v_exp_f32_e32 v75, v0
	v_sub_f32_e32 v0, v91, v219
	v_exp_f32_e32 v76, v0
	v_sub_f32_e32 v0, v92, v219
	v_exp_f32_e32 v77, v0
	v_sub_f32_e32 v0, v93, v219
	v_exp_f32_e32 v78, v0
	v_sub_f32_e32 v0, v94, v219
	v_exp_f32_e32 v79, v0
	v_sub_f32_e32 v0, v95, v219
	v_exp_f32_e32 v80, v0
	v_sub_f32_e32 v0, v96, v219
	v_exp_f32_e32 v81, v0
	v_sub_f32_e32 v97, v89, v219
	v_sub_f32_e32 v96, v88, v219
	v_sub_f32_e32 v95, v87, v219
	v_sub_f32_e32 v94, v86, v219
	v_sub_f32_e32 v93, v85, v219
	v_sub_f32_e32 v92, v84, v219
	v_sub_f32_e32 v91, v83, v219
	v_sub_f32_e32 v90, v82, v219
	v_sub_f32_e32 v89, v65, v219
	v_sub_f32_e32 v88, v64, v219
	v_sub_f32_e32 v87, v63, v219
	v_sub_f32_e32 v86, v62, v219
	v_sub_f32_e32 v85, v61, v219
	v_sub_f32_e32 v84, v60, v219
	v_sub_f32_e32 v83, v59, v219
	v_sub_f32_e32 v82, v58, v219
	s_xor_b64 s[68:69], exec, -1

; #define SBAR() __builtin_amdgcn_sched_barrier(0)
; #define SLOAD(i, k0) do { sr_[i].vs0 = *reinterpret_cast<const bf16x8*>(&Vh[(size_t)((k0) + sr) * LDQK + sc]); sr_[i].vs1 = *reinterpret_cast<const bf16x8*>(&Vh[(size_t)((k0) + 32 + sr) * LDQK + sc]); \
;     sr_[i].ks0 = *reinterpret_cast<const bf16x8*>(&Kh[(size_t)((k0) + sr) * LDQK + sc]); sr_[i].ks1 = *reinterpret_cast<const bf16x8*>(&Kh[(size_t)((k0) + 32 + sr) * LDQK + sc]); } while (0)
; #define SWRITE(off, i) do { *(bf16x8*)(V_lds + (off) + vst0) = sr_[i].vs0;          \
;     *(bf16x8*)(V_lds + (off) + vst1) = sr_[i].vs1; int kc = sc * 2;               \
;     *(bf16x8*)(K_lds + (off) + KSWZ(sr, kc)) = sr_[i].ks0;                       \
;     *(bf16x8*)(K_lds + (off) + KSWZ(32 + sr, kc)) = sr_[i].ks1; } while (0)
; #define SWAIT() asm volatile("s_waitcnt vmcnt(4)" ::: "memory")
; #define RESC(a) do { if (__any((a) < 1.f)) { if (hi == 0) al_l[r32] = (a); asm volatile("s_waitcnt lgkmcnt(0)" ::: "memory"); \
;     _Pragma("unroll") for (int d = 0; d < 4; ++d) _Pragma("unroll") for (int r = 0; r < 16; ++r) o[d][r] *= al_l[crow(r, hi)]; } } while (0)
; #define PSM(P0, P1, MN, AL, J) partialSM<MODE>(P0, P1, m_reg, MN, AL, relq + 64 * (J), relwmin + 64 * (J), relwmax + 64 * (J), lut)
; template <int MODE>
; __device__ __forceinline__ void attn_body(const bf16_t* __restrict__ Qb, const bf16_t* __restrict__ Kh, const bf16_t* __restrict__ Vh, int NT, int krel0,
;                                           char* lds, const float* __restrict__ lutg, const AttnEpi& E) {
;     ...
;   SLOAD(SE, 0); SLOAD(SO, 64); asm volatile("s_waitcnt vmcnt(4)" ::: "memory"); SWRITE(0, SE); __syncthreads();
;   qkt<ND0, DOFF>(pA0, pA1, K_lds, qr, r32, hi); PSM(pA0, pA1, mnA, alA, 0);
;   if (2 < NT) SLOAD(SE, 2 * 64);
;   SWAIT(); SWRITE(SHM_V, SO);
;   int op = 0, oq = SHM_V, ow = 2 * SHM_V;
;   for (int j = 1; j + 1 < NT; j += 2) {
;     __syncthreads();
;     SBAR(); qkt<ND0, DOFF>(pB0, pB1, K_lds + oq, qr, r32, hi);
;     finishSM(pA0, pA1, alA, l_reg, pa0, pa1, pa2, pa3); SBAR();
;     SLOAD(SO, (j + 2) * 64); SBAR();
;     pv_d0(o, vb0 + op, pa0, pa1, pa2, pa3); PSM(pB0, pB1, mnB, alB, j);
;     SWAIT(); SWRITE(ow, SE);
;     RESC(alB);
;     { const int t = op; op = oq; oq = ow; ow = t; }
.LBB0_131:
	s_or_b64 exec, exec, s[64:65]
	v_add_u32_e32 v0, 0xa0, v50
	s_movk_i32 s64, 0x1200
	s_nop 3
	v_mad_i64_i32 v[2:3], s[6:7], v0, s64, 0
	v_add_u32_e32 v0, 0x80, v50
	v_or_b32_e32 v2, v2, v51
	v_mad_i64_i32 v[6:7], s[6:7], v0, s64, 0
	v_lshlrev_b64 v[2:3], 1, v[2:3]
	v_or_b32_e32 v6, v6, v51
	v_lshl_add_u64 v[4:5], s[58:59], 0, v[2:3]
	v_lshlrev_b64 v[6:7], 1, v[6:7]
	v_lshl_add_u64 v[2:3], s[0:1], 0, v[2:3]
	v_lshl_add_u64 v[8:9], s[58:59], 0, v[6:7]
	v_lshl_add_u64 v[4:5], s[0:1], 0, v[6:7]
	v_and_b32_e32 v0, 63, v188
	v_lshlrev_b32_e32 v3, 4, v0
	v_lshlrev_b32_e32 v2, 3, v0
	v_and_b32_e32 v3, 0xc0, v3
	v_lshlrev_b32_e32 v4, 1, v0
	v_and_or_b32 v3, v2, 24, v3
	v_and_b32_e32 v4, 32, v4
	v_and_b32_e32 v2, 0x100, v2
	s_cmp_lg_u32 0, -1
	v_or3_b32 v2, v3, v4, v2
	s_cselect_b32 s6, 0, 0
	v_add_u32_e32 v218, s6, v2
	v_and_b32_e32 v2, 0x3fffffc0, v188
	v_add_u32_e32 v3, s75, v211
	v_ashrrev_i32_e32 v51, 31, v50
	v_lshl_add_u32 v2, v2, 2, s89
	s_waitcnt vmcnt(0)
	s_waitcnt vmcnt(3)
	ds_write_b128 v56, v[34:37] offset:16384
	s_waitcnt vmcnt(1)
	ds_write_b128 v57, v[38:41] offset:16384
	ds_write_b128 v3, v[42:45]
	v_add_u32_e32 v3, s75, v212
	s_waitcnt vmcnt(0)
	ds_write_b128 v3, v[46:49]
	v_cmp_gt_u32_e64 s[6:7], 32, v0
	v_lshl_add_u32 v209, v52, 2, v2
	v_lshl_add_u32 v208, v54, 2, v2
	v_sub_u32_e32 v0, v54, v52
	v_lshl_add_u64 v[2:3], v[50:51], 0, s[2:3]
	s_movk_i32 s66, 0x2400
	v_sub_u32_e32 v222, v0, v53
	v_mad_u64_u32 v[4:5], s[64:65], v2, s66, 0
	v_and_b32_e32 v0, 15, v188
	v_mad_i32_i24 v3, v3, s66, v5
	v_or_b32_e32 v2, s82, v4
	v_lshlrev_b32_e32 v0, 4, v0
	v_readlane_b32 s64, v254, 14
	v_lshl_add_u64 v[2:3], v[2:3], 0, v[0:1]
	v_readlane_b32 s65, v254, 15
	v_mov_b32_e32 v14, v1
	v_mov_b32_e32 v15, v1
	v_sub_u32_e32 v220, 0, v55
	v_sub_u32_e32 v221, 0, v53
	v_lshl_add_u64 v[190:191], s[64:65], 0, v[2:3]
	v_mov_b32_e32 v0, v1
	v_mov_b32_e32 v2, v1
	v_mov_b32_e32 v3, v1
	v_mov_b32_e32 v4, v1
	v_mov_b32_e32 v5, v1
	v_mov_b32_e32 v6, v1
	v_mov_b32_e32 v7, v1
	v_mov_b32_e32 v8, v1
	v_mov_b32_e32 v9, v1
	v_mov_b32_e32 v10, v1
	v_mov_b32_e32 v11, v1
	v_mov_b32_e32 v12, v1
	v_mov_b32_e32 v13, v1
	v_mov_b64_e32 v[64:65], v[14:15]
	v_mov_b64_e32 v[48:49], v[14:15]
	v_mov_b64_e32 v[32:33], v[14:15]
	v_mov_b64_e32 v[62:63], v[12:13]
	v_mov_b64_e32 v[60:61], v[10:11]
	v_mov_b64_e32 v[58:59], v[8:9]
	v_mov_b64_e32 v[56:57], v[6:7]
	v_mov_b64_e32 v[54:55], v[4:5]
	v_mov_b64_e32 v[52:53], v[2:3]
	v_mov_b64_e32 v[50:51], v[0:1]
	v_mov_b64_e32 v[46:47], v[12:13]
	v_mov_b64_e32 v[44:45], v[10:11]
	v_mov_b64_e32 v[42:43], v[8:9]
	v_mov_b64_e32 v[40:41], v[6:7]
	v_mov_b64_e32 v[38:39], v[4:5]
	v_mov_b64_e32 v[36:37], v[2:3]
	v_mov_b64_e32 v[34:35], v[0:1]
	v_mov_b64_e32 v[30:31], v[12:13]
	v_mov_b64_e32 v[28:29], v[10:11]
	v_mov_b64_e32 v[26:27], v[8:9]
	v_mov_b64_e32 v[24:25], v[6:7]
	v_mov_b64_e32 v[22:23], v[4:5]
	v_mov_b64_e32 v[20:21], v[2:3]
	v_mov_b64_e32 v[18:19], v[0:1]
	v_mov_b64_e32 v[16:17], v[14:15]
	s_mov_b32 s80, 0
	s_mov_b32 s81, 2
	s_movk_i32 s83, 0x2400
	s_mov_b32 s74, s82
	v_mov_b32_e32 v210, 0
	s_movk_i32 s82, 0x4000
	s_mov_b32 s64, 0x8000
	v_mov_b64_e32 v[14:15], v[12:13]
	v_mov_b64_e32 v[12:13], v[10:11]
	v_mov_b64_e32 v[10:11], v[8:9]
	v_mov_b64_e32 v[8:9], v[6:7]
	v_mov_b64_e32 v[6:7], v[4:5]
	v_mov_b64_e32 v[4:5], v[2:3]
	v_mov_b64_e32 v[2:3], v[0:1]
	s_waitcnt vmcnt(0)
	v_readfirstlane_b32 s31, v179
	s_nop 3
	s_lshr_b32 s31, s31, 6
	s_lshl_b32 s30, s31, 11
	v_and_b32_e32 v150, 63, v179
	v_bfe_u32 v151, v150, 2, 3
	s_lshl_b32 s29, s31, 3
	v_or_b32_e32 v151, s29, v151
	v_and_b32_e32 v152, 4, v151
	v_lshlrev_b32_e32 v152, 1, v152
	v_and_b32_e32 v153, 8, v151
	v_lshrrev_b32_e32 v153, 1, v153
	v_and_b32_e32 v151, 0xfffffff3, v151
	v_or3_b32 v151, v151, v152, v153
	v_mul_u32_u24_e32 v151, 0x2400, v151
	v_lshrrev_b32_e32 v152, 5, v150
	v_lshlrev_b32_e32 v152, 6, v152
	v_and_b32_e32 v153, 3, v150
	v_lshlrev_b32_e32 v153, 4, v153
	v_add3_u32 v248, v151, v152, v153
	v_add_u32_e32 v249, 0x80, v248
	v_lshrrev_b32_e32 v151, 4, v150
	v_add_u32_e32 v151, s29, v151
	v_and_b32_e32 v152, 15, v150
	v_and_b32_e32 v153, 15, v151
	v_xor_b32_e32 v153, v152, v153
	v_mul_u32_u24_e32 v154, 0x2400, v151
	v_lshl_add_u32 v250, v153, 4, v154
	v_add_u32_e32 v151, 4, v151
	v_and_b32_e32 v153, 15, v151
	v_xor_b32_e32 v153, v152, v153
	v_mul_u32_u24_e32 v154, 0x2400, v151
	v_lshl_add_u32 v251, v153, 4, v154
	v_readfirstlane_b32 s26, v190
	v_readfirstlane_b32 s27, v191
	s_mul_i32 s29, s31, 0x9000
	s_add_u32 s29, s29, 0x168000
	s_sub_u32 s26, s26, s29
	s_subb_u32 s27, s27, 0
	s_sub_u32 s28, s26, 0x200
	s_subb_u32 s29, s27, 0
	s_add_i32 m0, s64, s30
	s_add_i32 m0, m0, 0xc000
	s_nop 0
	global_load_lds_dwordx4 v250, s[28:29]
	s_add_i32 m0, m0, 0x400
	s_nop 0
	global_load_lds_dwordx4 v251, s[28:29]
	s_add_i32 m0, m0, 0xfffffc00
	s_nop 0
	global_load_lds_dwordx4 v250, s[28:29]
	s_add_i32 m0, m0, 0x400
	s_nop 0
	global_load_lds_dwordx4 v251, s[28:29]
	s_add_u32 s28, s28, 0x90000
	s_addc_u32 s29, s29, 0
	s_waitcnt lgkmcnt(0)
	s_barrier
	v_mov_b32_e32 v160, s76
	ds_read_b32 v160, v160
	v_mov_b32_e32 v161, s41
	ds_read_b32 v161, v161
	s_waitcnt lgkmcnt(0)
.LBB0_132:
	v_readfirstlane_b32 s20, v221
	v_readfirstlane_b32 s21, v220
	s_nop 3
	s_add_i32 s22, s20, s77
	s_addk_i32 s22, 0x7f
	s_add_i32 s23, s21, s77
	s_addk_i32 s23, 0x40
	s_add_i32 s24, s22, 64
	s_add_i32 s25, s23, 64
	s_mov_b32 s79, s64
	s_cmp_lt_u32 s31, 4
	s_cbranch_scc0 .Ldp_6
	s_waitcnt vmcnt(2) lgkmcnt(0)
	s_barrier
; #define SBAR() __builtin_amdgcn_sched_barrier(0)
; #define SLOAD(i, k0) do { sr_[i].vs0 = *reinterpret_cast<const bf16x8*>(&Vh[(size_t)((k0) + sr) * LDQK + sc]); sr_[i].vs1 = *reinterpret_cast<const bf16x8*>(&Vh[(size_t)((k0) + 32 + sr) * LDQK + sc]); \
;     sr_[i].ks0 = *reinterpret_cast<const bf16x8*>(&Kh[(size_t)((k0) + sr) * LDQK + sc]); sr_[i].ks1 = *reinterpret_cast<const bf16x8*>(&Kh[(size_t)((k0) + 32 + sr) * LDQK + sc]); } while (0)
; #define SWRITE(off, i) do { *(bf16x8*)(V_lds + (off) + vst0) = sr_[i].vs0;          \
;     *(bf16x8*)(V_lds + (off) + vst1) = sr_[i].vs1; int kc = sc * 2;               \
;     *(bf16x8*)(K_lds + (off) + KSWZ(sr, kc)) = sr_[i].ks0;                       \
;     *(bf16x8*)(K_lds + (off) + KSWZ(32 + sr, kc)) = sr_[i].ks1; } while (0)
; #define SWAIT() asm volatile("s_waitcnt vmcnt(4)" ::: "memory")
; #define PSM(P0, P1, MN, AL, J) partialSM<MODE>(P0, P1, m_reg, MN, AL, relq + 64 * (J), relwmin + 64 * (J), relwmax + 64 * (J), lut)
; template <int MODE>
; __device__ __forceinline__ void attn_body(const bf16_t* __restrict__ Qb, const bf16_t* __restrict__ Kh, const bf16_t* __restrict__ Vh, int NT, int krel0,
;                                           char* lds, const float* __restrict__ lutg, const AttnEpi& E) {
;     ...
;     __syncthreads();
;     SBAR(); qkt<ND0, DOFF>(pB0, pB1, K_lds + oq, qr, r32, hi);
;     finishSM(pA0, pA1, alA, l_reg, pa0, pa1, pa2, pa3); SBAR();
;     SLOAD(SO, (j + 2) * 64); SBAR();
;     pv_d0(o, vb0 + op, pa0, pa1, pa2, pa3); PSM(pB0, pB1, mnB, alB, j);
;     SWAIT(); SWRITE(ow, SE);
.Ldp_6:
	s_add_i32 s64, s82, 0
	v_add_u32_e32 v0, s64, v213
	ds_read_b128 v[98:101], v0 offset:49152
	ds_read_b128 v[102:105], v0 offset:57344
	v_add_u32_e32 v0, s64, v214
	ds_read_b128 v[162:165], v0 offset:49152
	ds_read_b128 v[166:169], v0 offset:57344
	v_add_u32_e32 v0, s64, v215
	s_waitcnt lgkmcnt(3)
	v_mfma_f32_32x32x16_bf16 v[114:129], v[98:101], v[142:145], 0
	s_waitcnt lgkmcnt(2)
	v_mfma_f32_32x32x16_bf16 v[98:113], v[102:105], v[142:145], 0
	s_waitcnt lgkmcnt(1)
	v_mfma_f32_32x32x16_bf16 v[114:129], v[162:165], v[138:141], v[114:129]
	s_waitcnt lgkmcnt(0)
	v_mfma_f32_32x32x16_bf16 v[98:113], v[166:169], v[138:141], v[98:113]
	ds_read_b128 v[162:165], v0 offset:49152
	ds_read_b128 v[166:169], v0 offset:57344
	v_add_u32_e32 v0, s64, v216
	s_waitcnt lgkmcnt(1)
	v_mfma_f32_32x32x16_bf16 v[114:129], v[162:165], v[134:137], v[114:129]
	s_waitcnt lgkmcnt(0)
	v_mfma_f32_32x32x16_bf16 v[98:113], v[166:169], v[134:137], v[98:113]
	ds_read_b128 v[162:165], v0 offset:49152
	ds_read_b128 v[166:169], v0 offset:57344
	v_exp_f32_e32 v0, v82
	v_exp_f32_e32 v82, v83
	v_exp_f32_e32 v83, v84
	v_exp_f32_e32 v84, v85
	v_exp_f32_e32 v85, v86
	v_exp_f32_e32 v86, v87
	v_exp_f32_e32 v87, v88
	v_exp_f32_e32 v88, v89
	v_exp_f32_e32 v89, v90
	v_exp_f32_e32 v90, v91
	v_exp_f32_e32 v91, v92
	v_exp_f32_e32 v92, v93
	v_exp_f32_e32 v93, v94
	v_exp_f32_e32 v94, v95
	v_exp_f32_e32 v95, v96
	v_exp_f32_e32 v96, v97
	v_add_f32_e32 v97, v67, v66
	v_add_f32_e32 v97, v68, v97
	v_add_f32_e32 v97, v69, v97
	v_add_f32_e32 v97, v70, v97
	v_add_f32_e32 v97, v71, v97
	v_add_f32_e32 v97, v72, v97
	v_add_f32_e32 v97, v73, v97
	v_add_f32_e32 v97, v74, v97
	v_add_f32_e32 v97, v75, v97
	v_add_f32_e32 v97, v76, v97
	v_add_f32_e32 v97, v77, v97
	v_add_f32_e32 v97, v78, v97
	v_add_f32_e32 v97, v79, v97
	v_add_f32_e32 v97, v80, v97
	v_add_f32_e32 v97, v81, v97
	v_add_f32_e32 v97, v0, v97
	v_add_f32_e32 v97, v82, v97
	v_add_f32_e32 v97, v83, v97
	v_add_f32_e32 v97, v84, v97
	v_add_f32_e32 v97, v85, v97
	v_add_f32_e32 v97, v86, v97
	v_add_f32_e32 v97, v87, v97
	v_add_f32_e32 v97, v88, v97
	v_add_f32_e32 v97, v89, v97
	v_add_f32_e32 v97, v90, v97
	s_waitcnt lgkmcnt(1)
	v_mfma_f32_32x32x16_bf16 v[114:129], v[162:165], v[130:133], v[114:129]
	v_add_f32_e32 v97, v91, v97
	v_add_f32_e32 v97, v92, v97
	v_add_f32_e32 v97, v93, v97
	v_add_f32_e32 v97, v94, v97
	v_add_f32_e32 v97, v95, v97
	v_add_f32_e32 v223, v96, v97
	v_mov_b32_e32 v224, v223
	s_waitcnt lgkmcnt(0)
	v_mfma_f32_32x32x16_bf16 v[98:113], v[166:169], v[130:133], v[98:113]
	v_cvt_pk_bf16_f32 v66, v66, v67
	v_cvt_pk_bf16_f32 v67, v68, v69
	v_cvt_pk_bf16_f32 v68, v70, v71
	v_cvt_pk_bf16_f32 v69, v72, v73
	v_cvt_pk_bf16_f32 v70, v74, v75
	v_cvt_pk_bf16_f32 v71, v76, v77
	v_cvt_pk_bf16_f32 v72, v78, v79
	v_cvt_pk_bf16_f32 v73, v80, v81
	v_cvt_pk_bf16_f32 v74, v0, v82
	v_cvt_pk_bf16_f32 v75, v83, v84
	v_cvt_pk_bf16_f32 v76, v85, v86
	v_cvt_pk_bf16_f32 v77, v87, v88
	v_cvt_pk_bf16_f32 v78, v89, v90
	v_cvt_pk_bf16_f32 v79, v91, v92
	v_cvt_pk_bf16_f32 v80, v93, v94
	v_cvt_pk_bf16_f32 v81, v95, v96
	v_permlane32_swap_b32_e32 v223, v224
	v_permlane32_swap_b32_e32 v66, v68
	v_permlane32_swap_b32_e32 v67, v69
	v_permlane32_swap_b32_e32 v70, v72
	v_permlane32_swap_b32_e32 v71, v73
	v_permlane32_swap_b32_e32 v74, v76
	v_permlane32_swap_b32_e32 v75, v77
	v_permlane32_swap_b32_e32 v78, v80
	v_permlane32_swap_b32_e32 v79, v81
	s_cmp_lt_u32 s31, 4
	s_cbranch_scc1 .Ldp_5
	s_waitcnt vmcnt(2) lgkmcnt(0)
	s_barrier
.Ldp_5:
	s_setprio 0
	s_add_i32 m0, s80, s30
	s_add_i32 m0, m0, 0xc000
	s_nop 0
	global_load_lds_dwordx4 v250, s[28:29]
	s_add_i32 m0, m0, 0x400
	s_nop 0
	global_load_lds_dwordx4 v251, s[28:29]
	s_add_i32 m0, s79, s30
	s_nop 0
	global_load_lds_dwordx4 v248, s[26:27]
	s_add_i32 m0, m0, 0x400
	s_nop 0
	global_load_lds_dwordx4 v249, s[26:27]
	s_add_u32 s26, s26, 0x90000
	s_addc_u32 s27, s27, 0
	s_add_u32 s28, s28, 0x90000
	s_addc_u32 s29, s29, 0
	v_add_u32_e32 v0, s80, v218
	ds_read_b64_tr_b16 v[82:83], v0 offset:0
	ds_read_b64_tr_b16 v[84:85], v0 offset:0x800
	ds_read_b64_tr_b16 v[86:87], v0 offset:0x1000
	ds_read_b64_tr_b16 v[88:89], v0 offset:0x1800
	ds_read_b64_tr_b16 v[90:91], v0 offset:0x2000
	ds_read_b64_tr_b16 v[92:93], v0 offset:0x2800
	ds_read_b64_tr_b16 v[94:95], v0 offset:0x3000
	ds_read_b64_tr_b16 v[96:97], v0 offset:0x3800
	s_waitcnt lgkmcnt(0)
	s_nop 0
	v_mfma_f32_32x32x16_bf16 v[50:65], v[66:69], v[82:85], v[50:65]
	ds_read_b64_tr_b16 v[82:83], v0 offset:0x200
	ds_read_b64_tr_b16 v[84:85], v0 offset:0xa00
	v_mfma_f32_32x32x16_bf16 v[50:65], v[70:73], v[86:89], v[50:65]
	ds_read_b64_tr_b16 v[86:87], v0 offset:0x1200
	ds_read_b64_tr_b16 v[88:89], v0 offset:0x1a00
	v_mfma_f32_32x32x16_bf16 v[50:65], v[74:77], v[90:93], v[50:65]
	ds_read_b64_tr_b16 v[90:91], v0 offset:0x2200
	ds_read_b64_tr_b16 v[92:93], v0 offset:0x2a00
	v_mfma_f32_32x32x16_bf16 v[50:65], v[78:81], v[94:97], v[50:65]
	ds_read_b64_tr_b16 v[94:95], v0 offset:0x3200
	ds_read_b64_tr_b16 v[96:97], v0 offset:0x3a00
	s_waitcnt lgkmcnt(0)
	v_mfma_f32_32x32x16_bf16 v[34:49], v[66:69], v[82:85], v[34:49]
	ds_read_b64_tr_b16 v[82:83], v0 offset:0x400
	ds_read_b64_tr_b16 v[84:85], v0 offset:0xc00
	v_mfma_f32_32x32x16_bf16 v[34:49], v[70:73], v[86:89], v[34:49]
	ds_read_b64_tr_b16 v[86:87], v0 offset:0x1400
	ds_read_b64_tr_b16 v[88:89], v0 offset:0x1c00
	v_mfma_f32_32x32x16_bf16 v[34:49], v[74:77], v[90:93], v[34:49]
	ds_read_b64_tr_b16 v[90:91], v0 offset:0x2400
	ds_read_b64_tr_b16 v[92:93], v0 offset:0x2c00
	v_mfma_f32_32x32x16_bf16 v[34:49], v[78:81], v[94:97], v[34:49]
	ds_read_b64_tr_b16 v[94:95], v0 offset:0x3400
	ds_read_b64_tr_b16 v[96:97], v0 offset:0x3c00
	s_waitcnt lgkmcnt(0)
	v_mfma_f32_32x32x16_bf16 v[18:33], v[66:69], v[82:85], v[18:33]
	ds_read_b64_tr_b16 v[82:83], v0 offset:0x600
	ds_read_b64_tr_b16 v[84:85], v0 offset:0xe00
	v_mfma_f32_32x32x16_bf16 v[18:33], v[70:73], v[86:89], v[18:33]
	ds_read_b64_tr_b16 v[86:87], v0 offset:0x1600
	ds_read_b64_tr_b16 v[88:89], v0 offset:0x1e00
	v_mfma_f32_32x32x16_bf16 v[18:33], v[74:77], v[90:93], v[18:33]
	ds_read_b64_tr_b16 v[90:91], v0 offset:0x2600
	ds_read_b64_tr_b16 v[92:93], v0 offset:0x2e00
	v_mfma_f32_32x32x16_bf16 v[18:33], v[78:81], v[94:97], v[18:33]
	ds_read_b64_tr_b16 v[94:95], v0 offset:0x3600
	ds_read_b64_tr_b16 v[96:97], v0 offset:0x3e00
	s_waitcnt lgkmcnt(0)
	v_mfma_f32_32x32x16_bf16 v[2:17], v[66:69], v[82:85], v[2:17]
	s_cmp_gt_i32 s95, s22
	s_cselect_b64 s[64:65], -1, 0
	s_cmp_lt_i32 s15, s22
	s_cselect_b64 vcc, -1, 0
	v_mov_b32_e32 v229, v160
	v_mfma_f32_32x32x16_bf16 v[2:17], v[70:73], v[86:89], v[2:17]
	v_mfma_f32_32x32x16_bf16 v[2:17], v[74:77], v[90:93], v[2:17]
	v_mfma_f32_32x32x16_bf16 v[2:17], v[78:81], v[94:97], v[2:17]
	s_setprio 1
	s_and_saveexec_b64 s[66:67], vcc
	s_cbranch_execz .LBB0_136
; template <int MODE>
; __device__ __forceinline__ void partialSM(f32x16& p0, f32x16& p1, float& m_reg, float& mn, float& alpha, int relh, int relw_min, int relw_max, const float* lut) {
;     ...
;     if (nearT) {
; #pragma unroll
;       for (int r = 0; r < 16; ++r) { const int i0 = relh + (r & 3) + 8 * (r >> 2);
;         const int a0 = min(max(i0, -129), 129) + 129, a1 = min(max(i0 + 32, -129), 129) + 129;
;         p0[r] = fmaf(p0[r], C, lut[a0]); p1[r] = fmaf(p1[r], C, lut[a1]); }
	s_cmp_gt_i32 s91, s23
	s_cselect_b64 vcc, -1, 0
	s_mov_b64 s[70:71], -1
	s_and_saveexec_b64 s[68:69], vcc
	s_cbranch_execz .LBB0_135
	v_add_u32_e32 v227, s77, v222
	v_add_u32_e32 v66, 64, v227
	v_add_u32_e32 v68, 0x41, v227
	v_add_u32_e32 v70, 0x42, v227
	v_add_u32_e32 v72, 0x43, v227
	v_med3_i32 v67, v66, s39, v198
	v_med3_i32 v66, v66, s33, v199
	v_med3_i32 v69, v68, s39, v198
	v_med3_i32 v68, v68, s33, v199
	v_med3_i32 v71, v70, s39, v198
	v_med3_i32 v70, v70, s33, v199
	v_med3_i32 v73, v72, s39, v198
	v_med3_i32 v72, v72, s33, v199
	v_lshl_add_u32 v67, v67, 2, s76
	v_lshl_add_u32 v66, v66, 2, s76
	v_lshl_add_u32 v69, v69, 2, s76
	v_lshl_add_u32 v68, v68, 2, s76
	v_lshl_add_u32 v70, v70, 2, s76
	v_lshl_add_u32 v72, v72, 2, s76
	v_lshl_add_u32 v71, v71, 2, s76
	v_lshl_add_u32 v73, v73, 2, s76
	ds_read_b32 v194, v67 offset:516
	ds_read_b32 v66, v66 offset:644
	ds_read_b32 v195, v69 offset:516
	ds_read_b32 v67, v68 offset:644
	ds_read_b32 v229, v71 offset:516
	ds_read_b32 v68, v70 offset:644
	ds_read_b32 v230, v73 offset:516
	ds_read_b32 v69, v72 offset:644
	v_add_u32_e32 v70, 0x48, v227
	v_add_u32_e32 v72, 0x49, v227
	v_add_u32_e32 v74, 0x4a, v227
	v_add_u32_e32 v76, 0x4b, v227
	v_med3_i32 v71, v70, s39, v198
	v_med3_i32 v70, v70, s33, v199
	v_med3_i32 v73, v72, s39, v198
	v_med3_i32 v72, v72, s33, v199
	v_med3_i32 v75, v74, s39, v198
	v_med3_i32 v74, v74, s33, v199
	v_med3_i32 v77, v76, s39, v198
	v_med3_i32 v76, v76, s33, v199
	v_lshl_add_u32 v71, v71, 2, s76
	v_lshl_add_u32 v70, v70, 2, s76
	v_lshl_add_u32 v73, v73, 2, s76
	v_lshl_add_u32 v72, v72, 2, s76
	v_lshl_add_u32 v74, v74, 2, s76
	v_lshl_add_u32 v76, v76, 2, s76
	v_lshl_add_u32 v75, v75, 2, s76
	v_lshl_add_u32 v77, v77, 2, s76
	ds_read_b32 v231, v71 offset:516
	ds_read_b32 v70, v70 offset:644
	ds_read_b32 v232, v73 offset:516
	ds_read_b32 v71, v72 offset:644
	ds_read_b32 v233, v75 offset:516
	ds_read_b32 v72, v74 offset:644
	ds_read_b32 v234, v77 offset:516
	ds_read_b32 v73, v76 offset:644
	v_add_u32_e32 v74, 0x50, v227
	v_add_u32_e32 v76, 0x51, v227
	v_add_u32_e32 v78, 0x52, v227
	v_add_u32_e32 v80, 0x53, v227
	v_med3_i32 v75, v74, s39, v198
	v_med3_i32 v74, v74, s33, v199
	v_med3_i32 v77, v76, s39, v198
	v_med3_i32 v76, v76, s33, v199
	v_med3_i32 v79, v78, s39, v198
	v_med3_i32 v78, v78, s33, v199
	v_med3_i32 v81, v80, s39, v198
	v_med3_i32 v80, v80, s33, v199
	v_lshl_add_u32 v75, v75, 2, s76
	v_lshl_add_u32 v74, v74, 2, s76
	v_lshl_add_u32 v77, v77, 2, s76
	v_lshl_add_u32 v76, v76, 2, s76
	v_lshl_add_u32 v78, v78, 2, s76
	v_lshl_add_u32 v80, v80, 2, s76
	v_lshl_add_u32 v79, v79, 2, s76
	v_lshl_add_u32 v81, v81, 2, s76
	ds_read_b32 v235, v75 offset:516
	ds_read_b32 v74, v74 offset:644
	ds_read_b32 v236, v77 offset:516
	ds_read_b32 v75, v76 offset:644
	ds_read_b32 v237, v79 offset:516
	ds_read_b32 v76, v78 offset:644
	ds_read_b32 v238, v81 offset:516
	ds_read_b32 v77, v80 offset:644
	v_add_u32_e32 v78, 0x58, v227
	v_add_u32_e32 v80, 0x59, v227
	v_add_u32_e32 v82, 0x5a, v227
	v_med3_i32 v79, v78, s39, v198
	v_med3_i32 v78, v78, s33, v199
	v_med3_i32 v81, v80, s39, v198
	v_med3_i32 v80, v80, s33, v199
	v_med3_i32 v83, v82, s39, v198
	v_med3_i32 v82, v82, s33, v199
	v_add_u32_e32 v84, 0x5b, v227
	s_waitcnt lgkmcnt(14)
	v_fmac_f32_e32 v194, 0x3e38aa3b, v114
	v_fmac_f32_e32 v195, 0x3e38aa3b, v115
	v_lshl_add_u32 v79, v79, 2, s76
	v_lshl_add_u32 v78, v78, 2, s76
	v_lshl_add_u32 v81, v81, 2, s76
	v_lshl_add_u32 v80, v80, 2, s76
	v_lshl_add_u32 v82, v82, 2, s76
	v_med3_i32 v85, v84, s39, v198
	v_med3_i32 v84, v84, s33, v199
	v_fmac_f32_e32 v229, 0x3e38aa3b, v116
	v_fmac_f32_e32 v230, 0x3e38aa3b, v117
	v_lshl_add_u32 v83, v83, 2, s76
	v_lshl_add_u32 v85, v85, 2, s76
	v_lshl_add_u32 v84, v84, 2, s76
	ds_read_b32 v239, v79 offset:516
	ds_read_b32 v78, v78 offset:644
	ds_read_b32 v240, v81 offset:516
	ds_read_b32 v79, v80 offset:644
	ds_read_b32 v241, v83 offset:516
	ds_read_b32 v80, v82 offset:644
	ds_read_b32 v242, v85 offset:516
	ds_read_b32 v81, v84 offset:644
	v_max_f32_e32 v82, v194, v195
	v_fmac_f32_e32 v231, 0x3e38aa3b, v118
	s_waitcnt lgkmcnt(14)
; template <int MODE>
; __device__ __forceinline__ void partialSM(f32x16& p0, f32x16& p1, float& m_reg, float& mn, float& alpha, int relh, int relw_min, int relw_max, const float* lut) {
;     ...
;     float pmax = p0[0];
; #pragma unroll
;     for (int r = 1; r < 16; ++r) pmax = fmaxf(pmax, p0[r]);
; #pragma unroll
;     for (int r = 0; r < 16; ++r) pmax = fmaxf(pmax, p1[r]);
;     { auto rr = __builtin_amdgcn_permlane32_swap(__float_as_uint(pmax), __float_as_uint(pmax), false, false);
;       pmax = fmaxf(__uint_as_float(rr[0]), __uint_as_float(rr[1])); }
;     if (__builtin_expect(__all(pmax - m_reg <= THR2), 1)) { mn = m_reg; alpha = 1.f; }
;     else { mn = fmaxf(m_reg, pmax); alpha = __builtin_amdgcn_exp2f(m_reg - mn); m_reg = mn; }
; #pragma unroll
;     for (int r = 0; r < 16; ++r) p0[r] = __builtin_amdgcn_exp2f(p0[r] - mn);
; #pragma unroll
;     for (int r = 0; r < 16; ++r) p1[r] = p1[r] - mn;
	v_fmac_f32_e32 v232, 0x3e38aa3b, v119
	v_max3_f32 v82, v82, v229, v230
	v_fmac_f32_e32 v233, 0x3e38aa3b, v120
	v_fmac_f32_e32 v234, 0x3e38aa3b, v121
	v_max3_f32 v82, v82, v231, v232
	v_fmac_f32_e32 v235, 0x3e38aa3b, v122
	s_waitcnt lgkmcnt(13)
	v_fmac_f32_e32 v236, 0x3e38aa3b, v123
	v_max3_f32 v82, v82, v233, v234
	s_waitcnt lgkmcnt(11)
	v_fmac_f32_e32 v237, 0x3e38aa3b, v124
	s_waitcnt lgkmcnt(9)
	v_fmac_f32_e32 v238, 0x3e38aa3b, v125
	v_max3_f32 v82, v82, v235, v236
	s_waitcnt lgkmcnt(7)
	v_fmac_f32_e32 v239, 0x3e38aa3b, v126
	s_waitcnt lgkmcnt(5)
	v_fmac_f32_e32 v240, 0x3e38aa3b, v127
	v_max3_f32 v82, v82, v237, v238
	s_waitcnt lgkmcnt(3)
	v_fmac_f32_e32 v241, 0x3e38aa3b, v128
	s_waitcnt lgkmcnt(1)
	v_fmac_f32_e32 v242, 0x3e38aa3b, v129
	v_max3_f32 v82, v82, v239, v240
	v_max3_f32 v84, v82, v241, v242
	v_pk_fma_f32 v[82:83], v[98:99], s[48:49], v[66:67] op_sel_hi:[1,0,1]
	v_pk_fma_f32 v[86:87], v[102:103], s[48:49], v[70:71] op_sel_hi:[1,0,1]
	v_max3_f32 v66, v84, v82, v83
	v_pk_fma_f32 v[84:85], v[100:101], s[48:49], v[68:69] op_sel_hi:[1,0,1]
	v_pk_fma_f32 v[88:89], v[104:105], s[48:49], v[72:73] op_sel_hi:[1,0,1]
	v_max3_f32 v66, v66, v84, v85
	v_max3_f32 v66, v66, v86, v87
	v_max3_f32 v66, v66, v88, v89
	v_pk_fma_f32 v[90:91], v[106:107], s[48:49], v[74:75] op_sel_hi:[1,0,1]
	v_pk_fma_f32 v[92:93], v[108:109], s[48:49], v[76:77] op_sel_hi:[1,0,1]
	v_max3_f32 v66, v66, v90, v91
	v_max3_f32 v66, v66, v92, v93
	v_pk_fma_f32 v[94:95], v[110:111], s[48:49], v[78:79] op_sel_hi:[1,0,1]
	s_waitcnt lgkmcnt(0)
	v_pk_fma_f32 v[96:97], v[112:113], s[48:49], v[80:81] op_sel_hi:[1,0,1]
	v_max3_f32 v66, v66, v94, v95
	v_max3_f32 v66, v66, v96, v97
	v_mov_b32_e32 v67, v66
	s_nop 1
	v_permlane32_swap_b32_e32 v66, v67
	v_max_f32_e32 v66, v66, v67
	v_sub_f32_e32 v67, v66, v219
	v_cmp_ge_f32_e32 vcc, s94, v67
	v_max_f32_e32 v66, v219, v66
	v_sub_f32_e32 v67, v219, v66
	v_exp_f32_e32 v67, v67
	s_cmp_eq_u64 vcc, exec
	s_cselect_b64 vcc, -1, 0
	v_cndmask_b32_e32 v228, v66, v219, vcc
	v_cndmask_b32_e64 v226, v67, 1.0, vcc
	v_sub_f32_e32 v66, v194, v228
	v_sub_f32_e32 v67, v195, v228
	v_sub_f32_e32 v68, v229, v228
	v_sub_f32_e32 v69, v230, v228
	v_sub_f32_e32 v70, v231, v228
	v_sub_f32_e32 v71, v232, v228
	v_sub_f32_e32 v72, v233, v228
	v_sub_f32_e32 v73, v234, v228
	v_sub_f32_e32 v74, v235, v228
	v_sub_f32_e32 v75, v236, v228
	v_sub_f32_e32 v76, v237, v228
	v_sub_f32_e32 v77, v238, v228
	v_sub_f32_e32 v78, v239, v228
	v_sub_f32_e32 v79, v240, v228
	v_sub_f32_e32 v80, v241, v228
	v_sub_f32_e32 v81, v242, v228
	v_exp_f32_e32 v66, v66
	v_exp_f32_e32 v67, v67
	v_exp_f32_e32 v68, v68
	v_exp_f32_e32 v69, v69
	v_exp_f32_e32 v70, v70
	v_exp_f32_e32 v71, v71
	v_exp_f32_e32 v72, v72
	v_exp_f32_e32 v73, v73
	v_exp_f32_e32 v74, v74
	v_exp_f32_e32 v75, v75
	v_exp_f32_e32 v76, v76
	v_exp_f32_e32 v77, v77
	v_exp_f32_e32 v78, v78
	v_exp_f32_e32 v79, v79
	v_exp_f32_e32 v80, v80
	v_exp_f32_e32 v81, v81
	v_sub_f32_e32 v97, v97, v228
	v_sub_f32_e32 v96, v96, v228
	v_sub_f32_e32 v95, v95, v228
	v_sub_f32_e32 v94, v94, v228
	v_sub_f32_e32 v93, v93, v228
	v_sub_f32_e32 v92, v92, v228
	v_sub_f32_e32 v91, v91, v228
	v_sub_f32_e32 v90, v90, v228
	v_sub_f32_e32 v89, v89, v228
	v_sub_f32_e32 v88, v88, v228
	v_sub_f32_e32 v87, v87, v228
	v_sub_f32_e32 v86, v86, v228
	v_sub_f32_e32 v85, v85, v228
	v_sub_f32_e32 v84, v84, v228
	v_sub_f32_e32 v83, v83, v228
	v_sub_f32_e32 v82, v82, v228
	s_xor_b64 s[70:71], exec, -1

; #define SBAR() __builtin_amdgcn_sched_barrier(0)
; #define SLOAD(i, k0) do { sr_[i].vs0 = *reinterpret_cast<const bf16x8*>(&Vh[(size_t)((k0) + sr) * LDQK + sc]); sr_[i].vs1 = *reinterpret_cast<const bf16x8*>(&Vh[(size_t)((k0) + 32 + sr) * LDQK + sc]); \
;     sr_[i].ks0 = *reinterpret_cast<const bf16x8*>(&Kh[(size_t)((k0) + sr) * LDQK + sc]); sr_[i].ks1 = *reinterpret_cast<const bf16x8*>(&Kh[(size_t)((k0) + 32 + sr) * LDQK + sc]); } while (0)
; #define SWRITE(off, i) do { *(bf16x8*)(V_lds + (off) + vst0) = sr_[i].vs0;          \
;     *(bf16x8*)(V_lds + (off) + vst1) = sr_[i].vs1; int kc = sc * 2;               \
;     *(bf16x8*)(K_lds + (off) + KSWZ(sr, kc)) = sr_[i].ks0;                       \
;     *(bf16x8*)(K_lds + (off) + KSWZ(32 + sr, kc)) = sr_[i].ks1; } while (0)
; #define SWAIT() asm volatile("s_waitcnt vmcnt(4)" ::: "memory")
; #define PSM(P0, P1, MN, AL, J) partialSM<MODE>(P0, P1, m_reg, MN, AL, relq + 64 * (J), relwmin + 64 * (J), relwmax + 64 * (J), lut)
; template <int MODE>
; __device__ __forceinline__ void attn_body(const bf16_t* __restrict__ Qb, const bf16_t* __restrict__ Kh, const bf16_t* __restrict__ Vh, int NT, int krel0,
;                                           char* lds, const float* __restrict__ lutg, const AttnEpi& E) {
;     ...
;     __syncthreads();
;     SBAR(); qkt<ND0, DOFF>(pA0, pA1, K_lds + oq, qr, r32, hi);
;     finishSM(pB0, pB1, alB, l_reg, pa0, pa1, pa2, pa3); SBAR();
;     if (j + 3 < NT) SLOAD(SE, (j + 3) * 64); SBAR();
;     pv_d0(o, vb0 + op, pa0, pa1, pa2, pa3); PSM(pA0, pA1, mnA, alA, j + 1);
;     SWAIT(); SWRITE(ow, SO);
.LBB0_142:
	s_cmp_lt_u32 s31, 4
	s_cbranch_scc0 .Ldp_4
	s_waitcnt vmcnt(2) lgkmcnt(0)
	s_barrier
.Ldp_4:
	v_add_u32_e32 v102, s66, v213
	ds_read_b128 v[98:101], v102 offset:49152
	ds_read_b128 v[102:105], v102 offset:57344
	v_add_u32_e32 v194, s66, v214
	ds_read_b128 v[230:233], v194 offset:49152
	ds_read_b128 v[234:237], v194 offset:57344
	v_add_u32_e32 v194, s66, v215
	s_waitcnt lgkmcnt(3)
	v_mfma_f32_32x32x16_bf16 v[114:129], v[98:101], v[142:145], 0
	v_exp_f32_e32 v82, v82
	v_exp_f32_e32 v83, v83
	v_exp_f32_e32 v84, v84
	v_exp_f32_e32 v85, v85
	v_exp_f32_e32 v86, v86
	v_exp_f32_e32 v87, v87
	v_exp_f32_e32 v88, v88
	s_waitcnt lgkmcnt(2)
	v_mfma_f32_32x32x16_bf16 v[98:113], v[102:105], v[142:145], 0
	v_exp_f32_e32 v89, v89
	v_exp_f32_e32 v90, v90
	v_exp_f32_e32 v91, v91
	v_exp_f32_e32 v92, v92
	v_exp_f32_e32 v93, v93
	v_exp_f32_e32 v94, v94
	v_exp_f32_e32 v95, v95
	s_waitcnt lgkmcnt(1)
	v_mfma_f32_32x32x16_bf16 v[114:129], v[230:233], v[138:141], v[114:129]
	v_exp_f32_e32 v96, v96
	v_exp_f32_e32 v97, v97
	s_waitcnt lgkmcnt(0)
	v_mfma_f32_32x32x16_bf16 v[98:113], v[234:237], v[138:141], v[98:113]
	ds_read_b128 v[230:233], v194 offset:49152
	ds_read_b128 v[234:237], v194 offset:57344
	v_add_u32_e32 v194, s66, v216
	s_waitcnt lgkmcnt(1)
	v_mfma_f32_32x32x16_bf16 v[114:129], v[230:233], v[134:137], v[114:129]
	s_waitcnt lgkmcnt(0)
	v_mfma_f32_32x32x16_bf16 v[98:113], v[234:237], v[134:137], v[98:113]
	ds_read_b128 v[230:233], v194 offset:49152
	ds_read_b128 v[234:237], v194 offset:57344
	v_add_f32_e32 v194, v67, v66
	v_add_f32_e32 v194, v68, v194
	v_add_f32_e32 v194, v69, v194
	v_add_f32_e32 v194, v70, v194
	v_add_f32_e32 v194, v71, v194
	v_add_f32_e32 v194, v72, v194
	v_add_f32_e32 v194, v73, v194
	v_add_f32_e32 v194, v74, v194
	v_add_f32_e32 v194, v75, v194
	v_add_f32_e32 v194, v76, v194
	v_add_f32_e32 v194, v77, v194
	v_add_f32_e32 v194, v78, v194
	v_add_f32_e32 v194, v79, v194
	v_add_f32_e32 v194, v80, v194
	v_add_f32_e32 v194, v81, v194
	v_add_f32_e32 v194, v82, v194
	v_add_f32_e32 v194, v83, v194
	v_add_f32_e32 v194, v84, v194
	v_add_f32_e32 v194, v85, v194
	v_add_f32_e32 v194, v86, v194
	v_add_f32_e32 v194, v87, v194
	v_add_f32_e32 v194, v88, v194
	v_add_f32_e32 v194, v89, v194
	v_add_f32_e32 v194, v90, v194
	v_add_f32_e32 v194, v91, v194
	s_waitcnt lgkmcnt(1)
	v_mfma_f32_32x32x16_bf16 v[114:129], v[230:233], v[130:133], v[114:129]
	v_add_f32_e32 v194, v92, v194
	v_add_f32_e32 v194, v93, v194
	v_add_f32_e32 v194, v94, v194
	v_add_f32_e32 v194, v95, v194
	v_add_f32_e32 v194, v96, v194
	v_add_f32_e32 v229, v97, v194
	v_mov_b32_e32 v230, v229
	s_waitcnt lgkmcnt(0)
	v_mfma_f32_32x32x16_bf16 v[98:113], v[234:237], v[130:133], v[98:113]
	v_cvt_pk_bf16_f32 v66, v66, v67
	v_cvt_pk_bf16_f32 v67, v68, v69
	v_cvt_pk_bf16_f32 v68, v70, v71
	v_cvt_pk_bf16_f32 v69, v72, v73
	v_cvt_pk_bf16_f32 v70, v74, v75
	v_cvt_pk_bf16_f32 v71, v76, v77
	v_cvt_pk_bf16_f32 v72, v78, v79
	v_cvt_pk_bf16_f32 v73, v80, v81
	v_cvt_pk_bf16_f32 v74, v82, v83
	v_cvt_pk_bf16_f32 v75, v84, v85
	v_cvt_pk_bf16_f32 v76, v86, v87
	v_cvt_pk_bf16_f32 v77, v88, v89
	v_cvt_pk_bf16_f32 v78, v90, v91
	v_cvt_pk_bf16_f32 v79, v92, v93
	v_cvt_pk_bf16_f32 v80, v94, v95
	v_cvt_pk_bf16_f32 v81, v96, v97
	v_permlane32_swap_b32_e32 v229, v230
	v_permlane32_swap_b32_e32 v66, v68
	v_permlane32_swap_b32_e32 v67, v69
	v_permlane32_swap_b32_e32 v70, v72
	v_permlane32_swap_b32_e32 v71, v73
	v_permlane32_swap_b32_e32 v74, v76
	v_permlane32_swap_b32_e32 v75, v77
	v_permlane32_swap_b32_e32 v78, v80
	v_permlane32_swap_b32_e32 v79, v81
	s_add_i32 s81, s81, 2
	s_cmp_ge_u32 s81, s11
	s_cselect_b64 s[64:65], -1, 0
	s_cmp_lt_u32 s31, 4
	s_cbranch_scc1 .Ldp_3
	s_waitcnt vmcnt(2) lgkmcnt(0)
	s_barrier
.Ldp_3:
	s_setprio 0
	s_add_i32 m0, s82, s30
	s_add_i32 m0, m0, 0xc000
	s_nop 0
	global_load_lds_dwordx4 v250, s[28:29]
	s_add_i32 m0, m0, 0x400
	s_nop 0
	global_load_lds_dwordx4 v251, s[28:29]
	s_add_i32 m0, s80, s30
	s_nop 0
	global_load_lds_dwordx4 v248, s[26:27]
	s_add_i32 m0, m0, 0x400
	s_nop 0
	global_load_lds_dwordx4 v249, s[26:27]
	s_add_u32 s26, s26, 0x90000
	s_addc_u32 s27, s27, 0
	s_add_u32 s28, s28, 0x90000
	s_addc_u32 s29, s29, 0

; #define SBAR() __builtin_amdgcn_sched_barrier(0)
; __device__ __forceinline__ int crow(int r, int hi) { return (r & 3) + 8 * (r >> 2) + 4 * hi; }
; #define RESC(a) do { if (__any((a) < 1.f)) { if (hi == 0) al_l[r32] = (a); asm volatile("s_waitcnt lgkmcnt(0)" ::: "memory"); \
;     _Pragma("unroll") for (int d = 0; d < 4; ++d) _Pragma("unroll") for (int r = 0; r < 16; ++r) o[d][r] *= al_l[crow(r, hi)]; } } while (0)
; #define PSM(P0, P1, MN, AL, J) partialSM<MODE>(P0, P1, m_reg, MN, AL, relq + 64 * (J), relwmin + 64 * (J), relwmax + 64 * (J), lut)
; template <int MODE>
; __device__ __forceinline__ void attn_body(const bf16_t* __restrict__ Qb, const bf16_t* __restrict__ Kh, const bf16_t* __restrict__ Vh, int NT, int krel0,
;                                           char* lds, const float* __restrict__ lutg, const AttnEpi& E) {
;     ...
;   SBAR(); qkt<ND0, DOFF>(pB0, pB1, K_lds + oq, qr, r32, hi);
;   finishSM(pA0, pA1, alA, l_reg, pa0, pa1, pa2, pa3); SBAR();
;   pv_d0(o, vb0 + op, pa0, pa1, pa2, pa3); PSM(pB0, pB1, mnB, alB, NT - 1);
;   RESC(alB);
;   finishSM(pB0, pB1, alB, l_reg, pa0, pa1, pa2, pa3); SBAR();
;   pv_d0(o, vb0 + oq, pa0, pa1, pa2, pa3);
;   if constexpr (MODE == 1) l_reg += __builtin_amdgcn_exp2f(E.sinkl2 - m_reg);
;   if (hi == 0) li_l[r32] = l_reg; asm volatile("s_waitcnt lgkmcnt(0)" ::: "memory");
;   float rli[16];
; #pragma unroll
;   for (int r = 0; r < 16; ++r) rli[r] = __builtin_amdgcn_rcpf(li_l[crow(r, hi)]);
.LBB0_166:
	v_exp_f32_e32 v98, v82
	v_add_f32_e32 v82, 0, v66
	v_add_f32_e32 v82, v67, v82
	v_add_f32_e32 v82, v68, v82
	v_add_f32_e32 v82, v69, v82
	v_add_f32_e32 v82, v70, v82
	v_add_f32_e32 v82, v71, v82
	v_add_f32_e32 v82, v72, v82
	v_add_f32_e32 v82, v73, v82
	v_add_f32_e32 v82, v74, v82
	v_add_f32_e32 v82, v75, v82
	v_add_f32_e32 v82, v76, v82
	v_add_f32_e32 v82, v77, v82
	v_add_f32_e32 v82, v78, v82
	v_exp_f32_e32 v99, v83
	v_add_f32_e32 v82, v79, v82
	v_exp_f32_e32 v84, v84
	v_add_f32_e32 v82, v80, v82
	v_exp_f32_e32 v85, v85
	v_add_f32_e32 v82, v81, v82
	v_exp_f32_e32 v86, v86
	v_add_f32_e32 v82, v98, v82
	v_exp_f32_e32 v87, v87
	v_add_f32_e32 v82, v99, v82
	v_exp_f32_e32 v88, v88
	v_add_f32_e32 v82, v84, v82
	v_exp_f32_e32 v89, v89
	v_add_f32_e32 v82, v85, v82
	v_exp_f32_e32 v90, v90
	v_add_f32_e32 v82, v86, v82
	v_exp_f32_e32 v91, v91
	v_add_f32_e32 v82, v87, v82
	v_exp_f32_e32 v92, v92
	v_add_f32_e32 v82, v88, v82
	v_exp_f32_e32 v93, v93
	v_add_f32_e32 v82, v89, v82
	v_exp_f32_e32 v94, v94
	v_add_f32_e32 v82, v90, v82
	v_exp_f32_e32 v95, v95
	v_add_f32_e32 v82, v91, v82
	v_exp_f32_e32 v96, v96
	v_add_f32_e32 v82, v92, v82
	v_exp_f32_e32 v97, v97
	v_add_f32_e32 v82, v93, v82
	v_add_f32_e32 v82, v94, v82
	v_add_f32_e32 v82, v95, v82
	v_add_f32_e32 v82, v96, v82
	v_add_f32_e32 v82, v97, v82
	v_mov_b32_e32 v83, v82
	s_nop 1
	v_permlane32_swap_b32_e32 v82, v83
	v_cvt_pk_bf16_f32 v66, v66, v67
	v_cvt_pk_bf16_f32 v67, v68, v69
	v_cvt_pk_bf16_f32 v68, v70, v71
	v_cvt_pk_bf16_f32 v69, v72, v73
	v_cvt_pk_bf16_f32 v70, v74, v75
	v_cvt_pk_bf16_f32 v71, v76, v77
	v_cvt_pk_bf16_f32 v72, v78, v79
	v_cvt_pk_bf16_f32 v73, v80, v81
	v_cvt_pk_bf16_f32 v74, v98, v99
	v_cvt_pk_bf16_f32 v75, v84, v85
	v_cvt_pk_bf16_f32 v76, v86, v87
	v_cvt_pk_bf16_f32 v77, v88, v89
	v_cvt_pk_bf16_f32 v78, v90, v91
	v_cvt_pk_bf16_f32 v79, v92, v93
	v_cvt_pk_bf16_f32 v80, v94, v95
	v_cvt_pk_bf16_f32 v81, v96, v97
	v_permlane32_swap_b32_e32 v66, v68
	v_permlane32_swap_b32_e32 v67, v69
	v_permlane32_swap_b32_e32 v70, v72
	v_permlane32_swap_b32_e32 v71, v73
	v_permlane32_swap_b32_e32 v74, v76
	v_permlane32_swap_b32_e32 v75, v77
	v_permlane32_swap_b32_e32 v78, v80
	v_permlane32_swap_b32_e32 v79, v81
	ds_read_b64_tr_b16 v[84:85], v0 offset:0
	ds_read_b64_tr_b16 v[86:87], v0 offset:0x800
	ds_read_b64_tr_b16 v[88:89], v0 offset:0x1000
	ds_read_b64_tr_b16 v[90:91], v0 offset:0x1800
	ds_read_b64_tr_b16 v[92:93], v0 offset:0x2000
	ds_read_b64_tr_b16 v[94:95], v0 offset:0x2800
	ds_read_b64_tr_b16 v[96:97], v0 offset:0x3000
	ds_read_b64_tr_b16 v[98:99], v0 offset:0x3800
	s_waitcnt lgkmcnt(0)
	s_nop 0
	v_mfma_f32_32x32x16_bf16 v[50:65], v[66:69], v[84:87], v[50:65]
	ds_read_b64_tr_b16 v[84:85], v0 offset:0x200
	ds_read_b64_tr_b16 v[86:87], v0 offset:0xa00
	v_mfma_f32_32x32x16_bf16 v[50:65], v[70:73], v[88:91], v[50:65]
	ds_read_b64_tr_b16 v[88:89], v0 offset:0x1200
	ds_read_b64_tr_b16 v[90:91], v0 offset:0x1a00
	v_mfma_f32_32x32x16_bf16 v[50:65], v[74:77], v[92:95], v[50:65]
	ds_read_b64_tr_b16 v[92:93], v0 offset:0x2200
	ds_read_b64_tr_b16 v[94:95], v0 offset:0x2a00
	v_mfma_f32_32x32x16_bf16 v[50:65], v[78:81], v[96:99], v[50:65]
	ds_read_b64_tr_b16 v[96:97], v0 offset:0x3200
	ds_read_b64_tr_b16 v[98:99], v0 offset:0x3a00
	s_waitcnt lgkmcnt(0)
	v_mfma_f32_32x32x16_bf16 v[34:49], v[66:69], v[84:87], v[34:49]
	ds_read_b64_tr_b16 v[84:85], v0 offset:0x400
	ds_read_b64_tr_b16 v[86:87], v0 offset:0xc00
	v_mfma_f32_32x32x16_bf16 v[34:49], v[70:73], v[88:91], v[34:49]
	ds_read_b64_tr_b16 v[88:89], v0 offset:0x1400
	ds_read_b64_tr_b16 v[90:91], v0 offset:0x1c00
	v_mfma_f32_32x32x16_bf16 v[34:49], v[74:77], v[92:95], v[34:49]
	ds_read_b64_tr_b16 v[92:93], v0 offset:0x2400
	ds_read_b64_tr_b16 v[94:95], v0 offset:0x2c00
	v_mfma_f32_32x32x16_bf16 v[34:49], v[78:81], v[96:99], v[34:49]
	ds_read_b64_tr_b16 v[96:97], v0 offset:0x3400
	ds_read_b64_tr_b16 v[98:99], v0 offset:0x3c00
	s_waitcnt lgkmcnt(0)
	v_mfma_f32_32x32x16_bf16 v[18:33], v[66:69], v[84:87], v[18:33]
	ds_read_b64_tr_b16 v[84:85], v0 offset:0x600
	ds_read_b64_tr_b16 v[86:87], v0 offset:0xe00
	v_mfma_f32_32x32x16_bf16 v[18:33], v[70:73], v[88:91], v[18:33]
	ds_read_b64_tr_b16 v[88:89], v0 offset:0x1600
	ds_read_b64_tr_b16 v[90:91], v0 offset:0x1e00
	v_mfma_f32_32x32x16_bf16 v[18:33], v[74:77], v[92:95], v[18:33]
	ds_read_b64_tr_b16 v[92:93], v0 offset:0x2600
	ds_read_b64_tr_b16 v[94:95], v0 offset:0x2e00
	v_mfma_f32_32x32x16_bf16 v[18:33], v[78:81], v[96:99], v[18:33]
	ds_read_b64_tr_b16 v[96:97], v0 offset:0x3600
	ds_read_b64_tr_b16 v[98:99], v0 offset:0x3e00
	s_waitcnt lgkmcnt(0)
	v_mfma_f32_32x32x16_bf16 v[2:17], v[66:69], v[84:87], v[2:17]
	v_mfma_f32_32x32x16_bf16 v[2:17], v[70:73], v[88:91], v[2:17]
	v_mfma_f32_32x32x16_bf16 v[2:17], v[74:77], v[92:95], v[2:17]
	v_mfma_f32_32x32x16_bf16 v[2:17], v[78:81], v[96:99], v[2:17]
	s_and_saveexec_b64 s[64:65], s[6:7]
	v_add_f32_e32 v0, v130, v131
	v_fmac_f32_e32 v0, v210, v225
	v_add_f32_e32 v66, v82, v83
	v_fmac_f32_e32 v66, v0, v132
	ds_write_b32 v209, v66
	s_or_b64 exec, exec, s[64:65]
	s_waitcnt lgkmcnt(0)
	ds_read_b128 v[66:69], v208
	ds_read_b128 v[70:73], v208 offset:32
	s_movk_i32 s6, 0x103
	s_waitcnt lgkmcnt(1)
	v_rcp_f32_e32 v0, v66
	v_rcp_f32_e32 v74, v67
	v_rcp_f32_e32 v75, v68
	v_rcp_f32_e32 v76, v69
	ds_read_b128 v[66:69], v208 offset:64
	s_waitcnt lgkmcnt(1)
	v_rcp_f32_e32 v77, v70
	v_rcp_f32_e32 v78, v71
	v_rcp_f32_e32 v79, v72
	v_rcp_f32_e32 v80, v73
	ds_read_b128 v[70:73], v208 offset:96
	s_waitcnt lgkmcnt(1)
; template <int MODE>
; __device__ __forceinline__ void attn_body(const bf16_t* __restrict__ Qb, const bf16_t* __restrict__ Kh, const bf16_t* __restrict__ Vh, int NT, int krel0,
;                                           char* lds, const float* __restrict__ lutg, const AttnEpi& E) {
;     ...
;   } else if constexpr (MODE == 2) {
; #pragma unroll
;     for (int r = 0; r < 16; ++r)
; #pragma unroll
;       for (int d0 = 0; d0 < 4; ++d0) pk1[(d0 * 16 + r) * 512 + tid] = o[d0][r] * rli[r];
	v_rcp_f32_e32 v81, v66
	v_rcp_f32_e32 v82, v67
	v_mul_f32_e32 v50, v50, v0
	v_lshl_add_u64 v[66:67], v[188:189], 2, s[36:37]
	global_store_dword v[66:67], v50, off
	v_add_u32_e32 v66, 0x2000, v188
	v_ashrrev_i32_e32 v67, 31, v66
	v_mul_f32_e32 v34, v34, v0
	v_lshl_add_u64 v[66:67], v[66:67], 2, s[36:37]
	global_store_dword v[66:67], v34, off
	v_add_u32_e32 v66, 0x4000, v188
	v_ashrrev_i32_e32 v67, 31, v66
	v_mul_f32_e32 v18, v18, v0
	v_lshl_add_u64 v[66:67], v[66:67], 2, s[36:37]
	global_store_dword v[66:67], v18, off
	v_add_u32_e32 v66, 0x6000, v188
	v_ashrrev_i32_e32 v67, 31, v66
	v_mul_f32_e32 v0, v2, v0
	v_lshl_add_u64 v[66:67], v[66:67], 2, s[36:37]
	v_add_u32_e32 v50, 0x200, v188
	global_store_dword v[66:67], v0, off
	v_mul_f32_e32 v0, v51, v74
	v_ashrrev_i32_e32 v51, 31, v50
	v_lshl_add_u64 v[50:51], v[50:51], 2, s[36:37]
	v_add_u32_e32 v34, 0x2200, v188
	global_store_dword v[50:51], v0, off
	v_mul_f32_e32 v0, v35, v74
	v_ashrrev_i32_e32 v35, 31, v34
	v_lshl_add_u64 v[34:35], v[34:35], 2, s[36:37]
	v_add_u32_e32 v18, 0x4200, v188
	global_store_dword v[34:35], v0, off
	v_mul_f32_e32 v0, v19, v74
	v_ashrrev_i32_e32 v19, 31, v18
	v_lshl_add_u64 v[18:19], v[18:19], 2, s[36:37]
	v_add_u32_e32 v2, 0x6200, v188
	global_store_dword v[18:19], v0, off
	v_mul_f32_e32 v0, v3, v74
	v_ashrrev_i32_e32 v3, 31, v2
	v_lshl_add_u64 v[2:3], v[2:3], 2, s[36:37]
	global_store_dword v[2:3], v0, off
	v_add_u32_e32 v2, 0x400, v188
	v_ashrrev_i32_e32 v3, 31, v2
	v_mul_f32_e32 v0, v52, v75
	v_lshl_add_u64 v[2:3], v[2:3], 2, s[36:37]
	global_store_dword v[2:3], v0, off
	v_add_u32_e32 v2, 0x2400, v188
	v_ashrrev_i32_e32 v3, 31, v2
	v_mul_f32_e32 v0, v36, v75
	v_lshl_add_u64 v[2:3], v[2:3], 2, s[36:37]
	global_store_dword v[2:3], v0, off
	v_add_u32_e32 v2, 0x4400, v188
	v_ashrrev_i32_e32 v3, 31, v2
	v_mul_f32_e32 v0, v20, v75
	v_lshl_add_u64 v[2:3], v[2:3], 2, s[36:37]
	global_store_dword v[2:3], v0, off
	v_add_u32_e32 v2, 0x6400, v188
	v_ashrrev_i32_e32 v3, 31, v2
	v_mul_f32_e32 v0, v4, v75
	v_lshl_add_u64 v[2:3], v[2:3], 2, s[36:37]
	global_store_dword v[2:3], v0, off
	v_add_u32_e32 v2, 0x600, v188
	v_ashrrev_i32_e32 v3, 31, v2
	v_mul_f32_e32 v0, v53, v76
	v_lshl_add_u64 v[2:3], v[2:3], 2, s[36:37]
	global_store_dword v[2:3], v0, off
	v_add_u32_e32 v2, 0x2600, v188
	v_ashrrev_i32_e32 v3, 31, v2
	v_mul_f32_e32 v0, v37, v76
	v_lshl_add_u64 v[2:3], v[2:3], 2, s[36:37]
	global_store_dword v[2:3], v0, off
	v_add_u32_e32 v2, 0x4600, v188
	v_ashrrev_i32_e32 v3, 31, v2
	v_mul_f32_e32 v0, v21, v76
	v_lshl_add_u64 v[2:3], v[2:3], 2, s[36:37]
	global_store_dword v[2:3], v0, off
	v_add_u32_e32 v2, 0x6600, v188
	v_ashrrev_i32_e32 v3, 31, v2
	v_mul_f32_e32 v0, v5, v76
	v_lshl_add_u64 v[2:3], v[2:3], 2, s[36:37]
	global_store_dword v[2:3], v0, off
	v_add_u32_e32 v2, 0x800, v188
	v_ashrrev_i32_e32 v3, 31, v2
	v_mul_f32_e32 v0, v54, v77
	v_lshl_add_u64 v[2:3], v[2:3], 2, s[36:37]
	global_store_dword v[2:3], v0, off
	v_add_u32_e32 v2, 0x2800, v188
	v_ashrrev_i32_e32 v3, 31, v2
	v_mul_f32_e32 v0, v38, v77
	v_lshl_add_u64 v[2:3], v[2:3], 2, s[36:37]
	global_store_dword v[2:3], v0, off
	v_add_u32_e32 v2, 0x4800, v188
	v_ashrrev_i32_e32 v3, 31, v2
	v_mul_f32_e32 v0, v22, v77
	v_lshl_add_u64 v[2:3], v[2:3], 2, s[36:37]
	global_store_dword v[2:3], v0, off
	v_add_u32_e32 v2, 0x6800, v188
	v_ashrrev_i32_e32 v3, 31, v2
	v_mul_f32_e32 v0, v6, v77
	v_lshl_add_u64 v[2:3], v[2:3], 2, s[36:37]
	global_store_dword v[2:3], v0, off
	v_add_u32_e32 v2, 0xa00, v188
	v_ashrrev_i32_e32 v3, 31, v2
	v_mul_f32_e32 v0, v55, v78
	v_lshl_add_u64 v[2:3], v[2:3], 2, s[36:37]
	global_store_dword v[2:3], v0, off
	v_add_u32_e32 v2, 0x2a00, v188
	v_ashrrev_i32_e32 v3, 31, v2
	v_mul_f32_e32 v0, v39, v78
	v_lshl_add_u64 v[2:3], v[2:3], 2, s[36:37]
	global_store_dword v[2:3], v0, off
	v_add_u32_e32 v2, 0x4a00, v188
	v_ashrrev_i32_e32 v3, 31, v2
	v_mul_f32_e32 v0, v23, v78
	v_lshl_add_u64 v[2:3], v[2:3], 2, s[36:37]
	global_store_dword v[2:3], v0, off
	v_add_u32_e32 v2, 0x6a00, v188
	v_ashrrev_i32_e32 v3, 31, v2
	v_mul_f32_e32 v0, v7, v78
	v_lshl_add_u64 v[2:3], v[2:3], 2, s[36:37]
	global_store_dword v[2:3], v0, off
	v_add_u32_e32 v2, 0xc00, v188
	v_ashrrev_i32_e32 v3, 31, v2
	v_mul_f32_e32 v0, v56, v79
	v_lshl_add_u64 v[2:3], v[2:3], 2, s[36:37]
	global_store_dword v[2:3], v0, off
	v_add_u32_e32 v2, 0x2c00, v188
	v_ashrrev_i32_e32 v3, 31, v2
	v_mul_f32_e32 v0, v40, v79
	v_lshl_add_u64 v[2:3], v[2:3], 2, s[36:37]
	global_store_dword v[2:3], v0, off
	v_add_u32_e32 v2, 0x4c00, v188
	v_ashrrev_i32_e32 v3, 31, v2
	v_mul_f32_e32 v0, v24, v79
	v_lshl_add_u64 v[2:3], v[2:3], 2, s[36:37]
	global_store_dword v[2:3], v0, off
	v_add_u32_e32 v2, 0x6c00, v188
	v_ashrrev_i32_e32 v3, 31, v2
	v_mul_f32_e32 v0, v8, v79
	v_lshl_add_u64 v[2:3], v[2:3], 2, s[36:37]
	global_store_dword v[2:3], v0, off
	v_add_u32_e32 v2, 0xe00, v188
	v_ashrrev_i32_e32 v3, 31, v2
	v_mul_f32_e32 v0, v57, v80
	v_lshl_add_u64 v[2:3], v[2:3], 2, s[36:37]
	global_store_dword v[2:3], v0, off
	v_add_u32_e32 v2, 0x2e00, v188
	v_ashrrev_i32_e32 v3, 31, v2
	v_mul_f32_e32 v0, v41, v80
	v_lshl_add_u64 v[2:3], v[2:3], 2, s[36:37]
	global_store_dword v[2:3], v0, off
	v_add_u32_e32 v2, 0x4e00, v188
	v_ashrrev_i32_e32 v3, 31, v2
	v_mul_f32_e32 v0, v25, v80
	v_lshl_add_u64 v[2:3], v[2:3], 2, s[36:37]
	global_store_dword v[2:3], v0, off
	v_add_u32_e32 v2, 0x6e00, v188
	v_ashrrev_i32_e32 v3, 31, v2
	v_mul_f32_e32 v0, v9, v80
	v_lshl_add_u64 v[2:3], v[2:3], 2, s[36:37]
	global_store_dword v[2:3], v0, off
	v_add_u32_e32 v2, 0x1000, v188
	v_ashrrev_i32_e32 v3, 31, v2
	v_mul_f32_e32 v0, v58, v81
	v_lshl_add_u64 v[2:3], v[2:3], 2, s[36:37]
	global_store_dword v[2:3], v0, off
; template <int MODE>
; __device__ __forceinline__ void attn_body(const bf16_t* __restrict__ Qb, const bf16_t* __restrict__ Kh, const bf16_t* __restrict__ Vh, int NT, int krel0,
;                                           char* lds, const float* __restrict__ lutg, const AttnEpi& E) {
;     ...
;   __syncthreads();
;   if constexpr (MODE != 0) { if (tid < 259) lut[tid] = lutg[tid]; }
;     ...
;     for (int r = 0; r < 16; ++r)
; #pragma unroll
;       for (int d0 = 0; d0 < 4; ++d0) pk1[(d0 * 16 + r) * 512 + tid] = o[d0][r] * rli[r];
	v_add_u32_e32 v2, 0x3000, v188
	v_ashrrev_i32_e32 v3, 31, v2
	v_mul_f32_e32 v0, v42, v81
	v_lshl_add_u64 v[2:3], v[2:3], 2, s[36:37]
	global_store_dword v[2:3], v0, off
	v_add_u32_e32 v2, 0x5000, v188
	v_ashrrev_i32_e32 v3, 31, v2
	v_mul_f32_e32 v0, v26, v81
	v_lshl_add_u64 v[2:3], v[2:3], 2, s[36:37]
	global_store_dword v[2:3], v0, off
	v_add_u32_e32 v2, 0x7000, v188
	v_ashrrev_i32_e32 v3, 31, v2
	v_mul_f32_e32 v0, v10, v81
	v_lshl_add_u64 v[2:3], v[2:3], 2, s[36:37]
	global_store_dword v[2:3], v0, off
	v_add_u32_e32 v2, 0x1200, v188
	v_ashrrev_i32_e32 v3, 31, v2
	v_mul_f32_e32 v0, v59, v82
	v_lshl_add_u64 v[2:3], v[2:3], 2, s[36:37]
	global_store_dword v[2:3], v0, off
	v_add_u32_e32 v2, 0x3200, v188
	v_ashrrev_i32_e32 v3, 31, v2
	v_mul_f32_e32 v0, v43, v82
	v_lshl_add_u64 v[2:3], v[2:3], 2, s[36:37]
	global_store_dword v[2:3], v0, off
	v_add_u32_e32 v2, 0x5200, v188
	v_ashrrev_i32_e32 v3, 31, v2
	v_mul_f32_e32 v0, v27, v82
	v_lshl_add_u64 v[2:3], v[2:3], 2, s[36:37]
	global_store_dword v[2:3], v0, off
	v_add_u32_e32 v2, 0x7200, v188
	v_rcp_f32_e32 v68, v68
	v_ashrrev_i32_e32 v3, 31, v2
	v_mul_f32_e32 v0, v11, v82
	v_lshl_add_u64 v[2:3], v[2:3], 2, s[36:37]
	global_store_dword v[2:3], v0, off
	v_add_u32_e32 v2, 0x1400, v188
	v_ashrrev_i32_e32 v3, 31, v2
	v_mul_f32_e32 v0, v60, v68
	v_lshl_add_u64 v[2:3], v[2:3], 2, s[36:37]
	global_store_dword v[2:3], v0, off
	v_add_u32_e32 v2, 0x3400, v188
	v_ashrrev_i32_e32 v3, 31, v2
	v_mul_f32_e32 v0, v44, v68
	v_lshl_add_u64 v[2:3], v[2:3], 2, s[36:37]
	global_store_dword v[2:3], v0, off
	v_add_u32_e32 v2, 0x5400, v188
	v_ashrrev_i32_e32 v3, 31, v2
	v_mul_f32_e32 v0, v28, v68
	v_lshl_add_u64 v[2:3], v[2:3], 2, s[36:37]
	global_store_dword v[2:3], v0, off
	v_add_u32_e32 v2, 0x7400, v188
	v_rcp_f32_e32 v69, v69
	v_ashrrev_i32_e32 v3, 31, v2
	v_mul_f32_e32 v0, v12, v68
	v_lshl_add_u64 v[2:3], v[2:3], 2, s[36:37]
	global_store_dword v[2:3], v0, off
	v_add_u32_e32 v2, 0x1600, v188
	v_ashrrev_i32_e32 v3, 31, v2
	v_mul_f32_e32 v0, v61, v69
	v_lshl_add_u64 v[2:3], v[2:3], 2, s[36:37]
	global_store_dword v[2:3], v0, off
	v_add_u32_e32 v2, 0x3600, v188
	v_ashrrev_i32_e32 v3, 31, v2
	v_mul_f32_e32 v0, v45, v69
	v_lshl_add_u64 v[2:3], v[2:3], 2, s[36:37]
	global_store_dword v[2:3], v0, off
	v_add_u32_e32 v2, 0x5600, v188
	v_ashrrev_i32_e32 v3, 31, v2
	v_mul_f32_e32 v0, v29, v69
	v_lshl_add_u64 v[2:3], v[2:3], 2, s[36:37]
	global_store_dword v[2:3], v0, off
	v_add_u32_e32 v2, 0x7600, v188
	s_waitcnt lgkmcnt(0)
	v_rcp_f32_e32 v70, v70
	v_ashrrev_i32_e32 v3, 31, v2
	v_mul_f32_e32 v0, v13, v69
	v_lshl_add_u64 v[2:3], v[2:3], 2, s[36:37]
	global_store_dword v[2:3], v0, off
	v_add_u32_e32 v2, 0x1800, v188
	v_ashrrev_i32_e32 v3, 31, v2
	v_mul_f32_e32 v0, v62, v70
	v_lshl_add_u64 v[2:3], v[2:3], 2, s[36:37]
	global_store_dword v[2:3], v0, off
	v_add_u32_e32 v2, 0x3800, v188
	v_ashrrev_i32_e32 v3, 31, v2
	v_mul_f32_e32 v0, v46, v70
	v_lshl_add_u64 v[2:3], v[2:3], 2, s[36:37]
	global_store_dword v[2:3], v0, off
	v_add_u32_e32 v2, 0x5800, v188
	v_ashrrev_i32_e32 v3, 31, v2
	v_mul_f32_e32 v0, v30, v70
	v_lshl_add_u64 v[2:3], v[2:3], 2, s[36:37]
	global_store_dword v[2:3], v0, off
	v_add_u32_e32 v2, 0x7800, v188
	v_rcp_f32_e32 v71, v71
	v_ashrrev_i32_e32 v3, 31, v2
	v_mul_f32_e32 v0, v14, v70
	v_lshl_add_u64 v[2:3], v[2:3], 2, s[36:37]
	global_store_dword v[2:3], v0, off
	v_add_u32_e32 v2, 0x1a00, v188
	v_ashrrev_i32_e32 v3, 31, v2
	v_mul_f32_e32 v0, v63, v71
	v_lshl_add_u64 v[2:3], v[2:3], 2, s[36:37]
	global_store_dword v[2:3], v0, off
	v_add_u32_e32 v2, 0x3a00, v188
	v_ashrrev_i32_e32 v3, 31, v2
	v_mul_f32_e32 v0, v47, v71
	v_lshl_add_u64 v[2:3], v[2:3], 2, s[36:37]
	global_store_dword v[2:3], v0, off
	v_add_u32_e32 v2, 0x5a00, v188
	v_ashrrev_i32_e32 v3, 31, v2
	v_mul_f32_e32 v0, v31, v71
	v_lshl_add_u64 v[2:3], v[2:3], 2, s[36:37]
	global_store_dword v[2:3], v0, off
	v_add_u32_e32 v2, 0x7a00, v188
	v_rcp_f32_e32 v72, v72
	v_ashrrev_i32_e32 v3, 31, v2
	v_mul_f32_e32 v0, v15, v71
	v_lshl_add_u64 v[2:3], v[2:3], 2, s[36:37]
	global_store_dword v[2:3], v0, off
	v_add_u32_e32 v2, 0x1c00, v188
	v_ashrrev_i32_e32 v3, 31, v2
	v_mul_f32_e32 v0, v64, v72
	v_lshl_add_u64 v[2:3], v[2:3], 2, s[36:37]
	global_store_dword v[2:3], v0, off
	v_add_u32_e32 v2, 0x3c00, v188
	v_ashrrev_i32_e32 v3, 31, v2
	v_mul_f32_e32 v0, v48, v72
	v_lshl_add_u64 v[2:3], v[2:3], 2, s[36:37]
	global_store_dword v[2:3], v0, off
	v_add_u32_e32 v2, 0x5c00, v188
	v_ashrrev_i32_e32 v3, 31, v2
	v_mul_f32_e32 v0, v32, v72
	v_lshl_add_u64 v[2:3], v[2:3], 2, s[36:37]
	global_store_dword v[2:3], v0, off
	v_add_u32_e32 v2, 0x7c00, v188
	v_rcp_f32_e32 v73, v73
	v_ashrrev_i32_e32 v3, 31, v2
	v_mul_f32_e32 v0, v16, v72
	v_lshl_add_u64 v[2:3], v[2:3], 2, s[36:37]
	global_store_dword v[2:3], v0, off
	v_add_u32_e32 v2, 0x1e00, v188
	v_ashrrev_i32_e32 v3, 31, v2
	v_mul_f32_e32 v0, v65, v73
	v_lshl_add_u64 v[2:3], v[2:3], 2, s[36:37]
	global_store_dword v[2:3], v0, off
	v_add_u32_e32 v2, 0x3e00, v188
	v_ashrrev_i32_e32 v3, 31, v2
	v_mul_f32_e32 v0, v49, v73
	v_lshl_add_u64 v[2:3], v[2:3], 2, s[36:37]
	global_store_dword v[2:3], v0, off
	v_add_u32_e32 v2, 0x5e00, v188
	v_ashrrev_i32_e32 v3, 31, v2
	v_mul_f32_e32 v0, v33, v73
	v_lshl_add_u64 v[2:3], v[2:3], 2, s[36:37]
	global_store_dword v[2:3], v0, off
	v_add_u32_e32 v2, 0x7e00, v188
	v_ashrrev_i32_e32 v3, 31, v2
	v_mul_f32_e32 v0, v17, v73
	v_lshl_add_u64 v[2:3], v[2:3], 2, s[36:37]
	v_mov_b32_e32 v188, v179
	global_store_dword v[2:3], v0, off
	s_waitcnt vmcnt(63) expcnt(7) lgkmcnt(15)
	v_cmp_gt_i32_e32 vcc, s6, v188
	v_ashrrev_i32_e32 v189, 31, v188
	s_barrier
	v_lshl_add_u64 v[2:3], v[188:189], 2, s[60:61]
	global_load_dword v100, v[2:3], off
	v_lshl_add_u32 v101, v188, 2, 0
	v_add_u32_e32 v101, 0x18800, v101
; template <int MODE>
; __device__ __forceinline__ void attn_body(const bf16_t* __restrict__ Qb, const bf16_t* __restrict__ Kh, const bf16_t* __restrict__ Vh, int NT, int krel0,
;                                           char* lds, const float* __restrict__ lutg, const AttnEpi& E) {
;     ...
;   if constexpr (MODE != 0) { if (tid < 259) lut[tid] = lutg[tid]; }
;   float m_reg = -1e30f, l_reg = 0; f32x16 o[4] = {}; bf16x8 qr[ND0];
;   const bf16_t* Qw = Qb + (size_t)(wid * 32 + r32) * LDQK + hi * 8;
;   {
;     float qf[ND0][8]; float ss = 0.f;
; #pragma unroll
;     for (int d0 = 0; d0 < ND0; ++d0) { const bf16x8 raw = *reinterpret_cast<const bf16x8*>(Qw + d0 * 16);
; #pragma unroll
;       for (int j = 0; j < 8; ++j) { const float v = __uint_as_float(((unsigned)(unsigned short)raw[j]) << 16); qf[d0][j] = v; ss += v * v; } }
;     { auto rr = __builtin_amdgcn_permlane32_swap(__float_as_uint(ss), __float_as_uint(ss), false, false);
;       ss = __uint_as_float(rr[0]) + __uint_as_float(rr[1]); }
;     const float rs = rsqrtf(ss * (MODE < 2 ? (1.f / 128.f) : (1.f / 64.f)) + EPS);
.LBB0_170:
	v_ashrrev_i32_e32 v2, 1, v188
	s_movk_i32 s6, 0xffe0
	v_bfe_u32 v3, v188, 5, 1
	v_bfi_b32 v4, s6, v2, v188
	v_mov_b64_e32 v[6:7], s[62:63]
	v_mad_i64_i32 v[6:7], s[6:7], v4, s83, v[6:7]
	v_lshlrev_b32_e32 v0, 4, v3
	v_lshl_add_u64 v[18:19], v[6:7], 0, v[0:1]
	global_load_dwordx4 v[6:9], v[18:19], off offset:128
	global_load_dwordx4 v[10:13], v[18:19], off offset:160
	global_load_dwordx4 v[14:17], v[18:19], off offset:192
	s_nop 0
	global_load_dwordx4 v[18:21], v[18:19], off offset:224
	v_and_b32_e32 v5, 32, v188
	global_load_dwordx4 v[22:25], v5, s[52:53] offset:16
	global_load_dwordx4 v[26:29], v5, s[52:53]
	global_load_dwordx4 v[30:33], v5, s[52:53] offset:80
	global_load_dwordx4 v[34:37], v5, s[52:53] offset:64
	global_load_dwordx4 v[38:41], v5, s[52:53] offset:144
	global_load_dwordx4 v[42:45], v5, s[52:53] offset:128
	global_load_dwordx4 v[46:49], v5, s[52:53] offset:208
	global_load_dwordx4 v[50:53], v5, s[52:53] offset:192
	s_movk_i32 s60, 0x1200
	v_and_b32_e32 v204, 0xffffffe0, v2
	v_lshlrev_b32_e32 v205, 2, v3
	v_sub_u32_e32 v4, s77, v4
	v_add_u32_e32 v206, v4, v205
	v_and_b32_e32 v184, 31, v188
	v_sub_u32_e32 v208, s78, v204
	s_waitcnt vmcnt(12)
	ds_write_b32 v101, v100
	s_waitcnt vmcnt(11)
	v_and_b32_e32 v69, 0xffff0000, v7
	v_lshlrev_b32_e32 v68, 16, v7
	v_and_b32_e32 v7, 0xffff0000, v6
	v_lshlrev_b32_e32 v6, 16, v6
	v_mul_f32_e32 v70, v7, v7
	v_pk_fma_f32 v[70:71], v[6:7], v[6:7], v[70:71] op_sel_hi:[1,1,0]
	v_mul_f32_e32 v72, v69, v69
	v_pk_fma_f32 v[70:71], v[68:69], v[68:69], v[70:71]
	v_and_b32_e32 v67, 0xffff0000, v9
	v_lshlrev_b32_e32 v66, 16, v9
	v_and_b32_e32 v9, 0xffff0000, v8
	v_lshlrev_b32_e32 v8, 16, v8
	v_pk_add_f32 v[70:71], v[72:73], v[70:71] op_sel_hi:[0,1]
	v_pk_fma_f32 v[70:71], v[8:9], v[8:9], v[70:71]
	v_mul_f32_e32 v72, v9, v9
	v_pk_add_f32 v[70:71], v[72:73], v[70:71] op_sel_hi:[0,1]
	v_pk_fma_f32 v[70:71], v[66:67], v[66:67], v[70:71]
	v_mul_f32_e32 v72, v67, v67
	s_waitcnt vmcnt(10)
	v_and_b32_e32 v65, 0xffff0000, v11
	v_lshlrev_b32_e32 v64, 16, v11
	v_and_b32_e32 v11, 0xffff0000, v10
	v_lshlrev_b32_e32 v10, 16, v10
	v_pk_add_f32 v[70:71], v[72:73], v[70:71] op_sel_hi:[0,1]
	v_pk_fma_f32 v[70:71], v[10:11], v[10:11], v[70:71]
	v_mul_f32_e32 v72, v11, v11
	v_pk_add_f32 v[70:71], v[72:73], v[70:71] op_sel_hi:[0,1]
	v_pk_fma_f32 v[70:71], v[64:65], v[64:65], v[70:71]
	v_mul_f32_e32 v72, v65, v65
	v_and_b32_e32 v63, 0xffff0000, v13
	v_lshlrev_b32_e32 v62, 16, v13
	v_and_b32_e32 v13, 0xffff0000, v12
	v_lshlrev_b32_e32 v12, 16, v12
	v_pk_add_f32 v[70:71], v[72:73], v[70:71] op_sel_hi:[0,1]
	v_pk_fma_f32 v[70:71], v[12:13], v[12:13], v[70:71]
	v_mul_f32_e32 v72, v13, v13
	v_pk_add_f32 v[70:71], v[72:73], v[70:71] op_sel_hi:[0,1]
	v_pk_fma_f32 v[70:71], v[62:63], v[62:63], v[70:71]
	v_mul_f32_e32 v72, v63, v63
	s_waitcnt vmcnt(9)
	v_and_b32_e32 v61, 0xffff0000, v15
	v_lshlrev_b32_e32 v60, 16, v15
	v_and_b32_e32 v15, 0xffff0000, v14
	v_lshlrev_b32_e32 v14, 16, v14
	v_pk_add_f32 v[70:71], v[72:73], v[70:71] op_sel_hi:[0,1]
	v_pk_fma_f32 v[70:71], v[14:15], v[14:15], v[70:71]
	v_mul_f32_e32 v72, v15, v15
	v_pk_add_f32 v[70:71], v[72:73], v[70:71] op_sel_hi:[0,1]
	v_pk_fma_f32 v[70:71], v[60:61], v[60:61], v[70:71]
	v_mul_f32_e32 v72, v61, v61
	v_and_b32_e32 v59, 0xffff0000, v17
	v_lshlrev_b32_e32 v58, 16, v17
	v_and_b32_e32 v17, 0xffff0000, v16
	v_lshlrev_b32_e32 v16, 16, v16
	v_pk_add_f32 v[70:71], v[72:73], v[70:71] op_sel_hi:[0,1]
	v_pk_fma_f32 v[70:71], v[16:17], v[16:17], v[70:71]
	v_mul_f32_e32 v72, v17, v17
	v_pk_add_f32 v[70:71], v[72:73], v[70:71] op_sel_hi:[0,1]
	v_pk_fma_f32 v[70:71], v[58:59], v[58:59], v[70:71]
	v_mul_f32_e32 v72, v59, v59
	s_waitcnt vmcnt(8)
	v_and_b32_e32 v57, 0xffff0000, v19
	v_lshlrev_b32_e32 v56, 16, v19
	v_and_b32_e32 v19, 0xffff0000, v18
	v_lshlrev_b32_e32 v18, 16, v18
	v_pk_add_f32 v[70:71], v[72:73], v[70:71] op_sel_hi:[0,1]
	v_pk_fma_f32 v[70:71], v[18:19], v[18:19], v[70:71]
	v_mul_f32_e32 v72, v19, v19
	v_pk_add_f32 v[70:71], v[72:73], v[70:71] op_sel_hi:[0,1]
	v_pk_fma_f32 v[70:71], v[56:57], v[56:57], v[70:71]
	v_mul_f32_e32 v72, v57, v57
	v_and_b32_e32 v55, 0xffff0000, v21
	v_lshlrev_b32_e32 v54, 16, v21
	v_and_b32_e32 v21, 0xffff0000, v20
	v_lshlrev_b32_e32 v20, 16, v20
	v_pk_add_f32 v[70:71], v[72:73], v[70:71] op_sel_hi:[0,1]
	v_pk_fma_f32 v[70:71], v[20:21], v[20:21], v[70:71]
	v_mul_f32_e32 v72, v21, v21
	v_pk_add_f32 v[70:71], v[72:73], v[70:71] op_sel_hi:[0,1]
	v_pk_fma_f32 v[70:71], v[54:55], v[54:55], v[70:71]
	v_mul_f32_e32 v72, v55, v55
	v_pk_add_f32 v[70:71], v[72:73], v[70:71] op_sel_hi:[0,1]
	v_mov_b32_e32 v5, v70
	s_nop 1
	v_permlane32_swap_b32_e32 v70, v5
	v_add_f32_e32 v5, v70, v5
	v_fmamk_f32 v5, v5, 0x3c800000, v178
	v_cmp_gt_f32_e32 vcc, s49, v5
	v_mul_f32_e32 v70, 0x4b800000, v5
	s_nop 0
	v_cndmask_b32_e32 v5, v5, v70, vcc
	v_rsq_f32_e32 v5, v5
	s_nop 0
	v_mul_f32_e32 v70, 0x45800000, v5
	v_cndmask_b32_e32 v70, v5, v70, vcc
	v_pk_mul_f32 v[6:7], v[70:71], v[6:7] op_sel_hi:[0,1]
	v_pk_mul_f32 v[18:19], v[70:71], v[18:19] op_sel_hi:[0,1]
	s_waitcnt vmcnt(6)
	v_pk_mul_f32 v[6:7], v[26:27], v[6:7]
	s_waitcnt vmcnt(0)
; __device__ __forceinline__ unsigned cvtpk(float lo, float hi) { f32x2 v = {lo, hi}; bf16v2 b = __builtin_convertvector(v, bf16v2); return __builtin_bit_cast(unsigned, b); }
; template <int MODE>
; __device__ __forceinline__ void attn_body(const bf16_t* __restrict__ Qb, const bf16_t* __restrict__ Kh, const bf16_t* __restrict__ Vh, int NT, int krel0,
;                                           char* lds, const float* __restrict__ lutg, const AttnEpi& E) {
;     ...
;     for (int d0 = 0; d0 < ND0; ++d0) { const f32x4 g0 = *(const f32x4*)(E.gq + d0 * 16 + hi * 8), g1 = *(const f32x4*)(E.gq + d0 * 16 + hi * 8 + 4);
; #pragma unroll
;       for (int j = 0; j < 4; ++j) { qf[d0][j] = qf[d0][j] * rs * g0[j]; qf[d0][4 + j] = qf[d0][4 + j] * rs * g1[j]; } }
;     if constexpr (MODE == 0) {
;       const int sp = krel0 + wid * 32 + r32;
; #pragma unroll
;       for (int h = 0; h < 2; ++h) { const int pos = h == 0 ? (sp >> 6) : (sp & 63);
; #pragma unroll
;         for (int a = 0; a < 2; ++a) { const float* tb = lutg + (size_t)(pos * 32 + a * 16 + hi * 8) * 2;
; #pragma unroll
;           for (int jj = 0; jj < 4; ++jj) { const f32x4 cs = *(const f32x4*)(tb + jj * 4);
; #pragma unroll
;             for (int e = 0; e < 2; ++e) { const int j = 2 * jj + e; const float c = cs[2 * e], sn = cs[2 * e + 1];
;               const float x1 = qf[4 * h + a][j], x2 = qf[4 * h + 2 + a][j];
;               qf[4 * h + a][j] = x1 * c - x2 * sn; qf[4 * h + 2 + a][j] = x2 * c + x1 * sn; } } } }
;     }
; #pragma unroll
;     for (int d0 = 0; d0 < ND0; ++d0) { u32x4 w; w.x = cvtpk(qf[d0][0], qf[d0][1]); w.y = cvtpk(qf[d0][2], qf[d0][3]); w.z = cvtpk(qf[d0][4], qf[d0][5]); w.w = cvtpk(qf[d0][6], qf[d0][7]);
;       qr[d0] = *reinterpret_cast<bf16x8*>(&w); }
;   }
;   const int sr = tid >> 4, sc = (tid & 15) * 8, vst0 = v_st(sr, sc), vst1 = v_st(32 + sr, sc);
;   const int vb0 = (int)(uintptr_t)V_lds + v_rd_base(lane);
;   struct { bf16x8 vs0, vs1, ks0, ks1; } sr_[2];
;     ...
;   const int relq = krel0 - (wid * 32 + r32) + 4 * hi, relwmin = krel0 - (wid * 32 + 31), relwmax = krel0 + 63 - wid * 32;
;     ...
;   f32x16 pA0, pA1, pB0, pB1; float mnA, mnB, alA, alB; bf16x8 pa0, pa1, pa2, pa3;
;   constexpr int SE = 0, SO = 1;
;   SLOAD(SE, 0); SLOAD(SO, 64); asm volatile("s_waitcnt vmcnt(4)" ::: "memory"); SWRITE(0, SE); __syncthreads();
;   qkt<ND0, DOFF>(pA0, pA1, K_lds, qr, r32, hi); PSM(pA0, pA1, mnA, alA, 0);
	v_pk_mul_f32 v[18:19], v[50:51], v[18:19]
	v_ashrrev_i32_e32 v50, 4, v188
	v_pk_mul_f32 v[8:9], v[70:71], v[8:9] op_sel_hi:[0,1]
	v_cvt_pk_bf16_f32 v142, v6, v7
	v_and_b32_e32 v6, 0xfffff0, v50
	v_lshlrev_b32_e32 v7, 1, v50
	v_pk_mul_f32 v[8:9], v[22:23], v[8:9]
	v_lshlrev_b32_e32 v5, 3, v188
	v_and_or_b32 v6, v7, 8, v6
	v_cvt_pk_bf16_f32 v144, v8, v9
	v_and_b32_e32 v51, 0x78, v5
	v_lshrrev_b32_e32 v7, 1, v50
	v_lshrrev_b32_e32 v6, 1, v6
	v_bfe_u32 v5, v5, 5, 2
	v_and_b32_e32 v8, 3, v50
	v_cvt_pk_bf16_f32 v130, v18, v19
	v_or_b32_e32 v6, v6, v5
	v_and_or_b32 v7, v7, 4, v8
	v_lshlrev_b32_e32 v18, 1, v51
	v_lshlrev_b32_e32 v6, 9, v6
	v_lshlrev_b32_e32 v7, 6, v7
	v_and_b32_e32 v8, 48, v18
	v_add_u32_e32 v19, 32, v50
	v_pk_mul_f32 v[10:11], v[70:71], v[10:11] op_sel_hi:[0,1]
	v_or3_b32 v209, v6, v7, v8
	v_and_b32_e32 v6, 0xfffff0, v19
	v_lshlrev_b32_e32 v9, 1, v19
	v_pk_mul_f32 v[10:11], v[34:35], v[10:11]
	v_pk_mul_f32 v[34:35], v[70:71], v[56:57] op_sel_hi:[0,1]
	v_and_or_b32 v6, v9, 8, v6
	v_pk_mul_f32 v[34:35], v[52:53], v[34:35]
	v_lshrrev_b32_e32 v6, 1, v6
	v_or_b32_e32 v52, 31, v2
	v_mad_i64_i32 v[2:3], s[6:7], v50, s60, 0
	v_or_b32_e32 v5, v6, v5
	v_or_b32_e32 v2, v2, v51
	v_cvt_pk_bf16_f32 v138, v10, v11
	v_lshlrev_b32_e32 v5, 9, v5
	v_lshlrev_b64 v[10:11], 1, v[2:3]
	v_pk_mul_f32 v[14:15], v[70:71], v[14:15] op_sel_hi:[0,1]
	v_or3_b32 v211, v5, v7, v8
	v_lshl_add_u64 v[2:3], s[0:1], 0, v[10:11]
	v_mad_i64_i32 v[6:7], s[6:7], v19, s60, 0
	v_pk_mul_f32 v[14:15], v[42:43], v[14:15]
	global_load_dwordx4 v[2:5], v[2:3], off
	v_or_b32_e32 v6, v6, v51
	v_pk_mul_f32 v[12:13], v[70:71], v[12:13] op_sel_hi:[0,1]
	v_cvt_pk_bf16_f32 v134, v14, v15
	v_lshlrev_b64 v[14:15], 1, v[6:7]
	v_pk_mul_f32 v[12:13], v[30:31], v[12:13]
	v_lshl_add_u64 v[6:7], s[0:1], 0, v[14:15]
	v_lshl_add_u64 v[10:11], s[58:59], 0, v[10:11]
	v_cvt_pk_bf16_f32 v140, v12, v13
	global_load_dwordx4 v[6:9], v[6:7], off
	v_pk_mul_f32 v[16:17], v[70:71], v[16:17] op_sel_hi:[0,1]
	global_load_dwordx4 v[10:13], v[10:11], off
	v_pk_mul_f32 v[16:17], v[38:39], v[16:17]
	v_lshl_add_u64 v[14:15], s[58:59], 0, v[14:15]
	v_cvt_pk_bf16_f32 v136, v16, v17
	global_load_dwordx4 v[14:17], v[14:15], off
	v_pk_mul_f32 v[20:21], v[70:71], v[20:21] op_sel_hi:[0,1]
	v_pk_mul_f32 v[20:21], v[46:47], v[20:21]
	v_pk_mul_f32 v[26:27], v[70:71], v[66:67] op_sel_hi:[0,1]
	v_cvt_pk_bf16_f32 v132, v20, v21
	v_add_u32_e32 v20, 64, v50
	v_mad_i64_i32 v[20:21], s[6:7], v20, s60, 0
	v_pk_mul_f32 v[22:23], v[70:71], v[68:69] op_sel_hi:[0,1]
	v_pk_mul_f32 v[24:25], v[24:25], v[26:27]
	v_pk_mul_f32 v[26:27], v[70:71], v[64:65] op_sel_hi:[0,1]
	v_or_b32_e32 v20, v20, v51
	v_pk_mul_f32 v[22:23], v[28:29], v[22:23]
	v_pk_mul_f32 v[26:27], v[36:37], v[26:27]
	v_pk_mul_f32 v[36:37], v[70:71], v[54:55] op_sel_hi:[0,1]
	v_lshlrev_b64 v[20:21], 1, v[20:21]
	v_pk_mul_f32 v[30:31], v[70:71], v[60:61] op_sel_hi:[0,1]
	v_pk_mul_f32 v[36:37], v[48:49], v[36:37]
	v_cvt_pk_bf16_f32 v143, v22, v23
	v_lshl_add_u64 v[22:23], s[0:1], 0, v[20:21]
	v_lshl_add_u64 v[20:21], s[58:59], 0, v[20:21]
	v_pk_mul_f32 v[30:31], v[44:45], v[30:31]
	v_cvt_pk_bf16_f32 v131, v34, v35
	v_cvt_pk_bf16_f32 v133, v36, v37
	global_load_dwordx4 v[34:37], v[22:23], off
	global_load_dwordx4 v[42:45], v[20:21], off
	v_add_u32_e32 v22, 0x60, v50
	v_mad_i64_i32 v[22:23], s[6:7], v22, s60, 0
	v_or_b32_e32 v22, v22, v51
	v_pk_mul_f32 v[28:29], v[70:71], v[62:63] op_sel_hi:[0,1]
	v_lshlrev_b64 v[22:23], 1, v[22:23]
	v_pk_mul_f32 v[28:29], v[32:33], v[28:29]
	v_pk_mul_f32 v[32:33], v[70:71], v[58:59] op_sel_hi:[0,1]
	v_cvt_pk_bf16_f32 v145, v24, v25
	v_lshl_add_u64 v[24:25], s[0:1], 0, v[22:23]
	v_lshl_add_u64 v[20:21], s[58:59], 0, v[22:23]
	v_pk_mul_f32 v[32:33], v[40:41], v[32:33]
	global_load_dwordx4 v[38:41], v[24:25], off
	global_load_dwordx4 v[46:49], v[20:21], off
	v_add_u32_e32 v53, 0, v209
	s_waitcnt vmcnt(4)
	v_add_u32_e32 v54, 0, v211
	v_lshlrev_b32_e32 v55, 8, v184
	v_cvt_pk_bf16_f32 v139, v26, v27
	v_cvt_pk_bf16_f32 v141, v28, v29
	v_cvt_pk_bf16_f32 v135, v30, v31
	v_cvt_pk_bf16_f32 v137, v32, v33
	v_or_b32_e32 v56, 0xa0, v0
	v_sub_u32_e32 v207, s77, v52
	v_cmp_gt_i32_e64 s[6:7], s95, v208
	v_cmp_lt_i32_e32 vcc, s15, v208
	s_waitcnt vmcnt(7)
	ds_write_b128 v53, v[2:5]
	v_lshlrev_b32_e32 v2, 8, v50
	v_and_b32_e32 v3, 0xf0, v188
	v_bitop3_b32 v214, v18, v2, v3 bitop3:0xde
	v_add_u32_e32 v2, 0, v214
	s_waitcnt vmcnt(6)
	ds_write_b128 v54, v[6:9]
	s_waitcnt vmcnt(5)
	ds_write_b128 v2, v[10:13] offset:49152
	v_lshlrev_b32_e32 v2, 8, v19
	v_bitop3_b32 v215, v18, v2, v3 bitop3:0xde
	v_add_u32_e32 v2, 0, v215
	v_lshlrev_b32_e32 v3, 4, v188
	s_waitcnt vmcnt(4)
	ds_write_b128 v2, v[14:17] offset:49152
	v_or_b32_e32 v2, 0x80, v0
	v_and_b32_e32 v64, 0xf0, v3
	v_bitop3_b32 v216, v2, v55, v64 bitop3:0xde
	v_add_u32_e32 v6, 0, v216
	s_waitcnt lgkmcnt(0)
	s_barrier
	ds_read_b128 v[2:5], v6 offset:49152
	ds_read_b128 v[6:9], v6 offset:57344
	s_waitcnt lgkmcnt(1)
	v_mfma_f32_32x32x16_bf16 v[18:33], v[2:5], v[142:145], 0
	v_bitop3_b32 v217, v56, v55, v64 bitop3:0xde
	v_add_u32_e32 v60, 0, v217
	ds_read_b128 v[56:59], v60 offset:49152
	ds_read_b128 v[60:63], v60 offset:57344
	s_waitcnt lgkmcnt(2)
	v_mfma_f32_32x32x16_bf16 v[2:17], v[6:9], v[142:145], 0
	s_waitcnt lgkmcnt(1)
	v_mfma_f32_32x32x16_bf16 v[18:33], v[56:59], v[138:141], v[18:33]
	v_or_b32_e32 v56, 0xc0, v0
	v_bitop3_b32 v218, v56, v55, v64 bitop3:0xde
	v_or_b32_e32 v0, 0xe0, v0
	v_bitop3_b32 v219, v0, v55, v64 bitop3:0xde
	v_add_u32_e32 v0, 0, v219
	s_waitcnt lgkmcnt(0)
	v_mfma_f32_32x32x16_bf16 v[2:17], v[60:63], v[138:141], v[2:17]
	v_add_u32_e32 v60, 0, v218
	ds_read_b128 v[56:59], v60 offset:49152
	ds_read_b128 v[60:63], v60 offset:57344
	s_waitcnt lgkmcnt(1)
	v_mfma_f32_32x32x16_bf16 v[18:33], v[56:59], v[134:137], v[18:33]
	s_waitcnt lgkmcnt(0)
	v_mfma_f32_32x32x16_bf16 v[2:17], v[60:63], v[134:137], v[2:17]
	ds_read_b128 v[56:59], v0 offset:49152
	ds_read_b128 v[60:63], v0 offset:57344
	v_mov_b32_e32 v0, s76
	s_waitcnt lgkmcnt(1)
	v_mfma_f32_32x32x16_bf16 v[18:33], v[56:59], v[130:133], v[18:33]
	s_waitcnt lgkmcnt(0)
	v_mfma_f32_32x32x16_bf16 v[2:17], v[60:63], v[130:133], v[2:17]
	s_and_saveexec_b64 s[60:61], vcc
	s_cbranch_execz .LBB0_174
; template <int MODE>
; __device__ __forceinline__ void partialSM(f32x16& p0, f32x16& p1, float& m_reg, float& mn, float& alpha, int relh, int relw_min, int relw_max, const float* lut) {
;     ...
;     if (nearT) {
; #pragma unroll
;       for (int r = 0; r < 16; ++r) { const int i0 = relh + (r & 3) + 8 * (r >> 2);
;         const int a0 = min(max(i0, -129), 129) + 129, a1 = min(max(i0 + 32, -129), 129) + 129;
;         p0[r] = fmaf(p0[r], C, lut[a0]); p1[r] = fmaf(p1[r], C, lut[a1]); }
	v_cmp_gt_i32_e32 vcc, s91, v207
	s_mov_b64 s[64:65], -1
	s_and_saveexec_b64 s[62:63], vcc
	s_cbranch_execz .LBB0_173
	v_add_u32_e32 v56, 1, v206
	v_med3_i32 v57, v56, s39, v198
	v_med3_i32 v56, v56, s33, v199
	v_lshl_add_u32 v58, v56, 2, s76
	v_add_u32_e32 v56, 2, v206
	v_med3_i32 v59, v56, s39, v198
	v_med3_i32 v56, v56, s33, v199
	v_lshl_add_u32 v60, v56, 2, s76
	v_add_u32_e32 v56, 3, v206
	v_med3_i32 v0, v206, s39, v198
	v_med3_i32 v55, v206, s33, v199
	v_med3_i32 v61, v56, s39, v198
	v_med3_i32 v56, v56, s33, v199
	v_lshl_add_u32 v0, v0, 2, s76
	v_lshl_add_u32 v55, v55, 2, s76
	v_lshl_add_u32 v57, v57, 2, s76
	v_lshl_add_u32 v59, v59, 2, s76
	v_lshl_add_u32 v62, v56, 2, s76
	v_lshl_add_u32 v61, v61, 2, s76
	ds_read_b32 v0, v0 offset:516
	ds_read_b32 v56, v55 offset:644
	ds_read_b32 v55, v57 offset:516
	ds_read_b32 v57, v58 offset:644
	ds_read_b32 v72, v59 offset:516
	ds_read_b32 v58, v60 offset:644
	ds_read_b32 v73, v61 offset:516
	ds_read_b32 v59, v62 offset:644
	v_add_u32_e32 v60, 8, v206
	v_add_u32_e32 v62, 9, v206
	v_add_u32_e32 v64, 10, v206
	v_add_u32_e32 v66, 11, v206
	v_med3_i32 v61, v60, s39, v198
	v_med3_i32 v60, v60, s33, v199
	v_med3_i32 v63, v62, s39, v198
	v_med3_i32 v62, v62, s33, v199
	v_med3_i32 v65, v64, s39, v198
	v_med3_i32 v64, v64, s33, v199
	v_med3_i32 v67, v66, s39, v198
	v_med3_i32 v66, v66, s33, v199
	v_lshl_add_u32 v61, v61, 2, s76
	v_lshl_add_u32 v60, v60, 2, s76
	v_lshl_add_u32 v63, v63, 2, s76
	v_lshl_add_u32 v62, v62, 2, s76
	v_lshl_add_u32 v64, v64, 2, s76
	v_lshl_add_u32 v66, v66, 2, s76
	v_lshl_add_u32 v65, v65, 2, s76
	v_lshl_add_u32 v67, v67, 2, s76
	ds_read_b32 v74, v61 offset:516
	ds_read_b32 v60, v60 offset:644
	ds_read_b32 v75, v63 offset:516
	ds_read_b32 v61, v62 offset:644
	ds_read_b32 v76, v65 offset:516
	ds_read_b32 v62, v64 offset:644
	ds_read_b32 v77, v67 offset:516
	ds_read_b32 v63, v66 offset:644
	v_add_u32_e32 v64, 16, v206
	v_add_u32_e32 v66, 17, v206
	v_add_u32_e32 v68, 18, v206
	v_add_u32_e32 v70, 19, v206
	v_med3_i32 v65, v64, s39, v198
	v_med3_i32 v64, v64, s33, v199
	v_med3_i32 v67, v66, s39, v198
	v_med3_i32 v66, v66, s33, v199
	v_med3_i32 v69, v68, s39, v198
	v_med3_i32 v68, v68, s33, v199
	v_med3_i32 v71, v70, s39, v198
	v_med3_i32 v70, v70, s33, v199
	v_lshl_add_u32 v65, v65, 2, s76
	v_lshl_add_u32 v64, v64, 2, s76
	v_lshl_add_u32 v67, v67, 2, s76
	v_lshl_add_u32 v66, v66, 2, s76
	v_lshl_add_u32 v68, v68, 2, s76
	v_lshl_add_u32 v70, v70, 2, s76
	v_lshl_add_u32 v69, v69, 2, s76
	v_lshl_add_u32 v71, v71, 2, s76
	ds_read_b32 v78, v65 offset:516
	ds_read_b32 v64, v64 offset:644
	ds_read_b32 v79, v67 offset:516
	ds_read_b32 v65, v66 offset:644
	ds_read_b32 v80, v69 offset:516
	ds_read_b32 v66, v68 offset:644
	ds_read_b32 v81, v71 offset:516
	ds_read_b32 v67, v70 offset:644
	v_add_u32_e32 v68, 24, v206
	v_add_u32_e32 v70, 25, v206
	v_add_u32_e32 v82, 26, v206
	v_med3_i32 v69, v68, s39, v198
	v_med3_i32 v68, v68, s33, v199
	v_med3_i32 v71, v70, s39, v198
	v_med3_i32 v70, v70, s33, v199
	v_med3_i32 v83, v82, s39, v198
	v_med3_i32 v82, v82, s33, v199
	v_add_u32_e32 v84, 27, v206
	s_waitcnt lgkmcnt(14)
	v_fmac_f32_e32 v0, 0x3e38aa3b, v18
	v_fmac_f32_e32 v55, 0x3e38aa3b, v19
	v_lshl_add_u32 v69, v69, 2, s76
	v_lshl_add_u32 v68, v68, 2, s76
	v_lshl_add_u32 v71, v71, 2, s76
	v_lshl_add_u32 v70, v70, 2, s76
	v_lshl_add_u32 v82, v82, 2, s76
	v_med3_i32 v85, v84, s39, v198
	v_med3_i32 v84, v84, s33, v199
	v_fmac_f32_e32 v72, 0x3e38aa3b, v20
	v_fmac_f32_e32 v73, 0x3e38aa3b, v21
	v_lshl_add_u32 v83, v83, 2, s76
	v_lshl_add_u32 v85, v85, 2, s76
	v_lshl_add_u32 v84, v84, 2, s76
	ds_read_b32 v88, v69 offset:516
	ds_read_b32 v68, v68 offset:644
	ds_read_b32 v89, v71 offset:516
	ds_read_b32 v69, v70 offset:644
	ds_read_b32 v90, v83 offset:516
	ds_read_b32 v70, v82 offset:644
	ds_read_b32 v91, v85 offset:516
	ds_read_b32 v71, v84 offset:644
	v_max_f32_e32 v82, v0, v55
	v_fmac_f32_e32 v74, 0x3e38aa3b, v22
	s_waitcnt lgkmcnt(14)
; template <int MODE>
; __device__ __forceinline__ void partialSM(f32x16& p0, f32x16& p1, float& m_reg, float& mn, float& alpha, int relh, int relw_min, int relw_max, const float* lut) {
;     ...
;     float pmax = p0[0];
; #pragma unroll
;     for (int r = 1; r < 16; ++r) pmax = fmaxf(pmax, p0[r]);
; #pragma unroll
;     for (int r = 0; r < 16; ++r) pmax = fmaxf(pmax, p1[r]);
;     { auto rr = __builtin_amdgcn_permlane32_swap(__float_as_uint(pmax), __float_as_uint(pmax), false, false);
;       pmax = fmaxf(__uint_as_float(rr[0]), __uint_as_float(rr[1])); }
;     if (__builtin_expect(__all(pmax - m_reg <= THR2), 1)) { mn = m_reg; alpha = 1.f; }
;     else { mn = fmaxf(m_reg, pmax); alpha = __builtin_amdgcn_exp2f(m_reg - mn); m_reg = mn; }
; #pragma unroll
;     for (int r = 0; r < 16; ++r) p0[r] = __builtin_amdgcn_exp2f(p0[r] - mn);
; #pragma unroll
;     for (int r = 0; r < 16; ++r) p1[r] = p1[r] - mn;
	v_fmac_f32_e32 v75, 0x3e38aa3b, v23
	v_max3_f32 v82, v82, v72, v73
	v_fmac_f32_e32 v76, 0x3e38aa3b, v24
	v_fmac_f32_e32 v77, 0x3e38aa3b, v25
	v_max3_f32 v82, v82, v74, v75
	v_fmac_f32_e32 v78, 0x3e38aa3b, v26
	s_waitcnt lgkmcnt(13)
	v_fmac_f32_e32 v79, 0x3e38aa3b, v27
	v_max3_f32 v82, v82, v76, v77
	s_waitcnt lgkmcnt(11)
	v_fmac_f32_e32 v80, 0x3e38aa3b, v28
	s_waitcnt lgkmcnt(9)
	v_fmac_f32_e32 v81, 0x3e38aa3b, v29
	v_max3_f32 v82, v82, v78, v79
	s_waitcnt lgkmcnt(7)
	v_fmac_f32_e32 v88, 0x3e38aa3b, v30
	s_waitcnt lgkmcnt(5)
	v_fmac_f32_e32 v89, 0x3e38aa3b, v31
	v_max3_f32 v82, v82, v80, v81
	s_waitcnt lgkmcnt(3)
	v_fmac_f32_e32 v90, 0x3e38aa3b, v32
	s_waitcnt lgkmcnt(1)
	v_fmac_f32_e32 v91, 0x3e38aa3b, v33
	v_max3_f32 v82, v82, v88, v89
	v_max3_f32 v82, v82, v90, v91
	v_pk_fma_f32 v[56:57], v[2:3], s[48:49], v[56:57] op_sel_hi:[1,0,1]
	v_pk_fma_f32 v[58:59], v[4:5], s[48:49], v[58:59] op_sel_hi:[1,0,1]
	v_max3_f32 v82, v82, v56, v57
	v_max3_f32 v82, v82, v58, v59
	v_pk_fma_f32 v[60:61], v[6:7], s[48:49], v[60:61] op_sel_hi:[1,0,1]
	v_pk_fma_f32 v[62:63], v[8:9], s[48:49], v[62:63] op_sel_hi:[1,0,1]
	v_max3_f32 v82, v82, v60, v61
	v_max3_f32 v82, v82, v62, v63
	v_pk_fma_f32 v[64:65], v[10:11], s[48:49], v[64:65] op_sel_hi:[1,0,1]
	s_waitcnt lgkmcnt(0)
	v_pk_fma_f32 v[86:87], v[16:17], s[48:49], v[70:71] op_sel_hi:[1,0,1]
	v_max3_f32 v84, v82, v64, v65
	v_pk_fma_f32 v[82:83], v[12:13], s[48:49], v[66:67] op_sel_hi:[1,0,1]
	s_nop 0
	v_max3_f32 v66, v84, v82, v83
	v_pk_fma_f32 v[84:85], v[14:15], s[48:49], v[68:69] op_sel_hi:[1,0,1]
	s_nop 0
	v_max3_f32 v66, v66, v84, v85
	v_max3_f32 v66, v66, v86, v87
	v_mov_b32_e32 v67, v66
	s_nop 1
	v_permlane32_swap_b32_e32 v66, v67
	v_max_f32_e32 v67, v67, v67
	v_max_f32_e32 v66, v66, v66
	v_max_f32_e32 v66, v66, v67
	v_add_f32_e32 v67, 0x7149f2ca, v66
	v_cmp_ge_f32_e32 vcc, s94, v67
	v_max_f32_e32 v66, 0xf149f2ca, v66
	v_sub_f32_e32 v67, 0xf149f2ca, v66
	s_cmp_eq_u64 vcc, exec
	v_exp_f32_e32 v67, v67
	s_cselect_b64 vcc, -1, 0
	v_cndmask_b32_e32 v222, v66, v197, vcc
	v_mov_b32_e32 v100, s76
	ds_read_b32 v101, v100
	ds_read_b32 v100, v100 offset:1032
	v_readlane_b32 s19, v255, 21
	s_waitcnt lgkmcnt(0)
	v_max_f32_e32 v101, v101, v100
	v_add_f32_e32 v222, s19, v101
	v_sub_f32_e32 v0, v0, v222
	v_exp_f32_e32 v66, v0
	v_sub_f32_e32 v0, v55, v222
	v_cndmask_b32_e64 v220, v67, 1.0, vcc
	v_exp_f32_e32 v67, v0
	v_sub_f32_e32 v0, v72, v222
	v_exp_f32_e32 v68, v0
	v_sub_f32_e32 v0, v73, v222
	v_exp_f32_e32 v69, v0
	v_sub_f32_e32 v0, v74, v222
	v_exp_f32_e32 v70, v0
	v_sub_f32_e32 v0, v75, v222
	v_exp_f32_e32 v71, v0
	v_sub_f32_e32 v0, v76, v222
	v_exp_f32_e32 v72, v0
	v_sub_f32_e32 v0, v77, v222
	v_exp_f32_e32 v73, v0
	v_sub_f32_e32 v0, v78, v222
	v_exp_f32_e32 v74, v0
	v_sub_f32_e32 v0, v79, v222
	v_exp_f32_e32 v75, v0
	v_sub_f32_e32 v0, v80, v222
	v_exp_f32_e32 v76, v0
	v_sub_f32_e32 v0, v81, v222
	v_exp_f32_e32 v77, v0
	v_sub_f32_e32 v0, v88, v222
	v_exp_f32_e32 v78, v0
	v_sub_f32_e32 v0, v89, v222
	v_exp_f32_e32 v79, v0
	v_sub_f32_e32 v0, v90, v222
	v_exp_f32_e32 v80, v0
	v_sub_f32_e32 v0, v91, v222
	v_exp_f32_e32 v81, v0
	v_sub_f32_e32 v97, v87, v222
	v_sub_f32_e32 v96, v86, v222
	v_sub_f32_e32 v95, v85, v222
	v_sub_f32_e32 v94, v84, v222
	v_sub_f32_e32 v93, v83, v222
	v_sub_f32_e32 v92, v82, v222
	v_sub_f32_e32 v91, v65, v222
	v_sub_f32_e32 v90, v64, v222
	v_sub_f32_e32 v89, v63, v222
	v_sub_f32_e32 v88, v62, v222
	v_sub_f32_e32 v87, v61, v222
	v_sub_f32_e32 v86, v60, v222
	v_sub_f32_e32 v85, v59, v222
	v_sub_f32_e32 v84, v58, v222
	v_sub_f32_e32 v83, v57, v222
	v_sub_f32_e32 v82, v56, v222
	s_xor_b64 s[64:65], exec, -1

; #define SBAR() __builtin_amdgcn_sched_barrier(0)
; #define SLOAD(i, k0) do { sr_[i].vs0 = *reinterpret_cast<const bf16x8*>(&Vh[(size_t)((k0) + sr) * LDQK + sc]); sr_[i].vs1 = *reinterpret_cast<const bf16x8*>(&Vh[(size_t)((k0) + 32 + sr) * LDQK + sc]); \
;     sr_[i].ks0 = *reinterpret_cast<const bf16x8*>(&Kh[(size_t)((k0) + sr) * LDQK + sc]); sr_[i].ks1 = *reinterpret_cast<const bf16x8*>(&Kh[(size_t)((k0) + 32 + sr) * LDQK + sc]); } while (0)
; #define SWRITE(off, i) do { *(bf16x8*)(V_lds + (off) + vst0) = sr_[i].vs0;          \
;     *(bf16x8*)(V_lds + (off) + vst1) = sr_[i].vs1; int kc = sc * 2;               \
;     *(bf16x8*)(K_lds + (off) + KSWZ(sr, kc)) = sr_[i].ks0;                       \
;     *(bf16x8*)(K_lds + (off) + KSWZ(32 + sr, kc)) = sr_[i].ks1; } while (0)
; #define SWAIT() asm volatile("s_waitcnt vmcnt(4)" ::: "memory")
; #define RESC(a) do { if (__any((a) < 1.f)) { if (hi == 0) al_l[r32] = (a); asm volatile("s_waitcnt lgkmcnt(0)" ::: "memory"); \
;     _Pragma("unroll") for (int d = 0; d < 4; ++d) _Pragma("unroll") for (int r = 0; r < 16; ++r) o[d][r] *= al_l[crow(r, hi)]; } } while (0)
; #define PSM(P0, P1, MN, AL, J) partialSM<MODE>(P0, P1, m_reg, MN, AL, relq + 64 * (J), relwmin + 64 * (J), relwmax + 64 * (J), lut)
; template <int MODE>
; __device__ __forceinline__ void attn_body(const bf16_t* __restrict__ Qb, const bf16_t* __restrict__ Kh, const bf16_t* __restrict__ Vh, int NT, int krel0,
;                                           char* lds, const float* __restrict__ lutg, const AttnEpi& E) {
;     ...
;   SLOAD(SE, 0); SLOAD(SO, 64); asm volatile("s_waitcnt vmcnt(4)" ::: "memory"); SWRITE(0, SE); __syncthreads();
;   qkt<ND0, DOFF>(pA0, pA1, K_lds, qr, r32, hi); PSM(pA0, pA1, mnA, alA, 0);
;   if (2 < NT) SLOAD(SE, 2 * 64);
;   SWAIT(); SWRITE(SHM_V, SO);
;   int op = 0, oq = SHM_V, ow = 2 * SHM_V;
;   for (int j = 1; j + 1 < NT; j += 2) {
;     __syncthreads();
;     SBAR(); qkt<ND0, DOFF>(pB0, pB1, K_lds + oq, qr, r32, hi);
;     finishSM(pA0, pA1, alA, l_reg, pa0, pa1, pa2, pa3); SBAR();
;     SLOAD(SO, (j + 2) * 64); SBAR();
;     pv_d0(o, vb0 + op, pa0, pa1, pa2, pa3); PSM(pB0, pB1, mnB, alB, j);
;     SWAIT(); SWRITE(ow, SE);
;     RESC(alB);
;     { const int t = op; op = oq; oq = ow; ow = t; }
.LBB0_176:
	s_or_b64 exec, exec, s[60:61]
	v_add_u32_e32 v0, 0xa0, v50
	s_movk_i32 s60, 0x1200
	s_nop 3
	v_mad_i64_i32 v[2:3], s[6:7], v0, s60, 0
	v_add_u32_e32 v0, 0x80, v50
	v_or_b32_e32 v2, v2, v51
	v_mad_i64_i32 v[6:7], s[6:7], v0, s60, 0
	v_lshlrev_b64 v[2:3], 1, v[2:3]
	v_or_b32_e32 v6, v6, v51
	v_lshl_add_u64 v[4:5], s[58:59], 0, v[2:3]
	v_lshlrev_b64 v[6:7], 1, v[6:7]
	v_lshl_add_u64 v[2:3], s[0:1], 0, v[2:3]
	v_lshl_add_u64 v[8:9], s[58:59], 0, v[6:7]
	v_lshl_add_u64 v[4:5], s[0:1], 0, v[6:7]
	v_and_b32_e32 v0, 63, v188
	v_lshlrev_b32_e32 v3, 4, v0
	v_lshlrev_b32_e32 v2, 3, v0
	v_and_b32_e32 v3, 0xc0, v3
	v_lshlrev_b32_e32 v4, 1, v0
	v_and_or_b32 v3, v2, 24, v3
	v_and_b32_e32 v4, 32, v4
	v_and_b32_e32 v2, 0x100, v2
	s_cmp_lg_u32 0, -1
	v_or3_b32 v2, v3, v4, v2
	s_cselect_b32 s0, 0, 0
	v_add_u32_e32 v221, s0, v2
	v_and_b32_e32 v2, 0x3fffffc0, v188
	v_add_u32_e32 v3, s75, v214
	v_ashrrev_i32_e32 v51, 31, v50
	v_lshl_add_u32 v2, v2, 2, s89
	s_waitcnt vmcnt(0)
	s_waitcnt vmcnt(3)
	ds_write_b128 v53, v[34:37] offset:16384
	s_waitcnt vmcnt(1)
	ds_write_b128 v54, v[38:41] offset:16384
	ds_write_b128 v3, v[42:45]
	v_add_u32_e32 v3, s75, v215
	s_waitcnt vmcnt(0)
	ds_write_b128 v3, v[46:49]
	v_cmp_gt_u32_e64 s[6:7], 32, v0
	v_lshl_add_u32 v212, v184, 2, v2
	v_lshl_add_u32 v210, v205, 2, v2
	v_sub_u32_e32 v0, v205, v184
	v_lshl_add_u64 v[2:3], v[50:51], 0, s[2:3]
	s_movk_i32 s2, 0x2400
	v_sub_u32_e32 v225, v0, v204
	v_mad_u64_u32 v[4:5], s[0:1], v2, s2, 0
	v_and_b32_e32 v0, 15, v188
	v_mad_i32_i24 v3, v3, s2, v5
	v_or_b32_e32 v2, s74, v4
	v_lshlrev_b32_e32 v0, 4, v0
	v_readlane_b32 s0, v254, 14
	v_lshl_add_u64 v[2:3], v[2:3], 0, v[0:1]
	v_readlane_b32 s1, v254, 15
	v_mov_b32_e32 v14, v1
	v_mov_b32_e32 v15, v1
	v_sub_u32_e32 v223, 0, v52
	v_lshl_add_u64 v[190:191], s[0:1], 0, v[2:3]
	v_mov_b32_e32 v0, v1
	v_mov_b32_e32 v2, v1
	v_mov_b32_e32 v3, v1
	v_mov_b32_e32 v4, v1
	v_mov_b32_e32 v5, v1
	v_mov_b32_e32 v6, v1
	v_mov_b32_e32 v7, v1
	v_mov_b32_e32 v8, v1
	v_mov_b32_e32 v9, v1
	v_mov_b32_e32 v10, v1
	v_mov_b32_e32 v11, v1
	v_mov_b32_e32 v12, v1
	v_mov_b32_e32 v13, v1
	v_mov_b64_e32 v[64:65], v[14:15]
	v_mov_b64_e32 v[48:49], v[14:15]
	v_mov_b64_e32 v[32:33], v[14:15]
	v_mov_b64_e32 v[62:63], v[12:13]
	v_mov_b64_e32 v[60:61], v[10:11]
	v_mov_b64_e32 v[58:59], v[8:9]
	v_mov_b64_e32 v[56:57], v[6:7]
	v_mov_b64_e32 v[54:55], v[4:5]
	v_mov_b64_e32 v[52:53], v[2:3]
	v_mov_b64_e32 v[50:51], v[0:1]
	v_mov_b64_e32 v[46:47], v[12:13]
	v_mov_b64_e32 v[44:45], v[10:11]
	v_mov_b64_e32 v[42:43], v[8:9]
	v_mov_b64_e32 v[40:41], v[6:7]
	v_mov_b64_e32 v[38:39], v[4:5]
	v_mov_b64_e32 v[36:37], v[2:3]
	v_mov_b64_e32 v[34:35], v[0:1]
	v_mov_b64_e32 v[30:31], v[12:13]
	v_mov_b64_e32 v[28:29], v[10:11]
	v_mov_b64_e32 v[26:27], v[8:9]
	v_mov_b64_e32 v[24:25], v[6:7]
	v_mov_b64_e32 v[22:23], v[4:5]
	v_mov_b64_e32 v[20:21], v[2:3]
	v_mov_b64_e32 v[18:19], v[0:1]
	v_mov_b64_e32 v[16:17], v[14:15]
	s_mov_b32 s66, 0
	s_mov_b32 s67, 2
	v_sub_u32_e32 v224, 0, v204
	v_mov_b32_e32 v213, 0
	s_movk_i32 s68, 0x4000
	s_mov_b32 s0, 0x8000
	v_mov_b64_e32 v[14:15], v[12:13]
	v_mov_b64_e32 v[12:13], v[10:11]
	v_mov_b64_e32 v[10:11], v[8:9]
	v_mov_b64_e32 v[8:9], v[6:7]
	v_mov_b64_e32 v[6:7], v[4:5]
	v_mov_b64_e32 v[4:5], v[2:3]
	v_mov_b64_e32 v[2:3], v[0:1]
	s_waitcnt vmcnt(0)
	v_readfirstlane_b32 s31, v179
	s_nop 3
	s_lshr_b32 s31, s31, 6
	s_lshl_b32 s30, s31, 11
	v_and_b32_e32 v150, 63, v179
	v_bfe_u32 v151, v150, 2, 3
	s_lshl_b32 s29, s31, 3
	v_or_b32_e32 v151, s29, v151
	v_and_b32_e32 v152, 4, v151
	v_lshlrev_b32_e32 v152, 1, v152
	v_and_b32_e32 v153, 8, v151
	v_lshrrev_b32_e32 v153, 1, v153
	v_and_b32_e32 v151, 0xfffffff3, v151
	v_or3_b32 v151, v151, v152, v153
	v_mul_u32_u24_e32 v151, 0x2400, v151
	v_lshrrev_b32_e32 v152, 5, v150
	v_lshlrev_b32_e32 v152, 6, v152
	v_and_b32_e32 v153, 3, v150
	v_lshlrev_b32_e32 v153, 4, v153
	v_add3_u32 v248, v151, v152, v153
	v_add_u32_e32 v249, 0x80, v248
	v_lshrrev_b32_e32 v151, 4, v150
	v_add_u32_e32 v151, s29, v151
	v_and_b32_e32 v152, 15, v150
	v_and_b32_e32 v153, 15, v151
	v_xor_b32_e32 v153, v152, v153
	v_mul_u32_u24_e32 v154, 0x2400, v151
	v_lshl_add_u32 v250, v153, 4, v154
	v_add_u32_e32 v151, 4, v151
	v_and_b32_e32 v153, 15, v151
	v_xor_b32_e32 v153, v152, v153
	v_mul_u32_u24_e32 v154, 0x2400, v151
	v_lshl_add_u32 v251, v153, 4, v154
	v_readfirstlane_b32 s26, v190
	v_readfirstlane_b32 s27, v191
	s_mul_i32 s29, s31, 0x9000
	s_add_u32 s29, s29, 0x168000
	s_sub_u32 s26, s26, s29
	s_subb_u32 s27, s27, 0
	s_sub_u32 s28, s26, 0x200
	s_subb_u32 s29, s27, 0
	s_add_i32 m0, s0, s30
	s_add_i32 m0, m0, 0xc000
	s_nop 0
	global_load_lds_dwordx4 v250, s[28:29]
	s_add_i32 m0, m0, 0x400
	s_nop 0
	global_load_lds_dwordx4 v251, s[28:29]
	s_add_i32 m0, m0, 0xfffffc00
	s_nop 0
	global_load_lds_dwordx4 v250, s[28:29]
	s_add_i32 m0, m0, 0x400
	s_nop 0
	global_load_lds_dwordx4 v251, s[28:29]
	s_add_u32 s28, s28, 0x90000
	s_addc_u32 s29, s29, 0
	s_waitcnt lgkmcnt(0)
	s_barrier
	v_mov_b32_e32 v160, s76
	ds_read_b32 v160, v160
	v_mov_b32_e32 v161, s41
	ds_read_b32 v161, v161
	s_waitcnt lgkmcnt(0)
.LBB0_177:
	v_readfirstlane_b32 s20, v224
	v_readfirstlane_b32 s21, v223
	s_nop 3
	s_add_i32 s22, s20, s77
	s_addk_i32 s22, 0x7f
	s_add_i32 s23, s21, s77
	s_addk_i32 s23, 0x40
	s_add_i32 s24, s22, 64
	s_add_i32 s25, s23, 64
	s_mov_b32 s2, s0
	s_cmp_lt_u32 s31, 4
	s_cbranch_scc0 .Ldp_12
	s_waitcnt vmcnt(2) lgkmcnt(0)
	s_barrier
; #define SBAR() __builtin_amdgcn_sched_barrier(0)
; #define SLOAD(i, k0) do { sr_[i].vs0 = *reinterpret_cast<const bf16x8*>(&Vh[(size_t)((k0) + sr) * LDQK + sc]); sr_[i].vs1 = *reinterpret_cast<const bf16x8*>(&Vh[(size_t)((k0) + 32 + sr) * LDQK + sc]); \
;     sr_[i].ks0 = *reinterpret_cast<const bf16x8*>(&Kh[(size_t)((k0) + sr) * LDQK + sc]); sr_[i].ks1 = *reinterpret_cast<const bf16x8*>(&Kh[(size_t)((k0) + 32 + sr) * LDQK + sc]); } while (0)
; #define SWRITE(off, i) do { *(bf16x8*)(V_lds + (off) + vst0) = sr_[i].vs0;          \
;     *(bf16x8*)(V_lds + (off) + vst1) = sr_[i].vs1; int kc = sc * 2;               \
;     *(bf16x8*)(K_lds + (off) + KSWZ(sr, kc)) = sr_[i].ks0;                       \
;     *(bf16x8*)(K_lds + (off) + KSWZ(32 + sr, kc)) = sr_[i].ks1; } while (0)
; #define SWAIT() asm volatile("s_waitcnt vmcnt(4)" ::: "memory")
; #define PSM(P0, P1, MN, AL, J) partialSM<MODE>(P0, P1, m_reg, MN, AL, relq + 64 * (J), relwmin + 64 * (J), relwmax + 64 * (J), lut)
; template <int MODE>
; __device__ __forceinline__ void attn_body(const bf16_t* __restrict__ Qb, const bf16_t* __restrict__ Kh, const bf16_t* __restrict__ Vh, int NT, int krel0,
;                                           char* lds, const float* __restrict__ lutg, const AttnEpi& E) {
;     ...
;     __syncthreads();
;     SBAR(); qkt<ND0, DOFF>(pB0, pB1, K_lds + oq, qr, r32, hi);
;     finishSM(pA0, pA1, alA, l_reg, pa0, pa1, pa2, pa3); SBAR();
;     SLOAD(SO, (j + 2) * 64); SBAR();
;     pv_d0(o, vb0 + op, pa0, pa1, pa2, pa3); PSM(pB0, pB1, mnB, alB, j);
;     SWAIT(); SWRITE(ow, SE);
.Ldp_12:
	s_add_i32 s0, s68, 0
	v_add_u32_e32 v0, s0, v216
	ds_read_b128 v[98:101], v0 offset:49152
	ds_read_b128 v[102:105], v0 offset:57344
	v_add_u32_e32 v0, s0, v217
	ds_read_b128 v[162:165], v0 offset:49152
	ds_read_b128 v[166:169], v0 offset:57344
	v_add_u32_e32 v0, s0, v218
	s_waitcnt lgkmcnt(3)
	v_mfma_f32_32x32x16_bf16 v[114:129], v[98:101], v[142:145], 0
	s_waitcnt lgkmcnt(2)
	v_mfma_f32_32x32x16_bf16 v[98:113], v[102:105], v[142:145], 0
	s_waitcnt lgkmcnt(1)
	v_mfma_f32_32x32x16_bf16 v[114:129], v[162:165], v[138:141], v[114:129]
	s_waitcnt lgkmcnt(0)
	v_mfma_f32_32x32x16_bf16 v[98:113], v[166:169], v[138:141], v[98:113]
	ds_read_b128 v[162:165], v0 offset:49152
	ds_read_b128 v[166:169], v0 offset:57344
	v_add_u32_e32 v0, s0, v219
	s_waitcnt lgkmcnt(1)
	v_mfma_f32_32x32x16_bf16 v[114:129], v[162:165], v[134:137], v[114:129]
	s_waitcnt lgkmcnt(0)
	v_mfma_f32_32x32x16_bf16 v[98:113], v[166:169], v[134:137], v[98:113]
	ds_read_b128 v[162:165], v0 offset:49152
	ds_read_b128 v[166:169], v0 offset:57344
	v_exp_f32_e32 v0, v82
	v_exp_f32_e32 v82, v83
	v_exp_f32_e32 v83, v84
	v_exp_f32_e32 v84, v85
	v_exp_f32_e32 v85, v86
	v_exp_f32_e32 v86, v87
	v_exp_f32_e32 v87, v88
	v_exp_f32_e32 v88, v89
	v_exp_f32_e32 v89, v90
	v_exp_f32_e32 v90, v91
	v_exp_f32_e32 v91, v92
	v_exp_f32_e32 v92, v93
	v_exp_f32_e32 v93, v94
	v_exp_f32_e32 v94, v95
	v_exp_f32_e32 v95, v96
	v_exp_f32_e32 v96, v97
	v_add_f32_e32 v97, v67, v66
	v_add_f32_e32 v97, v68, v97
	v_add_f32_e32 v97, v69, v97
	v_add_f32_e32 v97, v70, v97
	v_add_f32_e32 v97, v71, v97
	v_add_f32_e32 v97, v72, v97
	v_add_f32_e32 v97, v73, v97
	v_add_f32_e32 v97, v74, v97
	v_add_f32_e32 v97, v75, v97
	v_add_f32_e32 v97, v76, v97
	v_add_f32_e32 v97, v77, v97
	v_add_f32_e32 v97, v78, v97
	v_add_f32_e32 v97, v79, v97
	v_add_f32_e32 v97, v80, v97
	v_add_f32_e32 v97, v81, v97
	v_add_f32_e32 v97, v0, v97
	v_add_f32_e32 v97, v82, v97
	v_add_f32_e32 v97, v83, v97
	v_add_f32_e32 v97, v84, v97
	v_add_f32_e32 v97, v85, v97
	v_add_f32_e32 v97, v86, v97
	v_add_f32_e32 v97, v87, v97
	v_add_f32_e32 v97, v88, v97
	v_add_f32_e32 v97, v89, v97
	v_add_f32_e32 v97, v90, v97
	s_waitcnt lgkmcnt(1)
	v_mfma_f32_32x32x16_bf16 v[114:129], v[162:165], v[130:133], v[114:129]
	v_add_f32_e32 v97, v91, v97
	v_add_f32_e32 v97, v92, v97
	v_add_f32_e32 v97, v93, v97
	v_add_f32_e32 v97, v94, v97
	v_add_f32_e32 v97, v95, v97
	v_add_f32_e32 v226, v96, v97
	v_mov_b32_e32 v227, v226
	s_waitcnt lgkmcnt(0)
	v_mfma_f32_32x32x16_bf16 v[98:113], v[166:169], v[130:133], v[98:113]
	v_cvt_pk_bf16_f32 v66, v66, v67
	v_cvt_pk_bf16_f32 v67, v68, v69
	v_cvt_pk_bf16_f32 v68, v70, v71
	v_cvt_pk_bf16_f32 v69, v72, v73
	v_cvt_pk_bf16_f32 v70, v74, v75
	v_cvt_pk_bf16_f32 v71, v76, v77
	v_cvt_pk_bf16_f32 v72, v78, v79
	v_cvt_pk_bf16_f32 v73, v80, v81
	v_cvt_pk_bf16_f32 v74, v0, v82
	v_cvt_pk_bf16_f32 v75, v83, v84
	v_cvt_pk_bf16_f32 v76, v85, v86
	v_cvt_pk_bf16_f32 v77, v87, v88
	v_cvt_pk_bf16_f32 v78, v89, v90
	v_cvt_pk_bf16_f32 v79, v91, v92
	v_cvt_pk_bf16_f32 v80, v93, v94
	v_cvt_pk_bf16_f32 v81, v95, v96
	v_permlane32_swap_b32_e32 v226, v227
	v_permlane32_swap_b32_e32 v66, v68
	v_permlane32_swap_b32_e32 v67, v69
	v_permlane32_swap_b32_e32 v70, v72
	v_permlane32_swap_b32_e32 v71, v73
	v_permlane32_swap_b32_e32 v74, v76
	v_permlane32_swap_b32_e32 v75, v77
	v_permlane32_swap_b32_e32 v78, v80
	v_permlane32_swap_b32_e32 v79, v81
	s_cmp_lt_u32 s31, 4
	s_cbranch_scc1 .Ldp_11
	s_waitcnt vmcnt(2) lgkmcnt(0)
	s_barrier
.Ldp_11:
	s_setprio 0
	s_add_i32 m0, s66, s30
	s_add_i32 m0, m0, 0xc000
	s_nop 0
	global_load_lds_dwordx4 v250, s[28:29]
	s_add_i32 m0, m0, 0x400
	s_nop 0
	global_load_lds_dwordx4 v251, s[28:29]
	s_add_i32 m0, s2, s30
	s_nop 0
	global_load_lds_dwordx4 v248, s[26:27]
	s_add_i32 m0, m0, 0x400
	s_nop 0
	global_load_lds_dwordx4 v249, s[26:27]
	s_add_u32 s26, s26, 0x90000
	s_addc_u32 s27, s27, 0
	s_add_u32 s28, s28, 0x90000
	s_addc_u32 s29, s29, 0
	v_add_u32_e32 v0, s66, v221
	ds_read_b64_tr_b16 v[82:83], v0 offset:0
	ds_read_b64_tr_b16 v[84:85], v0 offset:0x800
	ds_read_b64_tr_b16 v[86:87], v0 offset:0x1000
	ds_read_b64_tr_b16 v[88:89], v0 offset:0x1800
	ds_read_b64_tr_b16 v[90:91], v0 offset:0x2000
	ds_read_b64_tr_b16 v[92:93], v0 offset:0x2800
	ds_read_b64_tr_b16 v[94:95], v0 offset:0x3000
	ds_read_b64_tr_b16 v[96:97], v0 offset:0x3800
	s_waitcnt lgkmcnt(0)
	s_nop 0
	v_mfma_f32_32x32x16_bf16 v[50:65], v[66:69], v[82:85], v[50:65]
	ds_read_b64_tr_b16 v[82:83], v0 offset:0x200
	ds_read_b64_tr_b16 v[84:85], v0 offset:0xa00
	v_mfma_f32_32x32x16_bf16 v[50:65], v[70:73], v[86:89], v[50:65]
	ds_read_b64_tr_b16 v[86:87], v0 offset:0x1200
	ds_read_b64_tr_b16 v[88:89], v0 offset:0x1a00
	v_mfma_f32_32x32x16_bf16 v[50:65], v[74:77], v[90:93], v[50:65]
	ds_read_b64_tr_b16 v[90:91], v0 offset:0x2200
	ds_read_b64_tr_b16 v[92:93], v0 offset:0x2a00
	v_mfma_f32_32x32x16_bf16 v[50:65], v[78:81], v[94:97], v[50:65]
	ds_read_b64_tr_b16 v[94:95], v0 offset:0x3200
	ds_read_b64_tr_b16 v[96:97], v0 offset:0x3a00
	s_waitcnt lgkmcnt(0)
	v_mfma_f32_32x32x16_bf16 v[34:49], v[66:69], v[82:85], v[34:49]
	ds_read_b64_tr_b16 v[82:83], v0 offset:0x400
	ds_read_b64_tr_b16 v[84:85], v0 offset:0xc00
	v_mfma_f32_32x32x16_bf16 v[34:49], v[70:73], v[86:89], v[34:49]
	ds_read_b64_tr_b16 v[86:87], v0 offset:0x1400
	ds_read_b64_tr_b16 v[88:89], v0 offset:0x1c00
	v_mfma_f32_32x32x16_bf16 v[34:49], v[74:77], v[90:93], v[34:49]
	ds_read_b64_tr_b16 v[90:91], v0 offset:0x2400
	ds_read_b64_tr_b16 v[92:93], v0 offset:0x2c00
	v_mfma_f32_32x32x16_bf16 v[34:49], v[78:81], v[94:97], v[34:49]
	ds_read_b64_tr_b16 v[94:95], v0 offset:0x3400
	ds_read_b64_tr_b16 v[96:97], v0 offset:0x3c00
	s_waitcnt lgkmcnt(0)
	v_mfma_f32_32x32x16_bf16 v[18:33], v[66:69], v[82:85], v[18:33]
	ds_read_b64_tr_b16 v[82:83], v0 offset:0x600
	ds_read_b64_tr_b16 v[84:85], v0 offset:0xe00
	v_mfma_f32_32x32x16_bf16 v[18:33], v[70:73], v[86:89], v[18:33]
	ds_read_b64_tr_b16 v[86:87], v0 offset:0x1600
	ds_read_b64_tr_b16 v[88:89], v0 offset:0x1e00
	v_mfma_f32_32x32x16_bf16 v[18:33], v[74:77], v[90:93], v[18:33]
	ds_read_b64_tr_b16 v[90:91], v0 offset:0x2600
	ds_read_b64_tr_b16 v[92:93], v0 offset:0x2e00
	v_mfma_f32_32x32x16_bf16 v[18:33], v[78:81], v[94:97], v[18:33]
	ds_read_b64_tr_b16 v[94:95], v0 offset:0x3600
	ds_read_b64_tr_b16 v[96:97], v0 offset:0x3e00
	s_waitcnt lgkmcnt(0)
	v_mfma_f32_32x32x16_bf16 v[2:17], v[66:69], v[82:85], v[2:17]
	s_cmp_gt_i32 s95, s22
	s_cselect_b64 s[0:1], -1, 0
	s_cmp_lt_i32 s15, s22
	s_cselect_b64 vcc, -1, 0
	v_mov_b32_e32 v232, v160
	v_mfma_f32_32x32x16_bf16 v[2:17], v[70:73], v[86:89], v[2:17]
	v_mfma_f32_32x32x16_bf16 v[2:17], v[74:77], v[90:93], v[2:17]
	v_mfma_f32_32x32x16_bf16 v[2:17], v[78:81], v[94:97], v[2:17]
	s_setprio 1
	s_and_saveexec_b64 s[58:59], vcc
	s_cbranch_execz .LBB0_181
; template <int MODE>
; __device__ __forceinline__ void partialSM(f32x16& p0, f32x16& p1, float& m_reg, float& mn, float& alpha, int relh, int relw_min, int relw_max, const float* lut) {
;     ...
;     if (nearT) {
; #pragma unroll
;       for (int r = 0; r < 16; ++r) { const int i0 = relh + (r & 3) + 8 * (r >> 2);
;         const int a0 = min(max(i0, -129), 129) + 129, a1 = min(max(i0 + 32, -129), 129) + 129;
;         p0[r] = fmaf(p0[r], C, lut[a0]); p1[r] = fmaf(p1[r], C, lut[a1]); }
;     } else {
; #pragma unroll
;       for (int r = 0; r < 16; ++r) { p0[r] = fmaf(p0[r], C, cfar); p1[r] = fmaf(p1[r], C, cfar); }
;     }
;     float pmax = p0[0];
; #pragma unroll
;     for (int r = 1; r < 16; ++r) pmax = fmaxf(pmax, p0[r]);
; #pragma unroll
;     for (int r = 0; r < 16; ++r) pmax = fmaxf(pmax, p1[r]);
	s_cmp_gt_i32 s91, s23
	s_cselect_b64 vcc, -1, 0
	s_mov_b64 s[62:63], -1
	s_and_saveexec_b64 s[60:61], vcc
	s_cbranch_execz .LBB0_180
	v_add_u32_e32 v230, s77, v225
	v_add_u32_e32 v66, 64, v230
	v_add_u32_e32 v68, 0x41, v230
	v_add_u32_e32 v70, 0x42, v230
	v_add_u32_e32 v72, 0x43, v230
	v_med3_i32 v67, v66, s39, v198
	v_med3_i32 v66, v66, s33, v199
	v_med3_i32 v69, v68, s39, v198
	v_med3_i32 v68, v68, s33, v199
	v_med3_i32 v71, v70, s39, v198
	v_med3_i32 v70, v70, s33, v199
	v_med3_i32 v73, v72, s39, v198
	v_med3_i32 v72, v72, s33, v199
	v_lshl_add_u32 v67, v67, 2, s76
	v_lshl_add_u32 v66, v66, 2, s76
	v_lshl_add_u32 v69, v69, 2, s76
	v_lshl_add_u32 v68, v68, 2, s76
	v_lshl_add_u32 v70, v70, 2, s76
	v_lshl_add_u32 v72, v72, 2, s76
	v_lshl_add_u32 v71, v71, 2, s76
	v_lshl_add_u32 v73, v73, 2, s76
	ds_read_b32 v194, v67 offset:516
	ds_read_b32 v66, v66 offset:644
	ds_read_b32 v195, v69 offset:516
	ds_read_b32 v67, v68 offset:644
	ds_read_b32 v232, v71 offset:516
	ds_read_b32 v68, v70 offset:644
	ds_read_b32 v233, v73 offset:516
	ds_read_b32 v69, v72 offset:644
	v_add_u32_e32 v70, 0x48, v230
	v_add_u32_e32 v72, 0x49, v230
	v_add_u32_e32 v74, 0x4a, v230
	v_add_u32_e32 v76, 0x4b, v230
	v_med3_i32 v71, v70, s39, v198
	v_med3_i32 v70, v70, s33, v199
	v_med3_i32 v73, v72, s39, v198
	v_med3_i32 v72, v72, s33, v199
	v_med3_i32 v75, v74, s39, v198
	v_med3_i32 v74, v74, s33, v199
	v_med3_i32 v77, v76, s39, v198
	v_med3_i32 v76, v76, s33, v199
	v_lshl_add_u32 v71, v71, 2, s76
	v_lshl_add_u32 v70, v70, 2, s76
	v_lshl_add_u32 v73, v73, 2, s76
	v_lshl_add_u32 v72, v72, 2, s76
	v_lshl_add_u32 v74, v74, 2, s76
	v_lshl_add_u32 v76, v76, 2, s76
	v_lshl_add_u32 v75, v75, 2, s76
	v_lshl_add_u32 v77, v77, 2, s76
	ds_read_b32 v234, v71 offset:516
	ds_read_b32 v70, v70 offset:644
	ds_read_b32 v235, v73 offset:516
	ds_read_b32 v71, v72 offset:644
	ds_read_b32 v236, v75 offset:516
	ds_read_b32 v72, v74 offset:644
	ds_read_b32 v237, v77 offset:516
	ds_read_b32 v73, v76 offset:644
	v_add_u32_e32 v74, 0x50, v230
	v_add_u32_e32 v76, 0x51, v230
	v_add_u32_e32 v78, 0x52, v230
	v_add_u32_e32 v80, 0x53, v230
	v_med3_i32 v75, v74, s39, v198
	v_med3_i32 v74, v74, s33, v199
	v_med3_i32 v77, v76, s39, v198
	v_med3_i32 v76, v76, s33, v199
	v_med3_i32 v79, v78, s39, v198
	v_med3_i32 v78, v78, s33, v199
	v_med3_i32 v81, v80, s39, v198
	v_med3_i32 v80, v80, s33, v199
	v_lshl_add_u32 v75, v75, 2, s76
	v_lshl_add_u32 v74, v74, 2, s76
	v_lshl_add_u32 v77, v77, 2, s76
	v_lshl_add_u32 v76, v76, 2, s76
	v_lshl_add_u32 v78, v78, 2, s76
	v_lshl_add_u32 v80, v80, 2, s76
	v_lshl_add_u32 v79, v79, 2, s76
	v_lshl_add_u32 v81, v81, 2, s76
	ds_read_b32 v238, v75 offset:516
	ds_read_b32 v74, v74 offset:644
	ds_read_b32 v239, v77 offset:516
	ds_read_b32 v75, v76 offset:644
	ds_read_b32 v240, v79 offset:516
	ds_read_b32 v76, v78 offset:644
	ds_read_b32 v241, v81 offset:516
	ds_read_b32 v77, v80 offset:644
	v_add_u32_e32 v78, 0x58, v230
	v_add_u32_e32 v80, 0x59, v230
	v_add_u32_e32 v82, 0x5a, v230
	v_med3_i32 v79, v78, s39, v198
	v_med3_i32 v78, v78, s33, v199
	v_med3_i32 v81, v80, s39, v198
	v_med3_i32 v80, v80, s33, v199
	v_med3_i32 v83, v82, s39, v198
	v_med3_i32 v82, v82, s33, v199
	v_add_u32_e32 v84, 0x5b, v230
	s_waitcnt lgkmcnt(14)
	v_fmac_f32_e32 v194, 0x3e38aa3b, v114
	v_fmac_f32_e32 v195, 0x3e38aa3b, v115
	v_lshl_add_u32 v79, v79, 2, s76
	v_lshl_add_u32 v78, v78, 2, s76
	v_lshl_add_u32 v81, v81, 2, s76
	v_lshl_add_u32 v80, v80, 2, s76
	v_lshl_add_u32 v82, v82, 2, s76
	v_med3_i32 v85, v84, s39, v198
	v_med3_i32 v84, v84, s33, v199
	v_fmac_f32_e32 v232, 0x3e38aa3b, v116
	v_fmac_f32_e32 v233, 0x3e38aa3b, v117
	v_lshl_add_u32 v83, v83, 2, s76
	v_lshl_add_u32 v85, v85, 2, s76
	v_lshl_add_u32 v84, v84, 2, s76
	ds_read_b32 v242, v79 offset:516
	ds_read_b32 v78, v78 offset:644
	ds_read_b32 v243, v81 offset:516
	ds_read_b32 v79, v80 offset:644
	ds_read_b32 v244, v83 offset:516
	ds_read_b32 v80, v82 offset:644
	ds_read_b32 v245, v85 offset:516
	ds_read_b32 v81, v84 offset:644
	v_max_f32_e32 v82, v194, v195
	v_fmac_f32_e32 v234, 0x3e38aa3b, v118
	s_waitcnt lgkmcnt(14)
; template <int MODE>
; __device__ __forceinline__ void partialSM(f32x16& p0, f32x16& p1, float& m_reg, float& mn, float& alpha, int relh, int relw_min, int relw_max, const float* lut) {
;     ...
;         p0[r] = fmaf(p0[r], C, lut[a0]); p1[r] = fmaf(p1[r], C, lut[a1]); }
;     } else {
; #pragma unroll
;       for (int r = 0; r < 16; ++r) { p0[r] = fmaf(p0[r], C, cfar); p1[r] = fmaf(p1[r], C, cfar); }
;     }
;     float pmax = p0[0];
; #pragma unroll
;     for (int r = 1; r < 16; ++r) pmax = fmaxf(pmax, p0[r]);
; #pragma unroll
;     for (int r = 0; r < 16; ++r) pmax = fmaxf(pmax, p1[r]);
;     { auto rr = __builtin_amdgcn_permlane32_swap(__float_as_uint(pmax), __float_as_uint(pmax), false, false);
;       pmax = fmaxf(__uint_as_float(rr[0]), __uint_as_float(rr[1])); }
;     if (__builtin_expect(__all(pmax - m_reg <= THR2), 1)) { mn = m_reg; alpha = 1.f; }
;     else { mn = fmaxf(m_reg, pmax); alpha = __builtin_amdgcn_exp2f(m_reg - mn); m_reg = mn; }
; #pragma unroll
;     for (int r = 0; r < 16; ++r) p0[r] = __builtin_amdgcn_exp2f(p0[r] - mn);
; #pragma unroll
;     for (int r = 0; r < 16; ++r) p1[r] = p1[r] - mn;
	v_fmac_f32_e32 v235, 0x3e38aa3b, v119
	v_max3_f32 v82, v82, v232, v233
	v_fmac_f32_e32 v236, 0x3e38aa3b, v120
	v_fmac_f32_e32 v237, 0x3e38aa3b, v121
	v_max3_f32 v82, v82, v234, v235
	v_fmac_f32_e32 v238, 0x3e38aa3b, v122
	s_waitcnt lgkmcnt(13)
	v_fmac_f32_e32 v239, 0x3e38aa3b, v123
	v_max3_f32 v82, v82, v236, v237
	s_waitcnt lgkmcnt(11)
	v_fmac_f32_e32 v240, 0x3e38aa3b, v124
	s_waitcnt lgkmcnt(9)
	v_fmac_f32_e32 v241, 0x3e38aa3b, v125
	v_max3_f32 v82, v82, v238, v239
	s_waitcnt lgkmcnt(7)
	v_fmac_f32_e32 v242, 0x3e38aa3b, v126
	s_waitcnt lgkmcnt(5)
	v_fmac_f32_e32 v243, 0x3e38aa3b, v127
	v_max3_f32 v82, v82, v240, v241
	s_waitcnt lgkmcnt(3)
	v_fmac_f32_e32 v244, 0x3e38aa3b, v128
	s_waitcnt lgkmcnt(1)
	v_fmac_f32_e32 v245, 0x3e38aa3b, v129
	v_max3_f32 v82, v82, v242, v243
	v_max3_f32 v84, v82, v244, v245
	v_pk_fma_f32 v[82:83], v[98:99], s[48:49], v[66:67] op_sel_hi:[1,0,1]
	v_pk_fma_f32 v[86:87], v[102:103], s[48:49], v[70:71] op_sel_hi:[1,0,1]
	v_max3_f32 v66, v84, v82, v83
	v_pk_fma_f32 v[84:85], v[100:101], s[48:49], v[68:69] op_sel_hi:[1,0,1]
	v_pk_fma_f32 v[88:89], v[104:105], s[48:49], v[72:73] op_sel_hi:[1,0,1]
	v_max3_f32 v66, v66, v84, v85
	v_max3_f32 v66, v66, v86, v87
	v_max3_f32 v66, v66, v88, v89
	v_pk_fma_f32 v[90:91], v[106:107], s[48:49], v[74:75] op_sel_hi:[1,0,1]
	v_pk_fma_f32 v[92:93], v[108:109], s[48:49], v[76:77] op_sel_hi:[1,0,1]
	v_max3_f32 v66, v66, v90, v91
	v_max3_f32 v66, v66, v92, v93
	v_pk_fma_f32 v[94:95], v[110:111], s[48:49], v[78:79] op_sel_hi:[1,0,1]
	s_waitcnt lgkmcnt(0)
	v_pk_fma_f32 v[96:97], v[112:113], s[48:49], v[80:81] op_sel_hi:[1,0,1]
	v_max3_f32 v66, v66, v94, v95
	v_max3_f32 v66, v66, v96, v97
	v_mov_b32_e32 v67, v66
	s_nop 1
	v_permlane32_swap_b32_e32 v66, v67
	v_max_f32_e32 v66, v66, v67
	v_sub_f32_e32 v67, v66, v222
	v_cmp_ge_f32_e32 vcc, s94, v67
	v_max_f32_e32 v66, v222, v66
	v_sub_f32_e32 v67, v222, v66
	v_exp_f32_e32 v67, v67
	s_cmp_eq_u64 vcc, exec
	s_cselect_b64 vcc, -1, 0
	v_cndmask_b32_e32 v231, v66, v222, vcc
	v_cndmask_b32_e64 v229, v67, 1.0, vcc
	v_sub_f32_e32 v66, v194, v231
	v_sub_f32_e32 v67, v195, v231
	v_sub_f32_e32 v68, v232, v231
	v_sub_f32_e32 v69, v233, v231
	v_sub_f32_e32 v70, v234, v231
	v_sub_f32_e32 v71, v235, v231
	v_sub_f32_e32 v72, v236, v231
	v_sub_f32_e32 v73, v237, v231
	v_sub_f32_e32 v74, v238, v231
	v_sub_f32_e32 v75, v239, v231
	v_sub_f32_e32 v76, v240, v231
	v_sub_f32_e32 v77, v241, v231
	v_sub_f32_e32 v78, v242, v231
	v_sub_f32_e32 v79, v243, v231
	v_sub_f32_e32 v80, v244, v231
	v_sub_f32_e32 v81, v245, v231
	v_exp_f32_e32 v66, v66
	v_exp_f32_e32 v67, v67
	v_exp_f32_e32 v68, v68
	v_exp_f32_e32 v69, v69
	v_exp_f32_e32 v70, v70
	v_exp_f32_e32 v71, v71
	v_exp_f32_e32 v72, v72
	v_exp_f32_e32 v73, v73
	v_exp_f32_e32 v74, v74
	v_exp_f32_e32 v75, v75
	v_exp_f32_e32 v76, v76
	v_exp_f32_e32 v77, v77
	v_exp_f32_e32 v78, v78
	v_exp_f32_e32 v79, v79
	v_exp_f32_e32 v80, v80
	v_exp_f32_e32 v81, v81
	v_sub_f32_e32 v97, v97, v231
	v_sub_f32_e32 v96, v96, v231
	v_sub_f32_e32 v95, v95, v231
	v_sub_f32_e32 v94, v94, v231
	v_sub_f32_e32 v93, v93, v231
	v_sub_f32_e32 v92, v92, v231
	v_sub_f32_e32 v91, v91, v231
	v_sub_f32_e32 v90, v90, v231
	v_sub_f32_e32 v89, v89, v231
	v_sub_f32_e32 v88, v88, v231
	v_sub_f32_e32 v87, v87, v231
	v_sub_f32_e32 v86, v86, v231
	v_sub_f32_e32 v85, v85, v231
	v_sub_f32_e32 v84, v84, v231
	v_sub_f32_e32 v83, v83, v231
	v_sub_f32_e32 v82, v82, v231
	s_xor_b64 s[62:63], exec, -1

; #define SBAR() __builtin_amdgcn_sched_barrier(0)
; #define SLOAD(i, k0) do { sr_[i].vs0 = *reinterpret_cast<const bf16x8*>(&Vh[(size_t)((k0) + sr) * LDQK + sc]); sr_[i].vs1 = *reinterpret_cast<const bf16x8*>(&Vh[(size_t)((k0) + 32 + sr) * LDQK + sc]); \
;     sr_[i].ks0 = *reinterpret_cast<const bf16x8*>(&Kh[(size_t)((k0) + sr) * LDQK + sc]); sr_[i].ks1 = *reinterpret_cast<const bf16x8*>(&Kh[(size_t)((k0) + 32 + sr) * LDQK + sc]); } while (0)
; #define SWAIT() asm volatile("s_waitcnt vmcnt(4)" ::: "memory")
; __device__ __forceinline__ void finishSM(f32x16& p0, f32x16& p1, float alpha, float& l_reg, bf16x8& pa0, bf16x8& pa1, bf16x8& pa2, bf16x8& pa3) {
; #pragma unroll
;   for (int r = 0; r < 16; ++r) p1[r] = __builtin_amdgcn_exp2f(p1[r]);
;   float ps = 0;
; #pragma unroll
;   for (int r = 0; r < 16; ++r) ps += p0[r];
; #pragma unroll
;   for (int r = 0; r < 16; ++r) ps += p1[r];
;   { auto rr = __builtin_amdgcn_permlane32_swap(__float_as_uint(ps), __float_as_uint(ps), false, false);
;     ps = __uint_as_float(rr[0]) + __uint_as_float(rr[1]); }
;   l_reg = l_reg * alpha + ps;
;     ...
;   PK4(p0, 0, pa0); PK4(p0, 8, pa1); PK4(p1, 0, pa2); PK4(p1, 8, pa3);
;     ...
; }
; template <int ND0, int DOFF>
; __device__ __forceinline__ void qkt(f32x16& p0, f32x16& p1, const char* Ks, const bf16x8* qr, int r32, int hi) {
;   p0 = f32x16{}; p1 = f32x16{};
; #pragma unroll
;   for (int d0 = 0; d0 < ND0; ++d0) { const int cb = ((d0 + DOFF) * 16 + hi * 8) * 2;
;     bf16x8 b0 = *reinterpret_cast<const bf16x8*>(Ks + KSWZ(r32, cb));
;     bf16x8 b1 = *reinterpret_cast<const bf16x8*>(Ks + KSWZ(32 + r32, cb));
;     p0 = __builtin_amdgcn_mfma_f32_32x32x16_bf16(b0, qr[d0], p0, 0, 0, 0);
;     p1 = __builtin_amdgcn_mfma_f32_32x32x16_bf16(b1, qr[d0], p1, 0, 0, 0); }
; template <int MODE>
; __device__ __forceinline__ void attn_body(const bf16_t* __restrict__ Qb, const bf16_t* __restrict__ Kh, const bf16_t* __restrict__ Vh, int NT, int krel0,
;                                           char* lds, const float* __restrict__ lutg, const AttnEpi& E) {
;     ...
;   for (int j = 1; j + 1 < NT; j += 2) {
;     __syncthreads();
;     SBAR(); qkt<ND0, DOFF>(pB0, pB1, K_lds + oq, qr, r32, hi);
;     finishSM(pA0, pA1, alA, l_reg, pa0, pa1, pa2, pa3); SBAR();
;     SLOAD(SO, (j + 2) * 64); SBAR();
;     pv_d0(o, vb0 + op, pa0, pa1, pa2, pa3); PSM(pB0, pB1, mnB, alB, j);
;     SWAIT(); SWRITE(ow, SE);
.Ldp_10:
	v_add_u32_e32 v102, s58, v216
	ds_read_b128 v[98:101], v102 offset:49152
	ds_read_b128 v[102:105], v102 offset:57344
	v_add_u32_e32 v194, s58, v217
	ds_read_b128 v[232:235], v194 offset:49152
	ds_read_b128 v[236:239], v194 offset:57344
	v_add_u32_e32 v194, s58, v218
	s_waitcnt lgkmcnt(3)
	v_mfma_f32_32x32x16_bf16 v[114:129], v[98:101], v[142:145], 0
	v_exp_f32_e32 v82, v82
	v_exp_f32_e32 v83, v83
	v_exp_f32_e32 v84, v84
	v_exp_f32_e32 v85, v85
	v_exp_f32_e32 v86, v86
	v_exp_f32_e32 v87, v87
	v_exp_f32_e32 v88, v88
	s_waitcnt lgkmcnt(2)
	v_mfma_f32_32x32x16_bf16 v[98:113], v[102:105], v[142:145], 0
	v_exp_f32_e32 v89, v89
	v_exp_f32_e32 v90, v90
	v_exp_f32_e32 v91, v91
	v_exp_f32_e32 v92, v92
	v_exp_f32_e32 v93, v93
	v_exp_f32_e32 v94, v94
	v_exp_f32_e32 v95, v95
	s_waitcnt lgkmcnt(1)
	v_mfma_f32_32x32x16_bf16 v[114:129], v[232:235], v[138:141], v[114:129]
	v_exp_f32_e32 v96, v96
	v_exp_f32_e32 v97, v97
	s_waitcnt lgkmcnt(0)
	v_mfma_f32_32x32x16_bf16 v[98:113], v[236:239], v[138:141], v[98:113]
	ds_read_b128 v[232:235], v194 offset:49152
	ds_read_b128 v[236:239], v194 offset:57344
	v_add_u32_e32 v194, s58, v219
	s_waitcnt lgkmcnt(1)
	v_mfma_f32_32x32x16_bf16 v[114:129], v[232:235], v[134:137], v[114:129]
	s_waitcnt lgkmcnt(0)
	v_mfma_f32_32x32x16_bf16 v[98:113], v[236:239], v[134:137], v[98:113]
	ds_read_b128 v[232:235], v194 offset:49152
	ds_read_b128 v[236:239], v194 offset:57344
	v_add_f32_e32 v194, v67, v66
	v_add_f32_e32 v194, v68, v194
	v_add_f32_e32 v194, v69, v194
	v_add_f32_e32 v194, v70, v194
	v_add_f32_e32 v194, v71, v194
	v_add_f32_e32 v194, v72, v194
	v_add_f32_e32 v194, v73, v194
	v_add_f32_e32 v194, v74, v194
	v_add_f32_e32 v194, v75, v194
	v_add_f32_e32 v194, v76, v194
	v_add_f32_e32 v194, v77, v194
	v_add_f32_e32 v194, v78, v194
	v_add_f32_e32 v194, v79, v194
	v_add_f32_e32 v194, v80, v194
	v_add_f32_e32 v194, v81, v194
	v_add_f32_e32 v194, v82, v194
	v_add_f32_e32 v194, v83, v194
	v_add_f32_e32 v194, v84, v194
	v_add_f32_e32 v194, v85, v194
	v_add_f32_e32 v194, v86, v194
	v_add_f32_e32 v194, v87, v194
	v_add_f32_e32 v194, v88, v194
	v_add_f32_e32 v194, v89, v194
	v_add_f32_e32 v194, v90, v194
	v_add_f32_e32 v194, v91, v194
	s_waitcnt lgkmcnt(1)
	v_mfma_f32_32x32x16_bf16 v[114:129], v[232:235], v[130:133], v[114:129]
	v_add_f32_e32 v194, v92, v194
	v_add_f32_e32 v194, v93, v194
	v_add_f32_e32 v194, v94, v194
	v_add_f32_e32 v194, v95, v194
	v_add_f32_e32 v194, v96, v194
	v_add_f32_e32 v232, v97, v194
	v_mov_b32_e32 v233, v232
	s_waitcnt lgkmcnt(0)
	v_mfma_f32_32x32x16_bf16 v[98:113], v[236:239], v[130:133], v[98:113]
	v_cvt_pk_bf16_f32 v66, v66, v67
	v_cvt_pk_bf16_f32 v67, v68, v69
	v_cvt_pk_bf16_f32 v68, v70, v71
	v_cvt_pk_bf16_f32 v69, v72, v73
	v_cvt_pk_bf16_f32 v70, v74, v75
	v_cvt_pk_bf16_f32 v71, v76, v77
	v_cvt_pk_bf16_f32 v72, v78, v79
	v_cvt_pk_bf16_f32 v73, v80, v81
	v_cvt_pk_bf16_f32 v74, v82, v83
	v_cvt_pk_bf16_f32 v75, v84, v85
	v_cvt_pk_bf16_f32 v76, v86, v87
	v_cvt_pk_bf16_f32 v77, v88, v89
	v_cvt_pk_bf16_f32 v78, v90, v91
	v_cvt_pk_bf16_f32 v79, v92, v93
	v_cvt_pk_bf16_f32 v80, v94, v95
	v_cvt_pk_bf16_f32 v81, v96, v97
	v_permlane32_swap_b32_e32 v232, v233
	v_permlane32_swap_b32_e32 v66, v68
	v_permlane32_swap_b32_e32 v67, v69
	v_permlane32_swap_b32_e32 v70, v72
	v_permlane32_swap_b32_e32 v71, v73
	v_permlane32_swap_b32_e32 v74, v76
	v_permlane32_swap_b32_e32 v75, v77
	v_permlane32_swap_b32_e32 v78, v80
	v_permlane32_swap_b32_e32 v79, v81
	s_add_i32 s67, s67, 2
	s_cmp_ge_u32 s67, s11
	s_cselect_b64 s[0:1], -1, 0
	s_cmp_lt_u32 s31, 4
	s_cbranch_scc1 .Ldp_9
	s_waitcnt vmcnt(2) lgkmcnt(0)
	s_barrier
.Ldp_9:
	s_setprio 0
	s_add_i32 m0, s68, s30
	s_add_i32 m0, m0, 0xc000
	s_nop 0
	global_load_lds_dwordx4 v250, s[28:29]
	s_add_i32 m0, m0, 0x400
	s_nop 0
	global_load_lds_dwordx4 v251, s[28:29]
	s_add_i32 m0, s66, s30
	s_nop 0
	global_load_lds_dwordx4 v248, s[26:27]
	s_add_i32 m0, m0, 0x400
	s_nop 0
	global_load_lds_dwordx4 v249, s[26:27]
	s_add_u32 s26, s26, 0x90000
	s_addc_u32 s27, s27, 0
	s_add_u32 s28, s28, 0x90000
	s_addc_u32 s29, s29, 0
